# xor-16/32 butterfly steps via v_permlane16/32_swap instead of ds_bpermute (134 sites) on top of previous
# speedup vs baseline: 1.0380x; 1.0030x over previous
.LBB0_92:
	s_waitcnt lgkmcnt(0)
	global_load_dwordx4 v[10:13], v7, s[2:3]
	global_load_dwordx4 v[14:17], v7, s[34:35]
	global_load_dwordx4 v[18:21], v7, s[2:3] offset:1024
	global_load_dwordx4 v[22:25], v7, s[34:35] offset:1024
	global_load_dwordx4 v[26:29], v7, s[2:3] offset:2048
	global_load_dwordx4 v[30:33], v7, s[34:35] offset:2048
	global_load_dwordx4 v[34:37], v7, s[2:3] offset:3072
	global_load_dwordx4 v[38:41], v7, s[34:35] offset:3072
	s_waitcnt vmcnt(7)
	v_cvt_pk_bf16_f32 v42, v10, v11
	v_mul_f32_e32 v9, v11, v11
	v_mul_f32_e32 v44, v13, v13
	s_waitcnt vmcnt(6)
	v_mul_f32_e32 v45, v15, v15
	v_mul_f32_e32 v46, v17, v17
	s_waitcnt vmcnt(5)
	v_mul_f32_e32 v47, v19, v19
	v_mul_f32_e32 v48, v21, v21
	s_waitcnt vmcnt(4)
	v_mul_f32_e32 v49, v23, v23
	v_mul_f32_e32 v50, v25, v25
	s_waitcnt vmcnt(3)
	v_mul_f32_e32 v51, v27, v27
	v_mul_f32_e32 v52, v29, v29
	s_waitcnt vmcnt(2)
	v_mul_f32_e32 v53, v31, v31
	v_mul_f32_e32 v54, v33, v33
	v_fmac_f32_e32 v9, v10, v10
	v_fmac_f32_e32 v44, v12, v12
	v_fmac_f32_e32 v45, v14, v14
	v_fmac_f32_e32 v46, v16, v16
	v_fmac_f32_e32 v47, v18, v18
	v_fmac_f32_e32 v48, v20, v20
	v_fmac_f32_e32 v49, v22, v22
	v_fmac_f32_e32 v50, v24, v24
	s_waitcnt vmcnt(1)
	v_mul_f32_e32 v55, v35, v35
	v_mul_f32_e32 v56, v37, v37
	s_waitcnt vmcnt(0)
	v_mul_f32_e32 v57, v39, v39
	v_mul_f32_e32 v58, v41, v41
	v_cvt_pk_bf16_f32 v43, v12, v13
	v_fmac_f32_e32 v51, v26, v26
	v_fmac_f32_e32 v52, v28, v28
	v_fmac_f32_e32 v53, v30, v30
	v_fmac_f32_e32 v54, v32, v32
	v_add_f32_e32 v9, v9, v44
	v_add_f32_e32 v11, v45, v46
	v_add_f32_e32 v12, v47, v48
	v_add_f32_e32 v13, v49, v50
	v_fmac_f32_e32 v55, v34, v34
	v_fmac_f32_e32 v56, v36, v36
	v_fmac_f32_e32 v57, v38, v38
	v_fmac_f32_e32 v58, v40, v40
	global_store_dwordx2 v8, v[42:43], s[28:29]
	v_cvt_pk_bf16_f32 v10, v14, v15
	v_add_f32_e32 v14, v51, v52
	v_add_f32_e32 v15, v53, v54
	v_add_f32_e32 v9, v9, v12
	v_add_f32_e32 v11, v11, v13
	v_add_f32_e32 v42, v55, v56
	v_add_f32_e32 v43, v57, v58
	v_add_f32_e32 v9, v9, v14
	v_add_f32_e32 v11, v11, v15
	v_add_f32_e32 v9, v9, v42
	v_add_f32_e32 v12, v11, v43
	v_cvt_pk_bf16_f32 v11, v16, v17
	global_store_dwordx2 v8, v[10:11], s[30:31]
	v_cvt_pk_bf16_f32 v10, v18, v19
	s_waitcnt lgkmcnt(1)
	s_nop 1
	v_add_f32_dpp v9, v9, v9 quad_perm:[1,0,3,2] row_mask:0xf bank_mask:0xf
	s_waitcnt lgkmcnt(0)
	s_nop 1
	v_add_f32_dpp v12, v12, v12 quad_perm:[1,0,3,2] row_mask:0xf bank_mask:0xf
	v_cvt_pk_bf16_f32 v11, v20, v21
	global_store_dwordx2 v8, v[10:11], s[28:29] offset:512
	v_cvt_pk_bf16_f32 v10, v22, v23
	s_waitcnt lgkmcnt(1)
	s_nop 1
	v_add_f32_dpp v9, v9, v9 quad_perm:[2,3,0,1] row_mask:0xf bank_mask:0xf
	s_waitcnt lgkmcnt(0)
	s_nop 1
	v_add_f32_dpp v12, v12, v12 quad_perm:[2,3,0,1] row_mask:0xf bank_mask:0xf
	v_cvt_pk_bf16_f32 v11, v24, v25
	global_store_dwordx2 v8, v[10:11], s[30:31] offset:512
	v_cvt_pk_bf16_f32 v10, v26, v27
	s_waitcnt lgkmcnt(1)
	s_nop 1
	v_add_f32_dpp v9, v9, v9 row_half_mirror row_mask:0xf bank_mask:0xf
	s_waitcnt lgkmcnt(0)
	s_nop 1
	v_add_f32_dpp v12, v12, v12 row_half_mirror row_mask:0xf bank_mask:0xf
	v_cvt_pk_bf16_f32 v11, v28, v29
	global_store_dwordx2 v8, v[10:11], s[28:29] offset:1024
	v_cvt_pk_bf16_f32 v10, v30, v31
	s_waitcnt lgkmcnt(1)
	s_nop 1
	v_add_f32_dpp v9, v9, v9 row_mirror row_mask:0xf bank_mask:0xf
	s_waitcnt lgkmcnt(0)
	s_nop 1
	v_add_f32_dpp v12, v12, v12 row_mirror row_mask:0xf bank_mask:0xf
	v_mov_b32_e32 v13, v9
	s_nop 1
	v_permlane16_swap_b32_e32 v13, v9
	v_mov_b32_e32 v15, v12
	s_nop 1
	v_permlane16_swap_b32_e32 v15, v12
	v_cvt_pk_bf16_f32 v11, v32, v33
	global_store_dwordx2 v8, v[10:11], s[30:31] offset:1024
	v_cvt_pk_bf16_f32 v14, v34, v35
	s_waitcnt lgkmcnt(1)
	v_add_f32_e32 v9, v9, v13
	s_waitcnt lgkmcnt(0)
	v_add_f32_e32 v11, v12, v15
	v_mov_b32_e32 v10, v9
	s_nop 1
	v_permlane32_swap_b32_e32 v10, v9
	v_mov_b32_e32 v12, v11
	s_nop 1
	v_permlane32_swap_b32_e32 v12, v11
	v_cvt_pk_bf16_f32 v15, v36, v37
	global_store_dwordx2 v8, v[14:15], s[28:29] offset:1536
	v_cvt_pk_bf16_f32 v14, v38, v39
	v_cvt_pk_bf16_f32 v15, v40, v41
	global_store_dwordx2 v8, v[14:15], s[30:31] offset:1536
	s_and_saveexec_b64 s[2:3], s[0:1]
	s_cbranch_execz .LBB0_83
	s_waitcnt lgkmcnt(1)
	v_add_f32_e32 v9, v9, v10
	s_waitcnt lgkmcnt(0)
	v_add_f32_e32 v11, v11, v12
	v_mul_f32_e32 v9, 0x4b800000, v9
	v_mul_f32_e32 v10, 0x4b800000, v11
	v_trunc_f32_e32 v9, v9
	v_trunc_f32_e32 v10, v10
	v_mul_f32_e32 v12, 0x2f800000, v9
	v_mul_f32_e32 v11, 0x2f800000, v10
	v_floor_f32_e32 v13, v12
	v_floor_f32_e32 v11, v11
	v_fmac_f32_e32 v9, 0xcf800000, v13
	v_fmac_f32_e32 v10, 0xcf800000, v11
	v_cvt_u32_f32_e32 v12, v9
	v_cvt_u32_f32_e32 v13, v13
	v_cvt_u32_f32_e32 v10, v10
	v_cvt_u32_f32_e32 v11, v11
	global_store_dwordx2 v0, v[12:13], s[26:27]
	global_store_dwordx2 v0, v[10:11], s[6:7]
	s_branch .LBB0_83

.LBB0_740:
	s_or_b64 exec, exec, s[2:3]
	s_waitcnt lgkmcnt(0)
	s_barrier
	ds_read_b64 v[0:1], v33 offset:672
	v_readlane_b32 s72, v251, 1
	v_readlane_b32 s76, v251, 5
	v_readlane_b32 s77, v251, 6
	v_mov_b32_e32 v85, v33
	s_waitcnt lgkmcnt(0)
	v_lshl_add_u32 v2, v0, 7, v82
	v_ashrrev_i32_e32 v3, 31, v2
	v_lshlrev_b64 v[94:95], 11, v[2:3]
	v_lshl_add_u64 v[2:3], s[76:77], 0, v[94:95]
	v_lshl_add_u64 v[2:3], v[2:3], 0, s[8:9]
	v_lshl_add_u64 v[2:3], v[2:3], 0, v[84:85]
	s_mov_b32 s2, 0x8000
	v_add_co_u32_e32 v4, vcc, s2, v2
	s_mov_b32 s3, 0x10000
	s_nop 0
	v_addc_co_u32_e32 v5, vcc, 0, v3, vcc
	global_load_dwordx4 v[62:65], v[2:3], off
	global_load_dwordx4 v[54:57], v[4:5], off
	v_add_co_u32_e32 v4, vcc, s3, v2
	s_mov_b32 s11, 0x18000
	s_nop 0
	v_addc_co_u32_e32 v5, vcc, 0, v3, vcc
	v_add_co_u32_e32 v6, vcc, s11, v2
	s_mov_b32 s16, 0x28000
	s_nop 0
	v_addc_co_u32_e32 v7, vcc, 0, v3, vcc
	global_load_dwordx4 v[46:49], v[4:5], off
	global_load_dwordx4 v[38:41], v[6:7], off
	v_add_co_u32_e32 v4, vcc, s12, v2
	s_mov_b32 s18, 0x30000
	s_nop 0
	v_addc_co_u32_e32 v5, vcc, 0, v3, vcc
	v_add_co_u32_e32 v6, vcc, s16, v2
	v_lshl_add_u32 v0, v1, 7, v82
	s_nop 0
	v_addc_co_u32_e32 v7, vcc, 0, v3, vcc
	global_load_dwordx4 v[34:37], v[4:5], off
	global_load_dwordx4 v[24:27], v[6:7], off
	v_add_co_u32_e32 v4, vcc, s18, v2
	s_mov_b32 s19, 0x38000
	s_nop 0
	v_addc_co_u32_e32 v5, vcc, 0, v3, vcc
	v_ashrrev_i32_e32 v1, 31, v0
	v_add_co_u32_e32 v2, vcc, s19, v2
	v_lshl_add_u64 v[74:75], v[86:87], 0, s[8:9]
	v_lshlrev_b64 v[0:1], 11, v[0:1]
	v_addc_co_u32_e32 v3, vcc, 0, v3, vcc
	v_lshl_add_u64 v[0:1], v[74:75], 0, v[0:1]
	global_load_dwordx4 v[16:19], v[4:5], off
	global_load_dwordx4 v[8:11], v[2:3], off
	v_add_co_u32_e32 v2, vcc, s2, v0
	v_readlane_b32 s73, v251, 2
	s_nop 0
	v_addc_co_u32_e32 v3, vcc, 0, v1, vcc
	global_load_dwordx4 v[66:69], v[0:1], off
	global_load_dwordx4 v[58:61], v[2:3], off
	v_add_co_u32_e32 v2, vcc, s3, v0
	v_readlane_b32 s74, v251, 3
	s_nop 0
	v_addc_co_u32_e32 v3, vcc, 0, v1, vcc
	v_add_co_u32_e32 v4, vcc, s11, v0
	v_readlane_b32 s75, v251, 4
	s_nop 0
	v_addc_co_u32_e32 v5, vcc, 0, v1, vcc
	global_load_dwordx4 v[50:53], v[2:3], off
	global_load_dwordx4 v[42:45], v[4:5], off
	v_add_co_u32_e32 v2, vcc, s12, v0
	v_readlane_b32 s78, v251, 7
	s_nop 0
	v_addc_co_u32_e32 v3, vcc, 0, v1, vcc
	v_add_co_u32_e32 v4, vcc, s16, v0
	v_readlane_b32 s79, v251, 8
	s_nop 0
	v_addc_co_u32_e32 v5, vcc, 0, v1, vcc
	global_load_dwordx4 v[28:31], v[2:3], off
	global_load_dwordx4 v[20:23], v[4:5], off
	v_add_co_u32_e32 v2, vcc, s18, v0
	v_readlane_b32 s80, v251, 9
	s_nop 0
	v_addc_co_u32_e32 v3, vcc, 0, v1, vcc
	v_add_co_u32_e32 v0, vcc, s19, v0
	v_readlane_b32 s81, v251, 10
	s_nop 0
	v_addc_co_u32_e32 v1, vcc, 0, v1, vcc
	global_load_dwordx4 v[12:15], v[2:3], off
	global_load_dwordx4 v[4:7], v[0:1], off
	v_add_u32_e32 v0, 0, v84
	ds_read_b128 v[0:3], v0
	v_readlane_b32 s82, v251, 11
	v_readlane_b32 s83, v251, 12
	v_readlane_b32 s84, v251, 13
	v_readlane_b32 s85, v251, 14
	s_waitcnt vmcnt(15) lgkmcnt(0)
	v_mul_f32_e32 v63, v1, v63
	v_fmac_f32_e32 v63, v0, v62
	v_fmac_f32_e32 v63, v2, v64
	v_fmac_f32_e32 v63, v3, v65
	v_readlane_b32 s86, v251, 15
	v_readlane_b32 s87, v251, 16
	s_waitcnt lgkmcnt(0)
	s_nop 1
	v_add_f32_dpp v62, v63, v63 quad_perm:[1,0,3,2] row_mask:0xf bank_mask:0xf
	s_waitcnt lgkmcnt(0)
	s_nop 1
	v_add_f32_dpp v62, v62, v62 quad_perm:[2,3,0,1] row_mask:0xf bank_mask:0xf
	s_waitcnt lgkmcnt(0)
	s_nop 1
	v_add_f32_dpp v62, v62, v62 row_half_mirror row_mask:0xf bank_mask:0xf
	s_waitcnt lgkmcnt(0)
	s_nop 1
	v_add_f32_dpp v62, v62, v62 row_mirror row_mask:0xf bank_mask:0xf
	v_mov_b32_e32 v63, v62
	s_nop 1
	v_permlane16_swap_b32_e32 v63, v62
	s_and_saveexec_b64 s[2:3], s[44:45]
	s_cbranch_execz .LBB0_742
	s_waitcnt lgkmcnt(0)
	v_add_f32_e32 v62, v62, v63
	ds_write_b32 v102, v62 offset:1024
.LBB0_742:
	s_or_b64 exec, exec, s[2:3]
	s_waitcnt vmcnt(14)
	v_mul_f32_e32 v55, v1, v55
	v_fmac_f32_e32 v55, v0, v54
	v_fmac_f32_e32 v55, v2, v56
	v_fmac_f32_e32 v55, v3, v57
	s_waitcnt lgkmcnt(0)
	s_nop 1
	v_add_f32_dpp v54, v55, v55 quad_perm:[1,0,3,2] row_mask:0xf bank_mask:0xf
	s_waitcnt lgkmcnt(0)
	s_nop 1
	v_add_f32_dpp v54, v54, v54 quad_perm:[2,3,0,1] row_mask:0xf bank_mask:0xf
	s_waitcnt lgkmcnt(0)
	s_nop 1
	v_add_f32_dpp v54, v54, v54 row_half_mirror row_mask:0xf bank_mask:0xf
	s_waitcnt lgkmcnt(0)
	s_nop 1
	v_add_f32_dpp v54, v54, v54 row_mirror row_mask:0xf bank_mask:0xf
	v_mov_b32_e32 v55, v54
	s_nop 1
	v_permlane16_swap_b32_e32 v55, v54
	s_and_saveexec_b64 s[2:3], s[44:45]
	s_cbranch_execz .LBB0_744
	s_waitcnt lgkmcnt(0)
	v_add_f32_e32 v54, v54, v55
	ds_write_b32 v102, v54 offset:1088
.LBB0_744:
	s_or_b64 exec, exec, s[2:3]
	s_waitcnt vmcnt(13)
	v_mul_f32_e32 v47, v1, v47
	v_fmac_f32_e32 v47, v0, v46
	v_fmac_f32_e32 v47, v2, v48
	v_fmac_f32_e32 v47, v3, v49
	s_waitcnt lgkmcnt(0)
	s_nop 1
	v_add_f32_dpp v46, v47, v47 quad_perm:[1,0,3,2] row_mask:0xf bank_mask:0xf
	s_waitcnt lgkmcnt(0)
	s_nop 1
	v_add_f32_dpp v46, v46, v46 quad_perm:[2,3,0,1] row_mask:0xf bank_mask:0xf
	s_waitcnt lgkmcnt(0)
	s_nop 1
	v_add_f32_dpp v46, v46, v46 row_half_mirror row_mask:0xf bank_mask:0xf
	s_waitcnt lgkmcnt(0)
	s_nop 1
	v_add_f32_dpp v46, v46, v46 row_mirror row_mask:0xf bank_mask:0xf
	v_mov_b32_e32 v47, v46
	s_nop 1
	v_permlane16_swap_b32_e32 v47, v46
	s_and_saveexec_b64 s[2:3], s[44:45]
	s_cbranch_execz .LBB0_746
	s_waitcnt lgkmcnt(0)
	v_add_f32_e32 v46, v46, v47
	ds_write_b32 v102, v46 offset:1152
.LBB0_746:
	s_or_b64 exec, exec, s[2:3]
	s_waitcnt vmcnt(12)
	v_mul_f32_e32 v39, v1, v39
	v_fmac_f32_e32 v39, v0, v38
	v_fmac_f32_e32 v39, v2, v40
	v_fmac_f32_e32 v39, v3, v41
	s_waitcnt lgkmcnt(0)
	s_nop 1
	v_add_f32_dpp v38, v39, v39 quad_perm:[1,0,3,2] row_mask:0xf bank_mask:0xf
	s_waitcnt lgkmcnt(0)
	s_nop 1
	v_add_f32_dpp v38, v38, v38 quad_perm:[2,3,0,1] row_mask:0xf bank_mask:0xf
	s_waitcnt lgkmcnt(0)
	s_nop 1
	v_add_f32_dpp v38, v38, v38 row_half_mirror row_mask:0xf bank_mask:0xf
	s_waitcnt lgkmcnt(0)
	s_nop 1
	v_add_f32_dpp v38, v38, v38 row_mirror row_mask:0xf bank_mask:0xf
	v_mov_b32_e32 v39, v38
	s_nop 1
	v_permlane16_swap_b32_e32 v39, v38
	s_and_saveexec_b64 s[2:3], s[44:45]
	s_cbranch_execz .LBB0_748
	s_waitcnt lgkmcnt(0)
	v_add_f32_e32 v38, v38, v39
	ds_write_b32 v102, v38 offset:1216
.LBB0_748:
	s_or_b64 exec, exec, s[2:3]
	s_waitcnt vmcnt(11)
	v_mul_f32_e32 v35, v1, v35
	v_fmac_f32_e32 v35, v0, v34
	v_fmac_f32_e32 v35, v2, v36
	v_fmac_f32_e32 v35, v3, v37
	s_waitcnt lgkmcnt(0)
	s_nop 1
	v_add_f32_dpp v34, v35, v35 quad_perm:[1,0,3,2] row_mask:0xf bank_mask:0xf
	s_waitcnt lgkmcnt(0)
	s_nop 1
	v_add_f32_dpp v34, v34, v34 quad_perm:[2,3,0,1] row_mask:0xf bank_mask:0xf
	s_waitcnt lgkmcnt(0)
	s_nop 1
	v_add_f32_dpp v34, v34, v34 row_half_mirror row_mask:0xf bank_mask:0xf
	s_waitcnt lgkmcnt(0)
	s_nop 1
	v_add_f32_dpp v34, v34, v34 row_mirror row_mask:0xf bank_mask:0xf
	v_mov_b32_e32 v35, v34
	s_nop 1
	v_permlane16_swap_b32_e32 v35, v34
	s_and_saveexec_b64 s[2:3], s[44:45]
	s_cbranch_execz .LBB0_750
	s_waitcnt lgkmcnt(0)
	v_add_f32_e32 v34, v34, v35
	ds_write_b32 v102, v34 offset:1280
.LBB0_750:
	s_or_b64 exec, exec, s[2:3]
	s_waitcnt vmcnt(10)
	v_mul_f32_e32 v25, v1, v25
	v_fmac_f32_e32 v25, v0, v24
	v_fmac_f32_e32 v25, v2, v26
	v_fmac_f32_e32 v25, v3, v27
	s_waitcnt lgkmcnt(0)
	s_nop 1
	v_add_f32_dpp v24, v25, v25 quad_perm:[1,0,3,2] row_mask:0xf bank_mask:0xf
	s_waitcnt lgkmcnt(0)
	s_nop 1
	v_add_f32_dpp v24, v24, v24 quad_perm:[2,3,0,1] row_mask:0xf bank_mask:0xf
	s_waitcnt lgkmcnt(0)
	s_nop 1
	v_add_f32_dpp v24, v24, v24 row_half_mirror row_mask:0xf bank_mask:0xf
	s_waitcnt lgkmcnt(0)
	s_nop 1
	v_add_f32_dpp v24, v24, v24 row_mirror row_mask:0xf bank_mask:0xf
	v_mov_b32_e32 v25, v24
	s_nop 1
	v_permlane16_swap_b32_e32 v25, v24
	s_and_saveexec_b64 s[2:3], s[44:45]
	s_cbranch_execz .LBB0_752
	s_waitcnt lgkmcnt(0)
	v_add_f32_e32 v24, v24, v25
	ds_write_b32 v102, v24 offset:1344
.LBB0_752:
	s_or_b64 exec, exec, s[2:3]
	s_waitcnt vmcnt(9)
	v_mul_f32_e32 v17, v1, v17
	v_fmac_f32_e32 v17, v0, v16
	v_fmac_f32_e32 v17, v2, v18
	v_fmac_f32_e32 v17, v3, v19
	s_waitcnt lgkmcnt(0)
	s_nop 1
	v_add_f32_dpp v16, v17, v17 quad_perm:[1,0,3,2] row_mask:0xf bank_mask:0xf
	s_waitcnt lgkmcnt(0)
	s_nop 1
	v_add_f32_dpp v16, v16, v16 quad_perm:[2,3,0,1] row_mask:0xf bank_mask:0xf
	s_waitcnt lgkmcnt(0)
	s_nop 1
	v_add_f32_dpp v16, v16, v16 row_half_mirror row_mask:0xf bank_mask:0xf
	s_waitcnt lgkmcnt(0)
	s_nop 1
	v_add_f32_dpp v16, v16, v16 row_mirror row_mask:0xf bank_mask:0xf
	v_mov_b32_e32 v17, v16
	s_nop 1
	v_permlane16_swap_b32_e32 v17, v16
	s_and_saveexec_b64 s[2:3], s[44:45]
	s_cbranch_execz .LBB0_754
	s_waitcnt lgkmcnt(0)
	v_add_f32_e32 v16, v16, v17
	ds_write_b32 v102, v16 offset:1408
.LBB0_754:
	s_or_b64 exec, exec, s[2:3]
	s_waitcnt vmcnt(8)
	v_mul_f32_e32 v9, v1, v9
	v_fmac_f32_e32 v9, v0, v8
	v_fmac_f32_e32 v9, v2, v10
	v_fmac_f32_e32 v9, v3, v11
	s_waitcnt lgkmcnt(0)
	s_nop 1
	v_add_f32_dpp v8, v9, v9 quad_perm:[1,0,3,2] row_mask:0xf bank_mask:0xf
	s_waitcnt lgkmcnt(0)
	s_nop 1
	v_add_f32_dpp v8, v8, v8 quad_perm:[2,3,0,1] row_mask:0xf bank_mask:0xf
	s_waitcnt lgkmcnt(0)
	s_nop 1
	v_add_f32_dpp v8, v8, v8 row_half_mirror row_mask:0xf bank_mask:0xf
	s_waitcnt lgkmcnt(0)
	s_nop 1
	v_add_f32_dpp v8, v8, v8 row_mirror row_mask:0xf bank_mask:0xf
	v_mov_b32_e32 v9, v8
	s_nop 1
	v_permlane16_swap_b32_e32 v9, v8
	s_and_saveexec_b64 s[2:3], s[44:45]
	s_cbranch_execz .LBB0_756
	s_waitcnt lgkmcnt(0)
	v_add_f32_e32 v8, v8, v9
	ds_write_b32 v102, v8 offset:1472
.LBB0_756:
	s_or_b64 exec, exec, s[2:3]
	ds_read_b32 v8, v33 offset:680
	s_waitcnt vmcnt(7)
	v_mul_f32_e32 v67, v1, v67
	v_fmac_f32_e32 v67, v0, v66
	v_fmac_f32_e32 v67, v2, v68
	v_fmac_f32_e32 v67, v3, v69
	s_waitcnt lgkmcnt(0)
	v_lshl_add_u32 v8, v8, 7, v82
	v_ashrrev_i32_e32 v9, 31, v8
	v_lshlrev_b64 v[8:9], 11, v[8:9]
	v_lshl_add_u64 v[8:9], v[74:75], 0, v[8:9]
	v_add_co_u32_e32 v10, vcc, 0x8000, v8
	s_nop 0
	v_addc_co_u32_e32 v11, vcc, 0, v9, vcc
	global_load_dwordx4 v[62:65], v[8:9], off
	global_load_dwordx4 v[54:57], v[10:11], off
	v_add_co_u32_e32 v10, vcc, 0x10000, v8
	s_waitcnt lgkmcnt(0)
	s_nop 1
	v_add_f32_dpp v66, v67, v67 quad_perm:[1,0,3,2] row_mask:0xf bank_mask:0xf
	v_addc_co_u32_e32 v11, vcc, 0, v9, vcc
	v_add_co_u32_e32 v16, vcc, 0x18000, v8
	s_nop 0
	v_addc_co_u32_e32 v17, vcc, 0, v9, vcc
	global_load_dwordx4 v[46:49], v[10:11], off
	global_load_dwordx4 v[38:41], v[16:17], off
	v_add_co_u32_e32 v10, vcc, s12, v8
	s_waitcnt lgkmcnt(0)
	s_nop 1
	v_add_f32_dpp v66, v66, v66 quad_perm:[2,3,0,1] row_mask:0xf bank_mask:0xf
	v_addc_co_u32_e32 v11, vcc, 0, v9, vcc
	v_add_co_u32_e32 v16, vcc, 0x28000, v8
	s_nop 0
	v_addc_co_u32_e32 v17, vcc, 0, v9, vcc
	global_load_dwordx4 v[34:37], v[10:11], off
	global_load_dwordx4 v[24:27], v[16:17], off
	v_add_co_u32_e32 v10, vcc, 0x30000, v8
	s_waitcnt lgkmcnt(0)
	s_nop 1
	v_add_f32_dpp v66, v66, v66 row_half_mirror row_mask:0xf bank_mask:0xf
	v_addc_co_u32_e32 v11, vcc, 0, v9, vcc
	v_add_co_u32_e32 v8, vcc, 0x38000, v8
	s_nop 0
	v_addc_co_u32_e32 v9, vcc, 0, v9, vcc
	global_load_dwordx4 v[16:19], v[10:11], off
	s_nop 0
	global_load_dwordx4 v[8:11], v[8:9], off
	s_waitcnt lgkmcnt(0)
	s_nop 1
	v_add_f32_dpp v66, v66, v66 row_mirror row_mask:0xf bank_mask:0xf
	v_mov_b32_e32 v67, v66
	s_nop 1
	v_permlane16_swap_b32_e32 v67, v66
	s_and_saveexec_b64 s[2:3], s[44:45]
	s_cbranch_execz .LBB0_758
	s_waitcnt lgkmcnt(0)
	v_add_f32_e32 v66, v66, v67
	ds_write_b32 v102, v66 offset:1536
.LBB0_758:
	s_or_b64 exec, exec, s[2:3]
	s_waitcnt vmcnt(14)
	v_mul_f32_e32 v59, v1, v59
	v_fmac_f32_e32 v59, v0, v58
	v_fmac_f32_e32 v59, v2, v60
	v_fmac_f32_e32 v59, v3, v61
	s_waitcnt lgkmcnt(0)
	s_nop 1
	v_add_f32_dpp v58, v59, v59 quad_perm:[1,0,3,2] row_mask:0xf bank_mask:0xf
	s_waitcnt lgkmcnt(0)
	s_nop 1
	v_add_f32_dpp v58, v58, v58 quad_perm:[2,3,0,1] row_mask:0xf bank_mask:0xf
	s_waitcnt lgkmcnt(0)
	s_nop 1
	v_add_f32_dpp v58, v58, v58 row_half_mirror row_mask:0xf bank_mask:0xf
	s_waitcnt lgkmcnt(0)
	s_nop 1
	v_add_f32_dpp v58, v58, v58 row_mirror row_mask:0xf bank_mask:0xf
	v_mov_b32_e32 v59, v58
	s_nop 1
	v_permlane16_swap_b32_e32 v59, v58
	s_and_saveexec_b64 s[2:3], s[44:45]
	s_cbranch_execz .LBB0_760
	s_waitcnt lgkmcnt(0)
	v_add_f32_e32 v58, v58, v59
	ds_write_b32 v102, v58 offset:1600
.LBB0_760:
	s_or_b64 exec, exec, s[2:3]
	s_waitcnt vmcnt(13)
	v_mul_f32_e32 v51, v1, v51
	v_fmac_f32_e32 v51, v0, v50
	v_fmac_f32_e32 v51, v2, v52
	v_fmac_f32_e32 v51, v3, v53
	s_waitcnt lgkmcnt(0)
	s_nop 1
	v_add_f32_dpp v50, v51, v51 quad_perm:[1,0,3,2] row_mask:0xf bank_mask:0xf
	s_waitcnt lgkmcnt(0)
	s_nop 1
	v_add_f32_dpp v50, v50, v50 quad_perm:[2,3,0,1] row_mask:0xf bank_mask:0xf
	s_waitcnt lgkmcnt(0)
	s_nop 1
	v_add_f32_dpp v50, v50, v50 row_half_mirror row_mask:0xf bank_mask:0xf
	s_waitcnt lgkmcnt(0)
	s_nop 1
	v_add_f32_dpp v50, v50, v50 row_mirror row_mask:0xf bank_mask:0xf
	v_mov_b32_e32 v51, v50
	s_nop 1
	v_permlane16_swap_b32_e32 v51, v50
	s_and_saveexec_b64 s[2:3], s[44:45]
	s_cbranch_execz .LBB0_762
	s_waitcnt lgkmcnt(0)
	v_add_f32_e32 v50, v50, v51
	ds_write_b32 v102, v50 offset:1664
.LBB0_762:
	s_or_b64 exec, exec, s[2:3]
	s_waitcnt vmcnt(12)
	v_mul_f32_e32 v43, v1, v43
	v_fmac_f32_e32 v43, v0, v42
	v_fmac_f32_e32 v43, v2, v44
	v_fmac_f32_e32 v43, v3, v45
	s_waitcnt lgkmcnt(0)
	s_nop 1
	v_add_f32_dpp v42, v43, v43 quad_perm:[1,0,3,2] row_mask:0xf bank_mask:0xf
	s_waitcnt lgkmcnt(0)
	s_nop 1
	v_add_f32_dpp v42, v42, v42 quad_perm:[2,3,0,1] row_mask:0xf bank_mask:0xf
	s_waitcnt lgkmcnt(0)
	s_nop 1
	v_add_f32_dpp v42, v42, v42 row_half_mirror row_mask:0xf bank_mask:0xf
	s_waitcnt lgkmcnt(0)
	s_nop 1
	v_add_f32_dpp v42, v42, v42 row_mirror row_mask:0xf bank_mask:0xf
	v_mov_b32_e32 v43, v42
	s_nop 1
	v_permlane16_swap_b32_e32 v43, v42
	s_and_saveexec_b64 s[2:3], s[44:45]
	s_cbranch_execz .LBB0_764
	s_waitcnt lgkmcnt(0)
	v_add_f32_e32 v42, v42, v43
	ds_write_b32 v102, v42 offset:1728
.LBB0_764:
	s_or_b64 exec, exec, s[2:3]
	s_waitcnt vmcnt(11)
	v_mul_f32_e32 v29, v1, v29
	v_fmac_f32_e32 v29, v0, v28
	v_fmac_f32_e32 v29, v2, v30
	v_fmac_f32_e32 v29, v3, v31
	s_waitcnt lgkmcnt(0)
	s_nop 1
	v_add_f32_dpp v28, v29, v29 quad_perm:[1,0,3,2] row_mask:0xf bank_mask:0xf
	s_waitcnt lgkmcnt(0)
	s_nop 1
	v_add_f32_dpp v28, v28, v28 quad_perm:[2,3,0,1] row_mask:0xf bank_mask:0xf
	s_waitcnt lgkmcnt(0)
	s_nop 1
	v_add_f32_dpp v28, v28, v28 row_half_mirror row_mask:0xf bank_mask:0xf
	s_waitcnt lgkmcnt(0)
	s_nop 1
	v_add_f32_dpp v28, v28, v28 row_mirror row_mask:0xf bank_mask:0xf
	v_mov_b32_e32 v29, v28
	s_nop 1
	v_permlane16_swap_b32_e32 v29, v28
	s_and_saveexec_b64 s[2:3], s[44:45]
	s_cbranch_execz .LBB0_766
	s_waitcnt lgkmcnt(0)
	v_add_f32_e32 v28, v28, v29
	ds_write_b32 v102, v28 offset:1792
.LBB0_766:
	s_or_b64 exec, exec, s[2:3]
	s_waitcnt vmcnt(10)
	v_mul_f32_e32 v21, v1, v21
	v_fmac_f32_e32 v21, v0, v20
	v_fmac_f32_e32 v21, v2, v22
	v_fmac_f32_e32 v21, v3, v23
	s_waitcnt lgkmcnt(0)
	s_nop 1
	v_add_f32_dpp v20, v21, v21 quad_perm:[1,0,3,2] row_mask:0xf bank_mask:0xf
	s_waitcnt lgkmcnt(0)
	s_nop 1
	v_add_f32_dpp v20, v20, v20 quad_perm:[2,3,0,1] row_mask:0xf bank_mask:0xf
	s_waitcnt lgkmcnt(0)
	s_nop 1
	v_add_f32_dpp v20, v20, v20 row_half_mirror row_mask:0xf bank_mask:0xf
	s_waitcnt lgkmcnt(0)
	s_nop 1
	v_add_f32_dpp v20, v20, v20 row_mirror row_mask:0xf bank_mask:0xf
	v_mov_b32_e32 v21, v20
	s_nop 1
	v_permlane16_swap_b32_e32 v21, v20
	s_and_saveexec_b64 s[2:3], s[44:45]
	s_cbranch_execz .LBB0_768
	s_waitcnt lgkmcnt(0)
	v_add_f32_e32 v20, v20, v21
	ds_write_b32 v102, v20 offset:1856
.LBB0_768:
	s_or_b64 exec, exec, s[2:3]
	s_waitcnt vmcnt(9)
	v_mul_f32_e32 v13, v1, v13
	v_fmac_f32_e32 v13, v0, v12
	v_fmac_f32_e32 v13, v2, v14
	v_fmac_f32_e32 v13, v3, v15
	s_waitcnt lgkmcnt(0)
	s_nop 1
	v_add_f32_dpp v12, v13, v13 quad_perm:[1,0,3,2] row_mask:0xf bank_mask:0xf
	s_waitcnt lgkmcnt(0)
	s_nop 1
	v_add_f32_dpp v12, v12, v12 quad_perm:[2,3,0,1] row_mask:0xf bank_mask:0xf
	s_waitcnt lgkmcnt(0)
	s_nop 1
	v_add_f32_dpp v12, v12, v12 row_half_mirror row_mask:0xf bank_mask:0xf
	s_waitcnt lgkmcnt(0)
	s_nop 1
	v_add_f32_dpp v12, v12, v12 row_mirror row_mask:0xf bank_mask:0xf
	v_mov_b32_e32 v13, v12
	s_nop 1
	v_permlane16_swap_b32_e32 v13, v12
	s_and_saveexec_b64 s[2:3], s[44:45]
	s_cbranch_execz .LBB0_770
	s_waitcnt lgkmcnt(0)
	v_add_f32_e32 v12, v12, v13
	ds_write_b32 v102, v12 offset:1920
.LBB0_770:
	s_or_b64 exec, exec, s[2:3]
	s_waitcnt vmcnt(8)
	v_mul_f32_e32 v5, v1, v5
	v_fmac_f32_e32 v5, v0, v4
	v_fmac_f32_e32 v5, v2, v6
	v_fmac_f32_e32 v5, v3, v7
	s_waitcnt lgkmcnt(0)
	s_nop 1
	v_add_f32_dpp v4, v5, v5 quad_perm:[1,0,3,2] row_mask:0xf bank_mask:0xf
	s_waitcnt lgkmcnt(0)
	s_nop 1
	v_add_f32_dpp v4, v4, v4 quad_perm:[2,3,0,1] row_mask:0xf bank_mask:0xf
	s_waitcnt lgkmcnt(0)
	s_nop 1
	v_add_f32_dpp v4, v4, v4 row_half_mirror row_mask:0xf bank_mask:0xf
	s_waitcnt lgkmcnt(0)
	s_nop 1
	v_add_f32_dpp v4, v4, v4 row_mirror row_mask:0xf bank_mask:0xf
	v_mov_b32_e32 v5, v4
	s_nop 1
	v_permlane16_swap_b32_e32 v5, v4
	s_and_saveexec_b64 s[2:3], s[44:45]
	s_cbranch_execz .LBB0_772
	s_waitcnt lgkmcnt(0)
	v_add_f32_e32 v4, v4, v5
	ds_write_b32 v102, v4 offset:1984
.LBB0_772:
	s_or_b64 exec, exec, s[2:3]
	ds_read_b32 v4, v33 offset:684
	s_waitcnt vmcnt(7)
	v_mul_f32_e32 v63, v1, v63
	v_fmac_f32_e32 v63, v0, v62
	v_fmac_f32_e32 v63, v2, v64
	v_fmac_f32_e32 v63, v3, v65
	s_waitcnt lgkmcnt(0)
	v_lshl_add_u32 v4, v4, 7, v82
	v_ashrrev_i32_e32 v5, 31, v4
	v_lshlrev_b64 v[4:5], 11, v[4:5]
	v_lshl_add_u64 v[4:5], v[74:75], 0, v[4:5]
	v_add_co_u32_e32 v6, vcc, 0x8000, v4
	s_nop 0
	v_addc_co_u32_e32 v7, vcc, 0, v5, vcc
	global_load_dwordx4 v[66:69], v[4:5], off
	global_load_dwordx4 v[58:61], v[6:7], off
	v_add_co_u32_e32 v6, vcc, 0x10000, v4
	s_waitcnt lgkmcnt(0)
	s_nop 1
	v_add_f32_dpp v62, v63, v63 quad_perm:[1,0,3,2] row_mask:0xf bank_mask:0xf
	v_addc_co_u32_e32 v7, vcc, 0, v5, vcc
	v_add_co_u32_e32 v12, vcc, 0x18000, v4
	s_nop 0
	v_addc_co_u32_e32 v13, vcc, 0, v5, vcc
	global_load_dwordx4 v[50:53], v[6:7], off
	global_load_dwordx4 v[42:45], v[12:13], off
	v_add_co_u32_e32 v6, vcc, s12, v4
	s_waitcnt lgkmcnt(0)
	s_nop 1
	v_add_f32_dpp v62, v62, v62 quad_perm:[2,3,0,1] row_mask:0xf bank_mask:0xf
	v_addc_co_u32_e32 v7, vcc, 0, v5, vcc
	v_add_co_u32_e32 v12, vcc, 0x28000, v4
	s_nop 0
	v_addc_co_u32_e32 v13, vcc, 0, v5, vcc
	global_load_dwordx4 v[28:31], v[6:7], off
	global_load_dwordx4 v[20:23], v[12:13], off
	v_add_co_u32_e32 v6, vcc, 0x30000, v4
	s_waitcnt lgkmcnt(0)
	s_nop 1
	v_add_f32_dpp v62, v62, v62 row_half_mirror row_mask:0xf bank_mask:0xf
	v_addc_co_u32_e32 v7, vcc, 0, v5, vcc
	v_add_co_u32_e32 v4, vcc, 0x38000, v4
	s_nop 0
	v_addc_co_u32_e32 v5, vcc, 0, v5, vcc
	global_load_dwordx4 v[12:15], v[6:7], off
	s_nop 0
	global_load_dwordx4 v[4:7], v[4:5], off
	s_waitcnt lgkmcnt(0)
	s_nop 1
	v_add_f32_dpp v62, v62, v62 row_mirror row_mask:0xf bank_mask:0xf
	v_mov_b32_e32 v63, v62
	s_nop 1
	v_permlane16_swap_b32_e32 v63, v62
	s_and_saveexec_b64 s[2:3], s[44:45]
	s_cbranch_execz .LBB0_774
	s_waitcnt lgkmcnt(0)
	v_add_f32_e32 v62, v62, v63
	ds_write_b32 v102, v62 offset:2048
.LBB0_774:
	s_or_b64 exec, exec, s[2:3]
	s_waitcnt vmcnt(14)
	v_mul_f32_e32 v55, v1, v55
	v_fmac_f32_e32 v55, v0, v54
	v_fmac_f32_e32 v55, v2, v56
	v_fmac_f32_e32 v55, v3, v57
	s_waitcnt lgkmcnt(0)
	s_nop 1
	v_add_f32_dpp v54, v55, v55 quad_perm:[1,0,3,2] row_mask:0xf bank_mask:0xf
	s_waitcnt lgkmcnt(0)
	s_nop 1
	v_add_f32_dpp v54, v54, v54 quad_perm:[2,3,0,1] row_mask:0xf bank_mask:0xf
	s_waitcnt lgkmcnt(0)
	s_nop 1
	v_add_f32_dpp v54, v54, v54 row_half_mirror row_mask:0xf bank_mask:0xf
	s_waitcnt lgkmcnt(0)
	s_nop 1
	v_add_f32_dpp v54, v54, v54 row_mirror row_mask:0xf bank_mask:0xf
	v_mov_b32_e32 v55, v54
	s_nop 1
	v_permlane16_swap_b32_e32 v55, v54
	s_and_saveexec_b64 s[2:3], s[44:45]
	s_cbranch_execz .LBB0_776
	s_waitcnt lgkmcnt(0)
	v_add_f32_e32 v54, v54, v55
	ds_write_b32 v102, v54 offset:2112
.LBB0_776:
	s_or_b64 exec, exec, s[2:3]
	s_waitcnt vmcnt(13)
	v_mul_f32_e32 v47, v1, v47
	v_fmac_f32_e32 v47, v0, v46
	v_fmac_f32_e32 v47, v2, v48
	v_fmac_f32_e32 v47, v3, v49
	s_waitcnt lgkmcnt(0)
	s_nop 1
	v_add_f32_dpp v46, v47, v47 quad_perm:[1,0,3,2] row_mask:0xf bank_mask:0xf
	s_waitcnt lgkmcnt(0)
	s_nop 1
	v_add_f32_dpp v46, v46, v46 quad_perm:[2,3,0,1] row_mask:0xf bank_mask:0xf
	s_waitcnt lgkmcnt(0)
	s_nop 1
	v_add_f32_dpp v46, v46, v46 row_half_mirror row_mask:0xf bank_mask:0xf
	s_waitcnt lgkmcnt(0)
	s_nop 1
	v_add_f32_dpp v46, v46, v46 row_mirror row_mask:0xf bank_mask:0xf
	v_mov_b32_e32 v47, v46
	s_nop 1
	v_permlane16_swap_b32_e32 v47, v46
	s_and_saveexec_b64 s[2:3], s[44:45]
	s_cbranch_execz .LBB0_778
	s_waitcnt lgkmcnt(0)
	v_add_f32_e32 v46, v46, v47
	ds_write_b32 v102, v46 offset:2176
.LBB0_778:
	s_or_b64 exec, exec, s[2:3]
	s_waitcnt vmcnt(12)
	v_mul_f32_e32 v39, v1, v39
	v_fmac_f32_e32 v39, v0, v38
	v_fmac_f32_e32 v39, v2, v40
	v_fmac_f32_e32 v39, v3, v41
	s_waitcnt lgkmcnt(0)
	s_nop 1
	v_add_f32_dpp v38, v39, v39 quad_perm:[1,0,3,2] row_mask:0xf bank_mask:0xf
	s_waitcnt lgkmcnt(0)
	s_nop 1
	v_add_f32_dpp v38, v38, v38 quad_perm:[2,3,0,1] row_mask:0xf bank_mask:0xf
	s_waitcnt lgkmcnt(0)
	s_nop 1
	v_add_f32_dpp v38, v38, v38 row_half_mirror row_mask:0xf bank_mask:0xf
	s_waitcnt lgkmcnt(0)
	s_nop 1
	v_add_f32_dpp v38, v38, v38 row_mirror row_mask:0xf bank_mask:0xf
	v_mov_b32_e32 v39, v38
	s_nop 1
	v_permlane16_swap_b32_e32 v39, v38
	s_and_saveexec_b64 s[2:3], s[44:45]
	s_cbranch_execz .LBB0_780
	s_waitcnt lgkmcnt(0)
	v_add_f32_e32 v38, v38, v39
	ds_write_b32 v102, v38 offset:2240
.LBB0_780:
	s_or_b64 exec, exec, s[2:3]
	s_waitcnt vmcnt(11)
	v_mul_f32_e32 v35, v1, v35
	v_fmac_f32_e32 v35, v0, v34
	v_fmac_f32_e32 v35, v2, v36
	v_fmac_f32_e32 v35, v3, v37
	s_waitcnt lgkmcnt(0)
	s_nop 1
	v_add_f32_dpp v34, v35, v35 quad_perm:[1,0,3,2] row_mask:0xf bank_mask:0xf
	s_waitcnt lgkmcnt(0)
	s_nop 1
	v_add_f32_dpp v34, v34, v34 quad_perm:[2,3,0,1] row_mask:0xf bank_mask:0xf
	s_waitcnt lgkmcnt(0)
	s_nop 1
	v_add_f32_dpp v34, v34, v34 row_half_mirror row_mask:0xf bank_mask:0xf
	s_waitcnt lgkmcnt(0)
	s_nop 1
	v_add_f32_dpp v34, v34, v34 row_mirror row_mask:0xf bank_mask:0xf
	v_mov_b32_e32 v35, v34
	s_nop 1
	v_permlane16_swap_b32_e32 v35, v34
	s_and_saveexec_b64 s[2:3], s[44:45]
	s_cbranch_execz .LBB0_782
	s_waitcnt lgkmcnt(0)
	v_add_f32_e32 v34, v34, v35
	ds_write_b32 v102, v34 offset:2304
.LBB0_782:
	s_or_b64 exec, exec, s[2:3]
	s_waitcnt vmcnt(10)
	v_mul_f32_e32 v25, v1, v25
	v_fmac_f32_e32 v25, v0, v24
	v_fmac_f32_e32 v25, v2, v26
	v_fmac_f32_e32 v25, v3, v27
	s_waitcnt lgkmcnt(0)
	s_nop 1
	v_add_f32_dpp v24, v25, v25 quad_perm:[1,0,3,2] row_mask:0xf bank_mask:0xf
	s_waitcnt lgkmcnt(0)
	s_nop 1
	v_add_f32_dpp v24, v24, v24 quad_perm:[2,3,0,1] row_mask:0xf bank_mask:0xf
	s_waitcnt lgkmcnt(0)
	s_nop 1
	v_add_f32_dpp v24, v24, v24 row_half_mirror row_mask:0xf bank_mask:0xf
	s_waitcnt lgkmcnt(0)
	s_nop 1
	v_add_f32_dpp v24, v24, v24 row_mirror row_mask:0xf bank_mask:0xf
	v_mov_b32_e32 v25, v24
	s_nop 1
	v_permlane16_swap_b32_e32 v25, v24
	s_and_saveexec_b64 s[2:3], s[44:45]
	s_cbranch_execz .LBB0_784
	s_waitcnt lgkmcnt(0)
	v_add_f32_e32 v24, v24, v25
	ds_write_b32 v102, v24 offset:2368
.LBB0_784:
	s_or_b64 exec, exec, s[2:3]
	s_waitcnt vmcnt(9)
	v_mul_f32_e32 v17, v1, v17
	v_fmac_f32_e32 v17, v0, v16
	v_fmac_f32_e32 v17, v2, v18
	v_fmac_f32_e32 v17, v3, v19
	s_waitcnt lgkmcnt(0)
	s_nop 1
	v_add_f32_dpp v16, v17, v17 quad_perm:[1,0,3,2] row_mask:0xf bank_mask:0xf
	s_waitcnt lgkmcnt(0)
	s_nop 1
	v_add_f32_dpp v16, v16, v16 quad_perm:[2,3,0,1] row_mask:0xf bank_mask:0xf
	s_waitcnt lgkmcnt(0)
	s_nop 1
	v_add_f32_dpp v16, v16, v16 row_half_mirror row_mask:0xf bank_mask:0xf
	s_waitcnt lgkmcnt(0)
	s_nop 1
	v_add_f32_dpp v16, v16, v16 row_mirror row_mask:0xf bank_mask:0xf
	v_mov_b32_e32 v17, v16
	s_nop 1
	v_permlane16_swap_b32_e32 v17, v16
	s_and_saveexec_b64 s[2:3], s[44:45]
	s_cbranch_execz .LBB0_786
	s_waitcnt lgkmcnt(0)
	v_add_f32_e32 v16, v16, v17
	ds_write_b32 v102, v16 offset:2432
.LBB0_786:
	s_or_b64 exec, exec, s[2:3]
	s_waitcnt vmcnt(8)
	v_mul_f32_e32 v9, v1, v9
	v_fmac_f32_e32 v9, v0, v8
	v_fmac_f32_e32 v9, v2, v10
	v_fmac_f32_e32 v9, v3, v11
	s_waitcnt lgkmcnt(0)
	s_nop 1
	v_add_f32_dpp v8, v9, v9 quad_perm:[1,0,3,2] row_mask:0xf bank_mask:0xf
	s_waitcnt lgkmcnt(0)
	s_nop 1
	v_add_f32_dpp v8, v8, v8 quad_perm:[2,3,0,1] row_mask:0xf bank_mask:0xf
	s_waitcnt lgkmcnt(0)
	s_nop 1
	v_add_f32_dpp v8, v8, v8 row_half_mirror row_mask:0xf bank_mask:0xf
	s_waitcnt lgkmcnt(0)
	s_nop 1
	v_add_f32_dpp v8, v8, v8 row_mirror row_mask:0xf bank_mask:0xf
	v_mov_b32_e32 v9, v8
	s_nop 1
	v_permlane16_swap_b32_e32 v9, v8
	s_and_saveexec_b64 s[2:3], s[44:45]
	s_cbranch_execz .LBB0_788
	s_waitcnt lgkmcnt(0)
	v_add_f32_e32 v8, v8, v9
	ds_write_b32 v102, v8 offset:2496
.LBB0_788:
	s_or_b64 exec, exec, s[2:3]
	ds_read_b32 v8, v33 offset:688
	s_waitcnt vmcnt(7)
	v_mul_f32_e32 v46, v1, v67
	v_fmac_f32_e32 v46, v0, v66
	v_fmac_f32_e32 v46, v2, v68
	v_fmac_f32_e32 v46, v3, v69
	s_waitcnt lgkmcnt(0)
	v_lshl_add_u32 v8, v8, 7, v82
	v_ashrrev_i32_e32 v9, 31, v8
	v_lshlrev_b64 v[8:9], 11, v[8:9]
	v_lshl_add_u64 v[8:9], v[74:75], 0, v[8:9]
	v_add_co_u32_e32 v10, vcc, 0x8000, v8
	s_nop 0
	v_addc_co_u32_e32 v11, vcc, 0, v9, vcc
	global_load_dwordx4 v[78:81], v[8:9], off
	global_load_dwordx4 v[70:73], v[10:11], off
	v_add_co_u32_e32 v10, vcc, 0x10000, v8
	s_waitcnt lgkmcnt(0)
	s_nop 1
	v_add_f32_dpp v46, v46, v46 quad_perm:[1,0,3,2] row_mask:0xf bank_mask:0xf
	v_addc_co_u32_e32 v11, vcc, 0, v9, vcc
	v_add_co_u32_e32 v16, vcc, 0x18000, v8
	s_nop 0
	v_addc_co_u32_e32 v17, vcc, 0, v9, vcc
	global_load_dwordx4 v[62:65], v[10:11], off
	global_load_dwordx4 v[38:41], v[16:17], off
	v_add_co_u32_e32 v10, vcc, s12, v8
	s_waitcnt lgkmcnt(0)
	s_nop 1
	v_add_f32_dpp v46, v46, v46 quad_perm:[2,3,0,1] row_mask:0xf bank_mask:0xf
	v_addc_co_u32_e32 v11, vcc, 0, v9, vcc
	v_add_co_u32_e32 v16, vcc, 0x28000, v8
	s_nop 0
	v_addc_co_u32_e32 v17, vcc, 0, v9, vcc
	global_load_dwordx4 v[34:37], v[10:11], off
	global_load_dwordx4 v[24:27], v[16:17], off
	v_add_co_u32_e32 v10, vcc, 0x30000, v8
	s_waitcnt lgkmcnt(0)
	s_nop 1
	v_add_f32_dpp v46, v46, v46 row_half_mirror row_mask:0xf bank_mask:0xf
	v_addc_co_u32_e32 v11, vcc, 0, v9, vcc
	v_add_co_u32_e32 v8, vcc, 0x38000, v8
	s_nop 0
	v_addc_co_u32_e32 v9, vcc, 0, v9, vcc
	global_load_dwordx4 v[16:19], v[10:11], off
	s_nop 0
	global_load_dwordx4 v[8:11], v[8:9], off
	s_waitcnt lgkmcnt(0)
	s_nop 1
	v_add_f32_dpp v46, v46, v46 row_mirror row_mask:0xf bank_mask:0xf
	v_mov_b32_e32 v47, v46
	s_nop 1
	v_permlane16_swap_b32_e32 v47, v46
	s_and_saveexec_b64 s[2:3], s[44:45]
	s_cbranch_execz .LBB0_790
	s_waitcnt lgkmcnt(0)
	v_add_f32_e32 v46, v46, v47
	ds_write_b32 v102, v46 offset:2560
.LBB0_790:
	s_or_b64 exec, exec, s[2:3]
	s_waitcnt vmcnt(14)
	v_mul_f32_e32 v46, v1, v59
	v_fmac_f32_e32 v46, v0, v58
	v_fmac_f32_e32 v46, v2, v60
	v_fmac_f32_e32 v46, v3, v61
	s_waitcnt lgkmcnt(0)
	s_waitcnt lgkmcnt(0)
	s_nop 1
	v_add_f32_dpp v46, v46, v46 quad_perm:[1,0,3,2] row_mask:0xf bank_mask:0xf
	s_waitcnt lgkmcnt(0)
	s_nop 1
	v_add_f32_dpp v46, v46, v46 quad_perm:[2,3,0,1] row_mask:0xf bank_mask:0xf
	s_waitcnt lgkmcnt(0)
	s_nop 1
	v_add_f32_dpp v46, v46, v46 row_half_mirror row_mask:0xf bank_mask:0xf
	s_waitcnt lgkmcnt(0)
	s_nop 1
	v_add_f32_dpp v46, v46, v46 row_mirror row_mask:0xf bank_mask:0xf
	v_mov_b32_e32 v47, v46
	s_nop 1
	v_permlane16_swap_b32_e32 v47, v46
	s_and_saveexec_b64 s[2:3], s[44:45]
	s_cbranch_execz .LBB0_792
	s_waitcnt lgkmcnt(0)
	v_add_f32_e32 v46, v46, v47
	ds_write_b32 v102, v46 offset:2624
.LBB0_792:
	s_or_b64 exec, exec, s[2:3]
	s_waitcnt vmcnt(13)
	v_mul_f32_e32 v46, v1, v51
	v_fmac_f32_e32 v46, v0, v50
	v_fmac_f32_e32 v46, v2, v52
	v_fmac_f32_e32 v46, v3, v53
	s_waitcnt lgkmcnt(0)
	s_waitcnt lgkmcnt(0)
	s_nop 1
	v_add_f32_dpp v46, v46, v46 quad_perm:[1,0,3,2] row_mask:0xf bank_mask:0xf
	s_waitcnt lgkmcnt(0)
	s_nop 1
	v_add_f32_dpp v46, v46, v46 quad_perm:[2,3,0,1] row_mask:0xf bank_mask:0xf
	s_waitcnt lgkmcnt(0)
	s_nop 1
	v_add_f32_dpp v46, v46, v46 row_half_mirror row_mask:0xf bank_mask:0xf
	s_waitcnt lgkmcnt(0)
	s_nop 1
	v_add_f32_dpp v46, v46, v46 row_mirror row_mask:0xf bank_mask:0xf
	v_mov_b32_e32 v47, v46
	s_nop 1
	v_permlane16_swap_b32_e32 v47, v46
	s_and_saveexec_b64 s[2:3], s[44:45]
	s_cbranch_execz .LBB0_794
	s_waitcnt lgkmcnt(0)
	v_add_f32_e32 v46, v46, v47
	ds_write_b32 v102, v46 offset:2688
.LBB0_794:
	s_or_b64 exec, exec, s[2:3]
	s_waitcnt vmcnt(12)
	v_mul_f32_e32 v43, v1, v43
	v_fmac_f32_e32 v43, v0, v42
	v_fmac_f32_e32 v43, v2, v44
	v_fmac_f32_e32 v43, v3, v45
	s_waitcnt lgkmcnt(0)
	s_nop 1
	v_add_f32_dpp v42, v43, v43 quad_perm:[1,0,3,2] row_mask:0xf bank_mask:0xf
	s_waitcnt lgkmcnt(0)
	s_nop 1
	v_add_f32_dpp v42, v42, v42 quad_perm:[2,3,0,1] row_mask:0xf bank_mask:0xf
	s_waitcnt lgkmcnt(0)
	s_nop 1
	v_add_f32_dpp v42, v42, v42 row_half_mirror row_mask:0xf bank_mask:0xf
	s_waitcnt lgkmcnt(0)
	s_nop 1
	v_add_f32_dpp v42, v42, v42 row_mirror row_mask:0xf bank_mask:0xf
	v_mov_b32_e32 v43, v42
	s_nop 1
	v_permlane16_swap_b32_e32 v43, v42
	s_and_saveexec_b64 s[2:3], s[44:45]
	s_cbranch_execz .LBB0_796
	s_waitcnt lgkmcnt(0)
	v_add_f32_e32 v42, v42, v43
	ds_write_b32 v102, v42 offset:2752
.LBB0_796:
	s_or_b64 exec, exec, s[2:3]
	s_waitcnt vmcnt(11)
	v_mul_f32_e32 v29, v1, v29
	v_fmac_f32_e32 v29, v0, v28
	v_fmac_f32_e32 v29, v2, v30
	v_fmac_f32_e32 v29, v3, v31
	s_waitcnt lgkmcnt(0)
	s_nop 1
	v_add_f32_dpp v28, v29, v29 quad_perm:[1,0,3,2] row_mask:0xf bank_mask:0xf
	s_waitcnt lgkmcnt(0)
	s_nop 1
	v_add_f32_dpp v28, v28, v28 quad_perm:[2,3,0,1] row_mask:0xf bank_mask:0xf
	s_waitcnt lgkmcnt(0)
	s_nop 1
	v_add_f32_dpp v28, v28, v28 row_half_mirror row_mask:0xf bank_mask:0xf
	s_waitcnt lgkmcnt(0)
	s_nop 1
	v_add_f32_dpp v28, v28, v28 row_mirror row_mask:0xf bank_mask:0xf
	v_mov_b32_e32 v29, v28
	s_nop 1
	v_permlane16_swap_b32_e32 v29, v28
	s_and_saveexec_b64 s[2:3], s[44:45]
	s_cbranch_execz .LBB0_798
	s_waitcnt lgkmcnt(0)
	v_add_f32_e32 v28, v28, v29
	ds_write_b32 v102, v28 offset:2816
.LBB0_798:
	s_or_b64 exec, exec, s[2:3]
	s_waitcnt vmcnt(10)
	v_mul_f32_e32 v21, v1, v21
	v_fmac_f32_e32 v21, v0, v20
	v_fmac_f32_e32 v21, v2, v22
	v_fmac_f32_e32 v21, v3, v23
	s_waitcnt lgkmcnt(0)
	s_nop 1
	v_add_f32_dpp v20, v21, v21 quad_perm:[1,0,3,2] row_mask:0xf bank_mask:0xf
	s_waitcnt lgkmcnt(0)
	s_nop 1
	v_add_f32_dpp v20, v20, v20 quad_perm:[2,3,0,1] row_mask:0xf bank_mask:0xf
	s_waitcnt lgkmcnt(0)
	s_nop 1
	v_add_f32_dpp v20, v20, v20 row_half_mirror row_mask:0xf bank_mask:0xf
	s_waitcnt lgkmcnt(0)
	s_nop 1
	v_add_f32_dpp v20, v20, v20 row_mirror row_mask:0xf bank_mask:0xf
	v_mov_b32_e32 v21, v20
	s_nop 1
	v_permlane16_swap_b32_e32 v21, v20
	s_and_saveexec_b64 s[2:3], s[44:45]
	s_cbranch_execz .LBB0_800
	s_waitcnt lgkmcnt(0)
	v_add_f32_e32 v20, v20, v21
	ds_write_b32 v102, v20 offset:2880
.LBB0_800:
	s_or_b64 exec, exec, s[2:3]
	s_waitcnt vmcnt(9)
	v_mul_f32_e32 v13, v1, v13
	v_fmac_f32_e32 v13, v0, v12
	v_fmac_f32_e32 v13, v2, v14
	v_fmac_f32_e32 v13, v3, v15
	s_waitcnt lgkmcnt(0)
	s_nop 1
	v_add_f32_dpp v12, v13, v13 quad_perm:[1,0,3,2] row_mask:0xf bank_mask:0xf
	s_waitcnt lgkmcnt(0)
	s_nop 1
	v_add_f32_dpp v12, v12, v12 quad_perm:[2,3,0,1] row_mask:0xf bank_mask:0xf
	s_waitcnt lgkmcnt(0)
	s_nop 1
	v_add_f32_dpp v12, v12, v12 row_half_mirror row_mask:0xf bank_mask:0xf
	s_waitcnt lgkmcnt(0)
	s_nop 1
	v_add_f32_dpp v12, v12, v12 row_mirror row_mask:0xf bank_mask:0xf
	v_mov_b32_e32 v13, v12
	s_nop 1
	v_permlane16_swap_b32_e32 v13, v12
	s_and_saveexec_b64 s[2:3], s[44:45]
	s_cbranch_execz .LBB0_802
	s_waitcnt lgkmcnt(0)
	v_add_f32_e32 v12, v12, v13
	ds_write_b32 v102, v12 offset:2944
.LBB0_802:
	s_or_b64 exec, exec, s[2:3]
	s_waitcnt vmcnt(8)
	v_mul_f32_e32 v5, v1, v5
	v_fmac_f32_e32 v5, v0, v4
	v_fmac_f32_e32 v5, v2, v6
	v_fmac_f32_e32 v5, v3, v7
	s_waitcnt lgkmcnt(0)
	s_nop 1
	v_add_f32_dpp v4, v5, v5 quad_perm:[1,0,3,2] row_mask:0xf bank_mask:0xf
	s_waitcnt lgkmcnt(0)
	s_nop 1
	v_add_f32_dpp v4, v4, v4 quad_perm:[2,3,0,1] row_mask:0xf bank_mask:0xf
	s_waitcnt lgkmcnt(0)
	s_nop 1
	v_add_f32_dpp v4, v4, v4 row_half_mirror row_mask:0xf bank_mask:0xf
	s_waitcnt lgkmcnt(0)
	s_nop 1
	v_add_f32_dpp v4, v4, v4 row_mirror row_mask:0xf bank_mask:0xf
	v_mov_b32_e32 v5, v4
	s_nop 1
	v_permlane16_swap_b32_e32 v5, v4
	s_and_saveexec_b64 s[2:3], s[44:45]
	s_cbranch_execz .LBB0_804
	s_waitcnt lgkmcnt(0)
	v_add_f32_e32 v4, v4, v5
	ds_write_b32 v102, v4 offset:3008
.LBB0_804:
	s_or_b64 exec, exec, s[2:3]
	ds_read_b32 v4, v33 offset:692
	s_waitcnt lgkmcnt(0)
	v_lshl_add_u32 v4, v4, 7, v82
	v_ashrrev_i32_e32 v5, 31, v4
	v_lshlrev_b64 v[4:5], 11, v[4:5]
	v_lshl_add_u64 v[4:5], v[74:75], 0, v[4:5]
	v_add_co_u32_e32 v6, vcc, 0x8000, v4
	s_nop 1
	v_addc_co_u32_e32 v7, vcc, 0, v5, vcc
	global_load_dwordx4 v[74:77], v[4:5], off
	global_load_dwordx4 v[66:69], v[6:7], off
	v_add_co_u32_e32 v6, vcc, 0x10000, v4
	s_nop 1
	v_addc_co_u32_e32 v7, vcc, 0, v5, vcc
	v_add_co_u32_e32 v12, vcc, 0x18000, v4
	s_nop 1
	v_addc_co_u32_e32 v13, vcc, 0, v5, vcc
	global_load_dwordx4 v[58:61], v[6:7], off
	global_load_dwordx4 v[54:57], v[12:13], off
	v_add_co_u32_e32 v6, vcc, s12, v4
	s_nop 1
	v_addc_co_u32_e32 v7, vcc, 0, v5, vcc
	v_add_co_u32_e32 v12, vcc, 0x28000, v4
	s_nop 1
	v_addc_co_u32_e32 v13, vcc, 0, v5, vcc
	global_load_dwordx4 v[50:53], v[6:7], off
	global_load_dwordx4 v[46:49], v[12:13], off
	v_add_co_u32_e32 v6, vcc, 0x30000, v4
	s_waitcnt vmcnt(13)
	v_mul_f32_e32 v12, v1, v79
	v_addc_co_u32_e32 v7, vcc, 0, v5, vcc
	v_add_co_u32_e32 v4, vcc, 0x38000, v4
	v_fmac_f32_e32 v12, v0, v78
	s_nop 0
	v_addc_co_u32_e32 v5, vcc, 0, v5, vcc
	global_load_dwordx4 v[42:45], v[6:7], off
	s_nop 0
	global_load_dwordx4 v[4:7], v[4:5], off
	v_fmac_f32_e32 v12, v2, v80
	v_fmac_f32_e32 v12, v3, v81
	s_waitcnt lgkmcnt(0)
	s_nop 1
	v_add_f32_dpp v12, v12, v12 quad_perm:[1,0,3,2] row_mask:0xf bank_mask:0xf
	s_waitcnt lgkmcnt(0)
	s_nop 1
	v_add_f32_dpp v12, v12, v12 quad_perm:[2,3,0,1] row_mask:0xf bank_mask:0xf
	s_waitcnt lgkmcnt(0)
	s_nop 1
	v_add_f32_dpp v12, v12, v12 row_half_mirror row_mask:0xf bank_mask:0xf
	s_waitcnt lgkmcnt(0)
	s_nop 1
	v_add_f32_dpp v12, v12, v12 row_mirror row_mask:0xf bank_mask:0xf
	v_mov_b32_e32 v13, v12
	s_nop 1
	v_permlane16_swap_b32_e32 v13, v12
	s_and_saveexec_b64 s[2:3], s[44:45]
	s_cbranch_execz .LBB0_806
	s_waitcnt lgkmcnt(0)
	v_add_f32_e32 v12, v12, v13
	ds_write_b32 v102, v12 offset:3072
.LBB0_806:
	s_or_b64 exec, exec, s[2:3]
	s_waitcnt vmcnt(14)
	v_mul_f32_e32 v12, v1, v71
	v_fmac_f32_e32 v12, v0, v70
	v_fmac_f32_e32 v12, v2, v72
	v_fmac_f32_e32 v12, v3, v73
	s_waitcnt lgkmcnt(0)
	s_waitcnt lgkmcnt(0)
	s_nop 1
	v_add_f32_dpp v12, v12, v12 quad_perm:[1,0,3,2] row_mask:0xf bank_mask:0xf
	s_waitcnt lgkmcnt(0)
	s_nop 1
	v_add_f32_dpp v12, v12, v12 quad_perm:[2,3,0,1] row_mask:0xf bank_mask:0xf
	s_waitcnt lgkmcnt(0)
	s_nop 1
	v_add_f32_dpp v12, v12, v12 row_half_mirror row_mask:0xf bank_mask:0xf
	s_waitcnt lgkmcnt(0)
	s_nop 1
	v_add_f32_dpp v12, v12, v12 row_mirror row_mask:0xf bank_mask:0xf
	v_mov_b32_e32 v13, v12
	s_nop 1
	v_permlane16_swap_b32_e32 v13, v12
	s_and_saveexec_b64 s[2:3], s[44:45]
	s_cbranch_execz .LBB0_808
	s_waitcnt lgkmcnt(0)
	v_add_f32_e32 v12, v12, v13
	ds_write_b32 v102, v12 offset:3136
.LBB0_808:
	s_or_b64 exec, exec, s[2:3]
	s_waitcnt vmcnt(13)
	v_mul_f32_e32 v12, v1, v63
	v_fmac_f32_e32 v12, v0, v62
	v_fmac_f32_e32 v12, v2, v64
	v_fmac_f32_e32 v12, v3, v65
	s_waitcnt lgkmcnt(0)
	s_waitcnt lgkmcnt(0)
	s_nop 1
	v_add_f32_dpp v12, v12, v12 quad_perm:[1,0,3,2] row_mask:0xf bank_mask:0xf
	s_waitcnt lgkmcnt(0)
	s_nop 1
	v_add_f32_dpp v12, v12, v12 quad_perm:[2,3,0,1] row_mask:0xf bank_mask:0xf
	s_waitcnt lgkmcnt(0)
	s_nop 1
	v_add_f32_dpp v12, v12, v12 row_half_mirror row_mask:0xf bank_mask:0xf
	s_waitcnt lgkmcnt(0)
	s_nop 1
	v_add_f32_dpp v12, v12, v12 row_mirror row_mask:0xf bank_mask:0xf
	v_mov_b32_e32 v13, v12
	s_nop 1
	v_permlane16_swap_b32_e32 v13, v12
	s_and_saveexec_b64 s[2:3], s[44:45]
	s_cbranch_execz .LBB0_810
	s_waitcnt lgkmcnt(0)
	v_add_f32_e32 v12, v12, v13
	ds_write_b32 v102, v12 offset:3200
.LBB0_810:
	s_or_b64 exec, exec, s[2:3]
	s_waitcnt vmcnt(12)
	v_mul_f32_e32 v12, v1, v39
	v_fmac_f32_e32 v12, v0, v38
	v_fmac_f32_e32 v12, v2, v40
	v_fmac_f32_e32 v12, v3, v41
	s_waitcnt lgkmcnt(0)
	s_waitcnt lgkmcnt(0)
	s_nop 1
	v_add_f32_dpp v12, v12, v12 quad_perm:[1,0,3,2] row_mask:0xf bank_mask:0xf
	s_waitcnt lgkmcnt(0)
	s_nop 1
	v_add_f32_dpp v12, v12, v12 quad_perm:[2,3,0,1] row_mask:0xf bank_mask:0xf
	s_waitcnt lgkmcnt(0)
	s_nop 1
	v_add_f32_dpp v12, v12, v12 row_half_mirror row_mask:0xf bank_mask:0xf
	s_waitcnt lgkmcnt(0)
	s_nop 1
	v_add_f32_dpp v12, v12, v12 row_mirror row_mask:0xf bank_mask:0xf
	v_mov_b32_e32 v13, v12
	s_nop 1
	v_permlane16_swap_b32_e32 v13, v12
	s_and_saveexec_b64 s[2:3], s[44:45]
	s_cbranch_execz .LBB0_812
	s_waitcnt lgkmcnt(0)
	v_add_f32_e32 v12, v12, v13
	ds_write_b32 v102, v12 offset:3264
.LBB0_812:
	s_or_b64 exec, exec, s[2:3]
	s_waitcnt vmcnt(11)
	v_mul_f32_e32 v12, v1, v35
	v_fmac_f32_e32 v12, v0, v34
	v_fmac_f32_e32 v12, v2, v36
	v_fmac_f32_e32 v12, v3, v37
	s_waitcnt lgkmcnt(0)
	s_waitcnt lgkmcnt(0)
	s_nop 1
	v_add_f32_dpp v12, v12, v12 quad_perm:[1,0,3,2] row_mask:0xf bank_mask:0xf
	s_waitcnt lgkmcnt(0)
	s_nop 1
	v_add_f32_dpp v12, v12, v12 quad_perm:[2,3,0,1] row_mask:0xf bank_mask:0xf
	s_waitcnt lgkmcnt(0)
	s_nop 1
	v_add_f32_dpp v12, v12, v12 row_half_mirror row_mask:0xf bank_mask:0xf
	s_waitcnt lgkmcnt(0)
	s_nop 1
	v_add_f32_dpp v12, v12, v12 row_mirror row_mask:0xf bank_mask:0xf
	v_mov_b32_e32 v13, v12
	s_nop 1
	v_permlane16_swap_b32_e32 v13, v12
	s_and_saveexec_b64 s[2:3], s[44:45]
	s_cbranch_execz .LBB0_814
	s_waitcnt lgkmcnt(0)
	v_add_f32_e32 v12, v12, v13
	ds_write_b32 v102, v12 offset:3328
.LBB0_814:
	s_or_b64 exec, exec, s[2:3]
	s_waitcnt vmcnt(10)
	v_mul_f32_e32 v12, v1, v25
	v_fmac_f32_e32 v12, v0, v24
	v_fmac_f32_e32 v12, v2, v26
	v_fmac_f32_e32 v12, v3, v27
	s_waitcnt lgkmcnt(0)
	s_waitcnt lgkmcnt(0)
	s_nop 1
	v_add_f32_dpp v12, v12, v12 quad_perm:[1,0,3,2] row_mask:0xf bank_mask:0xf
	s_waitcnt lgkmcnt(0)
	s_nop 1
	v_add_f32_dpp v12, v12, v12 quad_perm:[2,3,0,1] row_mask:0xf bank_mask:0xf
	s_waitcnt lgkmcnt(0)
	s_nop 1
	v_add_f32_dpp v12, v12, v12 row_half_mirror row_mask:0xf bank_mask:0xf
	s_waitcnt lgkmcnt(0)
	s_nop 1
	v_add_f32_dpp v12, v12, v12 row_mirror row_mask:0xf bank_mask:0xf
	v_mov_b32_e32 v13, v12
	s_nop 1
	v_permlane16_swap_b32_e32 v13, v12
	s_and_saveexec_b64 s[2:3], s[44:45]
	s_cbranch_execz .LBB0_816
	s_waitcnt lgkmcnt(0)
	v_add_f32_e32 v12, v12, v13
	ds_write_b32 v102, v12 offset:3392
.LBB0_816:
	s_or_b64 exec, exec, s[2:3]
	s_waitcnt vmcnt(9)
	v_mul_f32_e32 v12, v1, v17
	v_fmac_f32_e32 v12, v0, v16
	v_fmac_f32_e32 v12, v2, v18
	v_fmac_f32_e32 v12, v3, v19
	s_waitcnt lgkmcnt(0)
	s_waitcnt lgkmcnt(0)
	s_nop 1
	v_add_f32_dpp v12, v12, v12 quad_perm:[1,0,3,2] row_mask:0xf bank_mask:0xf
	s_waitcnt lgkmcnt(0)
	s_nop 1
	v_add_f32_dpp v12, v12, v12 quad_perm:[2,3,0,1] row_mask:0xf bank_mask:0xf
	s_waitcnt lgkmcnt(0)
	s_nop 1
	v_add_f32_dpp v12, v12, v12 row_half_mirror row_mask:0xf bank_mask:0xf
	s_waitcnt lgkmcnt(0)
	s_nop 1
	v_add_f32_dpp v12, v12, v12 row_mirror row_mask:0xf bank_mask:0xf
	v_mov_b32_e32 v13, v12
	s_nop 1
	v_permlane16_swap_b32_e32 v13, v12
	s_and_saveexec_b64 s[2:3], s[44:45]
	s_cbranch_execz .LBB0_818
	s_waitcnt lgkmcnt(0)
	v_add_f32_e32 v12, v12, v13
	ds_write_b32 v102, v12 offset:3456
.LBB0_818:
	s_or_b64 exec, exec, s[2:3]
	s_waitcnt vmcnt(8)
	v_mul_f32_e32 v9, v1, v9
	v_fmac_f32_e32 v9, v0, v8
	v_fmac_f32_e32 v9, v2, v10
	v_fmac_f32_e32 v9, v3, v11
	s_waitcnt lgkmcnt(0)
	s_nop 1
	v_add_f32_dpp v8, v9, v9 quad_perm:[1,0,3,2] row_mask:0xf bank_mask:0xf
	s_waitcnt lgkmcnt(0)
	s_nop 1
	v_add_f32_dpp v8, v8, v8 quad_perm:[2,3,0,1] row_mask:0xf bank_mask:0xf
	s_waitcnt lgkmcnt(0)
	s_nop 1
	v_add_f32_dpp v8, v8, v8 row_half_mirror row_mask:0xf bank_mask:0xf
	s_waitcnt lgkmcnt(0)
	s_nop 1
	v_add_f32_dpp v8, v8, v8 row_mirror row_mask:0xf bank_mask:0xf
	v_mov_b32_e32 v9, v8
	s_nop 1
	v_permlane16_swap_b32_e32 v9, v8
	s_and_saveexec_b64 s[2:3], s[44:45]
	s_cbranch_execz .LBB0_820
	s_waitcnt lgkmcnt(0)
	v_add_f32_e32 v8, v8, v9
	ds_write_b32 v102, v8 offset:3520
.LBB0_820:
	s_or_b64 exec, exec, s[2:3]
	v_readlane_b32 s72, v251, 1
	v_readlane_b32 s78, v251, 7
	v_readlane_b32 s79, v251, 8
	v_mov_b32_e32 v85, v33
	s_waitcnt vmcnt(7)
	v_mul_f32_e32 v62, v1, v75
	s_waitcnt lgkmcnt(0)
	v_lshl_add_u64 v[8:9], s[78:79], 0, v[94:95]
	v_lshl_add_u64 v[8:9], v[8:9], 0, s[8:9]
	v_lshl_add_u64 v[34:35], v[8:9], 0, v[84:85]
	v_add_co_u32_e32 v12, vcc, 0x8000, v34
	v_fmac_f32_e32 v62, v0, v74
	s_nop 0
	v_addc_co_u32_e32 v13, vcc, 0, v35, vcc
	v_add_co_u32_e32 v16, vcc, 0x10000, v34
	global_load_dwordx4 v[8:11], v[34:35], off
	s_nop 0
	global_load_dwordx4 v[12:15], v[12:13], off
	v_addc_co_u32_e32 v17, vcc, 0, v35, vcc
	v_add_co_u32_e32 v20, vcc, 0x18000, v34
	v_fmac_f32_e32 v62, v2, v76
	s_nop 0
	v_addc_co_u32_e32 v21, vcc, 0, v35, vcc
	v_add_co_u32_e32 v24, vcc, s12, v34
	global_load_dwordx4 v[16:19], v[16:17], off
	s_nop 0
	global_load_dwordx4 v[20:23], v[20:21], off
	v_addc_co_u32_e32 v25, vcc, 0, v35, vcc
	v_add_co_u32_e32 v28, vcc, 0x28000, v34
	v_fmac_f32_e32 v62, v3, v77
	s_nop 0
	v_addc_co_u32_e32 v29, vcc, 0, v35, vcc
	v_add_co_u32_e32 v36, vcc, 0x30000, v34
	global_load_dwordx4 v[24:27], v[24:25], off
	s_nop 0
	global_load_dwordx4 v[28:31], v[28:29], off
	v_addc_co_u32_e32 v37, vcc, 0, v35, vcc
	v_add_co_u32_e32 v38, vcc, 0x38000, v34
	s_nop 0
	v_addc_co_u32_e32 v39, vcc, 0, v35, vcc
	global_load_dwordx4 v[34:37], v[36:37], off
	s_nop 0
	global_load_dwordx4 v[38:41], v[38:39], off
	v_readlane_b32 s73, v251, 2
	s_waitcnt lgkmcnt(0)
	s_nop 1
	v_add_f32_dpp v62, v62, v62 quad_perm:[1,0,3,2] row_mask:0xf bank_mask:0xf
	v_readlane_b32 s74, v251, 3
	v_readlane_b32 s75, v251, 4
	v_readlane_b32 s76, v251, 5
	v_readlane_b32 s77, v251, 6
	s_waitcnt lgkmcnt(0)
	s_nop 1
	v_add_f32_dpp v62, v62, v62 quad_perm:[2,3,0,1] row_mask:0xf bank_mask:0xf
	v_readlane_b32 s80, v251, 9
	v_readlane_b32 s81, v251, 10
	v_readlane_b32 s82, v251, 11
	v_readlane_b32 s83, v251, 12
	s_waitcnt lgkmcnt(0)
	s_nop 1
	v_add_f32_dpp v62, v62, v62 row_half_mirror row_mask:0xf bank_mask:0xf
	v_readlane_b32 s84, v251, 13
	v_readlane_b32 s85, v251, 14
	v_readlane_b32 s86, v251, 15
	v_readlane_b32 s87, v251, 16
	s_waitcnt lgkmcnt(0)
	s_nop 1
	v_add_f32_dpp v62, v62, v62 row_mirror row_mask:0xf bank_mask:0xf
	v_mov_b32_e32 v63, v62
	s_nop 1
	v_permlane16_swap_b32_e32 v63, v62
	s_and_saveexec_b64 s[2:3], s[44:45]
	s_cbranch_execz .LBB0_822
	s_waitcnt lgkmcnt(0)
	v_add_f32_e32 v62, v62, v63
	ds_write_b32 v102, v62 offset:3584
.LBB0_822:
	s_or_b64 exec, exec, s[2:3]
	s_waitcnt vmcnt(14)
	v_mul_f32_e32 v62, v1, v67
	v_fmac_f32_e32 v62, v0, v66
	v_fmac_f32_e32 v62, v2, v68
	v_fmac_f32_e32 v62, v3, v69
	s_waitcnt lgkmcnt(0)
	s_waitcnt lgkmcnt(0)
	s_nop 1
	v_add_f32_dpp v62, v62, v62 quad_perm:[1,0,3,2] row_mask:0xf bank_mask:0xf
	s_waitcnt lgkmcnt(0)
	s_nop 1
	v_add_f32_dpp v62, v62, v62 quad_perm:[2,3,0,1] row_mask:0xf bank_mask:0xf
	s_waitcnt lgkmcnt(0)
	s_nop 1
	v_add_f32_dpp v62, v62, v62 row_half_mirror row_mask:0xf bank_mask:0xf
	s_waitcnt lgkmcnt(0)
	s_nop 1
	v_add_f32_dpp v62, v62, v62 row_mirror row_mask:0xf bank_mask:0xf
	v_mov_b32_e32 v63, v62
	s_nop 1
	v_permlane16_swap_b32_e32 v63, v62
	s_and_saveexec_b64 s[2:3], s[44:45]
	s_cbranch_execz .LBB0_824
	s_waitcnt lgkmcnt(0)
	v_add_f32_e32 v62, v62, v63
	ds_write_b32 v102, v62 offset:3648
.LBB0_824:
	s_or_b64 exec, exec, s[2:3]
	s_waitcnt vmcnt(13)
	v_mul_f32_e32 v59, v1, v59
	v_fmac_f32_e32 v59, v0, v58
	v_fmac_f32_e32 v59, v2, v60
	v_fmac_f32_e32 v59, v3, v61
	s_waitcnt lgkmcnt(0)
	s_nop 1
	v_add_f32_dpp v58, v59, v59 quad_perm:[1,0,3,2] row_mask:0xf bank_mask:0xf
	s_waitcnt lgkmcnt(0)
	s_nop 1
	v_add_f32_dpp v58, v58, v58 quad_perm:[2,3,0,1] row_mask:0xf bank_mask:0xf
	s_waitcnt lgkmcnt(0)
	s_nop 1
	v_add_f32_dpp v58, v58, v58 row_half_mirror row_mask:0xf bank_mask:0xf
	s_waitcnt lgkmcnt(0)
	s_nop 1
	v_add_f32_dpp v58, v58, v58 row_mirror row_mask:0xf bank_mask:0xf
	v_mov_b32_e32 v59, v58
	s_nop 1
	v_permlane16_swap_b32_e32 v59, v58
	s_and_saveexec_b64 s[2:3], s[44:45]
	s_cbranch_execz .LBB0_826
	s_waitcnt lgkmcnt(0)
	v_add_f32_e32 v58, v58, v59
	ds_write_b32 v102, v58 offset:3712
.LBB0_826:
	s_or_b64 exec, exec, s[2:3]
	s_waitcnt vmcnt(12)
	v_mul_f32_e32 v55, v1, v55
	v_fmac_f32_e32 v55, v0, v54
	v_fmac_f32_e32 v55, v2, v56
	v_fmac_f32_e32 v55, v3, v57
	s_waitcnt lgkmcnt(0)
	s_nop 1
	v_add_f32_dpp v54, v55, v55 quad_perm:[1,0,3,2] row_mask:0xf bank_mask:0xf
	s_waitcnt lgkmcnt(0)
	s_nop 1
	v_add_f32_dpp v54, v54, v54 quad_perm:[2,3,0,1] row_mask:0xf bank_mask:0xf
	s_waitcnt lgkmcnt(0)
	s_nop 1
	v_add_f32_dpp v54, v54, v54 row_half_mirror row_mask:0xf bank_mask:0xf
	s_waitcnt lgkmcnt(0)
	s_nop 1
	v_add_f32_dpp v54, v54, v54 row_mirror row_mask:0xf bank_mask:0xf
	v_mov_b32_e32 v55, v54
	s_nop 1
	v_permlane16_swap_b32_e32 v55, v54
	s_and_saveexec_b64 s[2:3], s[44:45]
	s_cbranch_execz .LBB0_828
	s_waitcnt lgkmcnt(0)
	v_add_f32_e32 v54, v54, v55
	ds_write_b32 v102, v54 offset:3776
.LBB0_828:
	s_or_b64 exec, exec, s[2:3]
	s_waitcnt vmcnt(11)
	v_mul_f32_e32 v51, v1, v51
	v_fmac_f32_e32 v51, v0, v50
	v_fmac_f32_e32 v51, v2, v52
	v_fmac_f32_e32 v51, v3, v53
	s_waitcnt lgkmcnt(0)
	s_nop 1
	v_add_f32_dpp v50, v51, v51 quad_perm:[1,0,3,2] row_mask:0xf bank_mask:0xf
	s_waitcnt lgkmcnt(0)
	s_nop 1
	v_add_f32_dpp v50, v50, v50 quad_perm:[2,3,0,1] row_mask:0xf bank_mask:0xf
	s_waitcnt lgkmcnt(0)
	s_nop 1
	v_add_f32_dpp v50, v50, v50 row_half_mirror row_mask:0xf bank_mask:0xf
	s_waitcnt lgkmcnt(0)
	s_nop 1
	v_add_f32_dpp v50, v50, v50 row_mirror row_mask:0xf bank_mask:0xf
	v_mov_b32_e32 v51, v50
	s_nop 1
	v_permlane16_swap_b32_e32 v51, v50
	s_and_saveexec_b64 s[2:3], s[44:45]
	s_cbranch_execz .LBB0_830
	s_waitcnt lgkmcnt(0)
	v_add_f32_e32 v50, v50, v51
	ds_write_b32 v102, v50 offset:3840
.LBB0_830:
	s_or_b64 exec, exec, s[2:3]
	s_waitcnt vmcnt(10)
	v_mul_f32_e32 v47, v1, v47
	v_fmac_f32_e32 v47, v0, v46
	v_fmac_f32_e32 v47, v2, v48
	v_fmac_f32_e32 v47, v3, v49
	s_waitcnt lgkmcnt(0)
	s_nop 1
	v_add_f32_dpp v46, v47, v47 quad_perm:[1,0,3,2] row_mask:0xf bank_mask:0xf
	s_waitcnt lgkmcnt(0)
	s_nop 1
	v_add_f32_dpp v46, v46, v46 quad_perm:[2,3,0,1] row_mask:0xf bank_mask:0xf
	s_waitcnt lgkmcnt(0)
	s_nop 1
	v_add_f32_dpp v46, v46, v46 row_half_mirror row_mask:0xf bank_mask:0xf
	s_waitcnt lgkmcnt(0)
	s_nop 1
	v_add_f32_dpp v46, v46, v46 row_mirror row_mask:0xf bank_mask:0xf
	v_mov_b32_e32 v47, v46
	s_nop 1
	v_permlane16_swap_b32_e32 v47, v46
	s_and_saveexec_b64 s[2:3], s[44:45]
	s_cbranch_execz .LBB0_832
	s_waitcnt lgkmcnt(0)
	v_add_f32_e32 v46, v46, v47
	ds_write_b32 v102, v46 offset:3904
.LBB0_832:
	s_or_b64 exec, exec, s[2:3]
	s_waitcnt vmcnt(9)
	v_mul_f32_e32 v43, v1, v43
	v_fmac_f32_e32 v43, v0, v42
	v_fmac_f32_e32 v43, v2, v44
	v_fmac_f32_e32 v43, v3, v45
	s_waitcnt lgkmcnt(0)
	s_nop 1
	v_add_f32_dpp v42, v43, v43 quad_perm:[1,0,3,2] row_mask:0xf bank_mask:0xf
	s_waitcnt lgkmcnt(0)
	s_nop 1
	v_add_f32_dpp v42, v42, v42 quad_perm:[2,3,0,1] row_mask:0xf bank_mask:0xf
	s_waitcnt lgkmcnt(0)
	s_nop 1
	v_add_f32_dpp v42, v42, v42 row_half_mirror row_mask:0xf bank_mask:0xf
	s_waitcnt lgkmcnt(0)
	s_nop 1
	v_add_f32_dpp v42, v42, v42 row_mirror row_mask:0xf bank_mask:0xf
	v_mov_b32_e32 v43, v42
	s_nop 1
	v_permlane16_swap_b32_e32 v43, v42
	s_and_saveexec_b64 s[2:3], s[44:45]
	s_cbranch_execz .LBB0_834
	s_waitcnt lgkmcnt(0)
	v_add_f32_e32 v42, v42, v43
	ds_write_b32 v102, v42 offset:3968
.LBB0_834:
	s_or_b64 exec, exec, s[2:3]
	s_waitcnt vmcnt(8)
	v_mul_f32_e32 v5, v1, v5
	v_fmac_f32_e32 v5, v0, v4
	v_fmac_f32_e32 v5, v2, v6
	v_fmac_f32_e32 v5, v3, v7
	s_waitcnt lgkmcnt(0)
	s_nop 1
	v_add_f32_dpp v4, v5, v5 quad_perm:[1,0,3,2] row_mask:0xf bank_mask:0xf
	s_waitcnt lgkmcnt(0)
	s_nop 1
	v_add_f32_dpp v4, v4, v4 quad_perm:[2,3,0,1] row_mask:0xf bank_mask:0xf
	s_waitcnt lgkmcnt(0)
	s_nop 1
	v_add_f32_dpp v4, v4, v4 row_half_mirror row_mask:0xf bank_mask:0xf
	s_waitcnt lgkmcnt(0)
	s_nop 1
	v_add_f32_dpp v4, v4, v4 row_mirror row_mask:0xf bank_mask:0xf
	v_mov_b32_e32 v5, v4
	s_nop 1
	v_permlane16_swap_b32_e32 v5, v4
	s_and_saveexec_b64 s[2:3], s[44:45]
	s_cbranch_execz .LBB0_836
	s_waitcnt lgkmcnt(0)
	v_add_f32_e32 v4, v4, v5
	ds_write_b32 v102, v4 offset:4032
.LBB0_836:
	s_or_b64 exec, exec, s[2:3]
	s_and_saveexec_b64 s[2:3], s[46:47]
	s_cbranch_execz .LBB0_839
	s_lshl_b32 s11, s68, 2
	s_or_b32 s20, s11, s69
	s_ashr_i32 s21, s20, 31
	s_lshl_b64 s[20:21], s[20:21], 9
	s_waitcnt lgkmcnt(0)
	v_lshl_add_u64 v[4:5], v[88:89], 0, s[20:21]
	global_load_dwordx4 v[4:7], v[4:5], off
	s_waitcnt vmcnt(0)
	v_mul_f32_e32 v1, v1, v5
	v_fmac_f32_e32 v1, v0, v4
	v_fmac_f32_e32 v1, v2, v6
	v_fmac_f32_e32 v1, v3, v7
	s_waitcnt lgkmcnt(0)
	s_nop 1
	v_add_f32_dpp v0, v1, v1 quad_perm:[1,0,3,2] row_mask:0xf bank_mask:0xf
	s_waitcnt lgkmcnt(0)
	s_nop 1
	v_add_f32_dpp v0, v0, v0 quad_perm:[2,3,0,1] row_mask:0xf bank_mask:0xf
	s_waitcnt lgkmcnt(0)
	s_nop 1
	v_add_f32_dpp v0, v0, v0 row_half_mirror row_mask:0xf bank_mask:0xf
	s_waitcnt lgkmcnt(0)
	s_nop 1
	v_add_f32_dpp v0, v0, v0 row_mirror row_mask:0xf bank_mask:0xf
	v_mov_b32_e32 v1, v0
	s_nop 1
	v_permlane16_swap_b32_e32 v1, v0
	s_and_b64 exec, exec, s[44:45]
	s_cbranch_execz .LBB0_839
	s_waitcnt lgkmcnt(0)
	v_add_f32_e32 v0, v0, v1
	ds_write_b32 v33, v0 offset:4096

.LBB0_857:
	s_or_b64 exec, exec, s[2:3]
	s_waitcnt lgkmcnt(0)
	s_waitcnt lgkmcnt(0)
	s_nop 1
	v_add_f32_dpp v0, v42, v42 quad_perm:[1,0,3,2] row_mask:0xf bank_mask:0xf
	s_waitcnt lgkmcnt(0)
	s_nop 1
	v_add_f32_dpp v0, v0, v0 quad_perm:[2,3,0,1] row_mask:0xf bank_mask:0xf
	s_waitcnt lgkmcnt(0)
	s_nop 1
	v_add_f32_dpp v0, v0, v0 row_half_mirror row_mask:0xf bank_mask:0xf
	s_waitcnt lgkmcnt(0)
	s_nop 1
	v_add_f32_dpp v0, v0, v0 row_mirror row_mask:0xf bank_mask:0xf
	v_mov_b32_e32 v1, v0
	s_nop 1
	v_permlane16_swap_b32_e32 v1, v0
	s_waitcnt lgkmcnt(0)
	v_add_f32_e32 v0, v0, v1
	v_mov_b32_e32 v1, v0
	s_nop 1
	v_permlane32_swap_b32_e32 v1, v0
	s_and_saveexec_b64 s[2:3], s[50:51]
	s_cbranch_execz .LBB0_859
	s_waitcnt lgkmcnt(0)
	v_add_f32_e32 v0, v0, v1
	v_mov_b32_e32 v1, s64
	ds_write_b32 v1, v0 offset:4352

.LBB0_982:
	s_add_i32 s2, s41, 16
	s_cmp_lt_i32 s2, s29
	s_cselect_b32 s2, s2, s41
	s_lshl_b32 s2, s2, 4
	s_add_i32 s2, s2, s23
	v_or_b32_e32 v24, s2, v132
	v_cmp_gt_i32_e32 vcc, s28, v24
	v_mov_b32_e32 v25, s2
	s_min_i32 s2, s17, 47
	v_cndmask_b32_e32 v24, v25, v24, vcc
	s_ashr_i32 s3, s2, 3
	v_ashrrev_i32_e32 v25, 31, v24
	s_lshl_b32 s3, s3, 2
	v_readlane_b32 s18, v254, 24
	v_lshl_add_u64 v[24:25], v[24:25], 2, s[46:47]
	s_add_i32 s3, s18, s3
	global_load_dword v233, v[24:25], off
	v_mov_b32_e32 v24, s3
	ds_read_b32 v24, v24
	s_lshl_b32 s2, s2, 4
	s_and_b32 s2, s2, 0x70
	v_readlane_b32 s48, v251, 1
	v_readlane_b32 s52, v251, 5
	s_waitcnt lgkmcnt(0)
	v_lshlrev_b32_e32 v24, 7, v24
	v_or_b32_e32 v24, s2, v24
	s_min_i32 s2, s17, 46
	s_add_i32 s2, s2, 1
	s_ashr_i32 s3, s2, 3
	s_lshl_b32 s3, s3, 2
	s_add_i32 s3, s18, s3
	s_waitcnt vmcnt(3)
	v_mov_b32_e32 v28, s3
	ds_read_b32 v28, v28
	s_lshl_b32 s2, s2, 4
	s_and_b32 s2, s2, 0x70
	v_add_u32_e32 v24, v24, v186
	v_ashrrev_i32_e32 v25, 31, v24
	s_waitcnt lgkmcnt(0)
	v_lshlrev_b32_e32 v28, 7, v28
	v_or_b32_e32 v28, s2, v28
	v_add_u32_e32 v28, v28, v186
	v_ashrrev_i32_e32 v29, 31, v28
	v_lshlrev_b64 v[24:25], 11, v[24:25]
	v_lshlrev_b64 v[28:29], 11, v[28:29]
	v_or_b32_e32 v24, v24, v227
	v_readlane_b32 s53, v251, 6
	v_readlane_b32 s54, v251, 7
	v_readlane_b32 s55, v251, 8
	v_or_b32_e32 v28, v28, v227
	v_lshl_add_u64 v[26:27], s[52:53], 0, v[24:25]
	v_lshl_add_u64 v[24:25], s[54:55], 0, v[24:25]
	v_lshl_add_u64 v[30:31], s[52:53], 0, v[28:29]
	v_lshl_add_u64 v[28:29], s[54:55], 0, v[28:29]
	global_load_dwordx4 v[34:37], v[26:27], off
	global_load_dwordx4 v[38:41], v[30:31], off
	v_and_b32_e32 v32, 0x1fff, v220
	global_load_dwordx4 v[24:27], v[24:25], off
	v_readlane_b32 s49, v251, 2
	global_load_dwordx4 v[28:31], v[28:29], off
	ds_read_b128 v[42:45], v136
	ds_read_b128 v[46:49], v137
	ds_read_b128 v[50:53], v228
	ds_read_b128 v[54:57], v229
	ds_read_b128 v[58:61], v136 offset:1024
	ds_read_b128 v[62:65], v137 offset:1024
	ds_read_b128 v[66:69], v228 offset:1024
	ds_read_b128 v[70:73], v229 offset:1024
	v_readlane_b32 s50, v251, 3
	v_readlane_b32 s51, v251, 4
	v_readlane_b32 s56, v251, 9
	v_readlane_b32 s57, v251, 10
	v_readlane_b32 s58, v251, 11
	v_readlane_b32 s59, v251, 12
	v_readlane_b32 s60, v251, 13
	v_readlane_b32 s61, v251, 14
	v_readlane_b32 s62, v251, 15
	v_readlane_b32 s63, v251, 16
	v_lshrrev_b32_e32 v118, 14, v220
	v_or_b32_e32 v120, s30, v32
	s_waitcnt lgkmcnt(7)
	v_mfma_f32_16x16x32_bf16 v[42:45], v[42:45], v[8:11], 0
	s_waitcnt lgkmcnt(6)
	v_mfma_f32_16x16x32_bf16 v[42:45], v[46:49], v[12:15], v[42:45]
	s_waitcnt lgkmcnt(5)
	v_mfma_f32_16x16x32_bf16 v[42:45], v[50:53], v[16:19], v[42:45]
	s_waitcnt vmcnt(5) lgkmcnt(4)
	v_mfma_f32_16x16x32_bf16 v[114:117], v[54:57], v[20:23], v[42:45]
	s_waitcnt lgkmcnt(3)
	v_mfma_f32_16x16x32_bf16 v[42:45], v[58:61], v[8:11], 0
	s_waitcnt lgkmcnt(2)
	v_mfma_f32_16x16x32_bf16 v[42:45], v[62:65], v[12:15], v[42:45]
	s_waitcnt lgkmcnt(1)
	v_mfma_f32_16x16x32_bf16 v[42:45], v[66:69], v[16:19], v[42:45]
	s_waitcnt lgkmcnt(0)
	v_mfma_f32_16x16x32_bf16 v[110:113], v[70:73], v[20:23], v[42:45]
	s_nop 5
	ds_read_b128 v[42:45], v136 offset:8192
	ds_read_b128 v[46:49], v136 offset:9216
	ds_read_b128 v[50:53], v137 offset:8192
	ds_read_b128 v[54:57], v137 offset:9216
	ds_read_b128 v[58:61], v228 offset:8192
	ds_read_b128 v[62:65], v228 offset:9216
	ds_read_b128 v[66:69], v229 offset:8192
	ds_read_b128 v[70:73], v229 offset:9216
	s_waitcnt lgkmcnt(7)
	v_mfma_f32_16x16x32_bf16 v[42:45], v[42:45], v[8:11], 0
	s_waitcnt lgkmcnt(5)
	v_mfma_f32_16x16x32_bf16 v[42:45], v[50:53], v[12:15], v[42:45]
	s_waitcnt lgkmcnt(3)
	v_mfma_f32_16x16x32_bf16 v[42:45], v[58:61], v[16:19], v[42:45]
	s_waitcnt lgkmcnt(1)
	v_mfma_f32_16x16x32_bf16 v[106:109], v[66:69], v[20:23], v[42:45]
	v_mfma_f32_16x16x32_bf16 v[42:45], v[46:49], v[8:11], 0
	v_mfma_f32_16x16x32_bf16 v[42:45], v[54:57], v[12:15], v[42:45]
	v_mfma_f32_16x16x32_bf16 v[42:45], v[62:65], v[16:19], v[42:45]
	s_waitcnt lgkmcnt(0)
	v_mfma_f32_16x16x32_bf16 v[102:105], v[70:73], v[20:23], v[42:45]
	s_nop 5
	ds_read_b128 v[42:45], v136 offset:16384
	ds_read_b128 v[46:49], v136 offset:17408
	ds_read_b128 v[50:53], v137 offset:16384
	ds_read_b128 v[54:57], v137 offset:17408
	ds_read_b128 v[58:61], v228 offset:16384
	ds_read_b128 v[62:65], v228 offset:17408
	ds_read_b128 v[66:69], v229 offset:16384
	ds_read_b128 v[70:73], v229 offset:17408
	s_waitcnt lgkmcnt(7)
	v_mfma_f32_16x16x32_bf16 v[42:45], v[42:45], v[8:11], 0
	s_waitcnt lgkmcnt(5)
	v_mfma_f32_16x16x32_bf16 v[42:45], v[50:53], v[12:15], v[42:45]
	s_waitcnt lgkmcnt(3)
	v_mfma_f32_16x16x32_bf16 v[42:45], v[58:61], v[16:19], v[42:45]
	s_waitcnt lgkmcnt(1)
	v_mfma_f32_16x16x32_bf16 v[98:101], v[66:69], v[20:23], v[42:45]
	v_mfma_f32_16x16x32_bf16 v[42:45], v[46:49], v[8:11], 0
	v_mfma_f32_16x16x32_bf16 v[42:45], v[54:57], v[12:15], v[42:45]
	v_mfma_f32_16x16x32_bf16 v[42:45], v[62:65], v[16:19], v[42:45]
	s_waitcnt lgkmcnt(0)
	v_mfma_f32_16x16x32_bf16 v[94:97], v[70:73], v[20:23], v[42:45]
	s_nop 5
	ds_read_b128 v[42:45], v136 offset:24576
	ds_read_b128 v[46:49], v136 offset:25600
	ds_read_b128 v[50:53], v137 offset:24576
	ds_read_b128 v[54:57], v137 offset:25600
	ds_read_b128 v[58:61], v228 offset:24576
	ds_read_b128 v[62:65], v228 offset:25600
	ds_read_b128 v[66:69], v229 offset:24576
	ds_read_b128 v[70:73], v229 offset:25600
	s_waitcnt lgkmcnt(7)
	v_mfma_f32_16x16x32_bf16 v[42:45], v[42:45], v[8:11], 0
	s_waitcnt lgkmcnt(5)
	v_mfma_f32_16x16x32_bf16 v[42:45], v[50:53], v[12:15], v[42:45]
	s_waitcnt lgkmcnt(3)
	v_mfma_f32_16x16x32_bf16 v[42:45], v[58:61], v[16:19], v[42:45]
	s_waitcnt lgkmcnt(1)
	v_mfma_f32_16x16x32_bf16 v[90:93], v[66:69], v[20:23], v[42:45]
	v_mfma_f32_16x16x32_bf16 v[42:45], v[46:49], v[8:11], 0
	v_mfma_f32_16x16x32_bf16 v[42:45], v[54:57], v[12:15], v[42:45]
	v_mfma_f32_16x16x32_bf16 v[42:45], v[62:65], v[16:19], v[42:45]
	s_waitcnt lgkmcnt(0)
	v_mfma_f32_16x16x32_bf16 v[86:89], v[70:73], v[20:23], v[42:45]
	s_nop 5
	ds_read_b128 v[42:45], v136 offset:32768
	ds_read_b128 v[46:49], v136 offset:33792
	ds_read_b128 v[50:53], v137 offset:32768
	ds_read_b128 v[54:57], v137 offset:33792
	ds_read_b128 v[58:61], v228 offset:32768
	ds_read_b128 v[62:65], v228 offset:33792
	ds_read_b128 v[66:69], v229 offset:32768
	ds_read_b128 v[70:73], v229 offset:33792
	s_waitcnt lgkmcnt(7)
	v_mfma_f32_16x16x32_bf16 v[42:45], v[42:45], v[8:11], 0
	s_waitcnt lgkmcnt(5)
	v_mfma_f32_16x16x32_bf16 v[42:45], v[50:53], v[12:15], v[42:45]
	s_waitcnt lgkmcnt(3)
	v_mfma_f32_16x16x32_bf16 v[42:45], v[58:61], v[16:19], v[42:45]
	s_waitcnt lgkmcnt(1)
	v_mfma_f32_16x16x32_bf16 v[82:85], v[66:69], v[20:23], v[42:45]
	v_mfma_f32_16x16x32_bf16 v[42:45], v[46:49], v[8:11], 0
	v_mfma_f32_16x16x32_bf16 v[42:45], v[54:57], v[12:15], v[42:45]
	v_mfma_f32_16x16x32_bf16 v[42:45], v[62:65], v[16:19], v[42:45]
	s_waitcnt lgkmcnt(0)
	v_mfma_f32_16x16x32_bf16 v[78:81], v[70:73], v[20:23], v[42:45]
	s_nop 5
	ds_read_b128 v[42:45], v136 offset:40960
	ds_read_b128 v[46:49], v136 offset:41984
	ds_read_b128 v[50:53], v137 offset:40960
	ds_read_b128 v[54:57], v137 offset:41984
	ds_read_b128 v[58:61], v228 offset:40960
	ds_read_b128 v[62:65], v228 offset:41984
	ds_read_b128 v[66:69], v229 offset:40960
	ds_read_b128 v[70:73], v229 offset:41984
	s_waitcnt lgkmcnt(7)
	v_mfma_f32_16x16x32_bf16 v[42:45], v[42:45], v[8:11], 0
	s_waitcnt lgkmcnt(5)
	v_mfma_f32_16x16x32_bf16 v[42:45], v[50:53], v[12:15], v[42:45]
	s_waitcnt lgkmcnt(3)
	v_mfma_f32_16x16x32_bf16 v[42:45], v[58:61], v[16:19], v[42:45]
	s_waitcnt lgkmcnt(1)
	v_mfma_f32_16x16x32_bf16 v[74:77], v[66:69], v[20:23], v[42:45]
	v_mfma_f32_16x16x32_bf16 v[42:45], v[46:49], v[8:11], 0
	v_mfma_f32_16x16x32_bf16 v[42:45], v[54:57], v[12:15], v[42:45]
	v_mfma_f32_16x16x32_bf16 v[42:45], v[62:65], v[16:19], v[42:45]
	s_waitcnt lgkmcnt(0)
	v_mfma_f32_16x16x32_bf16 v[70:73], v[70:73], v[20:23], v[42:45]
	s_nop 5
	ds_read_b128 v[42:45], v136 offset:49152
	ds_read_b128 v[46:49], v136 offset:50176
	ds_read_b128 v[50:53], v137 offset:49152
	ds_read_b128 v[54:57], v137 offset:50176
	ds_read_b128 v[58:61], v228 offset:49152
	ds_read_b128 v[62:65], v228 offset:50176
	ds_read_b128 v[66:69], v229 offset:49152
	ds_read_b128 v[234:237], v229 offset:50176
	s_waitcnt lgkmcnt(7)
	v_mfma_f32_16x16x32_bf16 v[42:45], v[42:45], v[8:11], 0
	s_waitcnt lgkmcnt(5)
	v_mfma_f32_16x16x32_bf16 v[42:45], v[50:53], v[12:15], v[42:45]
	s_waitcnt lgkmcnt(3)
	v_mfma_f32_16x16x32_bf16 v[42:45], v[58:61], v[16:19], v[42:45]
	s_waitcnt lgkmcnt(1)
	v_mfma_f32_16x16x32_bf16 v[66:69], v[66:69], v[20:23], v[42:45]
	v_mfma_f32_16x16x32_bf16 v[42:45], v[46:49], v[8:11], 0
	v_mfma_f32_16x16x32_bf16 v[42:45], v[54:57], v[12:15], v[42:45]
	v_mfma_f32_16x16x32_bf16 v[42:45], v[62:65], v[16:19], v[42:45]
	s_waitcnt lgkmcnt(0)
	v_mfma_f32_16x16x32_bf16 v[62:65], v[234:237], v[20:23], v[42:45]
	s_nop 5
	ds_read_b128 v[42:45], v136 offset:57344
	ds_read_b128 v[46:49], v136 offset:58368
	ds_read_b128 v[50:53], v137 offset:57344
	ds_read_b128 v[54:57], v137 offset:58368
	ds_read_b128 v[58:61], v228 offset:57344
	ds_read_b128 v[234:237], v228 offset:58368
	ds_read_b128 v[238:241], v229 offset:57344
	ds_read_b128 v[242:245], v229 offset:58368
	s_waitcnt lgkmcnt(7)
	v_mfma_f32_16x16x32_bf16 v[42:45], v[42:45], v[8:11], 0
	s_waitcnt lgkmcnt(6)
	v_mfma_f32_16x16x32_bf16 v[8:11], v[46:49], v[8:11], 0
	s_waitcnt lgkmcnt(4)
	v_mfma_f32_16x16x32_bf16 v[8:11], v[54:57], v[12:15], v[8:11]
	v_mfma_f32_16x16x32_bf16 v[42:45], v[50:53], v[12:15], v[42:45]
	s_waitcnt lgkmcnt(2)
	v_mfma_f32_16x16x32_bf16 v[8:11], v[234:237], v[16:19], v[8:11]
	v_mfma_f32_16x16x32_bf16 v[42:45], v[58:61], v[16:19], v[42:45]
	s_waitcnt lgkmcnt(0)
	v_mfma_f32_16x16x32_bf16 v[8:11], v[242:245], v[20:23], v[8:11]
	v_mfma_f32_16x16x32_bf16 v[58:61], v[238:241], v[20:23], v[42:45]
	v_max3_f32 v12, v217, v114, v115
	v_max3_f32 v13, v218, v116, v117
	s_nop 4
	ds_read_b128 v[42:45], v133
	ds_read_b128 v[46:49], v133 offset:8704
	ds_read_b128 v[50:53], v133 offset:17408
	ds_read_b128 v[54:57], v133 offset:26112
	v_max3_f32 v12, v12, v110, v111
	v_max3_f32 v13, v13, v112, v113
	s_nop 0
	v_max3_f32 v12, v12, v106, v107
	v_max3_f32 v13, v13, v108, v109
	s_nop 0
	v_max3_f32 v12, v12, v102, v103
	v_max3_f32 v13, v13, v104, v105
	s_nop 0
	v_max3_f32 v12, v12, v98, v99
	v_max3_f32 v13, v13, v100, v101
	s_nop 0
	v_max3_f32 v12, v12, v94, v95
	v_max3_f32 v13, v13, v96, v97
	s_nop 0
	v_max3_f32 v12, v12, v90, v91
	v_max3_f32 v13, v13, v92, v93
	s_nop 0
	v_max3_f32 v12, v12, v86, v87
	v_max3_f32 v13, v13, v88, v89
	s_nop 0
	v_max3_f32 v12, v12, v82, v83
	v_max3_f32 v13, v13, v84, v85
	s_nop 0
	v_max3_f32 v12, v12, v78, v79
	v_max3_f32 v13, v13, v80, v81
	s_nop 0
	v_max3_f32 v12, v12, v74, v75
	v_max3_f32 v13, v13, v76, v77
	s_nop 0
	v_max3_f32 v12, v12, v70, v71
	v_max3_f32 v13, v13, v72, v73
	s_nop 0
	v_max3_f32 v12, v12, v66, v67
	v_max3_f32 v13, v13, v68, v69
	s_nop 0
	v_max3_f32 v12, v12, v62, v63
	v_max3_f32 v13, v13, v64, v65
	s_nop 0
	v_max3_f32 v12, v12, v58, v59
	v_max3_f32 v13, v13, v60, v61
	s_nop 0
	v_max3_f32 v12, v12, v8, v9
	v_max3_f32 v13, v13, v10, v11
	s_nop 0
	v_max_f32 v12, v12, v13
	v_mov_b32_e32 v13, v12
	s_nop 1
	v_permlane16_swap_b32_e32 v13, v12
	s_waitcnt lgkmcnt(0)
	v_max_f32 v12, v12, v13
	v_mov_b32_e32 v13, v12
	s_nop 1
	v_permlane32_swap_b32_e32 v13, v12
	s_waitcnt lgkmcnt(0)
	v_max_f32 v130, v12, v13
	s_nop 0
	v_mov_b32_e32 v131, v130
	v_pk_add_f32 v[12:13], v[114:115], v[130:131] neg_lo:[0,1] neg_hi:[0,1]
	v_pk_add_f32 v[14:15], v[116:117], v[130:131] neg_lo:[0,1] neg_hi:[0,1]
	v_pk_add_f32 v[16:17], v[110:111], v[130:131] neg_lo:[0,1] neg_hi:[0,1]
	v_pk_add_f32 v[18:19], v[112:113], v[130:131] neg_lo:[0,1] neg_hi:[0,1]
	v_pk_add_f32 v[102:103], v[102:103], v[130:131] neg_lo:[0,1] neg_hi:[0,1]
	v_pk_add_f32 v[104:105], v[104:105], v[130:131] neg_lo:[0,1] neg_hi:[0,1]
	s_nop 0
	v_exp_f32_e32 v12, v12
	v_exp_f32_e32 v13, v13
	v_exp_f32_e32 v14, v14
	v_exp_f32_e32 v15, v15
	v_exp_f32_e32 v16, v16
	v_exp_f32_e32 v18, v18
	v_exp_f32_e32 v19, v19
	v_exp_f32_e32 v17, v17
	v_pk_add_f32 v[20:21], v[12:13], 0 op_sel_hi:[1,0]
	v_pk_add_f32 v[22:23], v[14:15], 0 op_sel_hi:[1,0]
	v_exp_f32_e32 v102, v102
	v_pk_add_f32 v[110:111], v[22:23], v[18:19]
	v_pk_add_f32 v[112:113], v[20:21], v[16:17]
	v_pk_add_f32 v[20:21], v[106:107], v[130:131] neg_lo:[0,1] neg_hi:[0,1]
	v_pk_add_f32 v[22:23], v[108:109], v[130:131] neg_lo:[0,1] neg_hi:[0,1]
	v_exp_f32_e32 v104, v104
	v_exp_f32_e32 v20, v20
	v_exp_f32_e32 v21, v21
	v_exp_f32_e32 v22, v22
	v_exp_f32_e32 v23, v23
	v_exp_f32_e32 v105, v105
	v_exp_f32_e32 v103, v103
	v_pk_add_f32 v[98:99], v[98:99], v[130:131] neg_lo:[0,1] neg_hi:[0,1]
	v_pk_add_f32 v[100:101], v[100:101], v[130:131] neg_lo:[0,1] neg_hi:[0,1]
	v_pk_add_f32 v[94:95], v[94:95], v[130:131] neg_lo:[0,1] neg_hi:[0,1]
	v_pk_add_f32 v[96:97], v[96:97], v[130:131] neg_lo:[0,1] neg_hi:[0,1]
	v_pk_add_f32 v[90:91], v[90:91], v[130:131] neg_lo:[0,1] neg_hi:[0,1]
	v_pk_add_f32 v[92:93], v[92:93], v[130:131] neg_lo:[0,1] neg_hi:[0,1]
	s_nop 0
	v_exp_f32_e32 v98, v98
	v_exp_f32_e32 v99, v99
	v_exp_f32_e32 v100, v100
	v_exp_f32_e32 v101, v101
	v_exp_f32_e32 v94, v94
	v_exp_f32_e32 v96, v96
	v_exp_f32_e32 v97, v97
	v_exp_f32_e32 v95, v95
	v_pk_add_f32 v[106:107], v[112:113], v[20:21]
	v_pk_add_f32 v[108:109], v[110:111], v[22:23]
	v_exp_f32_e32 v90, v90
	v_exp_f32_e32 v91, v91
	v_exp_f32_e32 v92, v92
	v_exp_f32_e32 v93, v93
	v_pk_add_f32 v[108:109], v[108:109], v[104:105]
	v_pk_add_f32 v[106:107], v[106:107], v[102:103]
	v_pk_add_f32 v[108:109], v[108:109], v[100:101]
	v_pk_add_f32 v[106:107], v[106:107], v[98:99]
	v_pk_add_f32 v[108:109], v[108:109], v[96:97]
	v_pk_add_f32 v[106:107], v[106:107], v[94:95]
	v_pk_add_f32 v[86:87], v[86:87], v[130:131] neg_lo:[0,1] neg_hi:[0,1]
	v_pk_add_f32 v[88:89], v[88:89], v[130:131] neg_lo:[0,1] neg_hi:[0,1]
	v_pk_add_f32 v[82:83], v[82:83], v[130:131] neg_lo:[0,1] neg_hi:[0,1]
	v_pk_add_f32 v[84:85], v[84:85], v[130:131] neg_lo:[0,1] neg_hi:[0,1]
	v_pk_add_f32 v[78:79], v[78:79], v[130:131] neg_lo:[0,1] neg_hi:[0,1]
	v_pk_add_f32 v[80:81], v[80:81], v[130:131] neg_lo:[0,1] neg_hi:[0,1]
	s_nop 0
	v_exp_f32_e32 v110, v86
	v_exp_f32_e32 v112, v88
	v_exp_f32_e32 v113, v89
	v_exp_f32_e32 v111, v87
	v_pk_add_f32 v[86:87], v[106:107], v[90:91]
	v_pk_add_f32 v[88:89], v[108:109], v[92:93]
	v_exp_f32_e32 v106, v82
	v_exp_f32_e32 v107, v83
	v_exp_f32_e32 v108, v84
	v_exp_f32_e32 v109, v85
	v_exp_f32_e32 v114, v78
	v_exp_f32_e32 v116, v80
	v_exp_f32_e32 v117, v81
	v_exp_f32_e32 v115, v79
	v_pk_add_f32 v[74:75], v[74:75], v[130:131] neg_lo:[0,1] neg_hi:[0,1]
	v_pk_add_f32 v[76:77], v[76:77], v[130:131] neg_lo:[0,1] neg_hi:[0,1]
	v_pk_add_f32 v[88:89], v[88:89], v[112:113]
	v_exp_f32_e32 v188, v74
	v_exp_f32_e32 v189, v75
	v_exp_f32_e32 v234, v76
	v_exp_f32_e32 v235, v77
	v_pk_add_f32 v[86:87], v[86:87], v[110:111]
	v_pk_add_f32 v[70:71], v[70:71], v[130:131] neg_lo:[0,1] neg_hi:[0,1]
	v_pk_add_f32 v[72:73], v[72:73], v[130:131] neg_lo:[0,1] neg_hi:[0,1]
	v_pk_add_f32 v[80:81], v[88:89], v[108:109]
	v_exp_f32_e32 v236, v70
	v_exp_f32_e32 v238, v72
	v_exp_f32_e32 v239, v73
	v_exp_f32_e32 v237, v71
	v_pk_add_f32 v[78:79], v[86:87], v[106:107]
	v_pk_add_f32 v[66:67], v[66:67], v[130:131] neg_lo:[0,1] neg_hi:[0,1]
	v_pk_add_f32 v[68:69], v[68:69], v[130:131] neg_lo:[0,1] neg_hi:[0,1]
	v_pk_add_f32 v[80:81], v[80:81], v[116:117]
	v_exp_f32_e32 v240, v66
	v_exp_f32_e32 v241, v67
	v_exp_f32_e32 v242, v68
	v_exp_f32_e32 v243, v69
	v_pk_add_f32 v[78:79], v[78:79], v[114:115]
	v_pk_add_f32 v[62:63], v[62:63], v[130:131] neg_lo:[0,1] neg_hi:[0,1]
	v_pk_add_f32 v[64:65], v[64:65], v[130:131] neg_lo:[0,1] neg_hi:[0,1]
	v_pk_add_f32 v[72:73], v[80:81], v[234:235]
	v_exp_f32_e32 v244, v62
	v_exp_f32_e32 v246, v64
	v_exp_f32_e32 v247, v65
	v_exp_f32_e32 v245, v63
	v_pk_add_f32 v[70:71], v[78:79], v[188:189]
	v_pk_add_f32 v[58:59], v[58:59], v[130:131] neg_lo:[0,1] neg_hi:[0,1]
	v_pk_add_f32 v[60:61], v[60:61], v[130:131] neg_lo:[0,1] neg_hi:[0,1]
	v_pk_add_f32 v[8:9], v[8:9], v[130:131] neg_lo:[0,1] neg_hi:[0,1]
	v_pk_add_f32 v[10:11], v[10:11], v[130:131] neg_lo:[0,1] neg_hi:[0,1]
	v_pk_add_f32 v[72:73], v[72:73], v[238:239]
	v_exp_f32_e32 v248, v58
	v_exp_f32_e32 v249, v59
	v_exp_f32_e32 v158, v60
	v_exp_f32_e32 v159, v61
	v_pk_add_f32 v[70:71], v[70:71], v[236:237]
	v_exp_f32_e32 v8, v8
	v_exp_f32_e32 v10, v10
	v_exp_f32_e32 v11, v11
	v_exp_f32_e32 v9, v9
	v_pk_add_f32 v[62:63], v[70:71], v[240:241]
	v_pk_add_f32 v[64:65], v[72:73], v[242:243]
	v_pk_add_f32 v[62:63], v[62:63], v[244:245]
	v_pk_add_f32 v[64:65], v[64:65], v[246:247]
	v_pk_add_f32 v[58:59], v[62:63], v[248:249]
	v_pk_add_f32 v[60:61], v[64:65], v[158:159]
	v_pk_add_f32 v[58:59], v[58:59], v[8:9]
	v_pk_add_f32 v[60:61], v[60:61], v[10:11]
	s_nop 0
	v_pk_mov_b32 v[62:63], v[58:59], v[60:61] op_sel:[1,0]
	v_mov_b32_e32 v59, v61
	v_pk_add_f32 v[58:59], v[62:63], v[58:59]
	s_nop 0
	v_add_f32_e32 v32, v58, v59
	ds_read_b128 v[58:61], v133 offset:34816
	ds_read_b128 v[62:65], v133 offset:43520
	ds_read_b128 v[66:69], v133 offset:52224
	ds_read_b128 v[70:73], v133 offset:60928
	v_mov_b32_e32 v74, v32
	s_nop 1
	v_permlane16_swap_b32_e32 v74, v32
	s_waitcnt lgkmcnt(0)
	v_add_f32_e32 v119, v32, v74
	v_cvt_pk_bf16_f32 v74, v12, v13
	v_cvt_pk_bf16_f32 v75, v14, v15
	v_cvt_pk_bf16_f32 v76, v16, v17
	v_cvt_pk_bf16_f32 v77, v18, v19
	v_cvt_pk_bf16_f32 v78, v20, v21
	v_cvt_pk_bf16_f32 v79, v22, v23
	v_cvt_pk_bf16_f32 v80, v102, v103
	v_cvt_pk_bf16_f32 v81, v104, v105
	v_cvt_pk_bf16_f32 v82, v98, v99
	v_cvt_pk_bf16_f32 v83, v100, v101
	v_cvt_pk_bf16_f32 v84, v94, v95
	v_cvt_pk_bf16_f32 v85, v96, v97
	v_cvt_pk_bf16_f32 v86, v90, v91
	v_cvt_pk_bf16_f32 v87, v92, v93
	v_cvt_pk_bf16_f32 v88, v110, v111
	v_cvt_pk_bf16_f32 v89, v112, v113
	v_cvt_pk_bf16_f32 v90, v106, v107
	v_cvt_pk_bf16_f32 v91, v108, v109
	v_cvt_pk_bf16_f32 v92, v114, v115
	v_cvt_pk_bf16_f32 v93, v116, v117
	v_cvt_pk_bf16_f32 v94, v188, v189
	v_cvt_pk_bf16_f32 v95, v234, v235
	v_cvt_pk_bf16_f32 v96, v236, v237
	v_cvt_pk_bf16_f32 v97, v238, v239
	v_cvt_pk_bf16_f32 v98, v240, v241
	v_cvt_pk_bf16_f32 v99, v242, v243
	v_cvt_pk_bf16_f32 v100, v244, v245
	v_cvt_pk_bf16_f32 v101, v246, v247
	v_mov_b32_e32 v106, v119
	s_nop 1
	v_permlane32_swap_b32_e32 v106, v119
	v_cvt_pk_bf16_f32 v102, v248, v249
	v_cvt_pk_bf16_f32 v103, v158, v159
	v_cvt_pk_bf16_f32 v104, v8, v9
	v_cvt_pk_bf16_f32 v105, v10, v11
	v_and_b32_e32 v8, 0x1fff, v230
	v_or_b32_e32 v8, s30, v8
	v_ashrrev_i32_e32 v9, 31, v8
	v_lshrrev_b32_e32 v10, 13, v230
	v_lshlrev_b64 v[8:9], 11, v[8:9]
	v_and_or_b32 v10, v10, 1, s31
	v_lshl_add_u64 v[8:9], s[4:5], 0, v[8:9]
	v_lshlrev_b32_e32 v32, 8, v10
	v_lshl_add_u64 v[8:9], v[8:9], 0, v[32:33]
	v_mov_b32_e32 v129, v33
	v_lshl_add_u64 v[20:21], v[8:9], 0, v[128:129]
	global_load_dwordx4 v[8:11], v[20:21], off
	global_load_dwordx4 v[12:15], v[20:21], off offset:64
	global_load_dwordx4 v[16:19], v[20:21], off offset:128
	s_nop 0
	global_load_dwordx4 v[20:23], v[20:21], off offset:192
	s_waitcnt lgkmcnt(0)
	v_add_f32_e32 v131, v119, v106
	v_bfe_u32 v129, v220, 13, 1
	v_ashrrev_i32_e32 v121, 31, v120
	v_mfma_f32_16x16x32_bf16 v[42:45], v[42:45], v[74:77], 0
	v_mfma_f32_16x16x32_bf16 v[46:49], v[46:49], v[74:77], 0
	v_mfma_f32_16x16x32_bf16 v[50:53], v[50:53], v[74:77], 0
	v_mfma_f32_16x16x32_bf16 v[54:57], v[54:57], v[74:77], 0
	v_mfma_f32_16x16x32_bf16 v[58:61], v[58:61], v[74:77], 0
	v_mfma_f32_16x16x32_bf16 v[62:65], v[62:65], v[74:77], 0
	v_mfma_f32_16x16x32_bf16 v[66:69], v[66:69], v[74:77], 0
	v_mfma_f32_16x16x32_bf16 v[70:73], v[70:73], v[74:77], 0
	ds_read_b128 v[74:77], v133 offset:64
	ds_read_b128 v[106:109], v133 offset:8768
	ds_read_b128 v[110:113], v133 offset:17472
	ds_read_b128 v[114:117], v133 offset:26176
	ds_read_b128 v[234:237], v133 offset:34880
	ds_read_b128 v[238:241], v133 offset:43584
	ds_read_b128 v[242:245], v133 offset:52288
	ds_read_b128 v[246:249], v133 offset:60992
	s_waitcnt lgkmcnt(7)
	v_mfma_f32_16x16x32_bf16 v[42:45], v[74:77], v[78:81], v[42:45]
	s_waitcnt lgkmcnt(6)
	v_mfma_f32_16x16x32_bf16 v[46:49], v[106:109], v[78:81], v[46:49]
	s_waitcnt lgkmcnt(5)
	v_mfma_f32_16x16x32_bf16 v[50:53], v[110:113], v[78:81], v[50:53]
	s_waitcnt lgkmcnt(4)
	v_mfma_f32_16x16x32_bf16 v[54:57], v[114:117], v[78:81], v[54:57]
	s_waitcnt lgkmcnt(3)
	v_mfma_f32_16x16x32_bf16 v[58:61], v[234:237], v[78:81], v[58:61]
	s_waitcnt lgkmcnt(2)
	v_mfma_f32_16x16x32_bf16 v[62:65], v[238:241], v[78:81], v[62:65]
	s_waitcnt lgkmcnt(1)
	v_mfma_f32_16x16x32_bf16 v[66:69], v[242:245], v[78:81], v[66:69]
	s_waitcnt lgkmcnt(0)
	v_mfma_f32_16x16x32_bf16 v[70:73], v[246:249], v[78:81], v[70:73]
	ds_read_b128 v[74:77], v133 offset:128
	ds_read_b128 v[78:81], v133 offset:8832
	ds_read_b128 v[106:109], v133 offset:17536
	ds_read_b128 v[110:113], v133 offset:26240
	ds_read_b128 v[114:117], v133 offset:34944
	ds_read_b128 v[234:237], v133 offset:43648
	ds_read_b128 v[238:241], v133 offset:52352
	ds_read_b128 v[242:245], v133 offset:61056
	s_waitcnt lgkmcnt(7)
	v_mfma_f32_16x16x32_bf16 v[42:45], v[74:77], v[82:85], v[42:45]
	s_waitcnt lgkmcnt(6)
	v_mfma_f32_16x16x32_bf16 v[46:49], v[78:81], v[82:85], v[46:49]
	s_waitcnt lgkmcnt(5)
	v_mfma_f32_16x16x32_bf16 v[50:53], v[106:109], v[82:85], v[50:53]
	s_waitcnt lgkmcnt(4)
	v_mfma_f32_16x16x32_bf16 v[54:57], v[110:113], v[82:85], v[54:57]
	s_waitcnt lgkmcnt(3)
	v_mfma_f32_16x16x32_bf16 v[58:61], v[114:117], v[82:85], v[58:61]
	s_waitcnt lgkmcnt(2)
	v_mfma_f32_16x16x32_bf16 v[62:65], v[234:237], v[82:85], v[62:65]
	s_waitcnt lgkmcnt(1)
	v_mfma_f32_16x16x32_bf16 v[66:69], v[238:241], v[82:85], v[66:69]
	s_waitcnt lgkmcnt(0)
	v_mfma_f32_16x16x32_bf16 v[70:73], v[242:245], v[82:85], v[70:73]
	ds_read_b128 v[74:77], v133 offset:192
	ds_read_b128 v[78:81], v133 offset:8896
	ds_read_b128 v[82:85], v133 offset:17600
	ds_read_b128 v[106:109], v133 offset:26304
	ds_read_b128 v[110:113], v133 offset:35008
	ds_read_b128 v[114:117], v133 offset:43712
	ds_read_b128 v[234:237], v133 offset:52416
	ds_read_b128 v[238:241], v133 offset:61120
	s_waitcnt lgkmcnt(7)
	v_mfma_f32_16x16x32_bf16 v[42:45], v[74:77], v[86:89], v[42:45]
	s_waitcnt lgkmcnt(6)
	v_mfma_f32_16x16x32_bf16 v[46:49], v[78:81], v[86:89], v[46:49]
	s_waitcnt lgkmcnt(5)
	v_mfma_f32_16x16x32_bf16 v[50:53], v[82:85], v[86:89], v[50:53]
	s_waitcnt lgkmcnt(4)
	v_mfma_f32_16x16x32_bf16 v[54:57], v[106:109], v[86:89], v[54:57]
	s_waitcnt lgkmcnt(3)
	v_mfma_f32_16x16x32_bf16 v[58:61], v[110:113], v[86:89], v[58:61]
	s_waitcnt lgkmcnt(2)
	v_mfma_f32_16x16x32_bf16 v[62:65], v[114:117], v[86:89], v[62:65]
	s_waitcnt lgkmcnt(1)
	v_mfma_f32_16x16x32_bf16 v[66:69], v[234:237], v[86:89], v[66:69]
	s_waitcnt lgkmcnt(0)
	v_mfma_f32_16x16x32_bf16 v[70:73], v[238:241], v[86:89], v[70:73]
	ds_read_b128 v[74:77], v133 offset:256
	ds_read_b128 v[78:81], v133 offset:8960
	ds_read_b128 v[82:85], v133 offset:17664
	ds_read_b128 v[86:89], v133 offset:26368
	ds_read_b128 v[106:109], v133 offset:35072
	ds_read_b128 v[110:113], v133 offset:43776
	ds_read_b128 v[114:117], v133 offset:52480
	ds_read_b128 v[234:237], v133 offset:61184
	s_waitcnt lgkmcnt(7)
	v_mfma_f32_16x16x32_bf16 v[42:45], v[74:77], v[90:93], v[42:45]
	s_waitcnt lgkmcnt(6)
	v_mfma_f32_16x16x32_bf16 v[46:49], v[78:81], v[90:93], v[46:49]
	s_waitcnt lgkmcnt(5)
	v_mfma_f32_16x16x32_bf16 v[50:53], v[82:85], v[90:93], v[50:53]
	s_waitcnt lgkmcnt(4)
	v_mfma_f32_16x16x32_bf16 v[54:57], v[86:89], v[90:93], v[54:57]
	s_waitcnt lgkmcnt(3)
	v_mfma_f32_16x16x32_bf16 v[58:61], v[106:109], v[90:93], v[58:61]
	s_waitcnt lgkmcnt(2)
	v_mfma_f32_16x16x32_bf16 v[62:65], v[110:113], v[90:93], v[62:65]
	s_waitcnt lgkmcnt(1)
	v_mfma_f32_16x16x32_bf16 v[66:69], v[114:117], v[90:93], v[66:69]
	s_waitcnt lgkmcnt(0)
	v_mfma_f32_16x16x32_bf16 v[70:73], v[234:237], v[90:93], v[70:73]
	ds_read_b128 v[74:77], v133 offset:320
	ds_read_b128 v[78:81], v133 offset:9024
	ds_read_b128 v[82:85], v133 offset:17728
	ds_read_b128 v[86:89], v133 offset:26432
	ds_read_b128 v[90:93], v133 offset:35136
	ds_read_b128 v[106:109], v133 offset:43840
	ds_read_b128 v[110:113], v133 offset:52544
	ds_read_b128 v[114:117], v133 offset:61248
	s_waitcnt lgkmcnt(7)
	v_mfma_f32_16x16x32_bf16 v[42:45], v[74:77], v[94:97], v[42:45]
	s_waitcnt lgkmcnt(6)
	v_mfma_f32_16x16x32_bf16 v[46:49], v[78:81], v[94:97], v[46:49]
	s_waitcnt lgkmcnt(5)
	v_mfma_f32_16x16x32_bf16 v[50:53], v[82:85], v[94:97], v[50:53]
	s_waitcnt lgkmcnt(4)
	v_mfma_f32_16x16x32_bf16 v[54:57], v[86:89], v[94:97], v[54:57]
	s_waitcnt lgkmcnt(3)
	v_mfma_f32_16x16x32_bf16 v[58:61], v[90:93], v[94:97], v[58:61]
	s_waitcnt lgkmcnt(2)
	v_mfma_f32_16x16x32_bf16 v[62:65], v[106:109], v[94:97], v[62:65]
	s_waitcnt lgkmcnt(1)
	v_mfma_f32_16x16x32_bf16 v[66:69], v[110:113], v[94:97], v[66:69]
	s_waitcnt lgkmcnt(0)
	v_mfma_f32_16x16x32_bf16 v[70:73], v[114:117], v[94:97], v[70:73]
	ds_read_b128 v[74:77], v133 offset:384
	ds_read_b128 v[78:81], v133 offset:9088
	ds_read_b128 v[82:85], v133 offset:17792
	ds_read_b128 v[86:89], v133 offset:26496
	ds_read_b128 v[90:93], v133 offset:35200
	ds_read_b128 v[94:97], v133 offset:43904
	ds_read_b128 v[106:109], v133 offset:52608
	ds_read_b128 v[110:113], v133 offset:61312
	s_waitcnt lgkmcnt(7)
	v_mfma_f32_16x16x32_bf16 v[42:45], v[74:77], v[98:101], v[42:45]
	s_waitcnt lgkmcnt(6)
	v_mfma_f32_16x16x32_bf16 v[46:49], v[78:81], v[98:101], v[46:49]
	s_waitcnt lgkmcnt(5)
	v_mfma_f32_16x16x32_bf16 v[50:53], v[82:85], v[98:101], v[50:53]
	s_waitcnt lgkmcnt(4)
	v_mfma_f32_16x16x32_bf16 v[54:57], v[86:89], v[98:101], v[54:57]
	s_waitcnt lgkmcnt(3)
	v_mfma_f32_16x16x32_bf16 v[58:61], v[90:93], v[98:101], v[58:61]
	s_waitcnt lgkmcnt(2)
	v_mfma_f32_16x16x32_bf16 v[62:65], v[94:97], v[98:101], v[62:65]
	s_waitcnt lgkmcnt(1)
	v_mfma_f32_16x16x32_bf16 v[66:69], v[106:109], v[98:101], v[66:69]
	s_waitcnt lgkmcnt(0)
	v_mfma_f32_16x16x32_bf16 v[70:73], v[110:113], v[98:101], v[70:73]
	ds_read_b128 v[74:77], v133 offset:448
	ds_read_b128 v[78:81], v133 offset:9152
	ds_read_b128 v[82:85], v133 offset:17856
	ds_read_b128 v[86:89], v133 offset:26560
	ds_read_b128 v[90:93], v133 offset:35264
	ds_read_b128 v[94:97], v133 offset:43968
	ds_read_b128 v[98:101], v133 offset:52672
	ds_read_b128 v[106:109], v133 offset:61376
	s_waitcnt lgkmcnt(7)
	v_mfma_f32_16x16x32_bf16 v[74:77], v[74:77], v[102:105], v[42:45]
	s_waitcnt lgkmcnt(6)
	v_mfma_f32_16x16x32_bf16 v[44:47], v[78:81], v[102:105], v[46:49]
	s_waitcnt lgkmcnt(5)
	v_mfma_f32_16x16x32_bf16 v[48:51], v[82:85], v[102:105], v[50:53]
	s_waitcnt lgkmcnt(4)
	v_mfma_f32_16x16x32_bf16 v[52:55], v[86:89], v[102:105], v[54:57]
	s_waitcnt lgkmcnt(3)
	v_mfma_f32_16x16x32_bf16 v[56:59], v[90:93], v[102:105], v[58:61]
	s_waitcnt lgkmcnt(2)
	v_mfma_f32_16x16x32_bf16 v[60:63], v[94:97], v[102:105], v[62:65]
	s_waitcnt lgkmcnt(1)
	v_mfma_f32_16x16x32_bf16 v[64:67], v[98:101], v[102:105], v[66:69]
	s_waitcnt lgkmcnt(0)
	v_mfma_f32_16x16x32_bf16 v[68:71], v[106:109], v[102:105], v[70:73]
	s_nop 2
	v_lshlrev_b64 v[72:73], 3, v[120:121]
	v_rcp_f32_e32 v32, v131
	v_or3_b32 v42, v129, s31, v72
	v_mov_b32_e32 v119, v33
	v_mad_u64_u32 v[42:43], s[2:3], v42, 3, v[118:119]
	v_mad_i32_i24 v43, v73, 3, v43
	v_lshlrev_b64 v[72:73], 7, v[42:43]
	v_lshl_add_u64 v[78:79], v[124:125], 0, v[72:73]
	v_pk_mul_f32 v[44:45], v[32:33], v[44:45] op_sel_hi:[0,1]
	v_mov_b32_e32 v73, v33
	v_cvt_pk_fp8_f32 v73, v44, v45
	v_pk_mul_f32 v[74:75], v[32:33], v[74:75] op_sel_hi:[0,1]
	v_mov_b32_e32 v72, v33
	v_pk_mul_f32 v[46:47], v[32:33], v[46:47] op_sel_hi:[0,1]
	v_cvt_pk_fp8_f32 v72, v74, v75
	v_cvt_pk_fp8_f32 v73, v46, v47 op_sel:[0,0,1]
	v_pk_mul_f32 v[46:47], v[32:33], v[48:49] op_sel_hi:[0,1]
	v_mov_b32_e32 v74, v33
	v_cvt_pk_fp8_f32 v74, v46, v47
	v_pk_mul_f32 v[46:47], v[32:33], v[52:53] op_sel_hi:[0,1]
	v_mov_b32_e32 v75, v33
	v_cvt_pk_fp8_f32 v75, v46, v47
	v_pk_mul_f32 v[44:45], v[32:33], v[50:51] op_sel_hi:[0,1]
	v_cvt_pk_fp8_f32 v74, v44, v45 op_sel:[0,0,1]
	v_pk_mul_f32 v[44:45], v[32:33], v[54:55] op_sel_hi:[0,1]
	v_cvt_pk_fp8_f32 v75, v44, v45 op_sel:[0,0,1]
	v_pk_mul_f32 v[48:49], v[32:33], v[56:57] op_sel_hi:[0,1]
	v_mov_b32_e32 v44, v33
	v_cvt_pk_fp8_f32 v44, v48, v49
	v_pk_mul_f32 v[48:49], v[32:33], v[60:61] op_sel_hi:[0,1]
	v_mov_b32_e32 v45, v33
	v_cvt_pk_fp8_f32 v45, v48, v49
	v_pk_mul_f32 v[46:47], v[32:33], v[58:59] op_sel_hi:[0,1]
	v_cvt_pk_fp8_f32 v44, v46, v47 op_sel:[0,0,1]
	v_pk_mul_f32 v[46:47], v[32:33], v[62:63] op_sel_hi:[0,1]
	v_cvt_pk_fp8_f32 v45, v46, v47 op_sel:[0,0,1]
	v_pk_mul_f32 v[50:51], v[32:33], v[64:65] op_sel_hi:[0,1]
	v_mov_b32_e32 v46, v33
	v_cvt_pk_fp8_f32 v46, v50, v51
	v_pk_mul_f32 v[50:51], v[32:33], v[68:69] op_sel_hi:[0,1]
	v_mov_b32_e32 v47, v33
	v_cvt_pk_fp8_f32 v47, v50, v51
	v_pk_mul_f32 v[76:77], v[32:33], v[76:77] op_sel_hi:[0,1]
	v_pk_mul_f32 v[48:49], v[32:33], v[66:67] op_sel_hi:[0,1]
	v_cvt_pk_fp8_f32 v72, v76, v77 op_sel:[0,0,1]
	v_cvt_pk_fp8_f32 v46, v48, v49 op_sel:[0,0,1]
	v_pk_mul_f32 v[48:49], v[32:33], v[70:71] op_sel_hi:[0,1]
	v_cvt_pk_fp8_f32 v47, v48, v49 op_sel:[0,0,1]
	v_cmp_gt_i32_e32 vcc, s28, v232
	s_nop 1
	v_cndmask_b32_e32 v49, v123, v79, vcc
	v_cndmask_b32_e32 v48, v122, v78, vcc
	global_store_dwordx4 v[48:49], v[72:75], off
	global_store_dwordx4 v[48:49], v[44:47], off offset:16
	s_and_saveexec_b64 s[2:3], s[38:39]
	s_cbranch_execz .LBB0_984
	v_lshl_add_u64 v[42:43], v[42:43], 3, s[6:7]
	v_cndmask_b32_e32 v43, v127, v43, vcc
	v_cndmask_b32_e32 v42, v126, v42, vcc
	global_store_dwordx2 v[42:43], v[130:131], off
.LBB0_984:
	s_or_b64 exec, exec, s[2:3]
	s_waitcnt vmcnt(9)
	v_pk_mul_f32 v[34:35], v[0:1], v[34:35]
	v_pk_mul_f32 v[36:37], v[2:3], v[36:37]
	v_add_f32_e32 v32, v34, v35
	v_add_f32_e32 v32, v36, v32
	v_add_f32_e32 v32, v37, v32
	s_waitcnt vmcnt(8)
	v_pk_mul_f32 v[36:37], v[0:1], v[38:39]
	v_pk_mul_f32 v[34:35], v[2:3], v[40:41]
	v_add_f32_e32 v36, v36, v37
	v_add_f32_e32 v34, v34, v36
	v_add_f32_e32 v34, v35, v34
	s_cmp_lt_i32 s17, 48
	s_cselect_b64 vcc, -1, 0
	s_cmp_lt_i32 s17, 47
	s_waitcnt lgkmcnt(1)
	s_nop 1
	v_add_f32_dpp v32, v32, v32 quad_perm:[1,0,3,2] row_mask:0xf bank_mask:0xf
	s_waitcnt lgkmcnt(0)
	s_nop 1
	v_add_f32_dpp v34, v34, v34 quad_perm:[1,0,3,2] row_mask:0xf bank_mask:0xf
	v_add_u32_e32 v232, 0x80, v232
	s_waitcnt lgkmcnt(1)
	s_nop 1
	v_add_f32_dpp v32, v32, v32 quad_perm:[2,3,0,1] row_mask:0xf bank_mask:0xf
	s_waitcnt lgkmcnt(0)
	s_nop 1
	v_add_f32_dpp v34, v34, v34 quad_perm:[2,3,0,1] row_mask:0xf bank_mask:0xf
	s_waitcnt lgkmcnt(1)
	s_nop 1
	v_add_f32_dpp v32, v32, v32 row_half_mirror row_mask:0xf bank_mask:0xf
	s_waitcnt lgkmcnt(0)
	s_nop 1
	v_add_f32_dpp v34, v34, v34 row_half_mirror row_mask:0xf bank_mask:0xf
	s_waitcnt lgkmcnt(1)
	s_nop 1
	v_add_f32_dpp v32, v32, v32 row_mirror row_mask:0xf bank_mask:0xf
	s_waitcnt lgkmcnt(0)
	s_nop 1
	v_add_f32_dpp v34, v34, v34 row_mirror row_mask:0xf bank_mask:0xf
	v_mov_b32_e32 v35, v32
	s_nop 1
	v_permlane16_swap_b32_e32 v35, v32
	v_mov_b32_e32 v36, v34
	s_nop 1
	v_permlane16_swap_b32_e32 v36, v34
	s_waitcnt lgkmcnt(1)
	v_add_f32_e32 v32, v32, v35
	s_waitcnt lgkmcnt(0)
	v_add_f32_e32 v34, v34, v36
	v_cndmask_b32_e32 v32, v218, v32, vcc
	s_cselect_b64 vcc, -1, 0
	v_cndmask_b32_e32 v34, v218, v34, vcc
	v_max3_f32 v188, v231, v32, v34
	s_add_i32 s17, s17, 2
	v_sub_f32_e32 v34, v34, v188
	v_sub_f32_e32 v32, v32, v188
	v_exp_f32_e32 v34, v34
	v_sub_f32_e32 v35, v231, v188
	v_exp_f32_e32 v32, v32
	v_exp_f32_e32 v36, v35
	s_waitcnt vmcnt(6)
	v_pk_mul_f32 v[30:31], v[30:31], v[34:35] op_sel_hi:[1,0]
	v_pk_mul_f32 v[28:29], v[28:29], v[34:35] op_sel_hi:[1,0]
	v_add_f32_e32 v189, v32, v34
	v_pk_fma_f32 v[24:25], v[24:25], v[32:33], v[28:29] op_sel_hi:[1,0,1]
	v_pk_fma_f32 v[26:27], v[26:27], v[32:33], v[30:31] op_sel_hi:[1,0,1]
	s_add_i32 s41, s41, 8
	v_fmac_f32_e32 v189, v183, v36
	v_pk_fma_f32 v[6:7], v[6:7], v[36:37], v[26:27] op_sel_hi:[1,0,1]
	v_pk_fma_f32 v[4:5], v[4:5], v[36:37], v[24:25] op_sel_hi:[1,0,1]
	s_cmp_lt_i32 s41, s29
	s_cbranch_scc0 .LBB0_987
	v_mov_b32_e32 v231, v188
	v_mov_b32_e32 v183, v189
	v_mov_b32_e32 v220, v230
	v_mov_b32_e32 v230, v233
	s_branch .LBB0_982

.LBB0_996:
	s_min_i32 s0, s17, 39
	s_add_i32 s1, s0, 8
	s_ashr_i32 s1, s1, 3
	s_lshl_b32 s1, s1, 2
	v_readlane_b32 s2, v254, 24
	s_add_i32 s1, s2, s1
	s_waitcnt vmcnt(6)
	v_mov_b32_e32 v66, s1
	ds_read_b32 v66, v66
	s_lshl_b32 s0, s0, 4
	s_and_b32 s0, s0, 0x70
	v_readlane_b32 s48, v251, 1
	v_readlane_b32 s49, v251, 2
	s_waitcnt lgkmcnt(0)
	v_lshlrev_b32_e32 v66, 7, v66
	v_or_b32_e32 v66, s0, v66
	v_add_u32_e32 v66, v66, v186
	s_min_i32 s0, s17, 38
	v_ashrrev_i32_e32 v67, 31, v66
	v_readlane_b32 s50, v251, 3
	v_readlane_b32 s51, v251, 4
	v_readlane_b32 s52, v251, 5
	v_readlane_b32 s53, v251, 6
	v_readlane_b32 s54, v251, 7
	v_readlane_b32 s55, v251, 8
	v_readlane_b32 s56, v251, 9
	v_readlane_b32 s57, v251, 10
	v_readlane_b32 s58, v251, 11
	v_readlane_b32 s59, v251, 12
	s_add_i32 s0, s0, 9
	v_lshlrev_b64 v[66:67], 11, v[66:67]
	v_readlane_b32 s60, v251, 13
	v_readlane_b32 s61, v251, 14
	v_readlane_b32 s62, v251, 15
	v_readlane_b32 s63, v251, 16
	s_mov_b64 s[48:49], s[52:53]
	s_ashr_i32 s1, s0, 3
	v_or_b32_e32 v66, v66, v227
	s_mov_b64 s[50:51], s[54:55]
	s_lshl_b32 s1, s1, 2
	v_lshl_add_u64 v[68:69], s[48:49], 0, v[66:67]
	v_lshl_add_u64 v[66:67], s[50:51], 0, v[66:67]
	s_add_i32 s1, s2, s1
	global_load_dwordx4 v[106:109], v[66:67], off
	v_mov_b32_e32 v66, s1
	ds_read_b32 v66, v66
	s_lshl_b32 s0, s0, 4
	s_and_b32 s0, s0, 0x70
	global_load_dwordx4 v[118:121], v[68:69], off
	s_waitcnt vmcnt(16)
	v_pk_mul_f32 v[16:17], v[0:1], v[16:17]
	s_waitcnt lgkmcnt(0)
	v_lshlrev_b32_e32 v66, 7, v66
	v_or_b32_e32 v66, s0, v66
	s_min_i32 s0, s17, 37
	s_add_i32 s0, s0, 10
	s_ashr_i32 s1, s0, 3
	s_lshl_b32 s1, s1, 2
	s_add_i32 s1, s2, s1
	s_waitcnt vmcnt(7)
	v_mov_b32_e32 v70, s1
	ds_read_b32 v70, v70
	s_lshl_b32 s0, s0, 4
	s_and_b32 s0, s0, 0x70
	v_add_u32_e32 v66, v66, v186
	v_ashrrev_i32_e32 v67, 31, v66
	s_waitcnt lgkmcnt(0)
	v_lshlrev_b32_e32 v70, 7, v70
	v_or_b32_e32 v70, s0, v70
	s_min_i32 s0, s17, 36
	s_add_i32 s0, s0, 11
	s_ashr_i32 s1, s0, 3
	s_lshl_b32 s1, s1, 2
	s_add_i32 s1, s2, s1
	s_waitcnt vmcnt(6)
	v_mov_b32_e32 v74, s1
	ds_read_b32 v74, v74
	s_lshl_b32 s0, s0, 4
	s_and_b32 s0, s0, 0x70
	v_add_u32_e32 v70, v70, v186
	v_ashrrev_i32_e32 v71, 31, v70
	s_waitcnt lgkmcnt(0)
	v_lshlrev_b32_e32 v74, 7, v74
	v_or_b32_e32 v74, s0, v74
	s_min_i32 s0, s17, 35
	s_add_i32 s0, s0, 12
	s_ashr_i32 s1, s0, 3
	s_lshl_b32 s1, s1, 2
	s_add_i32 s1, s2, s1
	s_waitcnt vmcnt(5)
	v_mov_b32_e32 v82, s1
	ds_read_b32 v82, v82
	s_lshl_b32 s0, s0, 4
	s_and_b32 s0, s0, 0x70
	v_add_u32_e32 v74, v74, v186
	v_lshlrev_b64 v[70:71], 11, v[70:71]
	s_waitcnt lgkmcnt(0)
	v_lshlrev_b32_e32 v82, 7, v82
	v_or_b32_e32 v82, s0, v82
	s_min_i32 s0, s17, 34
	s_add_i32 s0, s0, 13
	s_ashr_i32 s1, s0, 3
	s_lshl_b32 s1, s1, 2
	s_add_i32 s1, s2, s1
	s_waitcnt vmcnt(4)
	v_mov_b32_e32 v90, s1
	ds_read_b32 v90, v90
	s_lshl_b32 s0, s0, 4
	s_and_b32 s0, s0, 0x70
	v_add_u32_e32 v82, v82, v186
	v_ashrrev_i32_e32 v75, 31, v74
	s_waitcnt lgkmcnt(0)
	v_lshlrev_b32_e32 v90, 7, v90
	v_or_b32_e32 v90, s0, v90
	s_min_i32 s0, s17, 33
	s_add_i32 s0, s0, 14
	s_ashr_i32 s1, s0, 3
	s_lshl_b32 s1, s1, 2
	s_add_i32 s1, s2, s1
	s_waitcnt vmcnt(3)
	v_mov_b32_e32 v98, s1
	ds_read_b32 v98, v98
	s_lshl_b32 s0, s0, 4
	s_and_b32 s0, s0, 0x70
	v_add_u32_e32 v90, v90, v186
	v_ashrrev_i32_e32 v83, 31, v82
	s_waitcnt lgkmcnt(0)
	v_lshlrev_b32_e32 v98, 7, v98
	v_or_b32_e32 v98, s0, v98
	s_min_i32 s0, s17, 32
	s_add_i32 s0, s0, 15
	s_ashr_i32 s1, s0, 3
	s_lshl_b32 s1, s1, 2
	s_add_i32 s1, s2, s1
	s_waitcnt vmcnt(2)
	v_mov_b32_e32 v130, s1
	ds_read_b32 v130, v130
	s_lshl_b32 s0, s0, 4
	s_and_b32 s0, s0, 0x70
	v_add_u32_e32 v98, v98, v186
	v_ashrrev_i32_e32 v91, 31, v90
	s_waitcnt lgkmcnt(0)
	v_lshlrev_b32_e32 v130, 7, v130
	v_or_b32_e32 v130, s0, v130
	v_add_u32_e32 v130, v130, v186
	v_ashrrev_i32_e32 v99, 31, v98
	v_ashrrev_i32_e32 v131, 31, v130
	v_lshlrev_b64 v[66:67], 11, v[66:67]
	v_or_b32_e32 v70, v70, v227
	v_lshlrev_b64 v[74:75], 11, v[74:75]
	v_lshlrev_b64 v[82:83], 11, v[82:83]
	v_lshlrev_b64 v[90:91], 11, v[90:91]
	v_lshlrev_b64 v[98:99], 11, v[98:99]
	v_lshlrev_b64 v[130:131], 11, v[130:131]
	v_or_b32_e32 v66, v66, v227
	v_lshl_add_u64 v[72:73], s[48:49], 0, v[70:71]
	v_or_b32_e32 v74, v74, v227
	v_or_b32_e32 v82, v82, v227
	v_or_b32_e32 v90, v90, v227
	v_or_b32_e32 v98, v98, v227
	v_or_b32_e32 v130, v130, v227
	global_load_dwordx4 v[78:81], v[72:73], off
	v_lshl_add_u64 v[68:69], s[48:49], 0, v[66:67]
	v_lshl_add_u64 v[66:67], s[50:51], 0, v[66:67]
	v_lshl_add_u64 v[70:71], s[50:51], 0, v[70:71]
	v_lshl_add_u64 v[76:77], s[48:49], 0, v[74:75]
	v_lshl_add_u64 v[74:75], s[50:51], 0, v[74:75]
	v_lshl_add_u64 v[84:85], s[48:49], 0, v[82:83]
	v_lshl_add_u64 v[82:83], s[50:51], 0, v[82:83]
	v_lshl_add_u64 v[92:93], s[48:49], 0, v[90:91]
	v_lshl_add_u64 v[90:91], s[50:51], 0, v[90:91]
	v_lshl_add_u64 v[100:101], s[48:49], 0, v[98:99]
	v_lshl_add_u64 v[98:99], s[50:51], 0, v[98:99]
	v_lshl_add_u64 v[132:133], s[48:49], 0, v[130:131]
	v_lshl_add_u64 v[130:131], s[50:51], 0, v[130:131]
	global_load_dwordx4 v[110:113], v[68:69], off
	global_load_dwordx4 v[86:89], v[76:77], off
	global_load_dwordx4 v[94:97], v[84:85], off
	global_load_dwordx4 v[102:105], v[92:93], off
	global_load_dwordx4 v[114:117], v[100:101], off
	global_load_dwordx4 v[134:137], v[132:133], off
	v_pk_mul_f32 v[18:19], v[2:3], v[18:19]
	global_load_dwordx4 v[66:69], v[66:67], off
	v_add_f32_e32 v16, v16, v17
	global_load_dwordx4 v[70:73], v[70:71], off
	v_add_f32_e32 v16, v18, v16
	global_load_dwordx4 v[74:77], v[74:75], off
	v_add_f32_e32 v16, v19, v16
	global_load_dwordx4 v[82:85], v[82:83], off
	global_load_dwordx4 v[90:93], v[90:91], off
	v_mov_b32_e32 v183, v188
	global_load_dwordx4 v[98:101], v[98:99], off
	v_mov_b32_e32 v32, v189
	global_load_dwordx4 v[130:133], v[130:131], off
	s_waitcnt lgkmcnt(0)
	s_nop 1
	v_add_f32_dpp v16, v16, v16 quad_perm:[1,0,3,2] row_mask:0xf bank_mask:0xf
	s_cmp_lt_i32 s17, 47
	s_mov_b64 s[52:53], s[56:57]
	s_mov_b64 s[54:55], s[58:59]
	s_mov_b64 s[56:57], s[60:61]
	s_waitcnt lgkmcnt(0)
	s_nop 1
	v_add_f32_dpp v16, v16, v16 quad_perm:[2,3,0,1] row_mask:0xf bank_mask:0xf
	s_mov_b64 s[58:59], s[62:63]
	s_waitcnt lgkmcnt(0)
	s_nop 1
	v_add_f32_dpp v16, v16, v16 row_half_mirror row_mask:0xf bank_mask:0xf
	s_waitcnt lgkmcnt(0)
	s_nop 1
	v_add_f32_dpp v16, v16, v16 row_mirror row_mask:0xf bank_mask:0xf
	v_mov_b32_e32 v17, v16
	s_nop 1
	v_permlane16_swap_b32_e32 v17, v16
	s_waitcnt lgkmcnt(0)
	v_add_f32_e32 v17, v16, v17
	v_max_f32_e32 v16, v183, v183
	v_max_f32_e32 v188, v16, v17
	v_sub_f32_e32 v17, v17, v188
	v_sub_f32_e32 v16, v183, v188
	v_exp_f32_e32 v18, v17
	v_exp_f32_e32 v16, v16
	v_pk_mul_f32 v[12:13], v[12:13], v[18:19] op_sel_hi:[1,0]
	s_nop 0
	v_pk_fma_f32 v[4:5], v[4:5], v[16:17], v[12:13] op_sel_hi:[1,0,1]
	s_waitcnt vmcnt(28)
	v_mul_f32_e32 v12, v1, v25
	v_fmac_f32_e32 v12, v0, v24
	v_fmac_f32_e32 v12, v2, v26
	v_fmac_f32_e32 v12, v3, v27
	v_mov_b32_e32 v189, v18
	v_pk_mul_f32 v[14:15], v[14:15], v[18:19] op_sel_hi:[1,0]
	v_fmac_f32_e32 v189, v32, v16
	v_pk_fma_f32 v[6:7], v[6:7], v[16:17], v[14:15] op_sel_hi:[1,0,1]
	s_waitcnt lgkmcnt(0)
	s_nop 1
	v_add_f32_dpp v12, v12, v12 quad_perm:[1,0,3,2] row_mask:0xf bank_mask:0xf
	s_waitcnt lgkmcnt(0)
	s_nop 1
	v_add_f32_dpp v12, v12, v12 quad_perm:[2,3,0,1] row_mask:0xf bank_mask:0xf
	s_waitcnt lgkmcnt(0)
	s_nop 1
	v_add_f32_dpp v12, v12, v12 row_half_mirror row_mask:0xf bank_mask:0xf
	s_waitcnt lgkmcnt(0)
	s_nop 1
	v_add_f32_dpp v12, v12, v12 row_mirror row_mask:0xf bank_mask:0xf
	ds_bpermute_b32 v13, v226, v12
	s_cbranch_scc0 .LBB0_998
	s_waitcnt lgkmcnt(0)
	v_add_f32_e32 v12, v12, v13
	v_max_f32_e32 v13, v188, v188
	v_max_f32_e32 v13, v13, v12
	v_sub_f32_e32 v12, v12, v13
	v_sub_f32_e32 v14, v188, v13
	v_exp_f32_e32 v12, v12
	v_exp_f32_e32 v14, v14
	v_mov_b32_e32 v188, v13
	v_mov_b32_e32 v15, v12
	v_fmac_f32_e32 v15, v189, v14
	s_waitcnt vmcnt(21)
	v_pk_mul_f32 v[8:9], v[8:9], v[12:13] op_sel_hi:[1,0]
	v_pk_mul_f32 v[10:11], v[10:11], v[12:13] op_sel_hi:[1,0]
	v_pk_fma_f32 v[4:5], v[4:5], v[14:15], v[8:9] op_sel_hi:[1,0,1]
	v_pk_fma_f32 v[6:7], v[6:7], v[14:15], v[10:11] op_sel_hi:[1,0,1]
	v_mov_b32_e32 v189, v15

.LBB0_1010:
	s_cmp_lt_i32 s17, 40
	s_mov_b64 s[0:1], -1
	s_cbranch_scc0 .LBB0_994
	s_add_i32 s2, s17, 16
	s_min_i32 s0, s2, 47
	s_ashr_i32 s1, s0, 3
	s_lshl_b32 s1, s1, 2
	v_readlane_b32 s3, v254, 24
	s_add_i32 s1, s3, s1
	v_mov_b32_e32 v8, s1
	ds_read_b32 v8, v8
	s_lshl_b32 s0, s0, 4
	s_and_b32 s0, s0, 0x70
	v_readlane_b32 s48, v251, 1
	v_readlane_b32 s49, v251, 2
	s_waitcnt lgkmcnt(0)
	v_lshlrev_b32_e32 v8, 7, v8
	v_or_b32_e32 v8, s0, v8
	v_add_u32_e32 v8, v8, v186
	s_min_i32 s0, s17, 30
	v_ashrrev_i32_e32 v9, 31, v8
	v_readlane_b32 s50, v251, 3
	v_readlane_b32 s51, v251, 4
	v_readlane_b32 s52, v251, 5
	v_readlane_b32 s53, v251, 6
	v_readlane_b32 s54, v251, 7
	v_readlane_b32 s55, v251, 8
	v_readlane_b32 s56, v251, 9
	v_readlane_b32 s57, v251, 10
	v_readlane_b32 s58, v251, 11
	v_readlane_b32 s59, v251, 12
	s_add_i32 s0, s0, 17
	v_lshlrev_b64 v[8:9], 11, v[8:9]
	v_readlane_b32 s60, v251, 13
	v_readlane_b32 s61, v251, 14
	v_readlane_b32 s62, v251, 15
	v_readlane_b32 s63, v251, 16
	s_mov_b64 s[48:49], s[52:53]
	s_ashr_i32 s1, s0, 3
	v_or_b32_e32 v8, v8, v227
	s_mov_b64 s[50:51], s[54:55]
	s_lshl_b32 s1, s1, 2
	v_lshl_add_u64 v[10:11], s[48:49], 0, v[8:9]
	v_lshl_add_u64 v[8:9], s[50:51], 0, v[8:9]
	s_add_i32 s1, s3, s1
	global_load_dwordx4 v[12:15], v[8:9], off
	v_mov_b32_e32 v8, s1
	ds_read_b32 v8, v8
	s_lshl_b32 s0, s0, 4
	s_and_b32 s0, s0, 0x70
	global_load_dwordx4 v[16:19], v[10:11], off
	s_waitcnt vmcnt(16)
	v_pk_mul_f32 v[118:119], v[0:1], v[118:119]
	s_waitcnt lgkmcnt(0)
	v_lshlrev_b32_e32 v8, 7, v8
	v_or_b32_e32 v8, s0, v8
	s_min_i32 s0, s17, 29
	s_add_i32 s0, s0, 18
	s_ashr_i32 s1, s0, 3
	s_lshl_b32 s1, s1, 2
	s_add_i32 s1, s3, s1
	v_mov_b32_e32 v20, s1
	ds_read_b32 v20, v20
	s_lshl_b32 s0, s0, 4
	s_and_b32 s0, s0, 0x70
	v_add_u32_e32 v8, v8, v186
	v_ashrrev_i32_e32 v9, 31, v8
	s_waitcnt lgkmcnt(0)
	v_lshlrev_b32_e32 v20, 7, v20
	v_or_b32_e32 v20, s0, v20
	s_min_i32 s0, s17, 28
	s_add_i32 s0, s0, 19
	s_ashr_i32 s1, s0, 3
	s_lshl_b32 s1, s1, 2
	s_add_i32 s1, s3, s1
	v_mov_b32_e32 v32, s1
	ds_read_b32 v32, v32
	s_lshl_b32 s0, s0, 4
	s_and_b32 s0, s0, 0x70
	v_add_u32_e32 v20, v20, v186
	v_ashrrev_i32_e32 v21, 31, v20
	s_waitcnt lgkmcnt(0)
	v_lshlrev_b32_e32 v32, 7, v32
	v_or_b32_e32 v32, s0, v32
	s_min_i32 s0, s17, 27
	s_add_i32 s0, s0, 20
	s_ashr_i32 s1, s0, 3
	s_lshl_b32 s1, s1, 2
	s_add_i32 s1, s3, s1
	v_add_u32_e32 v34, v32, v186
	v_mov_b32_e32 v32, s1
	ds_read_b32 v32, v32
	s_lshl_b32 s0, s0, 4
	s_and_b32 s0, s0, 0x70
	v_lshlrev_b64 v[20:21], 11, v[20:21]
	v_ashrrev_i32_e32 v35, 31, v34
	s_waitcnt lgkmcnt(0)
	v_lshlrev_b32_e32 v32, 7, v32
	v_or_b32_e32 v32, s0, v32
	s_min_i32 s0, s17, 26
	s_add_i32 s0, s0, 21
	s_ashr_i32 s1, s0, 3
	s_lshl_b32 s1, s1, 2
	s_add_i32 s1, s3, s1
	v_add_u32_e32 v42, v32, v186
	v_mov_b32_e32 v32, s1
	ds_read_b32 v32, v32
	s_lshl_b32 s0, s0, 4
	s_and_b32 s0, s0, 0x70
	v_ashrrev_i32_e32 v43, 31, v42
	v_lshlrev_b64 v[8:9], 11, v[8:9]
	s_waitcnt lgkmcnt(0)
	v_lshlrev_b32_e32 v32, 7, v32
	v_or_b32_e32 v32, s0, v32
	s_min_i32 s0, s17, 25
	s_add_i32 s0, s0, 22
	s_ashr_i32 s1, s0, 3
	s_lshl_b32 s1, s1, 2
	s_add_i32 s1, s3, s1
	v_add_u32_e32 v50, v32, v186
	v_mov_b32_e32 v32, s1
	ds_read_b32 v32, v32
	s_lshl_b32 s0, s0, 4
	s_and_b32 s0, s0, 0x70
	v_ashrrev_i32_e32 v51, 31, v50
	v_or_b32_e32 v20, v20, v227
	s_waitcnt lgkmcnt(0)
	v_lshlrev_b32_e32 v32, 7, v32
	v_or_b32_e32 v32, s0, v32
	s_min_i32 s0, s17, 24
	s_add_i32 s0, s0, 23
	s_ashr_i32 s1, s0, 3
	s_lshl_b32 s1, s1, 2
	s_add_i32 s1, s3, s1
	v_add_u32_e32 v58, v32, v186
	v_mov_b32_e32 v32, s1
	ds_read_b32 v32, v32
	s_lshl_b32 s0, s0, 4
	s_and_b32 s0, s0, 0x70
	v_ashrrev_i32_e32 v59, 31, v58
	v_lshlrev_b64 v[34:35], 11, v[34:35]
	s_waitcnt lgkmcnt(0)
	v_lshlrev_b32_e32 v32, 7, v32
	v_or_b32_e32 v32, s0, v32
	v_add_u32_e32 v122, v32, v186
	v_ashrrev_i32_e32 v123, 31, v122
	v_lshlrev_b64 v[42:43], 11, v[42:43]
	v_lshlrev_b64 v[50:51], 11, v[50:51]
	v_lshlrev_b64 v[58:59], 11, v[58:59]
	v_lshlrev_b64 v[122:123], 11, v[122:123]
	v_or_b32_e32 v8, v8, v227
	v_lshl_add_u64 v[22:23], s[48:49], 0, v[20:21]
	v_or_b32_e32 v34, v34, v227
	v_or_b32_e32 v42, v42, v227
	v_or_b32_e32 v50, v50, v227
	v_or_b32_e32 v58, v58, v227
	v_or_b32_e32 v122, v122, v227
	global_load_dwordx4 v[28:31], v[22:23], off
	v_lshl_add_u64 v[10:11], s[48:49], 0, v[8:9]
	v_lshl_add_u64 v[8:9], s[50:51], 0, v[8:9]
	v_lshl_add_u64 v[20:21], s[50:51], 0, v[20:21]
	v_lshl_add_u64 v[36:37], s[48:49], 0, v[34:35]
	v_lshl_add_u64 v[34:35], s[50:51], 0, v[34:35]
	v_lshl_add_u64 v[44:45], s[48:49], 0, v[42:43]
	v_lshl_add_u64 v[42:43], s[50:51], 0, v[42:43]
	v_lshl_add_u64 v[52:53], s[48:49], 0, v[50:51]
	v_lshl_add_u64 v[50:51], s[50:51], 0, v[50:51]
	v_lshl_add_u64 v[60:61], s[48:49], 0, v[58:59]
	v_lshl_add_u64 v[58:59], s[50:51], 0, v[58:59]
	v_lshl_add_u64 v[124:125], s[48:49], 0, v[122:123]
	v_lshl_add_u64 v[122:123], s[50:51], 0, v[122:123]
	global_load_dwordx4 v[24:27], v[10:11], off
	global_load_dwordx4 v[38:41], v[36:37], off
	global_load_dwordx4 v[46:49], v[44:45], off
	global_load_dwordx4 v[54:57], v[52:53], off
	global_load_dwordx4 v[62:65], v[60:61], off
	global_load_dwordx4 v[126:129], v[124:125], off
	v_pk_mul_f32 v[120:121], v[2:3], v[120:121]
	global_load_dwordx4 v[8:11], v[8:9], off
	v_add_f32_e32 v32, v118, v119
	global_load_dwordx4 v[20:23], v[20:21], off
	v_add_f32_e32 v32, v120, v32
	global_load_dwordx4 v[34:37], v[34:35], off
	v_add_f32_e32 v32, v121, v32
	global_load_dwordx4 v[42:45], v[42:43], off
	ds_bpermute_b32 v118, v191, v32
	global_load_dwordx4 v[50:53], v[50:51], off
	s_cmp_lg_u32 s17, 39
	global_load_dwordx4 v[58:61], v[58:59], off
	s_mov_b64 s[52:53], s[56:57]
	global_load_dwordx4 v[122:125], v[122:123], off
	s_waitcnt lgkmcnt(0)
	v_add_f32_e32 v32, v32, v118
	ds_bpermute_b32 v118, v192, v32
	s_mov_b64 s[54:55], s[58:59]
	s_mov_b64 s[56:57], s[60:61]
	s_mov_b64 s[58:59], s[62:63]
	s_waitcnt lgkmcnt(0)
	v_add_f32_e32 v32, v32, v118
	ds_bpermute_b32 v118, v193, v32
	s_waitcnt lgkmcnt(0)
	v_add_f32_e32 v32, v32, v118
	ds_bpermute_b32 v118, v194, v32
	s_waitcnt lgkmcnt(0)
	v_add_f32_e32 v32, v32, v118
	v_mov_b32_e32 v118, v32
	s_nop 1
	v_permlane16_swap_b32_e32 v118, v32
	s_waitcnt lgkmcnt(0)
	v_add_f32_e32 v32, v32, v118
	v_max_f32_e32 v118, v188, v188
	v_max_f32_e32 v118, v118, v32
	v_sub_f32_e32 v32, v32, v118
	v_sub_f32_e32 v119, v188, v118
	v_exp_f32_e32 v158, v32
	v_exp_f32_e32 v120, v119
	v_pk_mul_f32 v[106:107], v[106:107], v[158:159] op_sel_hi:[1,0]
	s_nop 0
	v_pk_fma_f32 v[4:5], v[4:5], v[120:121], v[106:107] op_sel_hi:[1,0,1]
	s_waitcnt vmcnt(28)
	v_mul_f32_e32 v106, v1, v111
	v_fmac_f32_e32 v106, v0, v110
	v_fmac_f32_e32 v106, v2, v112
	v_fmac_f32_e32 v106, v3, v113
	ds_bpermute_b32 v107, v191, v106
	v_mov_b32_e32 v32, v158
	v_pk_mul_f32 v[108:109], v[108:109], v[158:159] op_sel_hi:[1,0]
	v_fmac_f32_e32 v32, v189, v120
	v_pk_fma_f32 v[6:7], v[6:7], v[120:121], v[108:109] op_sel_hi:[1,0,1]
	s_waitcnt lgkmcnt(0)
	v_add_f32_e32 v106, v106, v107
	ds_bpermute_b32 v107, v192, v106
	s_waitcnt lgkmcnt(0)
	v_add_f32_e32 v106, v106, v107
	ds_bpermute_b32 v107, v193, v106
	s_waitcnt lgkmcnt(0)
	v_add_f32_e32 v106, v106, v107
	ds_bpermute_b32 v107, v194, v106
	s_waitcnt lgkmcnt(0)
	v_add_f32_e32 v106, v106, v107
	ds_bpermute_b32 v107, v226, v106
	s_cbranch_scc0 .LBB0_1013
	s_waitcnt lgkmcnt(0)
	v_add_f32_e32 v106, v106, v107
	v_max_f32_e32 v107, v118, v118
	v_max_f32_e32 v107, v107, v106
	v_sub_f32_e32 v106, v106, v107
	v_sub_f32_e32 v108, v118, v107
	v_exp_f32_e32 v106, v106
	v_exp_f32_e32 v108, v108
	v_mov_b32_e32 v118, v107
	v_mov_b32_e32 v109, v106
	v_fmac_f32_e32 v109, v32, v108
	s_waitcnt vmcnt(22)
	v_pk_mul_f32 v[66:67], v[66:67], v[106:107] op_sel_hi:[1,0]
	v_pk_mul_f32 v[68:69], v[68:69], v[106:107] op_sel_hi:[1,0]
	v_pk_fma_f32 v[4:5], v[4:5], v[108:109], v[66:67] op_sel_hi:[1,0,1]
	v_pk_fma_f32 v[6:7], v[6:7], v[108:109], v[68:69] op_sel_hi:[1,0,1]
	v_mov_b32_e32 v32, v109

.Latt2_wait_done:
	v_max3_f32 v42, v106, v110, v112
	s_waitcnt lgkmcnt(7)
	v_mfma_f32_16x16x32_bf16 v[44:47], v[44:47], v[38:41], 0
	v_cmp_gt_u32_e32 vcc, v138, v43
	s_waitcnt lgkmcnt(5)
	v_mfma_f32_16x16x32_bf16 v[44:47], v[52:55], v[34:37], v[44:47]
	v_mov_b32_e32 v52, s22
	s_waitcnt lgkmcnt(3)
	v_mfma_f32_16x16x32_bf16 v[44:47], v[56:59], v[28:31], v[44:47]
	v_mfma_f32_16x16x32_bf16 v[48:51], v[48:51], v[38:41], 0
	s_waitcnt lgkmcnt(1)
	v_mfma_f32_16x16x32_bf16 v[44:47], v[68:71], v[24:27], v[44:47]
	v_mfma_f32_16x16x32_bf16 v[48:51], v[60:63], v[34:37], v[48:51]
	v_mfma_f32_16x16x32_bf16 v[48:51], v[64:67], v[28:31], v[48:51]
	s_nop 5
	v_cndmask_b32_e32 v52, v44, v52, vcc
	v_cmp_lt_u32_e32 vcc, v138, v43
	s_nop 1
	v_cndmask_b32_e32 v58, v52, v44, vcc
	v_or_b32_e32 v44, 2, v138
	v_cndmask_b32_e32 v59, v217, v45, vcc
	v_cmp_le_u32_e32 vcc, v44, v43
	v_or_b32_e32 v44, 3, v138
	v_or_b32_e32 v45, 4, v138
	v_cndmask_b32_e32 v60, v217, v46, vcc
	v_cmp_le_u32_e32 vcc, v44, v43
	v_mov_b32_e32 v44, s22
	s_nop 0
	v_cndmask_b32_e32 v61, v217, v47, vcc
	s_waitcnt lgkmcnt(0)
	v_mfma_f32_16x16x32_bf16 v[46:49], v[72:75], v[24:27], v[48:51]
	v_cmp_gt_u32_e32 vcc, v45, v43
	s_nop 6
	v_cndmask_b32_e32 v62, v46, v44, vcc
	v_or_b32_e32 v44, 5, v138
	v_cmp_le_u32_e32 vcc, v44, v43
	v_or_b32_e32 v44, 6, v138
	s_nop 0
	v_cndmask_b32_e32 v63, v217, v47, vcc
	v_cmp_le_u32_e32 vcc, v44, v43
	v_or_b32_e32 v44, 7, v138
	s_nop 0
	v_cndmask_b32_e32 v64, v217, v48, vcc
	v_cmp_le_u32_e32 vcc, v44, v43
	s_nop 1
	v_cndmask_b32_e32 v65, v217, v49, vcc
	ds_read_b128 v[44:47], v248 offset:8192
	ds_read_b128 v[48:51], v248 offset:9216
	ds_read_b128 v[52:55], v249 offset:8192
	ds_read_b128 v[68:71], v249 offset:9216
	ds_read_b128 v[72:75], v250 offset:8192
	ds_read_b128 v[76:79], v250 offset:9216
	ds_read_b128 v[80:83], v220 offset:8192
	ds_read_b128 v[84:87], v220 offset:9216
	s_waitcnt lgkmcnt(7)
	v_mfma_f32_16x16x32_bf16 v[44:47], v[44:47], v[38:41], 0
	s_waitcnt lgkmcnt(5)
	v_mfma_f32_16x16x32_bf16 v[44:47], v[52:55], v[34:37], v[44:47]
	v_or_b32_e32 v53, 32, v138
	v_mov_b32_e32 v52, s22
	v_cmp_gt_u32_e32 vcc, v53, v43
	s_waitcnt lgkmcnt(3)
	v_mfma_f32_16x16x32_bf16 v[44:47], v[72:75], v[28:31], v[44:47]
	v_mfma_f32_16x16x32_bf16 v[48:51], v[48:51], v[38:41], 0
	s_waitcnt lgkmcnt(1)
	v_mfma_f32_16x16x32_bf16 v[44:47], v[80:83], v[24:27], v[44:47]
	v_mfma_f32_16x16x32_bf16 v[48:51], v[68:71], v[34:37], v[48:51]
	v_mfma_f32_16x16x32_bf16 v[48:51], v[76:79], v[28:31], v[48:51]
	s_nop 5
	v_cndmask_b32_e32 v66, v44, v52, vcc
	v_or_b32_e32 v44, 33, v138
	v_cmp_le_u32_e32 vcc, v44, v43
	v_or_b32_e32 v44, 34, v138
	s_nop 0
	v_cndmask_b32_e32 v67, v217, v45, vcc
	v_cmp_le_u32_e32 vcc, v44, v43
	v_or_b32_e32 v44, 35, v138
	v_or_b32_e32 v45, 36, v138
	v_cndmask_b32_e32 v68, v217, v46, vcc
	v_cmp_le_u32_e32 vcc, v44, v43
	v_mov_b32_e32 v44, s22
	s_nop 0
	v_cndmask_b32_e32 v69, v217, v47, vcc
	s_waitcnt lgkmcnt(0)
	v_mfma_f32_16x16x32_bf16 v[46:49], v[84:87], v[24:27], v[48:51]
	v_cmp_gt_u32_e32 vcc, v45, v43
	s_nop 6
	v_cndmask_b32_e32 v70, v46, v44, vcc
	v_or_b32_e32 v44, 37, v138
	v_cmp_le_u32_e32 vcc, v44, v43
	v_or_b32_e32 v44, 38, v138
	s_nop 0
	v_cndmask_b32_e32 v71, v217, v47, vcc
	v_cmp_le_u32_e32 vcc, v44, v43
	v_or_b32_e32 v44, 39, v138
	s_nop 0
	v_cndmask_b32_e32 v72, v217, v48, vcc
	v_cmp_le_u32_e32 vcc, v44, v43
	s_nop 1
	v_cndmask_b32_e32 v73, v217, v49, vcc
	ds_read_b128 v[44:47], v248 offset:16384
	ds_read_b128 v[48:51], v248 offset:17408
	ds_read_b128 v[52:55], v249 offset:16384
	ds_read_b128 v[76:79], v249 offset:17408
	ds_read_b128 v[80:83], v250 offset:16384
	ds_read_b128 v[84:87], v250 offset:17408
	ds_read_b128 v[88:91], v220 offset:16384
	ds_read_b128 v[92:95], v220 offset:17408
	s_waitcnt lgkmcnt(7)
	v_mfma_f32_16x16x32_bf16 v[44:47], v[44:47], v[38:41], 0
	s_waitcnt lgkmcnt(5)
	v_mfma_f32_16x16x32_bf16 v[44:47], v[52:55], v[34:37], v[44:47]
	v_or_b32_e32 v53, 64, v138
	v_mov_b32_e32 v52, s22
	v_cmp_gt_u32_e32 vcc, v53, v43
	s_waitcnt lgkmcnt(3)
	v_mfma_f32_16x16x32_bf16 v[44:47], v[80:83], v[28:31], v[44:47]
	v_mfma_f32_16x16x32_bf16 v[48:51], v[48:51], v[38:41], 0
	s_waitcnt lgkmcnt(1)
	v_mfma_f32_16x16x32_bf16 v[44:47], v[88:91], v[24:27], v[44:47]
	v_mfma_f32_16x16x32_bf16 v[48:51], v[76:79], v[34:37], v[48:51]
	v_mfma_f32_16x16x32_bf16 v[48:51], v[84:87], v[28:31], v[48:51]
	s_nop 5
	v_cndmask_b32_e32 v74, v44, v52, vcc
	v_or_b32_e32 v44, 0x41, v138
	v_cmp_le_u32_e32 vcc, v44, v43
	v_or_b32_e32 v44, 0x42, v138
	s_nop 0
	v_cndmask_b32_e32 v75, v217, v45, vcc
	v_cmp_le_u32_e32 vcc, v44, v43
	v_or_b32_e32 v44, 0x43, v138
	v_or_b32_e32 v45, 0x44, v138
	v_cndmask_b32_e32 v76, v217, v46, vcc
	v_cmp_le_u32_e32 vcc, v44, v43
	v_mov_b32_e32 v44, s22
	s_nop 0
	v_cndmask_b32_e32 v77, v217, v47, vcc
	s_waitcnt lgkmcnt(0)
	v_mfma_f32_16x16x32_bf16 v[46:49], v[92:95], v[24:27], v[48:51]
	v_cmp_gt_u32_e32 vcc, v45, v43
	s_nop 6
	v_cndmask_b32_e32 v78, v46, v44, vcc
	v_or_b32_e32 v44, 0x45, v138
	v_cmp_le_u32_e32 vcc, v44, v43
	v_or_b32_e32 v44, 0x46, v138
	s_nop 0
	v_cndmask_b32_e32 v79, v217, v47, vcc
	v_cmp_le_u32_e32 vcc, v44, v43
	v_or_b32_e32 v44, 0x47, v138
	s_nop 0
	v_cndmask_b32_e32 v80, v217, v48, vcc
	v_cmp_le_u32_e32 vcc, v44, v43
	s_nop 1
	v_cndmask_b32_e32 v81, v217, v49, vcc
	ds_read_b128 v[44:47], v248 offset:24576
	ds_read_b128 v[48:51], v248 offset:25600
	ds_read_b128 v[52:55], v249 offset:24576
	ds_read_b128 v[84:87], v249 offset:25600
	ds_read_b128 v[88:91], v250 offset:24576
	ds_read_b128 v[92:95], v250 offset:25600
	ds_read_b128 v[96:99], v220 offset:24576
	ds_read_b128 v[100:103], v220 offset:25600
	s_waitcnt lgkmcnt(7)
	v_mfma_f32_16x16x32_bf16 v[44:47], v[44:47], v[38:41], 0
	s_waitcnt lgkmcnt(5)
	v_mfma_f32_16x16x32_bf16 v[44:47], v[52:55], v[34:37], v[44:47]
	v_or_b32_e32 v53, 0x60, v138
	v_mov_b32_e32 v52, s22
	v_cmp_gt_u32_e32 vcc, v53, v43
	s_waitcnt lgkmcnt(3)
	v_mfma_f32_16x16x32_bf16 v[44:47], v[88:91], v[28:31], v[44:47]
	v_mfma_f32_16x16x32_bf16 v[48:51], v[48:51], v[38:41], 0
	s_waitcnt lgkmcnt(1)
	v_mfma_f32_16x16x32_bf16 v[44:47], v[96:99], v[24:27], v[44:47]
	v_mfma_f32_16x16x32_bf16 v[48:51], v[84:87], v[34:37], v[48:51]
	v_mfma_f32_16x16x32_bf16 v[48:51], v[92:95], v[28:31], v[48:51]
	s_nop 5
	v_cndmask_b32_e32 v82, v44, v52, vcc
	v_or_b32_e32 v44, 0x61, v138
	v_cmp_le_u32_e32 vcc, v44, v43
	v_or_b32_e32 v44, 0x62, v138
	s_nop 0
	v_cndmask_b32_e32 v83, v217, v45, vcc
	v_cmp_le_u32_e32 vcc, v44, v43
	v_or_b32_e32 v44, 0x63, v138
	v_or_b32_e32 v45, 0x64, v138
	v_cndmask_b32_e32 v84, v217, v46, vcc
	v_cmp_le_u32_e32 vcc, v44, v43
	v_mov_b32_e32 v44, s22
	s_nop 0
	v_cndmask_b32_e32 v85, v217, v47, vcc
	s_waitcnt lgkmcnt(0)
	v_mfma_f32_16x16x32_bf16 v[46:49], v[100:103], v[24:27], v[48:51]
	v_cmp_gt_u32_e32 vcc, v45, v43
	s_nop 6
	v_cndmask_b32_e32 v86, v46, v44, vcc
	v_or_b32_e32 v44, 0x65, v138
	v_cmp_le_u32_e32 vcc, v44, v43
	v_or_b32_e32 v44, 0x66, v138
	s_nop 0
	v_cndmask_b32_e32 v87, v217, v47, vcc
	v_cmp_le_u32_e32 vcc, v44, v43
	v_or_b32_e32 v44, 0x67, v138
	s_nop 0
	v_cndmask_b32_e32 v88, v217, v48, vcc
	v_cmp_le_u32_e32 vcc, v44, v43
	s_nop 1
	v_cndmask_b32_e32 v89, v217, v49, vcc
	ds_read_b128 v[44:47], v248 offset:32768
	ds_read_b128 v[48:51], v248 offset:33792
	ds_read_b128 v[52:55], v249 offset:32768
	ds_read_b128 v[92:95], v249 offset:33792
	ds_read_b128 v[96:99], v250 offset:32768
	ds_read_b128 v[100:103], v250 offset:33792
	ds_read_b128 v[114:117], v220 offset:32768
	ds_read_b128 v[118:121], v220 offset:33792
	s_waitcnt lgkmcnt(7)
	v_mfma_f32_16x16x32_bf16 v[44:47], v[44:47], v[38:41], 0
	s_waitcnt lgkmcnt(5)
	v_mfma_f32_16x16x32_bf16 v[44:47], v[52:55], v[34:37], v[44:47]
	v_or_b32_e32 v53, 0x80, v138
	v_mov_b32_e32 v52, s22
	v_cmp_gt_u32_e32 vcc, v53, v43
	s_waitcnt lgkmcnt(3)
	v_mfma_f32_16x16x32_bf16 v[44:47], v[96:99], v[28:31], v[44:47]
	v_mfma_f32_16x16x32_bf16 v[48:51], v[48:51], v[38:41], 0
	s_waitcnt lgkmcnt(1)
	v_mfma_f32_16x16x32_bf16 v[44:47], v[114:117], v[24:27], v[44:47]
	v_mfma_f32_16x16x32_bf16 v[48:51], v[92:95], v[34:37], v[48:51]
	v_mfma_f32_16x16x32_bf16 v[48:51], v[100:103], v[28:31], v[48:51]
	s_nop 5
	v_cndmask_b32_e32 v90, v44, v52, vcc
	v_or_b32_e32 v44, 0x81, v138
	v_cmp_le_u32_e32 vcc, v44, v43
	v_or_b32_e32 v44, 0x82, v138
	s_nop 0
	v_cndmask_b32_e32 v91, v217, v45, vcc
	v_cmp_le_u32_e32 vcc, v44, v43
	v_or_b32_e32 v44, 0x83, v138
	v_or_b32_e32 v45, 0x84, v138
	v_cndmask_b32_e32 v92, v217, v46, vcc
	v_cmp_le_u32_e32 vcc, v44, v43
	v_mov_b32_e32 v44, s22
	s_nop 0
	v_cndmask_b32_e32 v93, v217, v47, vcc
	s_waitcnt lgkmcnt(0)
	v_mfma_f32_16x16x32_bf16 v[46:49], v[118:121], v[24:27], v[48:51]
	v_cmp_gt_u32_e32 vcc, v45, v43
	s_nop 6
	v_cndmask_b32_e32 v94, v46, v44, vcc
	v_or_b32_e32 v44, 0x85, v138
	v_cmp_le_u32_e32 vcc, v44, v43
	v_or_b32_e32 v44, 0x86, v138
	s_nop 0
	v_cndmask_b32_e32 v95, v217, v47, vcc
	v_cmp_le_u32_e32 vcc, v44, v43
	v_or_b32_e32 v44, 0x87, v138
	s_nop 0
	v_cndmask_b32_e32 v96, v217, v48, vcc
	v_cmp_le_u32_e32 vcc, v44, v43
	s_nop 1
	v_cndmask_b32_e32 v97, v217, v49, vcc
	ds_read_b128 v[44:47], v248 offset:40960
	ds_read_b128 v[48:51], v248 offset:41984
	ds_read_b128 v[52:55], v249 offset:40960
	ds_read_b128 v[100:103], v249 offset:41984
	ds_read_b128 v[114:117], v250 offset:40960
	ds_read_b128 v[118:121], v250 offset:41984
	ds_read_b128 v[122:125], v220 offset:40960
	ds_read_b128 v[126:129], v220 offset:41984
	s_waitcnt lgkmcnt(7)
	v_mfma_f32_16x16x32_bf16 v[44:47], v[44:47], v[38:41], 0
	v_cmp_gt_u32_e32 vcc, v197, v43
	s_waitcnt lgkmcnt(5)
	v_mfma_f32_16x16x32_bf16 v[44:47], v[52:55], v[34:37], v[44:47]
	v_mov_b32_e32 v52, s22
	v_mfma_f32_16x16x32_bf16 v[48:51], v[48:51], v[38:41], 0
	s_waitcnt lgkmcnt(3)
	v_mfma_f32_16x16x32_bf16 v[44:47], v[114:117], v[28:31], v[44:47]
	v_mfma_f32_16x16x32_bf16 v[48:51], v[100:103], v[34:37], v[48:51]
	s_waitcnt lgkmcnt(1)
	v_mfma_f32_16x16x32_bf16 v[44:47], v[122:125], v[24:27], v[44:47]
	v_mfma_f32_16x16x32_bf16 v[48:51], v[118:121], v[28:31], v[48:51]
	s_nop 6
	v_cndmask_b32_e32 v98, v44, v52, vcc
	v_cmp_le_u32_e32 vcc, v199, v43
	v_mov_b32_e32 v44, s22
	s_nop 0
	v_cndmask_b32_e32 v99, v217, v45, vcc
	v_cmp_le_u32_e32 vcc, v201, v43
	s_nop 1
	v_cndmask_b32_e32 v102, v217, v46, vcc
	v_cmp_le_u32_e32 vcc, v202, v43
	s_nop 1
	v_cndmask_b32_e32 v103, v217, v47, vcc
	s_waitcnt lgkmcnt(0)
	v_mfma_f32_16x16x32_bf16 v[46:49], v[126:129], v[24:27], v[48:51]
	v_cmp_gt_u32_e32 vcc, v203, v43
	s_nop 6
	v_cndmask_b32_e32 v100, v46, v44, vcc
	v_cmp_le_u32_e32 vcc, v204, v43
	s_nop 1
	v_cndmask_b32_e32 v101, v217, v47, vcc
	v_cmp_le_u32_e32 vcc, v205, v43
	s_nop 1
	v_cndmask_b32_e32 v104, v217, v48, vcc
	v_cmp_le_u32_e32 vcc, v206, v43
	s_nop 1
	v_cndmask_b32_e32 v105, v217, v49, vcc
	ds_read_b128 v[44:47], v248 offset:49152
	ds_read_b128 v[48:51], v248 offset:50176
	ds_read_b128 v[52:55], v249 offset:49152
	ds_read_b128 v[114:117], v249 offset:50176
	ds_read_b128 v[118:121], v250 offset:49152
	ds_read_b128 v[122:125], v250 offset:50176
	ds_read_b128 v[126:129], v220 offset:49152
	ds_read_b128 v[130:133], v220 offset:50176
	s_waitcnt lgkmcnt(7)
	v_mfma_f32_16x16x32_bf16 v[44:47], v[44:47], v[38:41], 0
	v_cmp_gt_u32_e32 vcc, v207, v43
	s_waitcnt lgkmcnt(5)
	v_mfma_f32_16x16x32_bf16 v[44:47], v[52:55], v[34:37], v[44:47]
	v_mov_b32_e32 v52, s22
	v_mfma_f32_16x16x32_bf16 v[48:51], v[48:51], v[38:41], 0
	s_waitcnt lgkmcnt(3)
	v_mfma_f32_16x16x32_bf16 v[44:47], v[118:121], v[28:31], v[44:47]
	v_mfma_f32_16x16x32_bf16 v[48:51], v[114:117], v[34:37], v[48:51]
	s_waitcnt lgkmcnt(1)
	v_mfma_f32_16x16x32_bf16 v[44:47], v[126:129], v[24:27], v[44:47]
	v_mfma_f32_16x16x32_bf16 v[48:51], v[122:125], v[28:31], v[48:51]
	s_nop 6
	v_cndmask_b32_e32 v108, v44, v52, vcc
	v_cmp_le_u32_e32 vcc, v208, v43
	v_mov_b32_e32 v44, s22
	s_nop 0
	v_cndmask_b32_e32 v109, v217, v45, vcc
	v_cmp_le_u32_e32 vcc, v209, v43
	s_nop 1
	v_cndmask_b32_e32 v118, v217, v46, vcc
	v_cmp_le_u32_e32 vcc, v210, v43
	s_nop 1
	v_cndmask_b32_e32 v119, v217, v47, vcc
	s_waitcnt lgkmcnt(0)
	v_mfma_f32_16x16x32_bf16 v[46:49], v[130:133], v[24:27], v[48:51]
	v_cmp_gt_u32_e32 vcc, v211, v43
	s_nop 6
	v_cndmask_b32_e32 v116, v46, v44, vcc
	v_cmp_le_u32_e32 vcc, v212, v43
	s_nop 1
	v_cndmask_b32_e32 v117, v217, v47, vcc
	v_cmp_le_u32_e32 vcc, v213, v43
	s_nop 1
	v_cndmask_b32_e32 v120, v217, v48, vcc
	v_cmp_le_u32_e32 vcc, v221, v43
	s_nop 1
	v_cndmask_b32_e32 v121, v217, v49, vcc
	ds_read_b128 v[44:47], v248 offset:57344
	ds_read_b128 v[48:51], v248 offset:58368
	ds_read_b128 v[52:55], v249 offset:57344
	ds_read_b128 v[122:125], v249 offset:58368
	ds_read_b128 v[126:129], v250 offset:57344
	ds_read_b128 v[130:133], v250 offset:58368
	ds_read_b128 v[134:137], v220 offset:57344
	ds_read_b128 v[190:193], v220 offset:58368
	s_waitcnt lgkmcnt(7)
	v_mfma_f32_16x16x32_bf16 v[44:47], v[44:47], v[38:41], 0
	v_cmp_gt_u32_e32 vcc, v222, v43
	s_waitcnt lgkmcnt(5)
	v_mfma_f32_16x16x32_bf16 v[44:47], v[52:55], v[34:37], v[44:47]
	v_mfma_f32_16x16x32_bf16 v[48:51], v[48:51], v[38:41], 0
	v_mov_b32_e32 v38, s22
	s_waitcnt lgkmcnt(3)
	v_mfma_f32_16x16x32_bf16 v[44:47], v[126:129], v[28:31], v[44:47]
	v_mfma_f32_16x16x32_bf16 v[48:51], v[122:125], v[34:37], v[48:51]
	v_mov_b32_e32 v36, s22
	s_waitcnt lgkmcnt(1)
	v_mfma_f32_16x16x32_bf16 v[44:47], v[134:137], v[24:27], v[44:47]
	v_mfma_f32_16x16x32_bf16 v[28:31], v[130:133], v[28:31], v[48:51]
	s_waitcnt lgkmcnt(0)
	v_mfma_f32_16x16x32_bf16 v[24:27], v[190:193], v[24:27], v[28:31]
	s_nop 4
	v_cndmask_b32_e32 v38, v44, v38, vcc
	v_cmp_le_u32_e32 vcc, v223, v43
	s_nop 1
	v_cndmask_b32_e32 v39, v217, v45, vcc
	v_cmp_le_u32_e32 vcc, v224, v43
	s_nop 1
	v_cndmask_b32_e32 v34, v217, v46, vcc
	v_cmp_le_u32_e32 vcc, v225, v43
	s_nop 1
	v_cndmask_b32_e32 v35, v217, v47, vcc
	v_cmp_gt_u32_e32 vcc, v226, v43
	s_nop 1
	v_cndmask_b32_e32 v24, v24, v36, vcc
	v_cmp_le_u32_e32 vcc, v227, v43
	s_nop 1
	v_cndmask_b32_e32 v25, v217, v25, vcc
	v_cmp_le_u32_e32 vcc, v228, v43
	s_nop 1
	v_cndmask_b32_e32 v26, v217, v26, vcc
	v_cmp_le_u32_e32 vcc, v229, v43
	s_nop 1
	v_cndmask_b32_e32 v27, v217, v27, vcc
	v_max3_f32 v28, v42, v58, v59
	v_max3_f32 v29, v218, v60, v61
	v_and_b32_e32 v30, 64, v216
	v_max3_f32 v28, v28, v62, v63
	v_max3_f32 v29, v29, v64, v65
	v_add_u32_e32 v30, 64, v30
	v_max3_f32 v28, v28, v66, v67
	v_max3_f32 v29, v29, v68, v69
	ds_read_b128 v[42:45], v230
	ds_read_b128 v[46:49], v230 offset:8704
	ds_read_b128 v[50:53], v230 offset:17408
	ds_read_b128 v[54:57], v230 offset:26112
	v_max3_f32 v28, v28, v70, v71
	v_max3_f32 v29, v29, v72, v73
	s_nop 0
	v_max3_f32 v28, v28, v74, v75
	v_max3_f32 v29, v29, v76, v77
	s_nop 0
	v_max3_f32 v28, v28, v78, v79
	v_max3_f32 v29, v29, v80, v81
	s_nop 0
	v_max3_f32 v28, v28, v82, v83
	v_max3_f32 v29, v29, v84, v85
	s_nop 0
	v_max3_f32 v28, v28, v86, v87
	v_max3_f32 v29, v29, v88, v89
	s_nop 0
	v_max3_f32 v28, v28, v90, v91
	v_max3_f32 v29, v29, v92, v93
	s_nop 0
	v_max3_f32 v28, v28, v94, v95
	v_max3_f32 v29, v29, v96, v97
	s_nop 0
	v_max3_f32 v28, v28, v98, v99
	v_max3_f32 v29, v29, v102, v103
	s_nop 0
	v_max3_f32 v28, v28, v100, v101
	v_max3_f32 v29, v29, v104, v105
	s_nop 0
	v_max3_f32 v28, v28, v108, v109
	v_max3_f32 v29, v29, v118, v119
	s_nop 0
	v_max3_f32 v28, v28, v116, v117
	v_max3_f32 v29, v29, v120, v121
	s_nop 0
	v_max3_f32 v28, v28, v38, v39
	v_max3_f32 v29, v29, v34, v35
	s_nop 0
	v_max3_f32 v28, v28, v24, v25
	v_max3_f32 v29, v29, v26, v27
	s_nop 0
	v_max_f32 v28, v28, v29
	v_xor_b32_e32 v29, 16, v216
	v_cmp_lt_i32_e32 vcc, v29, v30
	s_nop 1
	v_cndmask_b32_e32 v29, v216, v29, vcc
	v_lshlrev_b32_e32 v160, 2, v29
	v_mov_b32_e32 v29, v28
	s_nop 1
	v_permlane16_swap_b32_e32 v29, v28
	s_waitcnt lgkmcnt(0)
	v_max_f32 v28, v28, v29
	v_xor_b32_e32 v29, 32, v216
	v_cmp_lt_i32_e32 vcc, v29, v30
	s_nop 1
	v_cndmask_b32_e32 v29, v216, v29, vcc
	v_lshlrev_b32_e32 v161, 2, v29
	v_mov_b32_e32 v29, v28
	s_nop 1
	v_permlane32_swap_b32_e32 v29, v28
	s_waitcnt lgkmcnt(0)
	v_max_f32 v114, v28, v29
	s_nop 0
	v_mov_b32_e32 v115, v114
	v_pk_add_f32 v[28:29], v[58:59], v[114:115] neg_lo:[0,1] neg_hi:[0,1]
	v_pk_add_f32 v[30:31], v[60:61], v[114:115] neg_lo:[0,1] neg_hi:[0,1]
	v_pk_add_f32 v[36:37], v[62:63], v[114:115] neg_lo:[0,1] neg_hi:[0,1]
	v_pk_add_f32 v[40:41], v[64:65], v[114:115] neg_lo:[0,1] neg_hi:[0,1]
	v_pk_add_f32 v[38:39], v[38:39], v[114:115] neg_lo:[0,1] neg_hi:[0,1]
	v_pk_add_f32 v[34:35], v[34:35], v[114:115] neg_lo:[0,1] neg_hi:[0,1]
	s_nop 0
	v_exp_f32_e32 v28, v28
	v_exp_f32_e32 v29, v29
	v_exp_f32_e32 v30, v30
	v_exp_f32_e32 v31, v31
	v_exp_f32_e32 v36, v36
	v_exp_f32_e32 v40, v40
	v_exp_f32_e32 v41, v41
	v_exp_f32_e32 v37, v37
	v_pk_add_f32 v[58:59], v[28:29], 0 op_sel_hi:[1,0]
	v_pk_add_f32 v[60:61], v[30:31], 0 op_sel_hi:[1,0]
	v_exp_f32_e32 v38, v38
	v_pk_add_f32 v[62:63], v[60:61], v[40:41]
	v_pk_add_f32 v[64:65], v[58:59], v[36:37]
	v_pk_add_f32 v[58:59], v[66:67], v[114:115] neg_lo:[0,1] neg_hi:[0,1]
	v_pk_add_f32 v[60:61], v[68:69], v[114:115] neg_lo:[0,1] neg_hi:[0,1]
	v_pk_add_f32 v[66:67], v[70:71], v[114:115] neg_lo:[0,1] neg_hi:[0,1]
	v_pk_add_f32 v[68:69], v[72:73], v[114:115] neg_lo:[0,1] neg_hi:[0,1]
	v_pk_add_f32 v[70:71], v[74:75], v[114:115] neg_lo:[0,1] neg_hi:[0,1]
	v_pk_add_f32 v[72:73], v[76:77], v[114:115] neg_lo:[0,1] neg_hi:[0,1]
	s_nop 0
	v_exp_f32_e32 v58, v58
	v_exp_f32_e32 v59, v59
	v_exp_f32_e32 v60, v60
	v_exp_f32_e32 v61, v61
	v_exp_f32_e32 v66, v66
	v_exp_f32_e32 v68, v68
	v_exp_f32_e32 v69, v69
	v_exp_f32_e32 v67, v67
	v_exp_f32_e32 v70, v70
	v_exp_f32_e32 v71, v71
	v_exp_f32_e32 v72, v72
	v_exp_f32_e32 v73, v73
	v_pk_add_f32 v[74:75], v[78:79], v[114:115] neg_lo:[0,1] neg_hi:[0,1]
	v_pk_add_f32 v[76:77], v[80:81], v[114:115] neg_lo:[0,1] neg_hi:[0,1]
	v_pk_add_f32 v[64:65], v[64:65], v[58:59]
	v_exp_f32_e32 v74, v74
	v_exp_f32_e32 v76, v76
	v_exp_f32_e32 v77, v77
	v_exp_f32_e32 v75, v75
	v_pk_add_f32 v[62:63], v[62:63], v[60:61]
	v_pk_add_f32 v[78:79], v[82:83], v[114:115] neg_lo:[0,1] neg_hi:[0,1]
	v_pk_add_f32 v[80:81], v[84:85], v[114:115] neg_lo:[0,1] neg_hi:[0,1]
	v_pk_add_f32 v[64:65], v[64:65], v[66:67]
	v_exp_f32_e32 v122, v78
	v_exp_f32_e32 v123, v79
	v_exp_f32_e32 v124, v80
	v_exp_f32_e32 v125, v81
	v_pk_add_f32 v[62:63], v[62:63], v[68:69]
	v_pk_add_f32 v[78:79], v[86:87], v[114:115] neg_lo:[0,1] neg_hi:[0,1]
	v_pk_add_f32 v[80:81], v[88:89], v[114:115] neg_lo:[0,1] neg_hi:[0,1]
	v_pk_add_f32 v[64:65], v[64:65], v[70:71]
	v_exp_f32_e32 v126, v78
	v_exp_f32_e32 v128, v80
	v_exp_f32_e32 v129, v81
	v_exp_f32_e32 v127, v79
	v_pk_add_f32 v[62:63], v[62:63], v[72:73]
	v_pk_add_f32 v[78:79], v[90:91], v[114:115] neg_lo:[0,1] neg_hi:[0,1]
	v_pk_add_f32 v[80:81], v[92:93], v[114:115] neg_lo:[0,1] neg_hi:[0,1]
	v_pk_add_f32 v[64:65], v[64:65], v[74:75]
	v_exp_f32_e32 v130, v78
	v_exp_f32_e32 v131, v79
	v_exp_f32_e32 v132, v80
	v_exp_f32_e32 v133, v81
	v_pk_add_f32 v[62:63], v[62:63], v[76:77]
	v_pk_add_f32 v[78:79], v[94:95], v[114:115] neg_lo:[0,1] neg_hi:[0,1]
	v_pk_add_f32 v[80:81], v[96:97], v[114:115] neg_lo:[0,1] neg_hi:[0,1]
	v_pk_add_f32 v[64:65], v[64:65], v[122:123]
	v_exp_f32_e32 v134, v78
	v_exp_f32_e32 v136, v80
	v_exp_f32_e32 v137, v81
	v_exp_f32_e32 v135, v79
	v_pk_add_f32 v[62:63], v[62:63], v[124:125]
	v_pk_add_f32 v[78:79], v[98:99], v[114:115] neg_lo:[0,1] neg_hi:[0,1]
	v_pk_add_f32 v[80:81], v[102:103], v[114:115] neg_lo:[0,1] neg_hi:[0,1]
	v_pk_add_f32 v[64:65], v[64:65], v[126:127]
	v_exp_f32_e32 v158, v78
	v_exp_f32_e32 v159, v79
	v_exp_f32_e32 v190, v80
	v_exp_f32_e32 v191, v81
	v_pk_add_f32 v[62:63], v[62:63], v[128:129]
	v_pk_add_f32 v[78:79], v[100:101], v[114:115] neg_lo:[0,1] neg_hi:[0,1]
	v_pk_add_f32 v[80:81], v[104:105], v[114:115] neg_lo:[0,1] neg_hi:[0,1]
	v_pk_add_f32 v[64:65], v[64:65], v[130:131]
	v_exp_f32_e32 v192, v78
	v_exp_f32_e32 v194, v80
	v_exp_f32_e32 v195, v81
	v_exp_f32_e32 v193, v79
	v_pk_add_f32 v[62:63], v[62:63], v[132:133]
	v_pk_add_f32 v[78:79], v[108:109], v[114:115] neg_lo:[0,1] neg_hi:[0,1]
	v_pk_add_f32 v[80:81], v[118:119], v[114:115] neg_lo:[0,1] neg_hi:[0,1]
	v_pk_add_f32 v[64:65], v[64:65], v[134:135]
	v_exp_f32_e32 v108, v78
	v_exp_f32_e32 v109, v79
	v_exp_f32_e32 v118, v80
	v_exp_f32_e32 v119, v81
	v_pk_add_f32 v[62:63], v[62:63], v[136:137]
	v_pk_add_f32 v[78:79], v[116:117], v[114:115] neg_lo:[0,1] neg_hi:[0,1]
	v_pk_add_f32 v[80:81], v[120:121], v[114:115] neg_lo:[0,1] neg_hi:[0,1]
	v_pk_add_f32 v[64:65], v[64:65], v[158:159]
	v_exp_f32_e32 v116, v78
	v_exp_f32_e32 v120, v80
	v_exp_f32_e32 v121, v81
	v_exp_f32_e32 v117, v79
	v_pk_add_f32 v[62:63], v[62:63], v[190:191]
	v_exp_f32_e32 v39, v39
	v_exp_f32_e32 v34, v34
	v_exp_f32_e32 v35, v35
	v_pk_add_f32 v[24:25], v[24:25], v[114:115] neg_lo:[0,1] neg_hi:[0,1]
	v_pk_add_f32 v[26:27], v[26:27], v[114:115] neg_lo:[0,1] neg_hi:[0,1]
	v_pk_add_f32 v[62:63], v[62:63], v[194:195]
	v_pk_add_f32 v[64:65], v[64:65], v[192:193]
	v_exp_f32_e32 v24, v24
	v_exp_f32_e32 v26, v26
	v_exp_f32_e32 v27, v27
	v_exp_f32_e32 v25, v25
	v_pk_add_f32 v[64:65], v[64:65], v[108:109]
	v_pk_add_f32 v[62:63], v[62:63], v[118:119]
	v_pk_add_f32 v[64:65], v[64:65], v[116:117]
	v_pk_add_f32 v[62:63], v[62:63], v[120:121]
	v_pk_add_f32 v[64:65], v[64:65], v[38:39]
	v_pk_add_f32 v[62:63], v[62:63], v[34:35]
	v_pk_add_f32 v[64:65], v[64:65], v[24:25]
	v_pk_add_f32 v[62:63], v[62:63], v[26:27]
	v_add_f32_e32 v64, v64, v65
	v_add_f32_e32 v62, v62, v63
	v_add_f32_e32 v62, v64, v62
	v_mov_b32_e32 v63, v62
	s_nop 1
	v_permlane16_swap_b32_e32 v63, v62
	ds_read_b128 v[90:93], v230 offset:34816
	ds_read_b128 v[94:97], v230 offset:43520
	ds_read_b128 v[98:101], v230 offset:52224
	ds_read_b128 v[86:89], v230 offset:60928
	v_cvt_pk_bf16_f32 v102, v28, v29
	v_cvt_pk_bf16_f32 v103, v30, v31
	v_cvt_pk_bf16_f32 v104, v36, v37
	s_waitcnt lgkmcnt(4)
	v_add_f32_e32 v185, v62, v63
	ds_bpermute_b32 v187, v161, v185
	v_cvt_pk_bf16_f32 v105, v40, v41
	v_cvt_pk_bf16_f32 v82, v58, v59
	v_cvt_pk_bf16_f32 v83, v60, v61
	v_cvt_pk_bf16_f32 v84, v66, v67
	v_cvt_pk_bf16_f32 v85, v68, v69
	v_cvt_pk_bf16_f32 v78, v70, v71
	v_cvt_pk_bf16_f32 v79, v72, v73
	v_cvt_pk_bf16_f32 v80, v74, v75
	v_cvt_pk_bf16_f32 v81, v76, v77
	v_cvt_pk_bf16_f32 v74, v122, v123
	v_cvt_pk_bf16_f32 v75, v124, v125
	v_cvt_pk_bf16_f32 v76, v126, v127
	v_cvt_pk_bf16_f32 v77, v128, v129
	v_cvt_pk_bf16_f32 v70, v130, v131
	v_cvt_pk_bf16_f32 v71, v132, v133
	v_cvt_pk_bf16_f32 v72, v134, v135
	v_cvt_pk_bf16_f32 v73, v136, v137
	v_cvt_pk_bf16_f32 v66, v158, v159
	v_cvt_pk_bf16_f32 v67, v190, v191
	v_cvt_pk_bf16_f32 v68, v192, v193
	v_cvt_pk_bf16_f32 v69, v194, v195
	v_cvt_pk_bf16_f32 v62, v108, v109
	v_cvt_pk_bf16_f32 v63, v118, v119
	v_cvt_pk_bf16_f32 v64, v116, v117
	v_cvt_pk_bf16_f32 v65, v120, v121
	v_cvt_pk_bf16_f32 v58, v38, v39
	v_cvt_pk_bf16_f32 v59, v34, v35
	v_cvt_pk_bf16_f32 v60, v24, v25
	v_cvt_pk_bf16_f32 v61, v26, v27
	s_add_i32 s28, s23, 8
	s_cmp_lg_u32 s23, 24
	s_cselect_b32 s23, s28, 24
	s_add_i32 s23, s23, s11
	s_lshl_b32 s29, s23, 4
	s_and_b32 s29, s29, 0xf0
	v_or_b32_e32 v108, s29, v183
	s_ashr_i32 s23, s23, 4
	v_ashrrev_i32_e32 v109, 31, v108
	s_add_i32 s23, s23, s19
	v_lshlrev_b64 v[24:25], 11, v[108:109]
	s_lshl_b32 s30, s23, 7
	v_lshl_add_u64 v[24:25], s[0:1], 0, v[24:25]
	s_ashr_i32 s31, s30, 31
	v_lshl_add_u64 v[24:25], s[30:31], 1, v[24:25]
	v_lshl_add_u64 v[24:25], v[24:25], 0, v[32:33]
	global_load_dwordx4 v[38:41], v[24:25], off
	global_load_dwordx4 v[34:37], v[24:25], off offset:64
	global_load_dwordx4 v[28:31], v[24:25], off offset:128
	s_nop 0
	global_load_dwordx4 v[24:27], v[24:25], off offset:192
	s_ashr_i32 s29, s23, 31
	v_mov_b32_e32 v116, s23
	v_mov_b32_e32 v117, s29
	s_and_b64 vcc, exec, s[38:39]
	v_lshl_add_u64 v[108:109], v[108:109], 3, v[116:117]
	s_cbranch_vccnz .LBB0_1128
	v_mad_u64_u32 v[116:117], s[30:31], v108, 24, s[4:5]
	v_mad_i32_i24 v117, v109, 24, v117
	global_load_dwordx2 v[190:191], v[116:117], off
	s_branch .LBB0_1129

.LBB0_1258:
	s_or_b64 exec, exec, s[38:39]
	s_waitcnt lgkmcnt(0)
	s_barrier
	ds_read_b32 v0, v44
	s_waitcnt vmcnt(1) lgkmcnt(0)
	v_add_f32_e32 v4, v18, v0
	v_add_u32_e32 v0, v16, v45
	v_ashrrev_i32_e32 v1, 31, v0
	v_lshl_add_u64 v[2:3], v[0:1], 2, s[46:47]
	v_lshl_add_u64 v[0:1], v[0:1], 1, s[48:49]
	global_store_dword v[2:3], v4, off
	v_cvt_pk_bf16_f32 v2, v4, v33
	global_store_short v[0:1], v2, off
	v_and_b32_e32 v0, 64, v216
	v_add_u32_e32 v6, 64, v0
	v_xor_b32_e32 v0, 1, v216
	v_cmp_lt_i32_e32 vcc, v0, v6
	v_mul_f32_e32 v1, v4, v4
	s_nop 0
	v_cndmask_b32_e32 v0, v216, v0, vcc
	v_lshlrev_b32_e32 v0, 2, v0
	ds_bpermute_b32 v2, v0, v1
	v_xor_b32_e32 v1, 2, v216
	v_cmp_lt_i32_e32 vcc, v1, v6
	s_waitcnt lgkmcnt(0)
	v_fmac_f32_e32 v2, v4, v4
	v_cndmask_b32_e32 v1, v216, v1, vcc
	v_lshlrev_b32_e32 v1, 2, v1
	s_waitcnt lgkmcnt(0)
	s_nop 1
	v_add_f32_dpp v3, v2, v2 quad_perm:[2,3,0,1] row_mask:0xf bank_mask:0xf
	v_xor_b32_e32 v2, 4, v216
	v_cmp_lt_i32_e32 vcc, v2, v6
	s_nop 1
	v_cndmask_b32_e32 v2, v216, v2, vcc
	v_lshlrev_b32_e32 v2, 2, v2
	s_waitcnt lgkmcnt(0)
	s_nop 1
	v_add_f32_dpp v4, v3, v3 row_half_mirror row_mask:0xf bank_mask:0xf
	v_xor_b32_e32 v3, 8, v216
	v_cmp_lt_i32_e32 vcc, v3, v6
	s_nop 1
	v_cndmask_b32_e32 v3, v216, v3, vcc
	v_lshlrev_b32_e32 v3, 2, v3
	s_waitcnt lgkmcnt(0)
	s_nop 1
	v_add_f32_dpp v5, v4, v4 row_mirror row_mask:0xf bank_mask:0xf
	v_xor_b32_e32 v4, 16, v216
	v_cmp_lt_i32_e32 vcc, v4, v6
	s_nop 1
	v_cndmask_b32_e32 v4, v216, v4, vcc
	v_lshlrev_b32_e32 v4, 2, v4
	v_mov_b32_e32 v6, v5
	s_nop 1
	v_permlane16_swap_b32_e32 v6, v5
	s_and_saveexec_b64 s[2:3], s[36:37]
	s_cbranch_execz .LBB0_1260
	s_waitcnt lgkmcnt(0)
	v_add_f32_e32 v5, v5, v6
	v_mul_f32_e32 v5, 0x4b800000, v5
	v_trunc_f32_e32 v5, v5
	v_mul_f32_e32 v6, 0x2f800000, v5
	v_floor_f32_e32 v7, v6
	v_fmac_f32_e32 v5, 0xcf800000, v7
	v_cvt_u32_f32_e32 v6, v5
	v_cvt_u32_f32_e32 v7, v7
	global_atomic_add_x2 v[46:47], v[6:7], off
.LBB0_1260:
	s_or_b64 exec, exec, s[2:3]
	v_add_u32_e32 v5, v42, v85
	ds_read_b32 v5, v5
	s_waitcnt lgkmcnt(1)
	v_add_u32_e32 v6, v16, v86
	v_ashrrev_i32_e32 v7, 31, v6
	v_lshl_add_u64 v[8:9], v[6:7], 2, s[46:47]
	v_lshl_add_u64 v[6:7], v[6:7], 1, s[48:49]
	s_waitcnt vmcnt(2) lgkmcnt(0)
	v_add_f32_e32 v5, v17, v5
	global_store_dword v[8:9], v5, off
	v_cvt_pk_bf16_f32 v8, v5, v33
	global_store_short v[6:7], v8, off
	v_mul_f32_e32 v6, v5, v5
	ds_bpermute_b32 v0, v0, v6
	s_waitcnt lgkmcnt(0)
	v_fmac_f32_e32 v0, v5, v5
	s_waitcnt lgkmcnt(0)
	s_nop 1
	v_add_f32_dpp v0, v0, v0 quad_perm:[2,3,0,1] row_mask:0xf bank_mask:0xf
	s_waitcnt lgkmcnt(0)
	s_nop 1
	v_add_f32_dpp v0, v0, v0 row_half_mirror row_mask:0xf bank_mask:0xf
	s_waitcnt lgkmcnt(0)
	s_nop 1
	v_add_f32_dpp v0, v0, v0 row_mirror row_mask:0xf bank_mask:0xf
	v_mov_b32_e32 v1, v0
	s_nop 1
	v_permlane16_swap_b32_e32 v1, v0
	s_and_saveexec_b64 s[2:3], s[36:37]
	s_cbranch_execz .LBB0_1254
	s_waitcnt lgkmcnt(0)
	v_add_f32_e32 v0, v0, v1
	v_mul_f32_e32 v0, 0x4b800000, v0
	v_trunc_f32_e32 v0, v0
	v_mul_f32_e32 v1, 0x2f800000, v0
	v_floor_f32_e32 v1, v1
	v_fmac_f32_e32 v0, 0xcf800000, v1
	v_cvt_u32_f32_e32 v0, v0
	v_cvt_u32_f32_e32 v1, v1
	global_atomic_add_x2 v[48:49], v[0:1], off
	s_branch .LBB0_1254

.LBB0_1341:
	s_or_b64 exec, exec, s[38:39]
	s_waitcnt lgkmcnt(0)
	s_barrier
	ds_read_b32 v0, v44
	s_waitcnt lgkmcnt(0)
	v_add_f32_e32 v4, v18, v0
	v_add_u32_e32 v0, v16, v45
	v_ashrrev_i32_e32 v1, 31, v0
	v_lshl_add_u64 v[2:3], v[0:1], 2, s[46:47]
	v_lshl_add_u64 v[0:1], v[0:1], 1, s[48:49]
	global_store_dword v[2:3], v4, off
	v_cvt_pk_bf16_f32 v2, v4, v33
	global_store_short v[0:1], v2, off
	v_and_b32_e32 v0, 64, v216
	v_add_u32_e32 v6, 64, v0
	v_xor_b32_e32 v0, 1, v216
	v_cmp_lt_i32_e32 vcc, v0, v6
	v_mul_f32_e32 v1, v4, v4
	s_nop 0
	v_cndmask_b32_e32 v0, v216, v0, vcc
	v_lshlrev_b32_e32 v0, 2, v0
	ds_bpermute_b32 v2, v0, v1
	v_xor_b32_e32 v1, 2, v216
	v_cmp_lt_i32_e32 vcc, v1, v6
	s_waitcnt lgkmcnt(0)
	v_fmac_f32_e32 v2, v4, v4
	v_cndmask_b32_e32 v1, v216, v1, vcc
	v_lshlrev_b32_e32 v1, 2, v1
	s_waitcnt lgkmcnt(0)
	s_nop 1
	v_add_f32_dpp v3, v2, v2 quad_perm:[2,3,0,1] row_mask:0xf bank_mask:0xf
	v_xor_b32_e32 v2, 4, v216
	v_cmp_lt_i32_e32 vcc, v2, v6
	s_nop 1
	v_cndmask_b32_e32 v2, v216, v2, vcc
	v_lshlrev_b32_e32 v2, 2, v2
	s_waitcnt lgkmcnt(0)
	s_nop 1
	v_add_f32_dpp v4, v3, v3 row_half_mirror row_mask:0xf bank_mask:0xf
	v_xor_b32_e32 v3, 8, v216
	v_cmp_lt_i32_e32 vcc, v3, v6
	s_nop 1
	v_cndmask_b32_e32 v3, v216, v3, vcc
	v_lshlrev_b32_e32 v3, 2, v3
	s_waitcnt lgkmcnt(0)
	s_nop 1
	v_add_f32_dpp v5, v4, v4 row_mirror row_mask:0xf bank_mask:0xf
	v_xor_b32_e32 v4, 16, v216
	v_cmp_lt_i32_e32 vcc, v4, v6
	s_nop 1
	v_cndmask_b32_e32 v4, v216, v4, vcc
	v_lshlrev_b32_e32 v4, 2, v4
	v_mov_b32_e32 v6, v5
	s_nop 1
	v_permlane16_swap_b32_e32 v6, v5
	s_and_saveexec_b64 s[2:3], s[36:37]
	s_cbranch_execz .LBB0_1343
	s_waitcnt lgkmcnt(0)
	v_add_f32_e32 v5, v5, v6
	v_mul_f32_e32 v5, 0x4b800000, v5
	v_trunc_f32_e32 v5, v5
	v_mul_f32_e32 v6, 0x2f800000, v5
	v_floor_f32_e32 v7, v6
	v_fmac_f32_e32 v5, 0xcf800000, v7
	v_cvt_u32_f32_e32 v6, v5
	v_cvt_u32_f32_e32 v7, v7
	global_atomic_add_x2 v[46:47], v[6:7], off
.LBB0_1343:
	s_or_b64 exec, exec, s[2:3]
	v_add_u32_e32 v5, v42, v85
	ds_read_b32 v5, v5
	s_waitcnt lgkmcnt(0)
	v_add_f32_e32 v5, v17, v5
	v_mul_f32_e32 v6, v5, v5
	ds_bpermute_b32 v0, v0, v6
	s_waitcnt lgkmcnt(0)
	v_fmac_f32_e32 v0, v5, v5
	s_waitcnt lgkmcnt(0)
	s_nop 1
	v_add_f32_dpp v0, v0, v0 quad_perm:[2,3,0,1] row_mask:0xf bank_mask:0xf
	v_add_u32_e32 v2, v16, v86
	s_waitcnt lgkmcnt(0)
	s_nop 1
	v_add_f32_dpp v0, v0, v0 row_half_mirror row_mask:0xf bank_mask:0xf
	v_ashrrev_i32_e32 v3, 31, v2
	v_lshl_add_u64 v[6:7], v[2:3], 2, s[46:47]
	v_lshl_add_u64 v[2:3], v[2:3], 1, s[48:49]
	global_store_dword v[6:7], v5, off
	s_waitcnt lgkmcnt(0)
	s_nop 1
	v_add_f32_dpp v0, v0, v0 row_mirror row_mask:0xf bank_mask:0xf
	v_mov_b32_e32 v1, v0
	s_nop 1
	v_permlane16_swap_b32_e32 v1, v0
	v_cvt_pk_bf16_f32 v4, v5, v33
	global_store_short v[2:3], v4, off
	s_and_saveexec_b64 s[2:3], s[36:37]
	s_cbranch_execz .LBB0_1337
	s_waitcnt lgkmcnt(0)
	v_add_f32_e32 v0, v0, v1
	v_mul_f32_e32 v0, 0x4b800000, v0
	v_trunc_f32_e32 v0, v0
	v_mul_f32_e32 v1, 0x2f800000, v0
	v_floor_f32_e32 v1, v1
	v_fmac_f32_e32 v0, 0xcf800000, v1
	v_cvt_u32_f32_e32 v0, v0
	v_cvt_u32_f32_e32 v1, v1
	global_atomic_add_x2 v[48:49], v[0:1], off
	s_branch .LBB0_1337

.LBB0_1427:
	v_lshl_or_b32 v172, s19, 8, v192
	v_lshl_add_u32 v176, s20, 8, v190
	v_ashrrev_i32_e32 v173, 31, v172
	v_lshlrev_b64 v[158:159], 1, v[172:173]
	v_ashrrev_i32_e32 v177, 31, v176
	v_lshl_add_u64 v[174:175], s[38:39], 0, v[158:159]
	v_lshlrev_b64 v[160:161], 11, v[176:177]
	v_lshl_add_u64 v[114:115], v[174:175], 0, v[160:161]
	global_load_dwordx4 v[194:197], v[114:115], off
	global_load_dwordx4 v[198:201], v[114:115], off offset:256
	v_or_b32_e32 v186, 16, v176
	v_ashrrev_i32_e32 v187, 31, v186
	v_or_b32_e32 v182, 32, v176
	v_lshlrev_b64 v[188:189], 11, v[186:187]
	v_ashrrev_i32_e32 v183, 31, v182
	v_or_b32_e32 v178, 48, v176
	v_lshl_add_u64 v[114:115], v[174:175], 0, v[188:189]
	v_lshlrev_b64 v[184:185], 11, v[182:183]
	v_ashrrev_i32_e32 v179, 31, v178
	global_load_dwordx4 v[150:153], v[114:115], off
	global_load_dwordx4 v[146:149], v[114:115], off offset:256
	v_lshl_add_u64 v[114:115], v[174:175], 0, v[184:185]
	v_lshlrev_b64 v[180:181], 11, v[178:179]
	global_load_dwordx4 v[142:145], v[114:115], off
	global_load_dwordx4 v[130:133], v[114:115], off offset:256
	v_lshl_add_u64 v[114:115], v[174:175], 0, v[180:181]
	global_load_dwordx4 v[122:125], v[114:115], off
	s_nop 0
	global_load_dwordx4 v[114:117], v[114:115], off offset:256
	v_lshl_add_u64 v[160:161], s[38:39], 0, v[160:161]
	v_lshl_add_u64 v[158:159], v[160:161], 0, v[158:159]
	s_waitcnt vmcnt(0)
	v_lshlrev_b32_e32 v202, 16, v194
	v_and_b32_e32 v203, 0xffff0000, v194
	v_lshlrev_b32_e32 v194, 16, v195
	v_and_b32_e32 v195, 0xffff0000, v195
	v_pk_add_f32 v[140:141], v[140:141], v[194:195]
	v_lshlrev_b32_e32 v194, 16, v196
	v_and_b32_e32 v195, 0xffff0000, v196
	v_lshlrev_b32_e32 v196, 16, v197
	v_and_b32_e32 v197, 0xffff0000, v197
	v_pk_add_f32 v[138:139], v[138:139], v[202:203]
	v_pk_add_f32 v[196:197], v[136:137], v[196:197]
	v_pk_add_f32 v[194:195], v[134:135], v[194:195]
	v_cvt_pk_bf16_f32 v134, v138, v139
	v_cvt_pk_bf16_f32 v135, v140, v141
	s_nop 0
	v_cvt_pk_bf16_f32 v136, v194, v195
	v_cvt_pk_bf16_f32 v137, v196, v197
	global_store_dwordx4 v[158:159], v[134:137], off
	s_nop 1
	v_pk_mul_f32 v[134:135], v[194:195], v[194:195]
	v_pk_mul_f32 v[136:137], v[196:197], v[196:197]
	v_pk_fma_f32 v[134:135], v[138:139], v[138:139], v[134:135]
	v_pk_fma_f32 v[136:137], v[140:141], v[140:141], v[136:137]
	v_add_f32_e32 v134, v134, v135
	v_add_f32_e32 v135, v136, v137
	v_add_f32_e32 v138, v134, v135
	v_lshlrev_b32_e32 v134, 16, v198
	v_and_b32_e32 v135, 0xffff0000, v198
	v_lshlrev_b32_e32 v136, 16, v199
	v_and_b32_e32 v137, 0xffff0000, v199
	v_pk_add_f32 v[128:129], v[128:129], v[136:137]
	v_pk_add_f32 v[126:127], v[126:127], v[134:135]
	v_lshlrev_b32_e32 v134, 16, v200
	v_and_b32_e32 v135, 0xffff0000, v200
	v_lshlrev_b32_e32 v136, 16, v201
	v_and_b32_e32 v137, 0xffff0000, v201
	v_pk_add_f32 v[136:137], v[120:121], v[136:137]
	v_pk_add_f32 v[134:135], v[118:119], v[134:135]
	v_cvt_pk_bf16_f32 v118, v126, v127
	v_cvt_pk_bf16_f32 v119, v128, v129
	s_nop 0
	v_cvt_pk_bf16_f32 v120, v134, v135
	v_cvt_pk_bf16_f32 v121, v136, v137
	global_store_dwordx4 v[158:159], v[118:121], off offset:256
	s_nop 1
	v_pk_mul_f32 v[118:119], v[134:135], v[134:135]
	v_pk_mul_f32 v[120:121], v[136:137], v[136:137]
	v_pk_fma_f32 v[118:119], v[126:127], v[126:127], v[118:119]
	v_pk_fma_f32 v[120:121], v[128:129], v[128:129], v[120:121]
	v_add_f32_e32 v118, v118, v119
	v_add_f32_e32 v119, v120, v121
	v_add_f32_e32 v118, v118, v119
	v_and_b32_e32 v120, 64, v216
	v_add_f32_e32 v119, v138, v118
	v_xor_b32_e32 v118, 16, v216
	v_add_u32_e32 v121, 64, v120
	v_cmp_lt_i32_e32 vcc, v118, v121
	s_nop 1
	v_cndmask_b32_e32 v118, v216, v118, vcc
	v_lshlrev_b32_e32 v118, 2, v118
	v_mov_b32_e32 v120, v119
	s_nop 1
	v_permlane16_swap_b32_e32 v120, v119
	s_waitcnt lgkmcnt(0)
	v_add_f32_e32 v120, v119, v120
	v_xor_b32_e32 v119, 32, v216
	v_cmp_lt_i32_e32 vcc, v119, v121
	s_nop 1
	v_cndmask_b32_e32 v119, v216, v119, vcc
	v_lshlrev_b32_e32 v119, 2, v119
	v_mov_b32_e32 v121, v120
	s_nop 1
	v_permlane32_swap_b32_e32 v121, v120
	s_and_saveexec_b64 s[2:3], s[34:35]
	s_cbranch_execz .LBB0_1429
	s_waitcnt lgkmcnt(0)
	v_add_f32_e32 v120, v120, v121
	v_mul_f32_e32 v120, 0x4b800000, v120
	v_trunc_f32_e32 v120, v120
	v_mul_f32_e32 v121, 0x2f800000, v120
	v_floor_f32_e32 v121, v121
	v_fmac_f32_e32 v120, 0xcf800000, v121
	v_cvt_u32_f32_e32 v120, v120
	v_cvt_u32_f32_e32 v121, v121
	v_lshl_add_u64 v[126:127], v[176:177], 3, s[0:1]
	global_atomic_add_x2 v[126:127], v[120:121], off
.LBB0_1429:
	s_or_b64 exec, exec, s[2:3]
	v_lshlrev_b32_e32 v120, 16, v150
	s_waitcnt lgkmcnt(0)
	v_and_b32_e32 v121, 0xffff0000, v150
	v_lshlrev_b32_e32 v126, 16, v151
	v_and_b32_e32 v127, 0xffff0000, v151
	v_pk_add_f32 v[112:113], v[112:113], v[126:127]
	v_pk_add_f32 v[110:111], v[110:111], v[120:121]
	v_lshlrev_b32_e32 v120, 16, v152
	v_and_b32_e32 v121, 0xffff0000, v152
	v_lshlrev_b32_e32 v126, 16, v153
	v_and_b32_e32 v127, 0xffff0000, v153
	v_pk_add_f32 v[126:127], v[108:109], v[126:127]
	v_pk_add_f32 v[120:121], v[106:107], v[120:121]
	v_cvt_pk_bf16_f32 v106, v110, v111
	v_cvt_pk_bf16_f32 v107, v112, v113
	s_nop 0
	v_cvt_pk_bf16_f32 v108, v120, v121
	v_cvt_pk_bf16_f32 v109, v126, v127
	v_pk_mul_f32 v[120:121], v[120:121], v[120:121]
	v_pk_mul_f32 v[126:127], v[126:127], v[126:127]
	v_pk_fma_f32 v[110:111], v[110:111], v[110:111], v[120:121]
	v_pk_fma_f32 v[112:113], v[112:113], v[112:113], v[126:127]
	v_add_f32_e32 v110, v110, v111
	v_add_f32_e32 v111, v112, v113
	v_add_f32_e32 v120, v110, v111
	v_lshlrev_b32_e32 v110, 16, v146
	v_and_b32_e32 v111, 0xffff0000, v146
	v_lshlrev_b32_e32 v112, 16, v147
	v_and_b32_e32 v113, 0xffff0000, v147
	v_pk_add_f32 v[104:105], v[104:105], v[112:113]
	v_pk_add_f32 v[102:103], v[102:103], v[110:111]
	v_lshlrev_b32_e32 v110, 16, v148
	v_and_b32_e32 v111, 0xffff0000, v148
	v_lshlrev_b32_e32 v112, 16, v149
	v_and_b32_e32 v113, 0xffff0000, v149
	v_pk_add_f32 v[112:113], v[100:101], v[112:113]
	v_pk_add_f32 v[110:111], v[98:99], v[110:111]
	v_pk_mul_f32 v[100:101], v[112:113], v[112:113]
	v_pk_mul_f32 v[98:99], v[110:111], v[110:111]
	v_pk_fma_f32 v[100:101], v[104:105], v[104:105], v[100:101]
	v_pk_fma_f32 v[98:99], v[102:103], v[102:103], v[98:99]
	s_nop 0
	v_add_f32_e32 v98, v98, v99
	v_add_f32_e32 v99, v100, v101
	v_add_f32_e32 v98, v98, v99
	v_add_f32_e32 v101, v120, v98
	ds_bpermute_b32 v126, v118, v101
	v_lshl_add_u64 v[98:99], s[38:39], 0, v[188:189]
	v_lshl_add_u64 v[120:121], v[172:173], 1, v[98:99]
	global_store_dwordx4 v[120:121], v[106:109], off
	v_cvt_pk_bf16_f32 v100, v102, v103
	s_waitcnt lgkmcnt(0)
	v_add_f32_e32 v98, v101, v126
	v_mov_b32_e32 v99, v98
	s_nop 1
	v_permlane32_swap_b32_e32 v99, v98
	v_cvt_pk_bf16_f32 v101, v104, v105
	v_cvt_pk_bf16_f32 v102, v110, v111
	v_cvt_pk_bf16_f32 v103, v112, v113
	global_store_dwordx4 v[120:121], v[100:103], off offset:256
	s_and_saveexec_b64 s[2:3], s[34:35]
	s_cbranch_execz .LBB0_1431
	s_waitcnt lgkmcnt(0)
	v_add_f32_e32 v98, v98, v99
	v_mul_f32_e32 v98, 0x4b800000, v98
	v_trunc_f32_e32 v98, v98
	v_mul_f32_e32 v99, 0x2f800000, v98
	v_floor_f32_e32 v99, v99
	v_fmac_f32_e32 v98, 0xcf800000, v99
	v_cvt_u32_f32_e32 v98, v98
	v_cvt_u32_f32_e32 v99, v99
	v_lshl_add_u64 v[100:101], v[186:187], 3, s[0:1]
	global_atomic_add_x2 v[100:101], v[98:99], off
.LBB0_1431:
	s_or_b64 exec, exec, s[2:3]
	v_lshlrev_b32_e32 v98, 16, v142
	s_waitcnt lgkmcnt(0)
	v_and_b32_e32 v99, 0xffff0000, v142
	v_lshlrev_b32_e32 v100, 16, v143
	v_and_b32_e32 v101, 0xffff0000, v143
	v_pk_add_f32 v[96:97], v[96:97], v[100:101]
	v_pk_add_f32 v[94:95], v[94:95], v[98:99]
	v_lshlrev_b32_e32 v98, 16, v144
	v_and_b32_e32 v99, 0xffff0000, v144
	v_lshlrev_b32_e32 v100, 16, v145
	v_and_b32_e32 v101, 0xffff0000, v145
	v_pk_add_f32 v[100:101], v[92:93], v[100:101]
	v_pk_add_f32 v[98:99], v[90:91], v[98:99]
	v_cvt_pk_bf16_f32 v90, v94, v95
	v_cvt_pk_bf16_f32 v91, v96, v97
	s_nop 0
	v_cvt_pk_bf16_f32 v92, v98, v99
	v_cvt_pk_bf16_f32 v93, v100, v101
	v_pk_mul_f32 v[98:99], v[98:99], v[98:99]
	v_pk_mul_f32 v[100:101], v[100:101], v[100:101]
	v_pk_fma_f32 v[94:95], v[94:95], v[94:95], v[98:99]
	v_pk_fma_f32 v[96:97], v[96:97], v[96:97], v[100:101]
	v_add_f32_e32 v94, v94, v95
	v_add_f32_e32 v95, v96, v97
	v_add_f32_e32 v98, v94, v95
	v_lshlrev_b32_e32 v94, 16, v130
	v_and_b32_e32 v95, 0xffff0000, v130
	v_lshlrev_b32_e32 v96, 16, v131
	v_and_b32_e32 v97, 0xffff0000, v131
	v_pk_add_f32 v[88:89], v[88:89], v[96:97]
	v_pk_add_f32 v[86:87], v[86:87], v[94:95]
	v_lshlrev_b32_e32 v94, 16, v132
	v_and_b32_e32 v95, 0xffff0000, v132
	v_lshlrev_b32_e32 v96, 16, v133
	v_and_b32_e32 v97, 0xffff0000, v133
	v_pk_add_f32 v[96:97], v[84:85], v[96:97]
	v_pk_add_f32 v[94:95], v[82:83], v[94:95]
	v_pk_mul_f32 v[84:85], v[96:97], v[96:97]
	v_pk_mul_f32 v[82:83], v[94:95], v[94:95]
	v_pk_fma_f32 v[84:85], v[88:89], v[88:89], v[84:85]
	v_pk_fma_f32 v[82:83], v[86:87], v[86:87], v[82:83]
	s_nop 0
	v_add_f32_e32 v82, v82, v83
	v_add_f32_e32 v83, v84, v85
	v_add_f32_e32 v82, v82, v83
	v_add_f32_e32 v85, v98, v82
	v_mov_b32_e32 v100, v85
	s_nop 1
	v_permlane16_swap_b32_e32 v100, v85
	v_lshl_add_u64 v[82:83], s[38:39], 0, v[184:185]
	v_lshl_add_u64 v[98:99], v[172:173], 1, v[82:83]
	global_store_dwordx4 v[98:99], v[90:93], off
	v_cvt_pk_bf16_f32 v84, v86, v87
	s_waitcnt lgkmcnt(0)
	v_add_f32_e32 v82, v85, v100
	v_mov_b32_e32 v83, v82
	s_nop 1
	v_permlane32_swap_b32_e32 v83, v82
	v_cvt_pk_bf16_f32 v85, v88, v89
	v_cvt_pk_bf16_f32 v86, v94, v95
	v_cvt_pk_bf16_f32 v87, v96, v97
	global_store_dwordx4 v[98:99], v[84:87], off offset:256
	s_and_saveexec_b64 s[2:3], s[34:35]
	s_cbranch_execz .LBB0_1433
	s_waitcnt lgkmcnt(0)
	v_add_f32_e32 v82, v82, v83
	v_mul_f32_e32 v82, 0x4b800000, v82
	v_trunc_f32_e32 v82, v82
	v_mul_f32_e32 v83, 0x2f800000, v82
	v_floor_f32_e32 v83, v83
	v_fmac_f32_e32 v82, 0xcf800000, v83
	v_cvt_u32_f32_e32 v82, v82
	v_cvt_u32_f32_e32 v83, v83
	v_lshl_add_u64 v[84:85], v[182:183], 3, s[0:1]
	global_atomic_add_x2 v[84:85], v[82:83], off
.LBB0_1433:
	s_or_b64 exec, exec, s[2:3]
	v_lshlrev_b32_e32 v82, 16, v122
	s_waitcnt lgkmcnt(0)
	v_and_b32_e32 v83, 0xffff0000, v122
	v_lshlrev_b32_e32 v84, 16, v123
	v_and_b32_e32 v85, 0xffff0000, v123
	v_pk_add_f32 v[80:81], v[80:81], v[84:85]
	v_pk_add_f32 v[78:79], v[78:79], v[82:83]
	v_lshlrev_b32_e32 v82, 16, v124
	v_and_b32_e32 v83, 0xffff0000, v124
	v_lshlrev_b32_e32 v84, 16, v125
	v_and_b32_e32 v85, 0xffff0000, v125
	v_pk_add_f32 v[84:85], v[76:77], v[84:85]
	v_pk_add_f32 v[82:83], v[74:75], v[82:83]
	v_cvt_pk_bf16_f32 v74, v78, v79
	v_cvt_pk_bf16_f32 v75, v80, v81
	s_nop 0
	v_cvt_pk_bf16_f32 v76, v82, v83
	v_cvt_pk_bf16_f32 v77, v84, v85
	v_pk_mul_f32 v[82:83], v[82:83], v[82:83]
	v_pk_mul_f32 v[84:85], v[84:85], v[84:85]
	v_pk_fma_f32 v[78:79], v[78:79], v[78:79], v[82:83]
	v_pk_fma_f32 v[80:81], v[80:81], v[80:81], v[84:85]
	v_add_f32_e32 v78, v78, v79
	v_add_f32_e32 v79, v80, v81
	v_add_f32_e32 v82, v78, v79
	v_lshlrev_b32_e32 v78, 16, v114
	v_and_b32_e32 v79, 0xffff0000, v114
	v_lshlrev_b32_e32 v80, 16, v115
	v_and_b32_e32 v81, 0xffff0000, v115
	v_pk_add_f32 v[72:73], v[72:73], v[80:81]
	v_pk_add_f32 v[70:71], v[70:71], v[78:79]
	v_lshlrev_b32_e32 v78, 16, v116
	v_and_b32_e32 v79, 0xffff0000, v116
	v_lshlrev_b32_e32 v80, 16, v117
	v_and_b32_e32 v81, 0xffff0000, v117
	v_pk_add_f32 v[80:81], v[68:69], v[80:81]
	v_pk_add_f32 v[78:79], v[66:67], v[78:79]
	v_pk_mul_f32 v[68:69], v[80:81], v[80:81]
	v_pk_mul_f32 v[66:67], v[78:79], v[78:79]
	v_pk_fma_f32 v[68:69], v[72:73], v[72:73], v[68:69]
	v_pk_fma_f32 v[66:67], v[70:71], v[70:71], v[66:67]
	s_nop 0
	v_add_f32_e32 v66, v66, v67
	v_add_f32_e32 v67, v68, v69
	v_add_f32_e32 v66, v66, v67
	v_add_f32_e32 v69, v82, v66
	v_mov_b32_e32 v84, v69
	s_nop 1
	v_permlane16_swap_b32_e32 v84, v69
	v_lshl_add_u64 v[66:67], s[38:39], 0, v[180:181]
	v_lshl_add_u64 v[82:83], v[172:173], 1, v[66:67]
	global_store_dwordx4 v[82:83], v[74:77], off
	v_cvt_pk_bf16_f32 v68, v70, v71
	s_waitcnt lgkmcnt(0)
	v_add_f32_e32 v66, v69, v84
	v_mov_b32_e32 v67, v66
	s_nop 1
	v_permlane32_swap_b32_e32 v67, v66
	v_cvt_pk_bf16_f32 v69, v72, v73
	v_cvt_pk_bf16_f32 v70, v78, v79
	v_cvt_pk_bf16_f32 v71, v80, v81
	global_store_dwordx4 v[82:83], v[68:71], off offset:256
	s_and_saveexec_b64 s[2:3], s[34:35]
	s_cbranch_execz .LBB0_1435
	s_waitcnt lgkmcnt(0)
	v_add_f32_e32 v66, v66, v67
	v_mul_f32_e32 v66, 0x4b800000, v66
	v_trunc_f32_e32 v66, v66
	v_mul_f32_e32 v67, 0x2f800000, v66
	v_floor_f32_e32 v67, v67
	v_fmac_f32_e32 v66, 0xcf800000, v67
	v_cvt_u32_f32_e32 v66, v66
	v_cvt_u32_f32_e32 v67, v67
	v_lshl_add_u64 v[68:69], v[178:179], 3, s[0:1]
	global_atomic_add_x2 v[68:69], v[66:67], off
.LBB0_1435:
	s_or_b64 exec, exec, s[2:3]
	v_add_u32_e32 v106, 0x80, v176
	v_ashrrev_i32_e32 v107, 31, v106
	v_lshlrev_b64 v[112:113], 11, v[106:107]
	s_waitcnt lgkmcnt(0)
	v_lshl_add_u64 v[66:67], v[174:175], 0, v[112:113]
	global_load_dwordx4 v[108:111], v[66:67], off
	global_load_dwordx4 v[90:93], v[66:67], off offset:256
	v_add_u32_e32 v102, 0x90, v176
	v_ashrrev_i32_e32 v103, 31, v102
	v_add_u32_e32 v98, 0xa0, v176
	v_lshlrev_b64 v[104:105], 11, v[102:103]
	v_ashrrev_i32_e32 v99, 31, v98
	v_add_u32_e32 v94, 0xb0, v176
	v_lshl_add_u64 v[66:67], v[174:175], 0, v[104:105]
	v_lshlrev_b64 v[100:101], 11, v[98:99]
	v_ashrrev_i32_e32 v95, 31, v94
	global_load_dwordx4 v[86:89], v[66:67], off
	global_load_dwordx4 v[82:85], v[66:67], off offset:256
	v_lshl_add_u64 v[66:67], v[174:175], 0, v[100:101]
	v_lshlrev_b64 v[96:97], 11, v[94:95]
	global_load_dwordx4 v[78:81], v[66:67], off
	global_load_dwordx4 v[74:77], v[66:67], off offset:256
	v_lshl_add_u64 v[66:67], v[174:175], 0, v[96:97]
	global_load_dwordx4 v[70:73], v[66:67], off
	s_nop 0
	global_load_dwordx4 v[66:69], v[66:67], off offset:256
	v_lshl_add_u64 v[112:113], s[38:39], 0, v[112:113]
	v_lshl_add_u64 v[112:113], v[172:173], 1, v[112:113]
	s_waitcnt vmcnt(7)
	v_lshlrev_b32_e32 v114, 16, v108
	v_and_b32_e32 v115, 0xffff0000, v108
	v_lshlrev_b32_e32 v108, 16, v109
	v_and_b32_e32 v109, 0xffff0000, v109
	v_pk_add_f32 v[64:65], v[64:65], v[108:109]
	v_lshlrev_b32_e32 v108, 16, v110
	v_and_b32_e32 v109, 0xffff0000, v110
	v_lshlrev_b32_e32 v110, 16, v111
	v_and_b32_e32 v111, 0xffff0000, v111
	v_pk_add_f32 v[62:63], v[62:63], v[114:115]
	v_pk_add_f32 v[110:111], v[60:61], v[110:111]
	v_pk_add_f32 v[108:109], v[58:59], v[108:109]
	v_cvt_pk_bf16_f32 v58, v62, v63
	v_cvt_pk_bf16_f32 v59, v64, v65
	s_nop 0
	v_cvt_pk_bf16_f32 v60, v108, v109
	v_cvt_pk_bf16_f32 v61, v110, v111
	global_store_dwordx4 v[112:113], v[58:61], off
	s_nop 1
	v_pk_mul_f32 v[58:59], v[108:109], v[108:109]
	v_pk_mul_f32 v[60:61], v[110:111], v[110:111]
	v_pk_fma_f32 v[58:59], v[62:63], v[62:63], v[58:59]
	v_pk_fma_f32 v[60:61], v[64:65], v[64:65], v[60:61]
	v_add_f32_e32 v58, v58, v59
	v_add_f32_e32 v59, v60, v61
	v_add_f32_e32 v62, v58, v59
	s_waitcnt vmcnt(7)
	v_lshlrev_b32_e32 v58, 16, v90
	v_and_b32_e32 v59, 0xffff0000, v90
	v_lshlrev_b32_e32 v60, 16, v91
	v_and_b32_e32 v61, 0xffff0000, v91
	v_pk_add_f32 v[56:57], v[56:57], v[60:61]
	v_pk_add_f32 v[54:55], v[54:55], v[58:59]
	v_lshlrev_b32_e32 v58, 16, v92
	v_and_b32_e32 v59, 0xffff0000, v92
	v_lshlrev_b32_e32 v60, 16, v93
	v_and_b32_e32 v61, 0xffff0000, v93
	v_pk_add_f32 v[60:61], v[52:53], v[60:61]
	v_pk_add_f32 v[58:59], v[50:51], v[58:59]
	v_cvt_pk_bf16_f32 v50, v54, v55
	v_cvt_pk_bf16_f32 v51, v56, v57
	s_nop 0
	v_cvt_pk_bf16_f32 v52, v58, v59
	v_cvt_pk_bf16_f32 v53, v60, v61
	global_store_dwordx4 v[112:113], v[50:53], off offset:256
	s_nop 1
	v_pk_mul_f32 v[50:51], v[58:59], v[58:59]
	v_pk_mul_f32 v[52:53], v[60:61], v[60:61]
	v_pk_fma_f32 v[50:51], v[54:55], v[54:55], v[50:51]
	v_pk_fma_f32 v[52:53], v[56:57], v[56:57], v[52:53]
	v_add_f32_e32 v50, v50, v51
	v_add_f32_e32 v51, v52, v53
	v_add_f32_e32 v50, v50, v51
	v_add_f32_e32 v50, v62, v50
	v_mov_b32_e32 v51, v50
	s_nop 1
	v_permlane16_swap_b32_e32 v51, v50
	s_waitcnt lgkmcnt(0)
	v_add_f32_e32 v50, v50, v51
	v_mov_b32_e32 v51, v50
	s_nop 1
	v_permlane32_swap_b32_e32 v51, v50
	s_and_saveexec_b64 s[2:3], s[34:35]
	s_cbranch_execz .LBB0_1437
	s_waitcnt lgkmcnt(0)
	v_add_f32_e32 v50, v50, v51
	v_mul_f32_e32 v50, 0x4b800000, v50
	v_trunc_f32_e32 v50, v50
	v_mul_f32_e32 v51, 0x2f800000, v50
	v_floor_f32_e32 v51, v51
	v_fmac_f32_e32 v50, 0xcf800000, v51
	v_cvt_u32_f32_e32 v50, v50
	v_cvt_u32_f32_e32 v51, v51
	v_lshl_add_u64 v[52:53], v[106:107], 3, s[0:1]
	global_atomic_add_x2 v[52:53], v[50:51], off
.LBB0_1437:
	s_or_b64 exec, exec, s[2:3]
	s_waitcnt vmcnt(7)
	v_lshlrev_b32_e32 v50, 16, v86
	s_waitcnt lgkmcnt(0)
	v_and_b32_e32 v51, 0xffff0000, v86
	v_lshlrev_b32_e32 v52, 16, v87
	v_and_b32_e32 v53, 0xffff0000, v87
	v_pk_add_f32 v[48:49], v[48:49], v[52:53]
	v_pk_add_f32 v[46:47], v[46:47], v[50:51]
	v_lshlrev_b32_e32 v50, 16, v88
	v_and_b32_e32 v51, 0xffff0000, v88
	v_lshlrev_b32_e32 v52, 16, v89
	v_and_b32_e32 v53, 0xffff0000, v89
	v_pk_add_f32 v[52:53], v[44:45], v[52:53]
	v_pk_add_f32 v[50:51], v[42:43], v[50:51]
	v_cvt_pk_bf16_f32 v42, v46, v47
	v_cvt_pk_bf16_f32 v43, v48, v49
	s_nop 0
	v_cvt_pk_bf16_f32 v44, v50, v51
	v_cvt_pk_bf16_f32 v45, v52, v53
	v_pk_mul_f32 v[50:51], v[50:51], v[50:51]
	v_pk_mul_f32 v[52:53], v[52:53], v[52:53]
	v_pk_fma_f32 v[46:47], v[46:47], v[46:47], v[50:51]
	v_pk_fma_f32 v[48:49], v[48:49], v[48:49], v[52:53]
	v_add_f32_e32 v46, v46, v47
	v_add_f32_e32 v47, v48, v49
	v_add_f32_e32 v50, v46, v47
	s_waitcnt vmcnt(6)
	v_lshlrev_b32_e32 v46, 16, v82
	v_and_b32_e32 v47, 0xffff0000, v82
	v_lshlrev_b32_e32 v48, 16, v83
	v_and_b32_e32 v49, 0xffff0000, v83
	v_pk_add_f32 v[40:41], v[40:41], v[48:49]
	v_pk_add_f32 v[38:39], v[38:39], v[46:47]
	v_lshlrev_b32_e32 v46, 16, v84
	v_and_b32_e32 v47, 0xffff0000, v84
	v_lshlrev_b32_e32 v48, 16, v85
	v_and_b32_e32 v49, 0xffff0000, v85
	v_pk_add_f32 v[48:49], v[36:37], v[48:49]
	v_pk_add_f32 v[46:47], v[34:35], v[46:47]
	v_pk_mul_f32 v[36:37], v[48:49], v[48:49]
	v_pk_mul_f32 v[34:35], v[46:47], v[46:47]
	v_pk_fma_f32 v[36:37], v[40:41], v[40:41], v[36:37]
	v_pk_fma_f32 v[34:35], v[38:39], v[38:39], v[34:35]
	s_nop 0
	v_add_f32_e32 v34, v34, v35
	v_add_f32_e32 v35, v36, v37
	v_add_f32_e32 v34, v34, v35
	v_add_f32_e32 v37, v50, v34
	ds_bpermute_b32 v52, v118, v37
	v_lshl_add_u64 v[34:35], s[38:39], 0, v[104:105]
	v_lshl_add_u64 v[50:51], v[172:173], 1, v[34:35]
	global_store_dwordx4 v[50:51], v[42:45], off
	v_cvt_pk_bf16_f32 v36, v38, v39
	s_waitcnt lgkmcnt(0)
	v_add_f32_e32 v34, v37, v52
	v_mov_b32_e32 v35, v34
	s_nop 1
	v_permlane32_swap_b32_e32 v35, v34
	v_cvt_pk_bf16_f32 v37, v40, v41
	v_cvt_pk_bf16_f32 v38, v46, v47
	v_cvt_pk_bf16_f32 v39, v48, v49
	global_store_dwordx4 v[50:51], v[36:39], off offset:256
	s_and_saveexec_b64 s[2:3], s[34:35]
	s_cbranch_execz .LBB0_1439
	s_waitcnt lgkmcnt(0)
	v_add_f32_e32 v34, v34, v35
	v_mul_f32_e32 v34, 0x4b800000, v34
	v_trunc_f32_e32 v34, v34
	v_mul_f32_e32 v35, 0x2f800000, v34
	v_floor_f32_e32 v35, v35
	v_fmac_f32_e32 v34, 0xcf800000, v35
	v_cvt_u32_f32_e32 v34, v34
	v_cvt_u32_f32_e32 v35, v35
	v_lshl_add_u64 v[36:37], v[102:103], 3, s[0:1]
	global_atomic_add_x2 v[36:37], v[34:35], off
.LBB0_1439:
	s_or_b64 exec, exec, s[2:3]
	s_waitcnt vmcnt(7)
	v_lshlrev_b32_e32 v34, 16, v78
	s_waitcnt lgkmcnt(0)
	v_and_b32_e32 v35, 0xffff0000, v78
	v_lshlrev_b32_e32 v36, 16, v79
	v_and_b32_e32 v37, 0xffff0000, v79
	v_pk_add_f32 v[30:31], v[30:31], v[36:37]
	v_pk_add_f32 v[28:29], v[28:29], v[34:35]
	v_lshlrev_b32_e32 v34, 16, v80
	v_and_b32_e32 v35, 0xffff0000, v80
	v_lshlrev_b32_e32 v36, 16, v81
	v_and_b32_e32 v37, 0xffff0000, v81
	v_pk_add_f32 v[36:37], v[26:27], v[36:37]
	v_pk_add_f32 v[34:35], v[24:25], v[34:35]
	v_cvt_pk_bf16_f32 v24, v28, v29
	v_cvt_pk_bf16_f32 v25, v30, v31
	s_nop 0
	v_cvt_pk_bf16_f32 v26, v34, v35
	v_cvt_pk_bf16_f32 v27, v36, v37
	v_pk_mul_f32 v[34:35], v[34:35], v[34:35]
	v_pk_mul_f32 v[36:37], v[36:37], v[36:37]
	v_pk_fma_f32 v[28:29], v[28:29], v[28:29], v[34:35]
	v_pk_fma_f32 v[30:31], v[30:31], v[30:31], v[36:37]
	v_add_f32_e32 v28, v28, v29
	v_add_f32_e32 v29, v30, v31
	v_add_f32_e32 v34, v28, v29
	s_waitcnt vmcnt(6)
	v_lshlrev_b32_e32 v28, 16, v74
	v_and_b32_e32 v29, 0xffff0000, v74
	v_lshlrev_b32_e32 v30, 16, v75
	v_and_b32_e32 v31, 0xffff0000, v75
	v_pk_add_f32 v[22:23], v[22:23], v[30:31]
	v_pk_add_f32 v[20:21], v[20:21], v[28:29]
	v_lshlrev_b32_e32 v28, 16, v76
	v_and_b32_e32 v29, 0xffff0000, v76
	v_lshlrev_b32_e32 v30, 16, v77
	v_and_b32_e32 v31, 0xffff0000, v77
	v_pk_add_f32 v[30:31], v[18:19], v[30:31]
	v_pk_add_f32 v[28:29], v[16:17], v[28:29]
	v_pk_mul_f32 v[18:19], v[30:31], v[30:31]
	v_pk_mul_f32 v[16:17], v[28:29], v[28:29]
	v_pk_fma_f32 v[18:19], v[22:23], v[22:23], v[18:19]
	v_pk_fma_f32 v[16:17], v[20:21], v[20:21], v[16:17]
	s_nop 0
	v_add_f32_e32 v16, v16, v17
	v_add_f32_e32 v17, v18, v19
	v_add_f32_e32 v16, v16, v17
	v_add_f32_e32 v19, v34, v16
	ds_bpermute_b32 v36, v118, v19
	v_lshl_add_u64 v[16:17], s[38:39], 0, v[100:101]
	v_lshl_add_u64 v[34:35], v[172:173], 1, v[16:17]
	global_store_dwordx4 v[34:35], v[24:27], off
	v_cvt_pk_bf16_f32 v18, v20, v21
	s_waitcnt lgkmcnt(0)
	v_add_f32_e32 v16, v19, v36
	v_mov_b32_e32 v17, v16
	s_nop 1
	v_permlane32_swap_b32_e32 v17, v16
	v_cvt_pk_bf16_f32 v19, v22, v23
	v_cvt_pk_bf16_f32 v20, v28, v29
	v_cvt_pk_bf16_f32 v21, v30, v31
	global_store_dwordx4 v[34:35], v[18:21], off offset:256
	s_and_saveexec_b64 s[2:3], s[34:35]
	s_cbranch_execz .LBB0_1441
	s_waitcnt lgkmcnt(0)
	v_add_f32_e32 v16, v16, v17
	v_mul_f32_e32 v16, 0x4b800000, v16
	v_trunc_f32_e32 v16, v16
	v_mul_f32_e32 v17, 0x2f800000, v16
	v_floor_f32_e32 v17, v17
	v_fmac_f32_e32 v16, 0xcf800000, v17
	v_cvt_u32_f32_e32 v16, v16
	v_cvt_u32_f32_e32 v17, v17
	v_lshl_add_u64 v[18:19], v[98:99], 3, s[0:1]
	global_atomic_add_x2 v[18:19], v[16:17], off
.LBB0_1441:
	s_or_b64 exec, exec, s[2:3]
	s_waitcnt vmcnt(7)
	v_lshlrev_b32_e32 v16, 16, v70
	s_waitcnt lgkmcnt(0)
	v_and_b32_e32 v17, 0xffff0000, v70
	v_lshlrev_b32_e32 v18, 16, v71
	v_and_b32_e32 v19, 0xffff0000, v71
	v_pk_add_f32 v[14:15], v[14:15], v[18:19]
	v_pk_add_f32 v[12:13], v[12:13], v[16:17]
	v_lshlrev_b32_e32 v16, 16, v72
	v_and_b32_e32 v17, 0xffff0000, v72
	v_lshlrev_b32_e32 v18, 16, v73
	v_and_b32_e32 v19, 0xffff0000, v73
	v_pk_add_f32 v[18:19], v[10:11], v[18:19]
	v_pk_add_f32 v[16:17], v[8:9], v[16:17]
	v_cvt_pk_bf16_f32 v8, v12, v13
	v_cvt_pk_bf16_f32 v9, v14, v15
	s_nop 0
	v_cvt_pk_bf16_f32 v10, v16, v17
	v_cvt_pk_bf16_f32 v11, v18, v19
	v_pk_mul_f32 v[16:17], v[16:17], v[16:17]
	v_pk_mul_f32 v[18:19], v[18:19], v[18:19]
	v_pk_fma_f32 v[12:13], v[12:13], v[12:13], v[16:17]
	v_pk_fma_f32 v[14:15], v[14:15], v[14:15], v[18:19]
	v_add_f32_e32 v12, v12, v13
	v_add_f32_e32 v13, v14, v15
	v_add_f32_e32 v16, v12, v13
	s_waitcnt vmcnt(6)
	v_lshlrev_b32_e32 v12, 16, v66
	v_and_b32_e32 v13, 0xffff0000, v66
	v_lshlrev_b32_e32 v14, 16, v67
	v_and_b32_e32 v15, 0xffff0000, v67
	v_pk_add_f32 v[6:7], v[6:7], v[14:15]
	v_pk_add_f32 v[4:5], v[4:5], v[12:13]
	v_lshlrev_b32_e32 v12, 16, v68
	v_and_b32_e32 v13, 0xffff0000, v68
	v_lshlrev_b32_e32 v14, 16, v69
	v_and_b32_e32 v15, 0xffff0000, v69
	v_pk_add_f32 v[14:15], v[2:3], v[14:15]
	v_pk_add_f32 v[12:13], v[0:1], v[12:13]
	v_pk_mul_f32 v[2:3], v[14:15], v[14:15]
	v_pk_mul_f32 v[0:1], v[12:13], v[12:13]
	v_pk_fma_f32 v[2:3], v[6:7], v[6:7], v[2:3]
	v_pk_fma_f32 v[0:1], v[4:5], v[4:5], v[0:1]
	s_nop 0
	v_add_f32_e32 v0, v0, v1
	v_add_f32_e32 v1, v2, v3
	v_add_f32_e32 v0, v0, v1
	v_add_f32_e32 v3, v16, v0
	ds_bpermute_b32 v18, v118, v3
	v_lshl_add_u64 v[0:1], s[38:39], 0, v[96:97]
	v_lshl_add_u64 v[16:17], v[172:173], 1, v[0:1]
	global_store_dwordx4 v[16:17], v[8:11], off
	v_cvt_pk_bf16_f32 v2, v4, v5
	s_waitcnt lgkmcnt(0)
	v_add_f32_e32 v0, v3, v18
	v_mov_b32_e32 v1, v0
	s_nop 1
	v_permlane32_swap_b32_e32 v1, v0
	v_cvt_pk_bf16_f32 v3, v6, v7
	v_cvt_pk_bf16_f32 v4, v12, v13
	v_cvt_pk_bf16_f32 v5, v14, v15
	global_store_dwordx4 v[16:17], v[2:5], off offset:256
	s_and_saveexec_b64 s[2:3], s[34:35]
	s_cbranch_execz .LBB0_1443
	s_waitcnt lgkmcnt(0)
	v_add_f32_e32 v0, v0, v1
	v_mul_f32_e32 v0, 0x4b800000, v0
	v_trunc_f32_e32 v0, v0
	v_mul_f32_e32 v1, 0x2f800000, v0
	v_floor_f32_e32 v1, v1
	v_fmac_f32_e32 v0, 0xcf800000, v1
	v_cvt_u32_f32_e32 v0, v0
	v_cvt_u32_f32_e32 v1, v1
	v_lshl_add_u64 v[2:3], v[94:95], 3, s[0:1]
	global_atomic_add_x2 v[2:3], v[0:1], off

.LBB0_2059:
	s_or_b64 exec, exec, s[0:1]
	s_waitcnt lgkmcnt(0)
	s_barrier
	ds_read_b32 v0, v44
	s_waitcnt vmcnt(1) lgkmcnt(0)
	v_add_f32_e32 v4, v18, v0
	v_add_u32_e32 v0, v16, v45
	v_ashrrev_i32_e32 v1, 31, v0
	v_lshl_add_u64 v[2:3], v[0:1], 2, s[90:91]
	v_lshl_add_u64 v[0:1], v[0:1], 1, s[92:93]
	global_store_dword v[2:3], v4, off
	v_cvt_pk_bf16_f32 v2, v4, v33
	global_store_short v[0:1], v2, off
	v_and_b32_e32 v0, 64, v216
	v_add_u32_e32 v6, 64, v0
	v_xor_b32_e32 v0, 1, v216
	v_cmp_lt_i32_e32 vcc, v0, v6
	v_mul_f32_e32 v1, v4, v4
	s_nop 0
	v_cndmask_b32_e32 v0, v216, v0, vcc
	v_lshlrev_b32_e32 v0, 2, v0
	ds_bpermute_b32 v2, v0, v1
	v_xor_b32_e32 v1, 2, v216
	v_cmp_lt_i32_e32 vcc, v1, v6
	s_waitcnt lgkmcnt(0)
	v_fmac_f32_e32 v2, v4, v4
	v_cndmask_b32_e32 v1, v216, v1, vcc
	v_lshlrev_b32_e32 v1, 2, v1
	s_waitcnt lgkmcnt(0)
	s_nop 1
	v_add_f32_dpp v3, v2, v2 quad_perm:[2,3,0,1] row_mask:0xf bank_mask:0xf
	v_xor_b32_e32 v2, 4, v216
	v_cmp_lt_i32_e32 vcc, v2, v6
	s_nop 1
	v_cndmask_b32_e32 v2, v216, v2, vcc
	v_lshlrev_b32_e32 v2, 2, v2
	s_waitcnt lgkmcnt(0)
	s_nop 1
	v_add_f32_dpp v4, v3, v3 row_half_mirror row_mask:0xf bank_mask:0xf
	v_xor_b32_e32 v3, 8, v216
	v_cmp_lt_i32_e32 vcc, v3, v6
	s_nop 1
	v_cndmask_b32_e32 v3, v216, v3, vcc
	v_lshlrev_b32_e32 v3, 2, v3
	s_waitcnt lgkmcnt(0)
	s_nop 1
	v_add_f32_dpp v5, v4, v4 row_mirror row_mask:0xf bank_mask:0xf
	v_xor_b32_e32 v4, 16, v216
	v_cmp_lt_i32_e32 vcc, v4, v6
	s_nop 1
	v_cndmask_b32_e32 v4, v216, v4, vcc
	v_lshlrev_b32_e32 v4, 2, v4
	v_mov_b32_e32 v6, v5
	s_nop 1
	v_permlane16_swap_b32_e32 v6, v5
	s_and_saveexec_b64 s[0:1], s[96:97]
	s_cbranch_execz .LBB0_2061
	s_waitcnt lgkmcnt(0)
	v_add_f32_e32 v5, v5, v6
	v_mul_f32_e32 v5, 0x4b800000, v5
	v_trunc_f32_e32 v5, v5
	v_mul_f32_e32 v6, 0x2f800000, v5
	v_floor_f32_e32 v7, v6
	v_fmac_f32_e32 v5, 0xcf800000, v7
	v_cvt_u32_f32_e32 v6, v5
	v_cvt_u32_f32_e32 v7, v7
	global_atomic_add_x2 v[46:47], v[6:7], off
.LBB0_2061:
	s_or_b64 exec, exec, s[0:1]
	v_add_u32_e32 v5, v42, v85
	ds_read_b32 v5, v5
	s_waitcnt lgkmcnt(1)
	v_add_u32_e32 v6, v16, v86
	v_ashrrev_i32_e32 v7, 31, v6
	v_lshl_add_u64 v[8:9], v[6:7], 2, s[90:91]
	v_lshl_add_u64 v[6:7], v[6:7], 1, s[92:93]
	s_waitcnt vmcnt(2) lgkmcnt(0)
	v_add_f32_e32 v5, v17, v5
	global_store_dword v[8:9], v5, off
	v_cvt_pk_bf16_f32 v8, v5, v33
	global_store_short v[6:7], v8, off
	v_mul_f32_e32 v6, v5, v5
	ds_bpermute_b32 v0, v0, v6
	s_waitcnt lgkmcnt(0)
	v_fmac_f32_e32 v0, v5, v5
	s_waitcnt lgkmcnt(0)
	s_nop 1
	v_add_f32_dpp v0, v0, v0 quad_perm:[2,3,0,1] row_mask:0xf bank_mask:0xf
	s_waitcnt lgkmcnt(0)
	s_nop 1
	v_add_f32_dpp v0, v0, v0 row_half_mirror row_mask:0xf bank_mask:0xf
	s_waitcnt lgkmcnt(0)
	s_nop 1
	v_add_f32_dpp v0, v0, v0 row_mirror row_mask:0xf bank_mask:0xf
	v_mov_b32_e32 v1, v0
	s_nop 1
	v_permlane16_swap_b32_e32 v1, v0
	s_and_saveexec_b64 s[0:1], s[96:97]
	s_cbranch_execz .LBB0_2055
	s_waitcnt lgkmcnt(0)
	v_add_f32_e32 v0, v0, v1
	v_mul_f32_e32 v0, 0x4b800000, v0
	v_trunc_f32_e32 v0, v0
	v_mul_f32_e32 v1, 0x2f800000, v0
	v_floor_f32_e32 v1, v1
	v_fmac_f32_e32 v0, 0xcf800000, v1
	v_cvt_u32_f32_e32 v0, v0
	v_cvt_u32_f32_e32 v1, v1
	global_atomic_add_x2 v[48:49], v[0:1], off
	s_branch .LBB0_2055

.LBB0_2142:
	s_or_b64 exec, exec, s[0:1]
	s_waitcnt lgkmcnt(0)
	s_barrier
	ds_read_b32 v0, v44
	s_waitcnt lgkmcnt(0)
	v_add_f32_e32 v4, v18, v0
	v_add_u32_e32 v0, v16, v45
	v_ashrrev_i32_e32 v1, 31, v0
	v_lshl_add_u64 v[2:3], v[0:1], 2, s[90:91]
	v_lshl_add_u64 v[0:1], v[0:1], 1, s[92:93]
	global_store_dword v[2:3], v4, off
	v_cvt_pk_bf16_f32 v2, v4, v33
	global_store_short v[0:1], v2, off
	v_and_b32_e32 v0, 64, v216
	v_add_u32_e32 v6, 64, v0
	v_xor_b32_e32 v0, 1, v216
	v_cmp_lt_i32_e32 vcc, v0, v6
	v_mul_f32_e32 v1, v4, v4
	s_nop 0
	v_cndmask_b32_e32 v0, v216, v0, vcc
	v_lshlrev_b32_e32 v0, 2, v0
	ds_bpermute_b32 v2, v0, v1
	v_xor_b32_e32 v1, 2, v216
	v_cmp_lt_i32_e32 vcc, v1, v6
	s_waitcnt lgkmcnt(0)
	v_fmac_f32_e32 v2, v4, v4
	v_cndmask_b32_e32 v1, v216, v1, vcc
	v_lshlrev_b32_e32 v1, 2, v1
	s_waitcnt lgkmcnt(0)
	s_nop 1
	v_add_f32_dpp v3, v2, v2 quad_perm:[2,3,0,1] row_mask:0xf bank_mask:0xf
	v_xor_b32_e32 v2, 4, v216
	v_cmp_lt_i32_e32 vcc, v2, v6
	s_nop 1
	v_cndmask_b32_e32 v2, v216, v2, vcc
	v_lshlrev_b32_e32 v2, 2, v2
	s_waitcnt lgkmcnt(0)
	s_nop 1
	v_add_f32_dpp v4, v3, v3 row_half_mirror row_mask:0xf bank_mask:0xf
	v_xor_b32_e32 v3, 8, v216
	v_cmp_lt_i32_e32 vcc, v3, v6
	s_nop 1
	v_cndmask_b32_e32 v3, v216, v3, vcc
	v_lshlrev_b32_e32 v3, 2, v3
	s_waitcnt lgkmcnt(0)
	s_nop 1
	v_add_f32_dpp v5, v4, v4 row_mirror row_mask:0xf bank_mask:0xf
	v_xor_b32_e32 v4, 16, v216
	v_cmp_lt_i32_e32 vcc, v4, v6
	s_nop 1
	v_cndmask_b32_e32 v4, v216, v4, vcc
	v_lshlrev_b32_e32 v4, 2, v4
	v_mov_b32_e32 v6, v5
	s_nop 1
	v_permlane16_swap_b32_e32 v6, v5
	s_and_saveexec_b64 s[0:1], s[96:97]
	s_cbranch_execz .LBB0_2144
	s_waitcnt lgkmcnt(0)
	v_add_f32_e32 v5, v5, v6
	v_mul_f32_e32 v5, 0x4b800000, v5
	v_trunc_f32_e32 v5, v5
	v_mul_f32_e32 v6, 0x2f800000, v5
	v_floor_f32_e32 v7, v6
	v_fmac_f32_e32 v5, 0xcf800000, v7
	v_cvt_u32_f32_e32 v6, v5
	v_cvt_u32_f32_e32 v7, v7
	global_atomic_add_x2 v[46:47], v[6:7], off
.LBB0_2144:
	s_or_b64 exec, exec, s[0:1]
	v_add_u32_e32 v5, v42, v85
	ds_read_b32 v5, v5
	s_waitcnt lgkmcnt(0)
	v_add_f32_e32 v5, v17, v5
	v_mul_f32_e32 v6, v5, v5
	ds_bpermute_b32 v0, v0, v6
	s_waitcnt lgkmcnt(0)
	v_fmac_f32_e32 v0, v5, v5
	s_waitcnt lgkmcnt(0)
	s_nop 1
	v_add_f32_dpp v0, v0, v0 quad_perm:[2,3,0,1] row_mask:0xf bank_mask:0xf
	v_add_u32_e32 v2, v16, v86
	s_waitcnt lgkmcnt(0)
	s_nop 1
	v_add_f32_dpp v0, v0, v0 row_half_mirror row_mask:0xf bank_mask:0xf
	v_ashrrev_i32_e32 v3, 31, v2
	v_lshl_add_u64 v[6:7], v[2:3], 2, s[90:91]
	v_lshl_add_u64 v[2:3], v[2:3], 1, s[92:93]
	global_store_dword v[6:7], v5, off
	s_waitcnt lgkmcnt(0)
	s_nop 1
	v_add_f32_dpp v0, v0, v0 row_mirror row_mask:0xf bank_mask:0xf
	v_mov_b32_e32 v1, v0
	s_nop 1
	v_permlane16_swap_b32_e32 v1, v0
	v_cvt_pk_bf16_f32 v4, v5, v33
	global_store_short v[2:3], v4, off
	s_and_saveexec_b64 s[0:1], s[96:97]
	s_cbranch_execz .LBB0_2138
	s_waitcnt lgkmcnt(0)
	v_add_f32_e32 v0, v0, v1
	v_mul_f32_e32 v0, 0x4b800000, v0
	v_trunc_f32_e32 v0, v0
	v_mul_f32_e32 v1, 0x2f800000, v0
	v_floor_f32_e32 v1, v1
	v_fmac_f32_e32 v0, 0xcf800000, v1
	v_cvt_u32_f32_e32 v0, v0
	v_cvt_u32_f32_e32 v1, v1
	global_atomic_add_x2 v[48:49], v[0:1], off
	s_branch .LBB0_2138

.LBB0_2229:
	v_lshl_or_b32 v172, s19, 8, v192
	v_lshl_add_u32 v176, s20, 8, v190
	v_ashrrev_i32_e32 v173, 31, v172
	v_lshlrev_b64 v[202:203], 1, v[172:173]
	v_ashrrev_i32_e32 v177, 31, v176
	v_lshl_add_u64 v[174:175], s[38:39], 0, v[202:203]
	v_lshlrev_b64 v[204:205], 11, v[176:177]
	v_lshl_add_u64 v[114:115], v[174:175], 0, v[204:205]
	global_load_dwordx4 v[194:197], v[114:115], off
	global_load_dwordx4 v[198:201], v[114:115], off offset:256
	v_or_b32_e32 v186, 16, v176
	v_ashrrev_i32_e32 v187, 31, v186
	v_or_b32_e32 v182, 32, v176
	v_lshlrev_b64 v[188:189], 11, v[186:187]
	v_ashrrev_i32_e32 v183, 31, v182
	v_or_b32_e32 v178, 48, v176
	v_lshl_add_u64 v[114:115], v[174:175], 0, v[188:189]
	v_lshlrev_b64 v[184:185], 11, v[182:183]
	v_ashrrev_i32_e32 v179, 31, v178
	global_load_dwordx4 v[150:153], v[114:115], off
	global_load_dwordx4 v[146:149], v[114:115], off offset:256
	v_lshl_add_u64 v[114:115], v[174:175], 0, v[184:185]
	v_lshlrev_b64 v[180:181], 11, v[178:179]
	global_load_dwordx4 v[142:145], v[114:115], off
	global_load_dwordx4 v[130:133], v[114:115], off offset:256
	v_lshl_add_u64 v[114:115], v[174:175], 0, v[180:181]
	global_load_dwordx4 v[122:125], v[114:115], off
	s_nop 0
	global_load_dwordx4 v[114:117], v[114:115], off offset:256
	v_lshl_add_u64 v[204:205], s[38:39], 0, v[204:205]
	v_lshl_add_u64 v[202:203], v[204:205], 0, v[202:203]
	s_waitcnt vmcnt(0)
	v_lshlrev_b32_e32 v206, 16, v194
	v_and_b32_e32 v207, 0xffff0000, v194
	v_lshlrev_b32_e32 v194, 16, v195
	v_and_b32_e32 v195, 0xffff0000, v195
	v_pk_add_f32 v[140:141], v[140:141], v[194:195]
	v_lshlrev_b32_e32 v194, 16, v196
	v_and_b32_e32 v195, 0xffff0000, v196
	v_lshlrev_b32_e32 v196, 16, v197
	v_and_b32_e32 v197, 0xffff0000, v197
	v_pk_add_f32 v[138:139], v[138:139], v[206:207]
	v_pk_add_f32 v[196:197], v[136:137], v[196:197]
	v_pk_add_f32 v[194:195], v[134:135], v[194:195]
	v_cvt_pk_bf16_f32 v134, v138, v139
	v_cvt_pk_bf16_f32 v135, v140, v141
	s_nop 0
	v_cvt_pk_bf16_f32 v136, v194, v195
	v_cvt_pk_bf16_f32 v137, v196, v197
	global_store_dwordx4 v[202:203], v[134:137], off
	s_nop 1
	v_pk_mul_f32 v[134:135], v[194:195], v[194:195]
	v_pk_mul_f32 v[136:137], v[196:197], v[196:197]
	v_pk_fma_f32 v[134:135], v[138:139], v[138:139], v[134:135]
	v_pk_fma_f32 v[136:137], v[140:141], v[140:141], v[136:137]
	v_add_f32_e32 v134, v134, v135
	v_add_f32_e32 v135, v136, v137
	v_add_f32_e32 v138, v134, v135
	v_lshlrev_b32_e32 v134, 16, v198
	v_and_b32_e32 v135, 0xffff0000, v198
	v_lshlrev_b32_e32 v136, 16, v199
	v_and_b32_e32 v137, 0xffff0000, v199
	v_pk_add_f32 v[128:129], v[128:129], v[136:137]
	v_pk_add_f32 v[126:127], v[126:127], v[134:135]
	v_lshlrev_b32_e32 v134, 16, v200
	v_and_b32_e32 v135, 0xffff0000, v200
	v_lshlrev_b32_e32 v136, 16, v201
	v_and_b32_e32 v137, 0xffff0000, v201
	v_pk_add_f32 v[136:137], v[120:121], v[136:137]
	v_pk_add_f32 v[134:135], v[118:119], v[134:135]
	v_cvt_pk_bf16_f32 v118, v126, v127
	v_cvt_pk_bf16_f32 v119, v128, v129
	s_nop 0
	v_cvt_pk_bf16_f32 v120, v134, v135
	v_cvt_pk_bf16_f32 v121, v136, v137
	global_store_dwordx4 v[202:203], v[118:121], off offset:256
	s_nop 1
	v_pk_mul_f32 v[118:119], v[134:135], v[134:135]
	v_pk_mul_f32 v[120:121], v[136:137], v[136:137]
	v_pk_fma_f32 v[118:119], v[126:127], v[126:127], v[118:119]
	v_pk_fma_f32 v[120:121], v[128:129], v[128:129], v[120:121]
	v_add_f32_e32 v118, v118, v119
	v_add_f32_e32 v119, v120, v121
	v_add_f32_e32 v118, v118, v119
	v_and_b32_e32 v120, 64, v216
	v_add_f32_e32 v119, v138, v118
	v_xor_b32_e32 v118, 16, v216
	v_add_u32_e32 v121, 64, v120
	v_cmp_lt_i32_e32 vcc, v118, v121
	s_nop 1
	v_cndmask_b32_e32 v118, v216, v118, vcc
	v_lshlrev_b32_e32 v118, 2, v118
	v_mov_b32_e32 v120, v119
	s_nop 1
	v_permlane16_swap_b32_e32 v120, v119
	s_waitcnt lgkmcnt(0)
	v_add_f32_e32 v120, v119, v120
	v_xor_b32_e32 v119, 32, v216
	v_cmp_lt_i32_e32 vcc, v119, v121
	s_nop 1
	v_cndmask_b32_e32 v119, v216, v119, vcc
	v_lshlrev_b32_e32 v119, 2, v119
	v_mov_b32_e32 v121, v120
	s_nop 1
	v_permlane32_swap_b32_e32 v121, v120
	s_and_saveexec_b64 s[0:1], s[34:35]
	s_cbranch_execz .LBB0_2231
	s_waitcnt lgkmcnt(0)
	v_add_f32_e32 v120, v120, v121
	v_mul_f32_e32 v120, 0x4b800000, v120
	v_trunc_f32_e32 v120, v120
	v_mul_f32_e32 v121, 0x2f800000, v120
	v_floor_f32_e32 v121, v121
	v_fmac_f32_e32 v120, 0xcf800000, v121
	v_cvt_u32_f32_e32 v120, v120
	v_cvt_u32_f32_e32 v121, v121
	v_lshl_add_u64 v[126:127], v[176:177], 3, s[4:5]
	global_atomic_add_x2 v[126:127], v[120:121], off
.LBB0_2231:
	s_or_b64 exec, exec, s[0:1]
	v_lshlrev_b32_e32 v120, 16, v150
	s_waitcnt lgkmcnt(0)
	v_and_b32_e32 v121, 0xffff0000, v150
	v_lshlrev_b32_e32 v126, 16, v151
	v_and_b32_e32 v127, 0xffff0000, v151
	v_pk_add_f32 v[112:113], v[112:113], v[126:127]
	v_pk_add_f32 v[110:111], v[110:111], v[120:121]
	v_lshlrev_b32_e32 v120, 16, v152
	v_and_b32_e32 v121, 0xffff0000, v152
	v_lshlrev_b32_e32 v126, 16, v153
	v_and_b32_e32 v127, 0xffff0000, v153
	v_pk_add_f32 v[126:127], v[108:109], v[126:127]
	v_pk_add_f32 v[120:121], v[106:107], v[120:121]
	v_cvt_pk_bf16_f32 v106, v110, v111
	v_cvt_pk_bf16_f32 v107, v112, v113
	s_nop 0
	v_cvt_pk_bf16_f32 v108, v120, v121
	v_cvt_pk_bf16_f32 v109, v126, v127
	v_pk_mul_f32 v[120:121], v[120:121], v[120:121]
	v_pk_mul_f32 v[126:127], v[126:127], v[126:127]
	v_pk_fma_f32 v[110:111], v[110:111], v[110:111], v[120:121]
	v_pk_fma_f32 v[112:113], v[112:113], v[112:113], v[126:127]
	v_add_f32_e32 v110, v110, v111
	v_add_f32_e32 v111, v112, v113
	v_add_f32_e32 v120, v110, v111
	v_lshlrev_b32_e32 v110, 16, v146
	v_and_b32_e32 v111, 0xffff0000, v146
	v_lshlrev_b32_e32 v112, 16, v147
	v_and_b32_e32 v113, 0xffff0000, v147
	v_pk_add_f32 v[104:105], v[104:105], v[112:113]
	v_pk_add_f32 v[102:103], v[102:103], v[110:111]
	v_lshlrev_b32_e32 v110, 16, v148
	v_and_b32_e32 v111, 0xffff0000, v148
	v_lshlrev_b32_e32 v112, 16, v149
	v_and_b32_e32 v113, 0xffff0000, v149
	v_pk_add_f32 v[112:113], v[100:101], v[112:113]
	v_pk_add_f32 v[110:111], v[98:99], v[110:111]
	v_pk_mul_f32 v[100:101], v[112:113], v[112:113]
	v_pk_mul_f32 v[98:99], v[110:111], v[110:111]
	v_pk_fma_f32 v[100:101], v[104:105], v[104:105], v[100:101]
	v_pk_fma_f32 v[98:99], v[102:103], v[102:103], v[98:99]
	s_nop 0
	v_add_f32_e32 v98, v98, v99
	v_add_f32_e32 v99, v100, v101
	v_add_f32_e32 v98, v98, v99
	v_add_f32_e32 v101, v120, v98
	ds_bpermute_b32 v126, v118, v101
	v_lshl_add_u64 v[98:99], s[38:39], 0, v[188:189]
	v_lshl_add_u64 v[120:121], v[172:173], 1, v[98:99]
	global_store_dwordx4 v[120:121], v[106:109], off
	v_cvt_pk_bf16_f32 v100, v102, v103
	s_waitcnt lgkmcnt(0)
	v_add_f32_e32 v98, v101, v126
	v_mov_b32_e32 v99, v98
	s_nop 1
	v_permlane32_swap_b32_e32 v99, v98
	v_cvt_pk_bf16_f32 v101, v104, v105
	v_cvt_pk_bf16_f32 v102, v110, v111
	v_cvt_pk_bf16_f32 v103, v112, v113
	global_store_dwordx4 v[120:121], v[100:103], off offset:256
	s_and_saveexec_b64 s[0:1], s[34:35]
	s_cbranch_execz .LBB0_2233
	s_waitcnt lgkmcnt(0)
	v_add_f32_e32 v98, v98, v99
	v_mul_f32_e32 v98, 0x4b800000, v98
	v_trunc_f32_e32 v98, v98
	v_mul_f32_e32 v99, 0x2f800000, v98
	v_floor_f32_e32 v99, v99
	v_fmac_f32_e32 v98, 0xcf800000, v99
	v_cvt_u32_f32_e32 v98, v98
	v_cvt_u32_f32_e32 v99, v99
	v_lshl_add_u64 v[100:101], v[186:187], 3, s[4:5]
	global_atomic_add_x2 v[100:101], v[98:99], off
.LBB0_2233:
	s_or_b64 exec, exec, s[0:1]
	v_lshlrev_b32_e32 v98, 16, v142
	s_waitcnt lgkmcnt(0)
	v_and_b32_e32 v99, 0xffff0000, v142
	v_lshlrev_b32_e32 v100, 16, v143
	v_and_b32_e32 v101, 0xffff0000, v143
	v_pk_add_f32 v[96:97], v[96:97], v[100:101]
	v_pk_add_f32 v[94:95], v[94:95], v[98:99]
	v_lshlrev_b32_e32 v98, 16, v144
	v_and_b32_e32 v99, 0xffff0000, v144
	v_lshlrev_b32_e32 v100, 16, v145
	v_and_b32_e32 v101, 0xffff0000, v145
	v_pk_add_f32 v[100:101], v[92:93], v[100:101]
	v_pk_add_f32 v[98:99], v[90:91], v[98:99]
	v_cvt_pk_bf16_f32 v90, v94, v95
	v_cvt_pk_bf16_f32 v91, v96, v97
	s_nop 0
	v_cvt_pk_bf16_f32 v92, v98, v99
	v_cvt_pk_bf16_f32 v93, v100, v101
	v_pk_mul_f32 v[98:99], v[98:99], v[98:99]
	v_pk_mul_f32 v[100:101], v[100:101], v[100:101]
	v_pk_fma_f32 v[94:95], v[94:95], v[94:95], v[98:99]
	v_pk_fma_f32 v[96:97], v[96:97], v[96:97], v[100:101]
	v_add_f32_e32 v94, v94, v95
	v_add_f32_e32 v95, v96, v97
	v_add_f32_e32 v98, v94, v95
	v_lshlrev_b32_e32 v94, 16, v130
	v_and_b32_e32 v95, 0xffff0000, v130
	v_lshlrev_b32_e32 v96, 16, v131
	v_and_b32_e32 v97, 0xffff0000, v131
	v_pk_add_f32 v[88:89], v[88:89], v[96:97]
	v_pk_add_f32 v[86:87], v[86:87], v[94:95]
	v_lshlrev_b32_e32 v94, 16, v132
	v_and_b32_e32 v95, 0xffff0000, v132
	v_lshlrev_b32_e32 v96, 16, v133
	v_and_b32_e32 v97, 0xffff0000, v133
	v_pk_add_f32 v[96:97], v[84:85], v[96:97]
	v_pk_add_f32 v[94:95], v[82:83], v[94:95]
	v_pk_mul_f32 v[84:85], v[96:97], v[96:97]
	v_pk_mul_f32 v[82:83], v[94:95], v[94:95]
	v_pk_fma_f32 v[84:85], v[88:89], v[88:89], v[84:85]
	v_pk_fma_f32 v[82:83], v[86:87], v[86:87], v[82:83]
	s_nop 0
	v_add_f32_e32 v82, v82, v83
	v_add_f32_e32 v83, v84, v85
	v_add_f32_e32 v82, v82, v83
	v_add_f32_e32 v85, v98, v82
	v_mov_b32_e32 v100, v85
	s_nop 1
	v_permlane16_swap_b32_e32 v100, v85
	v_lshl_add_u64 v[82:83], s[38:39], 0, v[184:185]
	v_lshl_add_u64 v[98:99], v[172:173], 1, v[82:83]
	global_store_dwordx4 v[98:99], v[90:93], off
	v_cvt_pk_bf16_f32 v84, v86, v87
	s_waitcnt lgkmcnt(0)
	v_add_f32_e32 v82, v85, v100
	v_mov_b32_e32 v83, v82
	s_nop 1
	v_permlane32_swap_b32_e32 v83, v82
	v_cvt_pk_bf16_f32 v85, v88, v89
	v_cvt_pk_bf16_f32 v86, v94, v95
	v_cvt_pk_bf16_f32 v87, v96, v97
	global_store_dwordx4 v[98:99], v[84:87], off offset:256
	s_and_saveexec_b64 s[0:1], s[34:35]
	s_cbranch_execz .LBB0_2235
	s_waitcnt lgkmcnt(0)
	v_add_f32_e32 v82, v82, v83
	v_mul_f32_e32 v82, 0x4b800000, v82
	v_trunc_f32_e32 v82, v82
	v_mul_f32_e32 v83, 0x2f800000, v82
	v_floor_f32_e32 v83, v83
	v_fmac_f32_e32 v82, 0xcf800000, v83
	v_cvt_u32_f32_e32 v82, v82
	v_cvt_u32_f32_e32 v83, v83
	v_lshl_add_u64 v[84:85], v[182:183], 3, s[4:5]
	global_atomic_add_x2 v[84:85], v[82:83], off
.LBB0_2235:
	s_or_b64 exec, exec, s[0:1]
	v_lshlrev_b32_e32 v82, 16, v122
	s_waitcnt lgkmcnt(0)
	v_and_b32_e32 v83, 0xffff0000, v122
	v_lshlrev_b32_e32 v84, 16, v123
	v_and_b32_e32 v85, 0xffff0000, v123
	v_pk_add_f32 v[80:81], v[80:81], v[84:85]
	v_pk_add_f32 v[78:79], v[78:79], v[82:83]
	v_lshlrev_b32_e32 v82, 16, v124
	v_and_b32_e32 v83, 0xffff0000, v124
	v_lshlrev_b32_e32 v84, 16, v125
	v_and_b32_e32 v85, 0xffff0000, v125
	v_pk_add_f32 v[84:85], v[76:77], v[84:85]
	v_pk_add_f32 v[82:83], v[74:75], v[82:83]
	v_cvt_pk_bf16_f32 v74, v78, v79
	v_cvt_pk_bf16_f32 v75, v80, v81
	s_nop 0
	v_cvt_pk_bf16_f32 v76, v82, v83
	v_cvt_pk_bf16_f32 v77, v84, v85
	v_pk_mul_f32 v[82:83], v[82:83], v[82:83]
	v_pk_mul_f32 v[84:85], v[84:85], v[84:85]
	v_pk_fma_f32 v[78:79], v[78:79], v[78:79], v[82:83]
	v_pk_fma_f32 v[80:81], v[80:81], v[80:81], v[84:85]
	v_add_f32_e32 v78, v78, v79
	v_add_f32_e32 v79, v80, v81
	v_add_f32_e32 v82, v78, v79
	v_lshlrev_b32_e32 v78, 16, v114
	v_and_b32_e32 v79, 0xffff0000, v114
	v_lshlrev_b32_e32 v80, 16, v115
	v_and_b32_e32 v81, 0xffff0000, v115
	v_pk_add_f32 v[72:73], v[72:73], v[80:81]
	v_pk_add_f32 v[70:71], v[70:71], v[78:79]
	v_lshlrev_b32_e32 v78, 16, v116
	v_and_b32_e32 v79, 0xffff0000, v116
	v_lshlrev_b32_e32 v80, 16, v117
	v_and_b32_e32 v81, 0xffff0000, v117
	v_pk_add_f32 v[80:81], v[68:69], v[80:81]
	v_pk_add_f32 v[78:79], v[66:67], v[78:79]
	v_pk_mul_f32 v[68:69], v[80:81], v[80:81]
	v_pk_mul_f32 v[66:67], v[78:79], v[78:79]
	v_pk_fma_f32 v[68:69], v[72:73], v[72:73], v[68:69]
	v_pk_fma_f32 v[66:67], v[70:71], v[70:71], v[66:67]
	s_nop 0
	v_add_f32_e32 v66, v66, v67
	v_add_f32_e32 v67, v68, v69
	v_add_f32_e32 v66, v66, v67
	v_add_f32_e32 v69, v82, v66
	v_mov_b32_e32 v84, v69
	s_nop 1
	v_permlane16_swap_b32_e32 v84, v69
	v_lshl_add_u64 v[66:67], s[38:39], 0, v[180:181]
	v_lshl_add_u64 v[82:83], v[172:173], 1, v[66:67]
	global_store_dwordx4 v[82:83], v[74:77], off
	v_cvt_pk_bf16_f32 v68, v70, v71
	s_waitcnt lgkmcnt(0)
	v_add_f32_e32 v66, v69, v84
	v_mov_b32_e32 v67, v66
	s_nop 1
	v_permlane32_swap_b32_e32 v67, v66
	v_cvt_pk_bf16_f32 v69, v72, v73
	v_cvt_pk_bf16_f32 v70, v78, v79
	v_cvt_pk_bf16_f32 v71, v80, v81
	global_store_dwordx4 v[82:83], v[68:71], off offset:256
	s_and_saveexec_b64 s[0:1], s[34:35]
	s_cbranch_execz .LBB0_2237
	s_waitcnt lgkmcnt(0)
	v_add_f32_e32 v66, v66, v67
	v_mul_f32_e32 v66, 0x4b800000, v66
	v_trunc_f32_e32 v66, v66
	v_mul_f32_e32 v67, 0x2f800000, v66
	v_floor_f32_e32 v67, v67
	v_fmac_f32_e32 v66, 0xcf800000, v67
	v_cvt_u32_f32_e32 v66, v66
	v_cvt_u32_f32_e32 v67, v67
	v_lshl_add_u64 v[68:69], v[178:179], 3, s[4:5]
	global_atomic_add_x2 v[68:69], v[66:67], off
.LBB0_2237:
	s_or_b64 exec, exec, s[0:1]
	v_add_u32_e32 v106, 0x80, v176
	v_ashrrev_i32_e32 v107, 31, v106
	v_lshlrev_b64 v[112:113], 11, v[106:107]
	s_waitcnt lgkmcnt(0)
	v_lshl_add_u64 v[66:67], v[174:175], 0, v[112:113]
	global_load_dwordx4 v[108:111], v[66:67], off
	global_load_dwordx4 v[90:93], v[66:67], off offset:256
	v_add_u32_e32 v102, 0x90, v176
	v_ashrrev_i32_e32 v103, 31, v102
	v_add_u32_e32 v98, 0xa0, v176
	v_lshlrev_b64 v[104:105], 11, v[102:103]
	v_ashrrev_i32_e32 v99, 31, v98
	v_add_u32_e32 v94, 0xb0, v176
	v_lshl_add_u64 v[66:67], v[174:175], 0, v[104:105]
	v_lshlrev_b64 v[100:101], 11, v[98:99]
	v_ashrrev_i32_e32 v95, 31, v94
	global_load_dwordx4 v[86:89], v[66:67], off
	global_load_dwordx4 v[82:85], v[66:67], off offset:256
	v_lshl_add_u64 v[66:67], v[174:175], 0, v[100:101]
	v_lshlrev_b64 v[96:97], 11, v[94:95]
	global_load_dwordx4 v[78:81], v[66:67], off
	global_load_dwordx4 v[74:77], v[66:67], off offset:256
	v_lshl_add_u64 v[66:67], v[174:175], 0, v[96:97]
	global_load_dwordx4 v[70:73], v[66:67], off
	s_nop 0
	global_load_dwordx4 v[66:69], v[66:67], off offset:256
	v_lshl_add_u64 v[112:113], s[38:39], 0, v[112:113]
	v_lshl_add_u64 v[112:113], v[172:173], 1, v[112:113]
	s_waitcnt vmcnt(7)
	v_lshlrev_b32_e32 v114, 16, v108
	v_and_b32_e32 v115, 0xffff0000, v108
	v_lshlrev_b32_e32 v108, 16, v109
	v_and_b32_e32 v109, 0xffff0000, v109
	v_pk_add_f32 v[64:65], v[64:65], v[108:109]
	v_lshlrev_b32_e32 v108, 16, v110
	v_and_b32_e32 v109, 0xffff0000, v110
	v_lshlrev_b32_e32 v110, 16, v111
	v_and_b32_e32 v111, 0xffff0000, v111
	v_pk_add_f32 v[62:63], v[62:63], v[114:115]
	v_pk_add_f32 v[110:111], v[60:61], v[110:111]
	v_pk_add_f32 v[108:109], v[58:59], v[108:109]
	v_cvt_pk_bf16_f32 v58, v62, v63
	v_cvt_pk_bf16_f32 v59, v64, v65
	s_nop 0
	v_cvt_pk_bf16_f32 v60, v108, v109
	v_cvt_pk_bf16_f32 v61, v110, v111
	global_store_dwordx4 v[112:113], v[58:61], off
	s_nop 1
	v_pk_mul_f32 v[58:59], v[108:109], v[108:109]
	v_pk_mul_f32 v[60:61], v[110:111], v[110:111]
	v_pk_fma_f32 v[58:59], v[62:63], v[62:63], v[58:59]
	v_pk_fma_f32 v[60:61], v[64:65], v[64:65], v[60:61]
	v_add_f32_e32 v58, v58, v59
	v_add_f32_e32 v59, v60, v61
	v_add_f32_e32 v62, v58, v59
	s_waitcnt vmcnt(7)
	v_lshlrev_b32_e32 v58, 16, v90
	v_and_b32_e32 v59, 0xffff0000, v90
	v_lshlrev_b32_e32 v60, 16, v91
	v_and_b32_e32 v61, 0xffff0000, v91
	v_pk_add_f32 v[56:57], v[56:57], v[60:61]
	v_pk_add_f32 v[54:55], v[54:55], v[58:59]
	v_lshlrev_b32_e32 v58, 16, v92
	v_and_b32_e32 v59, 0xffff0000, v92
	v_lshlrev_b32_e32 v60, 16, v93
	v_and_b32_e32 v61, 0xffff0000, v93
	v_pk_add_f32 v[60:61], v[52:53], v[60:61]
	v_pk_add_f32 v[58:59], v[50:51], v[58:59]
	v_cvt_pk_bf16_f32 v50, v54, v55
	v_cvt_pk_bf16_f32 v51, v56, v57
	s_nop 0
	v_cvt_pk_bf16_f32 v52, v58, v59
	v_cvt_pk_bf16_f32 v53, v60, v61
	global_store_dwordx4 v[112:113], v[50:53], off offset:256
	s_nop 1
	v_pk_mul_f32 v[50:51], v[58:59], v[58:59]
	v_pk_mul_f32 v[52:53], v[60:61], v[60:61]
	v_pk_fma_f32 v[50:51], v[54:55], v[54:55], v[50:51]
	v_pk_fma_f32 v[52:53], v[56:57], v[56:57], v[52:53]
	v_add_f32_e32 v50, v50, v51
	v_add_f32_e32 v51, v52, v53
	v_add_f32_e32 v50, v50, v51
	v_add_f32_e32 v50, v62, v50
	v_mov_b32_e32 v51, v50
	s_nop 1
	v_permlane16_swap_b32_e32 v51, v50
	s_waitcnt lgkmcnt(0)
	v_add_f32_e32 v50, v50, v51
	v_mov_b32_e32 v51, v50
	s_nop 1
	v_permlane32_swap_b32_e32 v51, v50
	s_and_saveexec_b64 s[0:1], s[34:35]
	s_cbranch_execz .LBB0_2239
	s_waitcnt lgkmcnt(0)
	v_add_f32_e32 v50, v50, v51
	v_mul_f32_e32 v50, 0x4b800000, v50
	v_trunc_f32_e32 v50, v50
	v_mul_f32_e32 v51, 0x2f800000, v50
	v_floor_f32_e32 v51, v51
	v_fmac_f32_e32 v50, 0xcf800000, v51
	v_cvt_u32_f32_e32 v50, v50
	v_cvt_u32_f32_e32 v51, v51
	v_lshl_add_u64 v[52:53], v[106:107], 3, s[4:5]
	global_atomic_add_x2 v[52:53], v[50:51], off
.LBB0_2239:
	s_or_b64 exec, exec, s[0:1]
	s_waitcnt vmcnt(7)
	v_lshlrev_b32_e32 v50, 16, v86
	s_waitcnt lgkmcnt(0)
	v_and_b32_e32 v51, 0xffff0000, v86
	v_lshlrev_b32_e32 v52, 16, v87
	v_and_b32_e32 v53, 0xffff0000, v87
	v_pk_add_f32 v[48:49], v[48:49], v[52:53]
	v_pk_add_f32 v[46:47], v[46:47], v[50:51]
	v_lshlrev_b32_e32 v50, 16, v88
	v_and_b32_e32 v51, 0xffff0000, v88
	v_lshlrev_b32_e32 v52, 16, v89
	v_and_b32_e32 v53, 0xffff0000, v89
	v_pk_add_f32 v[52:53], v[44:45], v[52:53]
	v_pk_add_f32 v[50:51], v[42:43], v[50:51]
	v_cvt_pk_bf16_f32 v42, v46, v47
	v_cvt_pk_bf16_f32 v43, v48, v49
	s_nop 0
	v_cvt_pk_bf16_f32 v44, v50, v51
	v_cvt_pk_bf16_f32 v45, v52, v53
	v_pk_mul_f32 v[50:51], v[50:51], v[50:51]
	v_pk_mul_f32 v[52:53], v[52:53], v[52:53]
	v_pk_fma_f32 v[46:47], v[46:47], v[46:47], v[50:51]
	v_pk_fma_f32 v[48:49], v[48:49], v[48:49], v[52:53]
	v_add_f32_e32 v46, v46, v47
	v_add_f32_e32 v47, v48, v49
	v_add_f32_e32 v50, v46, v47
	s_waitcnt vmcnt(6)
	v_lshlrev_b32_e32 v46, 16, v82
	v_and_b32_e32 v47, 0xffff0000, v82
	v_lshlrev_b32_e32 v48, 16, v83
	v_and_b32_e32 v49, 0xffff0000, v83
	v_pk_add_f32 v[40:41], v[40:41], v[48:49]
	v_pk_add_f32 v[38:39], v[38:39], v[46:47]
	v_lshlrev_b32_e32 v46, 16, v84
	v_and_b32_e32 v47, 0xffff0000, v84
	v_lshlrev_b32_e32 v48, 16, v85
	v_and_b32_e32 v49, 0xffff0000, v85
	v_pk_add_f32 v[48:49], v[36:37], v[48:49]
	v_pk_add_f32 v[46:47], v[34:35], v[46:47]
	v_pk_mul_f32 v[36:37], v[48:49], v[48:49]
	v_pk_mul_f32 v[34:35], v[46:47], v[46:47]
	v_pk_fma_f32 v[36:37], v[40:41], v[40:41], v[36:37]
	v_pk_fma_f32 v[34:35], v[38:39], v[38:39], v[34:35]
	s_nop 0
	v_add_f32_e32 v34, v34, v35
	v_add_f32_e32 v35, v36, v37
	v_add_f32_e32 v34, v34, v35
	v_add_f32_e32 v37, v50, v34
	ds_bpermute_b32 v52, v118, v37
	v_lshl_add_u64 v[34:35], s[38:39], 0, v[104:105]
	v_lshl_add_u64 v[50:51], v[172:173], 1, v[34:35]
	global_store_dwordx4 v[50:51], v[42:45], off
	v_cvt_pk_bf16_f32 v36, v38, v39
	s_waitcnt lgkmcnt(0)
	v_add_f32_e32 v34, v37, v52
	v_mov_b32_e32 v35, v34
	s_nop 1
	v_permlane32_swap_b32_e32 v35, v34
	v_cvt_pk_bf16_f32 v37, v40, v41
	v_cvt_pk_bf16_f32 v38, v46, v47
	v_cvt_pk_bf16_f32 v39, v48, v49
	global_store_dwordx4 v[50:51], v[36:39], off offset:256
	s_and_saveexec_b64 s[0:1], s[34:35]
	s_cbranch_execz .LBB0_2241
	s_waitcnt lgkmcnt(0)
	v_add_f32_e32 v34, v34, v35
	v_mul_f32_e32 v34, 0x4b800000, v34
	v_trunc_f32_e32 v34, v34
	v_mul_f32_e32 v35, 0x2f800000, v34
	v_floor_f32_e32 v35, v35
	v_fmac_f32_e32 v34, 0xcf800000, v35
	v_cvt_u32_f32_e32 v34, v34
	v_cvt_u32_f32_e32 v35, v35
	v_lshl_add_u64 v[36:37], v[102:103], 3, s[4:5]
	global_atomic_add_x2 v[36:37], v[34:35], off
.LBB0_2241:
	s_or_b64 exec, exec, s[0:1]
	s_waitcnt vmcnt(7)
	v_lshlrev_b32_e32 v34, 16, v78
	s_waitcnt lgkmcnt(0)
	v_and_b32_e32 v35, 0xffff0000, v78
	v_lshlrev_b32_e32 v36, 16, v79
	v_and_b32_e32 v37, 0xffff0000, v79
	v_pk_add_f32 v[30:31], v[30:31], v[36:37]
	v_pk_add_f32 v[28:29], v[28:29], v[34:35]
	v_lshlrev_b32_e32 v34, 16, v80
	v_and_b32_e32 v35, 0xffff0000, v80
	v_lshlrev_b32_e32 v36, 16, v81
	v_and_b32_e32 v37, 0xffff0000, v81
	v_pk_add_f32 v[36:37], v[26:27], v[36:37]
	v_pk_add_f32 v[34:35], v[24:25], v[34:35]
	v_cvt_pk_bf16_f32 v24, v28, v29
	v_cvt_pk_bf16_f32 v25, v30, v31
	s_nop 0
	v_cvt_pk_bf16_f32 v26, v34, v35
	v_cvt_pk_bf16_f32 v27, v36, v37
	v_pk_mul_f32 v[34:35], v[34:35], v[34:35]
	v_pk_mul_f32 v[36:37], v[36:37], v[36:37]
	v_pk_fma_f32 v[28:29], v[28:29], v[28:29], v[34:35]
	v_pk_fma_f32 v[30:31], v[30:31], v[30:31], v[36:37]
	v_add_f32_e32 v28, v28, v29
	v_add_f32_e32 v29, v30, v31
	v_add_f32_e32 v34, v28, v29
	s_waitcnt vmcnt(6)
	v_lshlrev_b32_e32 v28, 16, v74
	v_and_b32_e32 v29, 0xffff0000, v74
	v_lshlrev_b32_e32 v30, 16, v75
	v_and_b32_e32 v31, 0xffff0000, v75
	v_pk_add_f32 v[22:23], v[22:23], v[30:31]
	v_pk_add_f32 v[20:21], v[20:21], v[28:29]
	v_lshlrev_b32_e32 v28, 16, v76
	v_and_b32_e32 v29, 0xffff0000, v76
	v_lshlrev_b32_e32 v30, 16, v77
	v_and_b32_e32 v31, 0xffff0000, v77
	v_pk_add_f32 v[30:31], v[18:19], v[30:31]
	v_pk_add_f32 v[28:29], v[16:17], v[28:29]
	v_pk_mul_f32 v[18:19], v[30:31], v[30:31]
	v_pk_mul_f32 v[16:17], v[28:29], v[28:29]
	v_pk_fma_f32 v[18:19], v[22:23], v[22:23], v[18:19]
	v_pk_fma_f32 v[16:17], v[20:21], v[20:21], v[16:17]
	s_nop 0
	v_add_f32_e32 v16, v16, v17
	v_add_f32_e32 v17, v18, v19
	v_add_f32_e32 v16, v16, v17
	v_add_f32_e32 v19, v34, v16
	ds_bpermute_b32 v36, v118, v19
	v_lshl_add_u64 v[16:17], s[38:39], 0, v[100:101]
	v_lshl_add_u64 v[34:35], v[172:173], 1, v[16:17]
	global_store_dwordx4 v[34:35], v[24:27], off
	v_cvt_pk_bf16_f32 v18, v20, v21
	s_waitcnt lgkmcnt(0)
	v_add_f32_e32 v16, v19, v36
	v_mov_b32_e32 v17, v16
	s_nop 1
	v_permlane32_swap_b32_e32 v17, v16
	v_cvt_pk_bf16_f32 v19, v22, v23
	v_cvt_pk_bf16_f32 v20, v28, v29
	v_cvt_pk_bf16_f32 v21, v30, v31
	global_store_dwordx4 v[34:35], v[18:21], off offset:256
	s_and_saveexec_b64 s[0:1], s[34:35]
	s_cbranch_execz .LBB0_2243
	s_waitcnt lgkmcnt(0)
	v_add_f32_e32 v16, v16, v17
	v_mul_f32_e32 v16, 0x4b800000, v16
	v_trunc_f32_e32 v16, v16
	v_mul_f32_e32 v17, 0x2f800000, v16
	v_floor_f32_e32 v17, v17
	v_fmac_f32_e32 v16, 0xcf800000, v17
	v_cvt_u32_f32_e32 v16, v16
	v_cvt_u32_f32_e32 v17, v17
	v_lshl_add_u64 v[18:19], v[98:99], 3, s[4:5]
	global_atomic_add_x2 v[18:19], v[16:17], off
.LBB0_2243:
	s_or_b64 exec, exec, s[0:1]
	s_waitcnt vmcnt(7)
	v_lshlrev_b32_e32 v16, 16, v70
	s_waitcnt lgkmcnt(0)
	v_and_b32_e32 v17, 0xffff0000, v70
	v_lshlrev_b32_e32 v18, 16, v71
	v_and_b32_e32 v19, 0xffff0000, v71
	v_pk_add_f32 v[14:15], v[14:15], v[18:19]
	v_pk_add_f32 v[12:13], v[12:13], v[16:17]
	v_lshlrev_b32_e32 v16, 16, v72
	v_and_b32_e32 v17, 0xffff0000, v72
	v_lshlrev_b32_e32 v18, 16, v73
	v_and_b32_e32 v19, 0xffff0000, v73
	v_pk_add_f32 v[18:19], v[10:11], v[18:19]
	v_pk_add_f32 v[16:17], v[8:9], v[16:17]
	v_cvt_pk_bf16_f32 v8, v12, v13
	v_cvt_pk_bf16_f32 v9, v14, v15
	s_nop 0
	v_cvt_pk_bf16_f32 v10, v16, v17
	v_cvt_pk_bf16_f32 v11, v18, v19
	v_pk_mul_f32 v[16:17], v[16:17], v[16:17]
	v_pk_mul_f32 v[18:19], v[18:19], v[18:19]
	v_pk_fma_f32 v[12:13], v[12:13], v[12:13], v[16:17]
	v_pk_fma_f32 v[14:15], v[14:15], v[14:15], v[18:19]
	v_add_f32_e32 v12, v12, v13
	v_add_f32_e32 v13, v14, v15
	v_add_f32_e32 v16, v12, v13
	s_waitcnt vmcnt(6)
	v_lshlrev_b32_e32 v12, 16, v66
	v_and_b32_e32 v13, 0xffff0000, v66
	v_lshlrev_b32_e32 v14, 16, v67
	v_and_b32_e32 v15, 0xffff0000, v67
	v_pk_add_f32 v[6:7], v[6:7], v[14:15]
	v_pk_add_f32 v[4:5], v[4:5], v[12:13]
	v_lshlrev_b32_e32 v12, 16, v68
	v_and_b32_e32 v13, 0xffff0000, v68
	v_lshlrev_b32_e32 v14, 16, v69
	v_and_b32_e32 v15, 0xffff0000, v69
	v_pk_add_f32 v[14:15], v[2:3], v[14:15]
	v_pk_add_f32 v[12:13], v[0:1], v[12:13]
	v_pk_mul_f32 v[2:3], v[14:15], v[14:15]
	v_pk_mul_f32 v[0:1], v[12:13], v[12:13]
	v_pk_fma_f32 v[2:3], v[6:7], v[6:7], v[2:3]
	v_pk_fma_f32 v[0:1], v[4:5], v[4:5], v[0:1]
	s_nop 0
	v_add_f32_e32 v0, v0, v1
	v_add_f32_e32 v1, v2, v3
	v_add_f32_e32 v0, v0, v1
	v_add_f32_e32 v3, v16, v0
	ds_bpermute_b32 v18, v118, v3
	v_lshl_add_u64 v[0:1], s[38:39], 0, v[96:97]
	v_lshl_add_u64 v[16:17], v[172:173], 1, v[0:1]
	global_store_dwordx4 v[16:17], v[8:11], off
	v_cvt_pk_bf16_f32 v2, v4, v5
	s_waitcnt lgkmcnt(0)
	v_add_f32_e32 v0, v3, v18
	v_mov_b32_e32 v1, v0
	s_nop 1
	v_permlane32_swap_b32_e32 v1, v0
	v_cvt_pk_bf16_f32 v3, v6, v7
	v_cvt_pk_bf16_f32 v4, v12, v13
	v_cvt_pk_bf16_f32 v5, v14, v15
	global_store_dwordx4 v[16:17], v[2:5], off offset:256
	s_and_saveexec_b64 s[0:1], s[34:35]
	s_cbranch_execz .LBB0_2245
	s_waitcnt lgkmcnt(0)
	v_add_f32_e32 v0, v0, v1
	v_mul_f32_e32 v0, 0x4b800000, v0
	v_trunc_f32_e32 v0, v0
	v_mul_f32_e32 v1, 0x2f800000, v0
	v_floor_f32_e32 v1, v1
	v_fmac_f32_e32 v0, 0xcf800000, v1
	v_cvt_u32_f32_e32 v0, v0
	v_cvt_u32_f32_e32 v1, v1
	v_lshl_add_u64 v[2:3], v[94:95], 3, s[4:5]
	global_atomic_add_x2 v[2:3], v[0:1], off

.LBB0_2660:
	s_or_b64 exec, exec, s[38:39]
	s_waitcnt lgkmcnt(0)
	s_barrier
	ds_read_b32 v0, v205
	s_waitcnt vmcnt(1) lgkmcnt(0)
	v_add_f32_e32 v4, v26, v0
	v_add_u32_e32 v0, v24, v206
	v_ashrrev_i32_e32 v1, 31, v0
	v_lshl_add_u64 v[2:3], v[0:1], 2, s[92:93]
	v_lshl_add_u64 v[0:1], v[0:1], 1, s[56:57]
	global_store_dword v[2:3], v4, off
	v_cvt_pk_bf16_f32 v2, v4, v33
	global_store_short v[0:1], v2, off
	v_and_b32_e32 v0, 64, v216
	v_add_u32_e32 v6, 64, v0
	v_xor_b32_e32 v0, 1, v216
	v_cmp_lt_i32_e32 vcc, v0, v6
	v_mul_f32_e32 v1, v4, v4
	s_nop 0
	v_cndmask_b32_e32 v0, v216, v0, vcc
	v_lshlrev_b32_e32 v0, 2, v0
	ds_bpermute_b32 v2, v0, v1
	v_xor_b32_e32 v1, 2, v216
	v_cmp_lt_i32_e32 vcc, v1, v6
	s_waitcnt lgkmcnt(0)
	v_fmac_f32_e32 v2, v4, v4
	v_cndmask_b32_e32 v1, v216, v1, vcc
	v_lshlrev_b32_e32 v1, 2, v1
	s_waitcnt lgkmcnt(0)
	s_nop 1
	v_add_f32_dpp v3, v2, v2 quad_perm:[2,3,0,1] row_mask:0xf bank_mask:0xf
	v_xor_b32_e32 v2, 4, v216
	v_cmp_lt_i32_e32 vcc, v2, v6
	s_nop 1
	v_cndmask_b32_e32 v2, v216, v2, vcc
	v_lshlrev_b32_e32 v2, 2, v2
	s_waitcnt lgkmcnt(0)
	s_nop 1
	v_add_f32_dpp v4, v3, v3 row_half_mirror row_mask:0xf bank_mask:0xf
	v_xor_b32_e32 v3, 8, v216
	v_cmp_lt_i32_e32 vcc, v3, v6
	s_nop 1
	v_cndmask_b32_e32 v3, v216, v3, vcc
	v_lshlrev_b32_e32 v3, 2, v3
	s_waitcnt lgkmcnt(0)
	s_nop 1
	v_add_f32_dpp v5, v4, v4 row_mirror row_mask:0xf bank_mask:0xf
	v_xor_b32_e32 v4, 16, v216
	v_cmp_lt_i32_e32 vcc, v4, v6
	s_nop 1
	v_cndmask_b32_e32 v4, v216, v4, vcc
	v_lshlrev_b32_e32 v4, 2, v4
	v_mov_b32_e32 v6, v5
	s_nop 1
	v_permlane16_swap_b32_e32 v6, v5
	s_and_saveexec_b64 s[2:3], s[90:91]
	s_cbranch_execz .LBB0_2662
	s_waitcnt lgkmcnt(0)
	v_add_f32_e32 v5, v5, v6
	v_mul_f32_e32 v5, 0x4b800000, v5
	v_trunc_f32_e32 v5, v5
	v_mul_f32_e32 v6, 0x2f800000, v5
	v_floor_f32_e32 v7, v6
	v_fmac_f32_e32 v5, 0xcf800000, v7
	v_cvt_u32_f32_e32 v6, v5
	v_cvt_u32_f32_e32 v7, v7
	global_atomic_add_x2 v[166:167], v[6:7], off
.LBB0_2662:
	s_or_b64 exec, exec, s[2:3]
	v_add_u32_e32 v5, v70, v208
	ds_read_b32 v5, v5
	s_waitcnt lgkmcnt(1)
	v_add_u32_e32 v6, v24, v207
	v_ashrrev_i32_e32 v7, 31, v6
	v_lshl_add_u64 v[8:9], v[6:7], 2, s[92:93]
	v_lshl_add_u64 v[6:7], v[6:7], 1, s[56:57]
	s_waitcnt vmcnt(2) lgkmcnt(0)
	v_add_f32_e32 v5, v25, v5
	global_store_dword v[8:9], v5, off
	v_cvt_pk_bf16_f32 v8, v5, v33
	global_store_short v[6:7], v8, off
	v_mul_f32_e32 v6, v5, v5
	ds_bpermute_b32 v0, v0, v6
	s_waitcnt lgkmcnt(0)
	v_fmac_f32_e32 v0, v5, v5
	s_waitcnt lgkmcnt(0)
	s_nop 1
	v_add_f32_dpp v0, v0, v0 quad_perm:[2,3,0,1] row_mask:0xf bank_mask:0xf
	s_waitcnt lgkmcnt(0)
	s_nop 1
	v_add_f32_dpp v0, v0, v0 row_half_mirror row_mask:0xf bank_mask:0xf
	s_waitcnt lgkmcnt(0)
	s_nop 1
	v_add_f32_dpp v0, v0, v0 row_mirror row_mask:0xf bank_mask:0xf
	v_mov_b32_e32 v1, v0
	s_nop 1
	v_permlane16_swap_b32_e32 v1, v0
	s_and_saveexec_b64 s[2:3], s[90:91]
	s_cbranch_execz .LBB0_2656
	s_waitcnt lgkmcnt(0)
	v_add_f32_e32 v0, v0, v1
	v_mul_f32_e32 v0, 0x4b800000, v0
	v_trunc_f32_e32 v0, v0
	v_mul_f32_e32 v1, 0x2f800000, v0
	v_floor_f32_e32 v1, v1
	v_fmac_f32_e32 v0, 0xcf800000, v1
	v_cvt_u32_f32_e32 v0, v0
	v_cvt_u32_f32_e32 v1, v1
	global_atomic_add_x2 v[168:169], v[0:1], off
	s_branch .LBB0_2656

.LBB0_2760:
	s_or_b64 exec, exec, s[2:3]
	v_add_u32_e32 v5, v70, v208
	ds_read_b32 v5, v5
	s_waitcnt vmcnt(2) lgkmcnt(0)
	v_add_f32_e32 v5, v25, v5
	v_mul_f32_e32 v6, v5, v5
	ds_bpermute_b32 v0, v0, v6
	s_waitcnt lgkmcnt(0)
	v_fmac_f32_e32 v0, v5, v5
	s_waitcnt lgkmcnt(0)
	s_nop 1
	v_add_f32_dpp v0, v0, v0 quad_perm:[2,3,0,1] row_mask:0xf bank_mask:0xf
	v_add_u32_e32 v2, v24, v207
	s_waitcnt lgkmcnt(0)
	s_nop 1
	v_add_f32_dpp v0, v0, v0 row_half_mirror row_mask:0xf bank_mask:0xf
	v_ashrrev_i32_e32 v3, 31, v2
	v_lshl_add_u64 v[6:7], v[2:3], 2, s[92:93]
	v_lshl_add_u64 v[2:3], v[2:3], 1, s[56:57]
	global_store_dword v[6:7], v5, off
	s_waitcnt lgkmcnt(0)
	s_nop 1
	v_add_f32_dpp v0, v0, v0 row_mirror row_mask:0xf bank_mask:0xf
	v_mov_b32_e32 v1, v0
	s_nop 1
	v_permlane16_swap_b32_e32 v1, v0
	v_cvt_pk_bf16_f32 v4, v5, v33
	global_store_short v[2:3], v4, off
	s_and_saveexec_b64 s[2:3], s[90:91]
	s_cbranch_execz .LBB0_2754
	s_waitcnt lgkmcnt(0)
	v_add_f32_e32 v0, v0, v1
	v_mul_f32_e32 v0, 0x4b800000, v0
	v_trunc_f32_e32 v0, v0
	v_mul_f32_e32 v1, 0x2f800000, v0
	v_floor_f32_e32 v1, v1
	v_fmac_f32_e32 v0, 0xcf800000, v1
	v_cvt_u32_f32_e32 v0, v0
	v_cvt_u32_f32_e32 v1, v1
	global_atomic_add_x2 v[168:169], v[0:1], off
	s_branch .LBB0_2754

.LBB0_2861:
	v_lshl_or_b32 v182, s21, 8, v211
	v_lshl_add_u32 v186, s23, 8, v209
	v_ashrrev_i32_e32 v183, 31, v182
	v_lshlrev_b64 v[158:159], 1, v[182:183]
	v_ashrrev_i32_e32 v187, 31, v186
	v_lshl_add_u64 v[184:185], s[82:83], 0, v[158:159]
	v_lshlrev_b64 v[160:161], 11, v[186:187]
	v_lshl_add_u64 v[114:115], v[184:185], 0, v[160:161]
	global_load_dwordx4 v[220:223], v[114:115], off
	global_load_dwordx4 v[224:227], v[114:115], off offset:256
	v_or_b32_e32 v196, 16, v186
	v_ashrrev_i32_e32 v197, 31, v196
	v_or_b32_e32 v192, 32, v186
	v_lshlrev_b64 v[198:199], 11, v[196:197]
	v_ashrrev_i32_e32 v193, 31, v192
	v_or_b32_e32 v188, 48, v186
	v_lshl_add_u64 v[114:115], v[184:185], 0, v[198:199]
	v_lshlrev_b64 v[194:195], 11, v[192:193]
	v_ashrrev_i32_e32 v189, 31, v188
	global_load_dwordx4 v[150:153], v[114:115], off
	global_load_dwordx4 v[146:149], v[114:115], off offset:256
	v_lshl_add_u64 v[114:115], v[184:185], 0, v[194:195]
	v_lshlrev_b64 v[190:191], 11, v[188:189]
	global_load_dwordx4 v[142:145], v[114:115], off
	global_load_dwordx4 v[130:133], v[114:115], off offset:256
	v_lshl_add_u64 v[114:115], v[184:185], 0, v[190:191]
	global_load_dwordx4 v[122:125], v[114:115], off
	s_nop 0
	global_load_dwordx4 v[114:117], v[114:115], off offset:256
	v_lshl_add_u64 v[160:161], s[82:83], 0, v[160:161]
	v_lshl_add_u64 v[158:159], v[160:161], 0, v[158:159]
	s_waitcnt vmcnt(0)
	v_lshlrev_b32_e32 v212, 16, v220
	v_and_b32_e32 v213, 0xffff0000, v220
	v_lshlrev_b32_e32 v220, 16, v221
	v_and_b32_e32 v221, 0xffff0000, v221
	v_pk_add_f32 v[140:141], v[140:141], v[220:221]
	v_pk_add_f32 v[138:139], v[138:139], v[212:213]
	v_lshlrev_b32_e32 v212, 16, v222
	v_and_b32_e32 v213, 0xffff0000, v222
	v_lshlrev_b32_e32 v220, 16, v223
	v_and_b32_e32 v221, 0xffff0000, v223
	v_pk_add_f32 v[220:221], v[136:137], v[220:221]
	v_pk_add_f32 v[212:213], v[134:135], v[212:213]
	v_cvt_pk_bf16_f32 v134, v138, v139
	v_cvt_pk_bf16_f32 v135, v140, v141
	s_nop 0
	v_cvt_pk_bf16_f32 v136, v212, v213
	v_cvt_pk_bf16_f32 v137, v220, v221
	global_store_dwordx4 v[158:159], v[134:137], off
	s_nop 1
	v_pk_mul_f32 v[134:135], v[212:213], v[212:213]
	v_pk_mul_f32 v[136:137], v[220:221], v[220:221]
	v_pk_fma_f32 v[134:135], v[138:139], v[138:139], v[134:135]
	v_pk_fma_f32 v[136:137], v[140:141], v[140:141], v[136:137]
	v_add_f32_e32 v134, v134, v135
	v_add_f32_e32 v135, v136, v137
	v_add_f32_e32 v138, v134, v135
	v_lshlrev_b32_e32 v134, 16, v224
	v_and_b32_e32 v135, 0xffff0000, v224
	v_lshlrev_b32_e32 v136, 16, v225
	v_and_b32_e32 v137, 0xffff0000, v225
	v_pk_add_f32 v[128:129], v[128:129], v[136:137]
	v_pk_add_f32 v[126:127], v[126:127], v[134:135]
	v_lshlrev_b32_e32 v134, 16, v226
	v_and_b32_e32 v135, 0xffff0000, v226
	v_lshlrev_b32_e32 v136, 16, v227
	v_and_b32_e32 v137, 0xffff0000, v227
	v_pk_add_f32 v[136:137], v[120:121], v[136:137]
	v_pk_add_f32 v[134:135], v[118:119], v[134:135]
	v_cvt_pk_bf16_f32 v118, v126, v127
	v_cvt_pk_bf16_f32 v119, v128, v129
	s_nop 0
	v_cvt_pk_bf16_f32 v120, v134, v135
	v_cvt_pk_bf16_f32 v121, v136, v137
	global_store_dwordx4 v[158:159], v[118:121], off offset:256
	s_nop 1
	v_pk_mul_f32 v[118:119], v[134:135], v[134:135]
	v_pk_mul_f32 v[120:121], v[136:137], v[136:137]
	v_pk_fma_f32 v[118:119], v[126:127], v[126:127], v[118:119]
	v_pk_fma_f32 v[120:121], v[128:129], v[128:129], v[120:121]
	v_add_f32_e32 v118, v118, v119
	v_add_f32_e32 v119, v120, v121
	v_add_f32_e32 v118, v118, v119
	v_and_b32_e32 v120, 64, v216
	v_add_f32_e32 v119, v138, v118
	v_xor_b32_e32 v118, 16, v216
	v_add_u32_e32 v121, 64, v120
	v_cmp_lt_i32_e32 vcc, v118, v121
	s_nop 1
	v_cndmask_b32_e32 v118, v216, v118, vcc
	v_lshlrev_b32_e32 v118, 2, v118
	v_mov_b32_e32 v120, v119
	s_nop 1
	v_permlane16_swap_b32_e32 v120, v119
	s_waitcnt lgkmcnt(0)
	v_add_f32_e32 v120, v119, v120
	v_xor_b32_e32 v119, 32, v216
	v_cmp_lt_i32_e32 vcc, v119, v121
	s_nop 1
	v_cndmask_b32_e32 v119, v216, v119, vcc
	v_lshlrev_b32_e32 v119, 2, v119
	v_mov_b32_e32 v121, v120
	s_nop 1
	v_permlane32_swap_b32_e32 v121, v120
	s_and_saveexec_b64 s[2:3], s[38:39]
	s_cbranch_execz .LBB0_2863
	s_waitcnt lgkmcnt(0)
	v_add_f32_e32 v120, v120, v121
	v_mul_f32_e32 v120, 0x4b800000, v120
	v_trunc_f32_e32 v120, v120
	v_mul_f32_e32 v121, 0x2f800000, v120
	v_floor_f32_e32 v121, v121
	v_fmac_f32_e32 v120, 0xcf800000, v121
	v_cvt_u32_f32_e32 v120, v120
	v_cvt_u32_f32_e32 v121, v121
	v_lshl_add_u64 v[126:127], v[186:187], 3, s[4:5]
	global_atomic_add_x2 v[126:127], v[120:121], off
.LBB0_2863:
	s_or_b64 exec, exec, s[2:3]
	v_lshlrev_b32_e32 v120, 16, v150
	s_waitcnt lgkmcnt(0)
	v_and_b32_e32 v121, 0xffff0000, v150
	v_lshlrev_b32_e32 v126, 16, v151
	v_and_b32_e32 v127, 0xffff0000, v151
	v_pk_add_f32 v[112:113], v[112:113], v[126:127]
	v_pk_add_f32 v[110:111], v[110:111], v[120:121]
	v_lshlrev_b32_e32 v120, 16, v152
	v_and_b32_e32 v121, 0xffff0000, v152
	v_lshlrev_b32_e32 v126, 16, v153
	v_and_b32_e32 v127, 0xffff0000, v153
	v_pk_add_f32 v[126:127], v[108:109], v[126:127]
	v_pk_add_f32 v[120:121], v[106:107], v[120:121]
	v_cvt_pk_bf16_f32 v106, v110, v111
	v_cvt_pk_bf16_f32 v107, v112, v113
	s_nop 0
	v_cvt_pk_bf16_f32 v108, v120, v121
	v_cvt_pk_bf16_f32 v109, v126, v127
	v_pk_mul_f32 v[120:121], v[120:121], v[120:121]
	v_pk_mul_f32 v[126:127], v[126:127], v[126:127]
	v_pk_fma_f32 v[110:111], v[110:111], v[110:111], v[120:121]
	v_pk_fma_f32 v[112:113], v[112:113], v[112:113], v[126:127]
	v_add_f32_e32 v110, v110, v111
	v_add_f32_e32 v111, v112, v113
	v_add_f32_e32 v120, v110, v111
	v_lshlrev_b32_e32 v110, 16, v146
	v_and_b32_e32 v111, 0xffff0000, v146
	v_lshlrev_b32_e32 v112, 16, v147
	v_and_b32_e32 v113, 0xffff0000, v147
	v_pk_add_f32 v[104:105], v[104:105], v[112:113]
	v_pk_add_f32 v[102:103], v[102:103], v[110:111]
	v_lshlrev_b32_e32 v110, 16, v148
	v_and_b32_e32 v111, 0xffff0000, v148
	v_lshlrev_b32_e32 v112, 16, v149
	v_and_b32_e32 v113, 0xffff0000, v149
	v_pk_add_f32 v[112:113], v[100:101], v[112:113]
	v_pk_add_f32 v[110:111], v[98:99], v[110:111]
	v_pk_mul_f32 v[100:101], v[112:113], v[112:113]
	v_pk_mul_f32 v[98:99], v[110:111], v[110:111]
	v_pk_fma_f32 v[100:101], v[104:105], v[104:105], v[100:101]
	v_pk_fma_f32 v[98:99], v[102:103], v[102:103], v[98:99]
	s_nop 0
	v_add_f32_e32 v98, v98, v99
	v_add_f32_e32 v99, v100, v101
	v_add_f32_e32 v98, v98, v99
	v_add_f32_e32 v101, v120, v98
	ds_bpermute_b32 v126, v118, v101
	v_lshl_add_u64 v[98:99], s[82:83], 0, v[198:199]
	v_lshl_add_u64 v[120:121], v[182:183], 1, v[98:99]
	global_store_dwordx4 v[120:121], v[106:109], off
	v_cvt_pk_bf16_f32 v100, v102, v103
	s_waitcnt lgkmcnt(0)
	v_add_f32_e32 v98, v101, v126
	v_mov_b32_e32 v99, v98
	s_nop 1
	v_permlane32_swap_b32_e32 v99, v98
	v_cvt_pk_bf16_f32 v101, v104, v105
	v_cvt_pk_bf16_f32 v102, v110, v111
	v_cvt_pk_bf16_f32 v103, v112, v113
	global_store_dwordx4 v[120:121], v[100:103], off offset:256
	s_and_saveexec_b64 s[2:3], s[38:39]
	s_cbranch_execz .LBB0_2865
	s_waitcnt lgkmcnt(0)
	v_add_f32_e32 v98, v98, v99
	v_mul_f32_e32 v98, 0x4b800000, v98
	v_trunc_f32_e32 v98, v98
	v_mul_f32_e32 v99, 0x2f800000, v98
	v_floor_f32_e32 v99, v99
	v_fmac_f32_e32 v98, 0xcf800000, v99
	v_cvt_u32_f32_e32 v98, v98
	v_cvt_u32_f32_e32 v99, v99
	v_lshl_add_u64 v[100:101], v[196:197], 3, s[4:5]
	global_atomic_add_x2 v[100:101], v[98:99], off
.LBB0_2865:
	s_or_b64 exec, exec, s[2:3]
	v_lshlrev_b32_e32 v98, 16, v142
	s_waitcnt lgkmcnt(0)
	v_and_b32_e32 v99, 0xffff0000, v142
	v_lshlrev_b32_e32 v100, 16, v143
	v_and_b32_e32 v101, 0xffff0000, v143
	v_pk_add_f32 v[96:97], v[96:97], v[100:101]
	v_pk_add_f32 v[94:95], v[94:95], v[98:99]
	v_lshlrev_b32_e32 v98, 16, v144
	v_and_b32_e32 v99, 0xffff0000, v144
	v_lshlrev_b32_e32 v100, 16, v145
	v_and_b32_e32 v101, 0xffff0000, v145
	v_pk_add_f32 v[100:101], v[92:93], v[100:101]
	v_pk_add_f32 v[98:99], v[90:91], v[98:99]
	v_cvt_pk_bf16_f32 v90, v94, v95
	v_cvt_pk_bf16_f32 v91, v96, v97
	s_nop 0
	v_cvt_pk_bf16_f32 v92, v98, v99
	v_cvt_pk_bf16_f32 v93, v100, v101
	v_pk_mul_f32 v[98:99], v[98:99], v[98:99]
	v_pk_mul_f32 v[100:101], v[100:101], v[100:101]
	v_pk_fma_f32 v[94:95], v[94:95], v[94:95], v[98:99]
	v_pk_fma_f32 v[96:97], v[96:97], v[96:97], v[100:101]
	v_add_f32_e32 v94, v94, v95
	v_add_f32_e32 v95, v96, v97
	v_add_f32_e32 v98, v94, v95
	v_lshlrev_b32_e32 v94, 16, v130
	v_and_b32_e32 v95, 0xffff0000, v130
	v_lshlrev_b32_e32 v96, 16, v131
	v_and_b32_e32 v97, 0xffff0000, v131
	v_pk_add_f32 v[88:89], v[88:89], v[96:97]
	v_pk_add_f32 v[86:87], v[86:87], v[94:95]
	v_lshlrev_b32_e32 v94, 16, v132
	v_and_b32_e32 v95, 0xffff0000, v132
	v_lshlrev_b32_e32 v96, 16, v133
	v_and_b32_e32 v97, 0xffff0000, v133
	v_pk_add_f32 v[96:97], v[84:85], v[96:97]
	v_pk_add_f32 v[94:95], v[82:83], v[94:95]
	v_pk_mul_f32 v[84:85], v[96:97], v[96:97]
	v_pk_mul_f32 v[82:83], v[94:95], v[94:95]
	v_pk_fma_f32 v[84:85], v[88:89], v[88:89], v[84:85]
	v_pk_fma_f32 v[82:83], v[86:87], v[86:87], v[82:83]
	s_nop 0
	v_add_f32_e32 v82, v82, v83
	v_add_f32_e32 v83, v84, v85
	v_add_f32_e32 v82, v82, v83
	v_add_f32_e32 v85, v98, v82
	v_mov_b32_e32 v100, v85
	s_nop 1
	v_permlane16_swap_b32_e32 v100, v85
	v_lshl_add_u64 v[82:83], s[82:83], 0, v[194:195]
	v_lshl_add_u64 v[98:99], v[182:183], 1, v[82:83]
	global_store_dwordx4 v[98:99], v[90:93], off
	v_cvt_pk_bf16_f32 v84, v86, v87
	s_waitcnt lgkmcnt(0)
	v_add_f32_e32 v82, v85, v100
	v_mov_b32_e32 v83, v82
	s_nop 1
	v_permlane32_swap_b32_e32 v83, v82
	v_cvt_pk_bf16_f32 v85, v88, v89
	v_cvt_pk_bf16_f32 v86, v94, v95
	v_cvt_pk_bf16_f32 v87, v96, v97
	global_store_dwordx4 v[98:99], v[84:87], off offset:256
	s_and_saveexec_b64 s[2:3], s[38:39]
	s_cbranch_execz .LBB0_2867
	s_waitcnt lgkmcnt(0)
	v_add_f32_e32 v82, v82, v83
	v_mul_f32_e32 v82, 0x4b800000, v82
	v_trunc_f32_e32 v82, v82
	v_mul_f32_e32 v83, 0x2f800000, v82
	v_floor_f32_e32 v83, v83
	v_fmac_f32_e32 v82, 0xcf800000, v83
	v_cvt_u32_f32_e32 v82, v82
	v_cvt_u32_f32_e32 v83, v83
	v_lshl_add_u64 v[84:85], v[192:193], 3, s[4:5]
	global_atomic_add_x2 v[84:85], v[82:83], off
.LBB0_2867:
	s_or_b64 exec, exec, s[2:3]
	v_lshlrev_b32_e32 v82, 16, v122
	s_waitcnt lgkmcnt(0)
	v_and_b32_e32 v83, 0xffff0000, v122
	v_lshlrev_b32_e32 v84, 16, v123
	v_and_b32_e32 v85, 0xffff0000, v123
	v_pk_add_f32 v[80:81], v[80:81], v[84:85]
	v_pk_add_f32 v[78:79], v[78:79], v[82:83]
	v_lshlrev_b32_e32 v82, 16, v124
	v_and_b32_e32 v83, 0xffff0000, v124
	v_lshlrev_b32_e32 v84, 16, v125
	v_and_b32_e32 v85, 0xffff0000, v125
	v_pk_add_f32 v[84:85], v[76:77], v[84:85]
	v_pk_add_f32 v[82:83], v[74:75], v[82:83]
	v_cvt_pk_bf16_f32 v74, v78, v79
	v_cvt_pk_bf16_f32 v75, v80, v81
	s_nop 0
	v_cvt_pk_bf16_f32 v76, v82, v83
	v_cvt_pk_bf16_f32 v77, v84, v85
	v_pk_mul_f32 v[82:83], v[82:83], v[82:83]
	v_pk_mul_f32 v[84:85], v[84:85], v[84:85]
	v_pk_fma_f32 v[78:79], v[78:79], v[78:79], v[82:83]
	v_pk_fma_f32 v[80:81], v[80:81], v[80:81], v[84:85]
	v_add_f32_e32 v78, v78, v79
	v_add_f32_e32 v79, v80, v81
	v_add_f32_e32 v82, v78, v79
	v_lshlrev_b32_e32 v78, 16, v114
	v_and_b32_e32 v79, 0xffff0000, v114
	v_lshlrev_b32_e32 v80, 16, v115
	v_and_b32_e32 v81, 0xffff0000, v115
	v_pk_add_f32 v[72:73], v[72:73], v[80:81]
	v_pk_add_f32 v[70:71], v[70:71], v[78:79]
	v_lshlrev_b32_e32 v78, 16, v116
	v_and_b32_e32 v79, 0xffff0000, v116
	v_lshlrev_b32_e32 v80, 16, v117
	v_and_b32_e32 v81, 0xffff0000, v117
	v_pk_add_f32 v[80:81], v[68:69], v[80:81]
	v_pk_add_f32 v[78:79], v[66:67], v[78:79]
	v_pk_mul_f32 v[68:69], v[80:81], v[80:81]
	v_pk_mul_f32 v[66:67], v[78:79], v[78:79]
	v_pk_fma_f32 v[68:69], v[72:73], v[72:73], v[68:69]
	v_pk_fma_f32 v[66:67], v[70:71], v[70:71], v[66:67]
	s_nop 0
	v_add_f32_e32 v66, v66, v67
	v_add_f32_e32 v67, v68, v69
	v_add_f32_e32 v66, v66, v67
	v_add_f32_e32 v69, v82, v66
	v_mov_b32_e32 v84, v69
	s_nop 1
	v_permlane16_swap_b32_e32 v84, v69
	v_lshl_add_u64 v[66:67], s[82:83], 0, v[190:191]
	v_lshl_add_u64 v[82:83], v[182:183], 1, v[66:67]
	global_store_dwordx4 v[82:83], v[74:77], off
	v_cvt_pk_bf16_f32 v68, v70, v71
	s_waitcnt lgkmcnt(0)
	v_add_f32_e32 v66, v69, v84
	v_mov_b32_e32 v67, v66
	s_nop 1
	v_permlane32_swap_b32_e32 v67, v66
	v_cvt_pk_bf16_f32 v69, v72, v73
	v_cvt_pk_bf16_f32 v70, v78, v79
	v_cvt_pk_bf16_f32 v71, v80, v81
	global_store_dwordx4 v[82:83], v[68:71], off offset:256
	s_and_saveexec_b64 s[2:3], s[38:39]
	s_cbranch_execz .LBB0_2869
	s_waitcnt lgkmcnt(0)
	v_add_f32_e32 v66, v66, v67
	v_mul_f32_e32 v66, 0x4b800000, v66
	v_trunc_f32_e32 v66, v66
	v_mul_f32_e32 v67, 0x2f800000, v66
	v_floor_f32_e32 v67, v67
	v_fmac_f32_e32 v66, 0xcf800000, v67
	v_cvt_u32_f32_e32 v66, v66
	v_cvt_u32_f32_e32 v67, v67
	v_lshl_add_u64 v[68:69], v[188:189], 3, s[4:5]
	global_atomic_add_x2 v[68:69], v[66:67], off
.LBB0_2869:
	s_or_b64 exec, exec, s[2:3]
	v_add_u32_e32 v106, 0x80, v186
	v_ashrrev_i32_e32 v107, 31, v106
	v_lshlrev_b64 v[112:113], 11, v[106:107]
	s_waitcnt lgkmcnt(0)
	v_lshl_add_u64 v[66:67], v[184:185], 0, v[112:113]
	global_load_dwordx4 v[108:111], v[66:67], off
	global_load_dwordx4 v[90:93], v[66:67], off offset:256
	v_add_u32_e32 v102, 0x90, v186
	v_ashrrev_i32_e32 v103, 31, v102
	v_add_u32_e32 v98, 0xa0, v186
	v_lshlrev_b64 v[104:105], 11, v[102:103]
	v_ashrrev_i32_e32 v99, 31, v98
	v_add_u32_e32 v94, 0xb0, v186
	v_lshl_add_u64 v[66:67], v[184:185], 0, v[104:105]
	v_lshlrev_b64 v[100:101], 11, v[98:99]
	v_ashrrev_i32_e32 v95, 31, v94
	global_load_dwordx4 v[86:89], v[66:67], off
	global_load_dwordx4 v[82:85], v[66:67], off offset:256
	v_lshl_add_u64 v[66:67], v[184:185], 0, v[100:101]
	v_lshlrev_b64 v[96:97], 11, v[94:95]
	global_load_dwordx4 v[78:81], v[66:67], off
	global_load_dwordx4 v[74:77], v[66:67], off offset:256
	v_lshl_add_u64 v[66:67], v[184:185], 0, v[96:97]
	global_load_dwordx4 v[70:73], v[66:67], off
	s_nop 0
	global_load_dwordx4 v[66:69], v[66:67], off offset:256
	v_lshl_add_u64 v[112:113], s[82:83], 0, v[112:113]
	v_lshl_add_u64 v[112:113], v[182:183], 1, v[112:113]
	s_waitcnt vmcnt(7)
	v_lshlrev_b32_e32 v114, 16, v108
	v_and_b32_e32 v115, 0xffff0000, v108
	v_lshlrev_b32_e32 v108, 16, v109
	v_and_b32_e32 v109, 0xffff0000, v109
	v_pk_add_f32 v[64:65], v[64:65], v[108:109]
	v_lshlrev_b32_e32 v108, 16, v110
	v_and_b32_e32 v109, 0xffff0000, v110
	v_lshlrev_b32_e32 v110, 16, v111
	v_and_b32_e32 v111, 0xffff0000, v111
	v_pk_add_f32 v[62:63], v[62:63], v[114:115]
	v_pk_add_f32 v[110:111], v[60:61], v[110:111]
	v_pk_add_f32 v[108:109], v[58:59], v[108:109]
	v_cvt_pk_bf16_f32 v58, v62, v63
	v_cvt_pk_bf16_f32 v59, v64, v65
	s_nop 0
	v_cvt_pk_bf16_f32 v60, v108, v109
	v_cvt_pk_bf16_f32 v61, v110, v111
	global_store_dwordx4 v[112:113], v[58:61], off
	s_nop 1
	v_pk_mul_f32 v[58:59], v[108:109], v[108:109]
	v_pk_mul_f32 v[60:61], v[110:111], v[110:111]
	v_pk_fma_f32 v[58:59], v[62:63], v[62:63], v[58:59]
	v_pk_fma_f32 v[60:61], v[64:65], v[64:65], v[60:61]
	v_add_f32_e32 v58, v58, v59
	v_add_f32_e32 v59, v60, v61
	v_add_f32_e32 v62, v58, v59
	s_waitcnt vmcnt(7)
	v_lshlrev_b32_e32 v58, 16, v90
	v_and_b32_e32 v59, 0xffff0000, v90
	v_lshlrev_b32_e32 v60, 16, v91
	v_and_b32_e32 v61, 0xffff0000, v91
	v_pk_add_f32 v[56:57], v[56:57], v[60:61]
	v_pk_add_f32 v[54:55], v[54:55], v[58:59]
	v_lshlrev_b32_e32 v58, 16, v92
	v_and_b32_e32 v59, 0xffff0000, v92
	v_lshlrev_b32_e32 v60, 16, v93
	v_and_b32_e32 v61, 0xffff0000, v93
	v_pk_add_f32 v[60:61], v[52:53], v[60:61]
	v_pk_add_f32 v[58:59], v[50:51], v[58:59]
	v_cvt_pk_bf16_f32 v50, v54, v55
	v_cvt_pk_bf16_f32 v51, v56, v57
	s_nop 0
	v_cvt_pk_bf16_f32 v52, v58, v59
	v_cvt_pk_bf16_f32 v53, v60, v61
	global_store_dwordx4 v[112:113], v[50:53], off offset:256
	s_nop 1
	v_pk_mul_f32 v[50:51], v[58:59], v[58:59]
	v_pk_mul_f32 v[52:53], v[60:61], v[60:61]
	v_pk_fma_f32 v[50:51], v[54:55], v[54:55], v[50:51]
	v_pk_fma_f32 v[52:53], v[56:57], v[56:57], v[52:53]
	v_add_f32_e32 v50, v50, v51
	v_add_f32_e32 v51, v52, v53
	v_add_f32_e32 v50, v50, v51
	v_add_f32_e32 v50, v62, v50
	v_mov_b32_e32 v51, v50
	s_nop 1
	v_permlane16_swap_b32_e32 v51, v50
	s_waitcnt lgkmcnt(0)
	v_add_f32_e32 v50, v50, v51
	v_mov_b32_e32 v51, v50
	s_nop 1
	v_permlane32_swap_b32_e32 v51, v50
	s_and_saveexec_b64 s[2:3], s[38:39]
	s_cbranch_execz .LBB0_2871
	s_waitcnt lgkmcnt(0)
	v_add_f32_e32 v50, v50, v51
	v_mul_f32_e32 v50, 0x4b800000, v50
	v_trunc_f32_e32 v50, v50
	v_mul_f32_e32 v51, 0x2f800000, v50
	v_floor_f32_e32 v51, v51
	v_fmac_f32_e32 v50, 0xcf800000, v51
	v_cvt_u32_f32_e32 v50, v50
	v_cvt_u32_f32_e32 v51, v51
	v_lshl_add_u64 v[52:53], v[106:107], 3, s[4:5]
	global_atomic_add_x2 v[52:53], v[50:51], off
.LBB0_2871:
	s_or_b64 exec, exec, s[2:3]
	s_waitcnt vmcnt(7)
	v_lshlrev_b32_e32 v50, 16, v86
	s_waitcnt lgkmcnt(0)
	v_and_b32_e32 v51, 0xffff0000, v86
	v_lshlrev_b32_e32 v52, 16, v87
	v_and_b32_e32 v53, 0xffff0000, v87
	v_pk_add_f32 v[48:49], v[48:49], v[52:53]
	v_pk_add_f32 v[46:47], v[46:47], v[50:51]
	v_lshlrev_b32_e32 v50, 16, v88
	v_and_b32_e32 v51, 0xffff0000, v88
	v_lshlrev_b32_e32 v52, 16, v89
	v_and_b32_e32 v53, 0xffff0000, v89
	v_pk_add_f32 v[52:53], v[44:45], v[52:53]
	v_pk_add_f32 v[50:51], v[42:43], v[50:51]
	v_cvt_pk_bf16_f32 v42, v46, v47
	v_cvt_pk_bf16_f32 v43, v48, v49
	s_nop 0
	v_cvt_pk_bf16_f32 v44, v50, v51
	v_cvt_pk_bf16_f32 v45, v52, v53
	v_pk_mul_f32 v[50:51], v[50:51], v[50:51]
	v_pk_mul_f32 v[52:53], v[52:53], v[52:53]
	v_pk_fma_f32 v[46:47], v[46:47], v[46:47], v[50:51]
	v_pk_fma_f32 v[48:49], v[48:49], v[48:49], v[52:53]
	v_add_f32_e32 v46, v46, v47
	v_add_f32_e32 v47, v48, v49
	v_add_f32_e32 v50, v46, v47
	s_waitcnt vmcnt(6)
	v_lshlrev_b32_e32 v46, 16, v82
	v_and_b32_e32 v47, 0xffff0000, v82
	v_lshlrev_b32_e32 v48, 16, v83
	v_and_b32_e32 v49, 0xffff0000, v83
	v_pk_add_f32 v[40:41], v[40:41], v[48:49]
	v_pk_add_f32 v[38:39], v[38:39], v[46:47]
	v_lshlrev_b32_e32 v46, 16, v84
	v_and_b32_e32 v47, 0xffff0000, v84
	v_lshlrev_b32_e32 v48, 16, v85
	v_and_b32_e32 v49, 0xffff0000, v85
	v_pk_add_f32 v[48:49], v[36:37], v[48:49]
	v_pk_add_f32 v[46:47], v[34:35], v[46:47]
	v_pk_mul_f32 v[36:37], v[48:49], v[48:49]
	v_pk_mul_f32 v[34:35], v[46:47], v[46:47]
	v_pk_fma_f32 v[36:37], v[40:41], v[40:41], v[36:37]
	v_pk_fma_f32 v[34:35], v[38:39], v[38:39], v[34:35]
	s_nop 0
	v_add_f32_e32 v34, v34, v35
	v_add_f32_e32 v35, v36, v37
	v_add_f32_e32 v34, v34, v35
	v_add_f32_e32 v37, v50, v34
	ds_bpermute_b32 v52, v118, v37
	v_lshl_add_u64 v[34:35], s[82:83], 0, v[104:105]
	v_lshl_add_u64 v[50:51], v[182:183], 1, v[34:35]
	global_store_dwordx4 v[50:51], v[42:45], off
	v_cvt_pk_bf16_f32 v36, v38, v39
	s_waitcnt lgkmcnt(0)
	v_add_f32_e32 v34, v37, v52
	v_mov_b32_e32 v35, v34
	s_nop 1
	v_permlane32_swap_b32_e32 v35, v34
	v_cvt_pk_bf16_f32 v37, v40, v41
	v_cvt_pk_bf16_f32 v38, v46, v47
	v_cvt_pk_bf16_f32 v39, v48, v49
	global_store_dwordx4 v[50:51], v[36:39], off offset:256
	s_and_saveexec_b64 s[2:3], s[38:39]
	s_cbranch_execz .LBB0_2873
	s_waitcnt lgkmcnt(0)
	v_add_f32_e32 v34, v34, v35
	v_mul_f32_e32 v34, 0x4b800000, v34
	v_trunc_f32_e32 v34, v34
	v_mul_f32_e32 v35, 0x2f800000, v34
	v_floor_f32_e32 v35, v35
	v_fmac_f32_e32 v34, 0xcf800000, v35
	v_cvt_u32_f32_e32 v34, v34
	v_cvt_u32_f32_e32 v35, v35
	v_lshl_add_u64 v[36:37], v[102:103], 3, s[4:5]
	global_atomic_add_x2 v[36:37], v[34:35], off
.LBB0_2873:
	s_or_b64 exec, exec, s[2:3]
	s_waitcnt vmcnt(7)
	v_lshlrev_b32_e32 v34, 16, v78
	s_waitcnt lgkmcnt(0)
	v_and_b32_e32 v35, 0xffff0000, v78
	v_lshlrev_b32_e32 v36, 16, v79
	v_and_b32_e32 v37, 0xffff0000, v79
	v_pk_add_f32 v[30:31], v[30:31], v[36:37]
	v_pk_add_f32 v[28:29], v[28:29], v[34:35]
	v_lshlrev_b32_e32 v34, 16, v80
	v_and_b32_e32 v35, 0xffff0000, v80
	v_lshlrev_b32_e32 v36, 16, v81
	v_and_b32_e32 v37, 0xffff0000, v81
	v_pk_add_f32 v[36:37], v[26:27], v[36:37]
	v_pk_add_f32 v[34:35], v[24:25], v[34:35]
	v_cvt_pk_bf16_f32 v24, v28, v29
	v_cvt_pk_bf16_f32 v25, v30, v31
	s_nop 0
	v_cvt_pk_bf16_f32 v26, v34, v35
	v_cvt_pk_bf16_f32 v27, v36, v37
	v_pk_mul_f32 v[34:35], v[34:35], v[34:35]
	v_pk_mul_f32 v[36:37], v[36:37], v[36:37]
	v_pk_fma_f32 v[28:29], v[28:29], v[28:29], v[34:35]
	v_pk_fma_f32 v[30:31], v[30:31], v[30:31], v[36:37]
	v_add_f32_e32 v28, v28, v29
	v_add_f32_e32 v29, v30, v31
	v_add_f32_e32 v34, v28, v29
	s_waitcnt vmcnt(6)
	v_lshlrev_b32_e32 v28, 16, v74
	v_and_b32_e32 v29, 0xffff0000, v74
	v_lshlrev_b32_e32 v30, 16, v75
	v_and_b32_e32 v31, 0xffff0000, v75
	v_pk_add_f32 v[22:23], v[22:23], v[30:31]
	v_pk_add_f32 v[20:21], v[20:21], v[28:29]
	v_lshlrev_b32_e32 v28, 16, v76
	v_and_b32_e32 v29, 0xffff0000, v76
	v_lshlrev_b32_e32 v30, 16, v77
	v_and_b32_e32 v31, 0xffff0000, v77
	v_pk_add_f32 v[30:31], v[18:19], v[30:31]
	v_pk_add_f32 v[28:29], v[16:17], v[28:29]
	v_pk_mul_f32 v[18:19], v[30:31], v[30:31]
	v_pk_mul_f32 v[16:17], v[28:29], v[28:29]
	v_pk_fma_f32 v[18:19], v[22:23], v[22:23], v[18:19]
	v_pk_fma_f32 v[16:17], v[20:21], v[20:21], v[16:17]
	s_nop 0
	v_add_f32_e32 v16, v16, v17
	v_add_f32_e32 v17, v18, v19
	v_add_f32_e32 v16, v16, v17
	v_add_f32_e32 v19, v34, v16
	ds_bpermute_b32 v36, v118, v19
	v_lshl_add_u64 v[16:17], s[82:83], 0, v[100:101]
	v_lshl_add_u64 v[34:35], v[182:183], 1, v[16:17]
	global_store_dwordx4 v[34:35], v[24:27], off
	v_cvt_pk_bf16_f32 v18, v20, v21
	s_waitcnt lgkmcnt(0)
	v_add_f32_e32 v16, v19, v36
	v_mov_b32_e32 v17, v16
	s_nop 1
	v_permlane32_swap_b32_e32 v17, v16
	v_cvt_pk_bf16_f32 v19, v22, v23
	v_cvt_pk_bf16_f32 v20, v28, v29
	v_cvt_pk_bf16_f32 v21, v30, v31
	global_store_dwordx4 v[34:35], v[18:21], off offset:256
	s_and_saveexec_b64 s[2:3], s[38:39]
	s_cbranch_execz .LBB0_2875
	s_waitcnt lgkmcnt(0)
	v_add_f32_e32 v16, v16, v17
	v_mul_f32_e32 v16, 0x4b800000, v16
	v_trunc_f32_e32 v16, v16
	v_mul_f32_e32 v17, 0x2f800000, v16
	v_floor_f32_e32 v17, v17
	v_fmac_f32_e32 v16, 0xcf800000, v17
	v_cvt_u32_f32_e32 v16, v16
	v_cvt_u32_f32_e32 v17, v17
	v_lshl_add_u64 v[18:19], v[98:99], 3, s[4:5]
	global_atomic_add_x2 v[18:19], v[16:17], off
.LBB0_2875:
	s_or_b64 exec, exec, s[2:3]
	s_waitcnt vmcnt(7)
	v_lshlrev_b32_e32 v16, 16, v70
	s_waitcnt lgkmcnt(0)
	v_and_b32_e32 v17, 0xffff0000, v70
	v_lshlrev_b32_e32 v18, 16, v71
	v_and_b32_e32 v19, 0xffff0000, v71
	v_pk_add_f32 v[14:15], v[14:15], v[18:19]
	v_pk_add_f32 v[12:13], v[12:13], v[16:17]
	v_lshlrev_b32_e32 v16, 16, v72
	v_and_b32_e32 v17, 0xffff0000, v72
	v_lshlrev_b32_e32 v18, 16, v73
	v_and_b32_e32 v19, 0xffff0000, v73
	v_pk_add_f32 v[18:19], v[10:11], v[18:19]
	v_pk_add_f32 v[16:17], v[8:9], v[16:17]
	v_cvt_pk_bf16_f32 v8, v12, v13
	v_cvt_pk_bf16_f32 v9, v14, v15
	s_nop 0
	v_cvt_pk_bf16_f32 v10, v16, v17
	v_cvt_pk_bf16_f32 v11, v18, v19
	v_pk_mul_f32 v[16:17], v[16:17], v[16:17]
	v_pk_mul_f32 v[18:19], v[18:19], v[18:19]
	v_pk_fma_f32 v[12:13], v[12:13], v[12:13], v[16:17]
	v_pk_fma_f32 v[14:15], v[14:15], v[14:15], v[18:19]
	v_add_f32_e32 v12, v12, v13
	v_add_f32_e32 v13, v14, v15
	v_add_f32_e32 v16, v12, v13
	s_waitcnt vmcnt(6)
	v_lshlrev_b32_e32 v12, 16, v66
	v_and_b32_e32 v13, 0xffff0000, v66
	v_lshlrev_b32_e32 v14, 16, v67
	v_and_b32_e32 v15, 0xffff0000, v67
	v_pk_add_f32 v[6:7], v[6:7], v[14:15]
	v_pk_add_f32 v[4:5], v[4:5], v[12:13]
	v_lshlrev_b32_e32 v12, 16, v68
	v_and_b32_e32 v13, 0xffff0000, v68
	v_lshlrev_b32_e32 v14, 16, v69
	v_and_b32_e32 v15, 0xffff0000, v69
	v_pk_add_f32 v[14:15], v[2:3], v[14:15]
	v_pk_add_f32 v[12:13], v[0:1], v[12:13]
	v_pk_mul_f32 v[2:3], v[14:15], v[14:15]
	v_pk_mul_f32 v[0:1], v[12:13], v[12:13]
	v_pk_fma_f32 v[2:3], v[6:7], v[6:7], v[2:3]
	v_pk_fma_f32 v[0:1], v[4:5], v[4:5], v[0:1]
	s_nop 0
	v_add_f32_e32 v0, v0, v1
	v_add_f32_e32 v1, v2, v3
	v_add_f32_e32 v0, v0, v1
	v_add_f32_e32 v3, v16, v0
	ds_bpermute_b32 v18, v118, v3
	v_lshl_add_u64 v[0:1], s[82:83], 0, v[96:97]
	v_lshl_add_u64 v[16:17], v[182:183], 1, v[0:1]
	global_store_dwordx4 v[16:17], v[8:11], off
	v_cvt_pk_bf16_f32 v2, v4, v5
	s_waitcnt lgkmcnt(0)
	v_add_f32_e32 v0, v3, v18
	v_mov_b32_e32 v1, v0
	s_nop 1
	v_permlane32_swap_b32_e32 v1, v0
	v_cvt_pk_bf16_f32 v3, v6, v7
	v_cvt_pk_bf16_f32 v4, v12, v13
	v_cvt_pk_bf16_f32 v5, v14, v15
	global_store_dwordx4 v[16:17], v[2:5], off offset:256
	s_and_saveexec_b64 s[2:3], s[38:39]
	s_cbranch_execz .LBB0_2877
	s_waitcnt lgkmcnt(0)
	v_add_f32_e32 v0, v0, v1
	v_mul_f32_e32 v0, 0x4b800000, v0
	v_trunc_f32_e32 v0, v0
	v_mul_f32_e32 v1, 0x2f800000, v0
	v_floor_f32_e32 v1, v1
	v_fmac_f32_e32 v0, 0xcf800000, v1
	v_cvt_u32_f32_e32 v0, v0
	v_cvt_u32_f32_e32 v1, v1
	v_lshl_add_u64 v[2:3], v[94:95], 3, s[4:5]
	global_atomic_add_x2 v[2:3], v[0:1], off

.LBB0_2888:
	s_or_b64 exec, exec, s[40:41]
	s_waitcnt lgkmcnt(0)
	s_barrier
	ds_read_b32 v1, v205
	v_and_b32_e32 v0, 64, v216
	v_add_u32_e32 v0, 64, v0
	v_xor_b32_e32 v2, 1, v216
	v_cmp_lt_i32_e32 vcc, v2, v0
	s_waitcnt vmcnt(1) lgkmcnt(0)
	v_add_f32_e32 v1, v28, v1
	v_mul_f32_e32 v3, v1, v1
	v_cndmask_b32_e32 v2, v216, v2, vcc
	v_lshlrev_b32_e32 v2, 2, v2
	ds_bpermute_b32 v5, v2, v3
	v_xor_b32_e32 v3, 2, v216
	v_cmp_lt_i32_e32 vcc, v3, v0
	v_xor_b32_e32 v4, 4, v216
	s_waitcnt lgkmcnt(0)
	v_fmac_f32_e32 v5, v1, v1
	v_cndmask_b32_e32 v3, v216, v3, vcc
	v_lshlrev_b32_e32 v3, 2, v3
	v_cmp_lt_i32_e32 vcc, v4, v0
	s_waitcnt lgkmcnt(0)
	s_nop 1
	v_add_f32_dpp v6, v5, v5 quad_perm:[2,3,0,1] row_mask:0xf bank_mask:0xf
	v_cndmask_b32_e32 v4, v216, v4, vcc
	v_lshlrev_b32_e32 v4, 2, v4
	v_xor_b32_e32 v5, 8, v216
	v_cmp_lt_i32_e32 vcc, v5, v0
	s_waitcnt lgkmcnt(0)
	s_nop 1
	v_add_f32_dpp v7, v6, v6 row_half_mirror row_mask:0xf bank_mask:0xf
	v_cndmask_b32_e32 v5, v216, v5, vcc
	v_lshlrev_b32_e32 v5, 2, v5
	v_xor_b32_e32 v6, 16, v216
	v_cmp_lt_i32_e32 vcc, v6, v0
	s_nop 1
	v_cndmask_b32_e32 v0, v216, v6, vcc
	v_lshlrev_b32_e32 v6, 2, v0
	s_waitcnt lgkmcnt(0)
	s_nop 1
	v_add_f32_dpp v0, v7, v7 row_mirror row_mask:0xf bank_mask:0xf
	v_mov_b32_e32 v7, v0
	s_nop 1
	v_permlane16_swap_b32_e32 v7, v0
	s_and_saveexec_b64 s[2:3], s[90:91]
	s_cbranch_execz .LBB0_2890
	s_waitcnt lgkmcnt(0)
	v_add_f32_e32 v0, v0, v7
	v_mul_f32_e32 v0, 0x4b800000, v0
	v_trunc_f32_e32 v0, v0
	v_mul_f32_e32 v7, 0x2f800000, v0
	v_floor_f32_e32 v7, v7
	v_fmac_f32_e32 v0, 0xcf800000, v7
	v_cvt_u32_f32_e32 v8, v0
	v_cvt_u32_f32_e32 v9, v7
	global_atomic_add_x2 v[166:167], v[8:9], off
.LBB0_2890:
	s_or_b64 exec, exec, s[2:3]
	ds_read_b32 v0, v27
	s_waitcnt vmcnt(0) lgkmcnt(0)
	v_add_f32_e32 v0, v25, v0
	v_mul_f32_e32 v7, v0, v0
	ds_bpermute_b32 v2, v2, v7
	s_waitcnt lgkmcnt(0)
	v_fmac_f32_e32 v2, v0, v0
	s_waitcnt lgkmcnt(0)
	s_nop 1
	v_add_f32_dpp v2, v2, v2 quad_perm:[2,3,0,1] row_mask:0xf bank_mask:0xf
	s_waitcnt lgkmcnt(0)
	s_nop 1
	v_add_f32_dpp v2, v2, v2 row_half_mirror row_mask:0xf bank_mask:0xf
	s_waitcnt lgkmcnt(0)
	s_nop 1
	v_add_f32_dpp v2, v2, v2 row_mirror row_mask:0xf bank_mask:0xf
	v_mov_b32_e32 v3, v2
	s_nop 1
	v_permlane16_swap_b32_e32 v3, v2
	s_and_saveexec_b64 s[2:3], s[90:91]
	s_cbranch_execz .LBB0_2892
	s_waitcnt lgkmcnt(0)
	v_add_f32_e32 v2, v2, v3
	v_mul_f32_e32 v2, 0x4b800000, v2
	v_trunc_f32_e32 v2, v2
	v_mul_f32_e32 v3, 0x2f800000, v2
	v_floor_f32_e32 v3, v3
	v_fmac_f32_e32 v2, 0xcf800000, v3
	v_cvt_u32_f32_e32 v2, v2
	v_cvt_u32_f32_e32 v3, v3
	global_atomic_add_x2 v[168:169], v[2:3], off

.LBB0_2915:
	s_or_b64 exec, exec, s[54:55]
	s_waitcnt lgkmcnt(0)
	s_barrier
	ds_read_b32 v0, v205
	v_ashrrev_i32_e32 v25, 31, v24
	s_waitcnt vmcnt(1) lgkmcnt(0)
	v_add_f32_e32 v1, v44, v0
	v_mul_f32_e32 v0, v1, v1
	ds_bpermute_b32 v0, v38, v0
	s_waitcnt lgkmcnt(0)
	v_fmac_f32_e32 v0, v1, v1
	s_waitcnt lgkmcnt(0)
	s_nop 1
	v_add_f32_dpp v0, v0, v0 quad_perm:[2,3,0,1] row_mask:0xf bank_mask:0xf
	s_waitcnt lgkmcnt(0)
	s_nop 1
	v_add_f32_dpp v0, v0, v0 row_half_mirror row_mask:0xf bank_mask:0xf
	s_waitcnt lgkmcnt(0)
	s_nop 1
	v_add_f32_dpp v0, v0, v0 row_mirror row_mask:0xf bank_mask:0xf
	v_mov_b32_e32 v2, v0
	s_nop 1
	v_permlane16_swap_b32_e32 v2, v0
	s_and_saveexec_b64 s[2:3], s[90:91]
	s_cbranch_execz .LBB0_2917
	s_waitcnt lgkmcnt(0)
	v_add_f32_e32 v0, v0, v2
	v_mul_f32_e32 v0, 0x4b800000, v0
	v_trunc_f32_e32 v0, v0
	v_mul_f32_e32 v2, 0x2f800000, v0
	v_floor_f32_e32 v3, v2
	v_fmac_f32_e32 v0, 0xcf800000, v3
	v_cvt_u32_f32_e32 v2, v0
	v_cvt_u32_f32_e32 v3, v3
	global_atomic_add_x2 v[166:167], v[2:3], off
.LBB0_2917:
	s_or_b64 exec, exec, s[2:3]
	ds_read_b32 v0, v27
	s_waitcnt vmcnt(0) lgkmcnt(0)
	v_add_f32_e32 v0, v43, v0
	v_mul_f32_e32 v2, v0, v0
	ds_bpermute_b32 v2, v38, v2
	s_waitcnt lgkmcnt(0)
	v_fmac_f32_e32 v2, v0, v0
	s_waitcnt lgkmcnt(0)
	s_nop 1
	v_add_f32_dpp v2, v2, v2 quad_perm:[2,3,0,1] row_mask:0xf bank_mask:0xf
	s_waitcnt lgkmcnt(0)
	s_nop 1
	v_add_f32_dpp v2, v2, v2 row_half_mirror row_mask:0xf bank_mask:0xf
	s_waitcnt lgkmcnt(0)
	s_nop 1
	v_add_f32_dpp v2, v2, v2 row_mirror row_mask:0xf bank_mask:0xf
	v_mov_b32_e32 v3, v2
	s_nop 1
	v_permlane16_swap_b32_e32 v3, v2
	s_and_saveexec_b64 s[2:3], s[90:91]
	s_cbranch_execz .LBB0_2919
	s_waitcnt lgkmcnt(0)
	v_add_f32_e32 v2, v2, v3
	v_mul_f32_e32 v2, 0x4b800000, v2
	v_trunc_f32_e32 v2, v2
	v_mul_f32_e32 v3, 0x2f800000, v2
	v_floor_f32_e32 v3, v3
	v_fmac_f32_e32 v2, 0xcf800000, v3
	v_cvt_u32_f32_e32 v2, v2
	v_cvt_u32_f32_e32 v3, v3
	global_atomic_add_x2 v[168:169], v[2:3], off

.LBB0_2954:
	s_lshl_b32 s2, s19, 5
	s_lshl_b32 s3, s30, 8
	s_or_b32 s2, s3, s2
	v_lshl_or_b32 v170, v191, 3, s2
	s_lshl_b32 s2, s20, 8
	v_add_u32_e32 v130, 64, v145
	s_add_i32 s2, s2, s21
	v_cmp_lt_i32_e32 vcc, v144, v130
	v_xor_b32_e32 v131, 32, v216
	v_or_b32_e32 v168, s2, v190
	v_cndmask_b32_e32 v32, v216, v144, vcc
	v_cmp_lt_i32_e32 vcc, v131, v130
	v_ashrrev_i32_e32 v171, 31, v170
	v_ashrrev_i32_e32 v169, 31, v168
	v_cndmask_b32_e32 v130, v216, v131, vcc
	v_lshlrev_b32_e32 v192, 2, v130
	v_lshl_add_u64 v[188:189], v[170:171], 1, s[82:83]
	v_lshlrev_b64 v[130:131], 11, v[168:169]
	v_lshl_add_u64 v[130:131], v[188:189], 0, v[130:131]
	s_barrier
	global_load_dwordx4 v[172:175], v[130:131], off
	global_load_dwordx4 v[176:179], v[130:131], off offset:256
	v_or_b32_e32 v166, 16, v168
	v_ashrrev_i32_e32 v167, 31, v166
	v_lshlrev_b64 v[130:131], 11, v[166:167]
	v_or_b32_e32 v164, 32, v168
	v_lshl_add_u64 v[130:131], v[188:189], 0, v[130:131]
	v_ashrrev_i32_e32 v165, 31, v164
	global_load_dwordx4 v[150:153], v[130:131], off
	global_load_dwordx4 v[146:149], v[130:131], off offset:256
	v_lshlrev_b64 v[130:131], 11, v[164:165]
	v_or_b32_e32 v162, 48, v168
	v_lshl_add_u64 v[130:131], v[188:189], 0, v[130:131]
	v_ashrrev_i32_e32 v163, 31, v162
	global_load_dwordx4 v[142:145], v[130:131], off
	global_load_dwordx4 v[134:137], v[130:131], off offset:256
	v_lshlrev_b64 v[130:131], 11, v[162:163]
	v_lshl_add_u64 v[130:131], v[188:189], 0, v[130:131]
	global_load_dwordx4 v[138:141], v[130:131], off
	s_nop 0
	global_load_dwordx4 v[130:133], v[130:131], off offset:256
	v_lshlrev_b32_e32 v32, 2, v32
	v_cmp_eq_u32_e32 vcc, 0, v191
	v_lshl_add_u64 v[180:181], v[168:169], 3, s[4:5]
	s_waitcnt vmcnt(0)
	v_lshlrev_b32_e32 v158, 16, v172
	v_and_b32_e32 v159, 0xffff0000, v172
	v_lshlrev_b32_e32 v160, 16, v173
	v_and_b32_e32 v161, 0xffff0000, v173
	v_pk_add_f32 v[128:129], v[128:129], v[160:161]
	v_pk_add_f32 v[126:127], v[126:127], v[158:159]
	v_lshlrev_b32_e32 v158, 16, v174
	v_and_b32_e32 v159, 0xffff0000, v174
	v_lshlrev_b32_e32 v160, 16, v175
	v_and_b32_e32 v161, 0xffff0000, v175
	v_pk_add_f32 v[124:125], v[124:125], v[160:161]
	v_pk_add_f32 v[122:123], v[122:123], v[158:159]
	v_pk_mul_f32 v[160:161], v[124:125], v[124:125]
	v_pk_mul_f32 v[158:159], v[122:123], v[122:123]
	v_pk_fma_f32 v[160:161], v[128:129], v[128:129], v[160:161]
	v_pk_fma_f32 v[158:159], v[126:127], v[126:127], v[158:159]
	s_nop 0
	v_add_f32_e32 v158, v158, v159
	v_add_f32_e32 v159, v160, v161
	v_add_f32_e32 v172, v158, v159
	v_lshlrev_b32_e32 v158, 16, v176
	v_and_b32_e32 v159, 0xffff0000, v176
	v_lshlrev_b32_e32 v160, 16, v177
	v_and_b32_e32 v161, 0xffff0000, v177
	v_pk_add_f32 v[120:121], v[120:121], v[160:161]
	v_pk_add_f32 v[118:119], v[118:119], v[158:159]
	v_lshlrev_b32_e32 v158, 16, v178
	v_and_b32_e32 v159, 0xffff0000, v178
	v_lshlrev_b32_e32 v160, 16, v179
	v_and_b32_e32 v161, 0xffff0000, v179
	v_pk_add_f32 v[116:117], v[116:117], v[160:161]
	v_pk_add_f32 v[114:115], v[114:115], v[158:159]
	v_pk_mul_f32 v[160:161], v[116:117], v[116:117]
	v_pk_mul_f32 v[158:159], v[114:115], v[114:115]
	v_pk_fma_f32 v[160:161], v[120:121], v[120:121], v[160:161]
	v_pk_fma_f32 v[158:159], v[118:119], v[118:119], v[158:159]
	s_nop 0
	v_add_f32_e32 v158, v158, v159
	v_add_f32_e32 v159, v160, v161
	v_add_f32_e32 v158, v158, v159
	v_add_f32_e32 v158, v172, v158
	v_mov_b32_e32 v159, v158
	s_nop 1
	v_permlane16_swap_b32_e32 v159, v158
	s_waitcnt lgkmcnt(0)
	v_add_f32_e32 v172, v158, v159
	v_mov_b32_e32 v173, v172
	s_nop 1
	v_permlane32_swap_b32_e32 v173, v172
	s_and_saveexec_b64 s[2:3], vcc
	s_cbranch_execz .LBB0_2956
	s_waitcnt lgkmcnt(0)
	v_add_f32_e32 v158, v172, v173
	v_mul_f32_e32 v158, 0x4b800000, v158
	v_trunc_f32_e32 v158, v158
	v_mul_f32_e32 v159, 0x2f800000, v158
	v_floor_f32_e32 v159, v159
	v_fmac_f32_e32 v158, 0xcf800000, v159
	v_cvt_u32_f32_e32 v158, v158
	v_cvt_u32_f32_e32 v159, v159
	global_atomic_add_x2 v[180:181], v[158:159], off
.LBB0_2956:
	s_or_b64 exec, exec, s[2:3]
	v_lshlrev_b32_e32 v158, 16, v150
	v_and_b32_e32 v159, 0xffff0000, v150
	v_lshlrev_b32_e32 v150, 16, v151
	v_and_b32_e32 v151, 0xffff0000, v151
	v_pk_add_f32 v[112:113], v[112:113], v[150:151]
	v_lshlrev_b32_e32 v150, 16, v152
	v_and_b32_e32 v151, 0xffff0000, v152
	v_lshlrev_b32_e32 v152, 16, v153
	v_and_b32_e32 v153, 0xffff0000, v153
	v_pk_add_f32 v[108:109], v[108:109], v[152:153]
	v_pk_add_f32 v[106:107], v[106:107], v[150:151]
	v_pk_add_f32 v[110:111], v[110:111], v[158:159]
	v_pk_mul_f32 v[150:151], v[106:107], v[106:107]
	v_pk_mul_f32 v[152:153], v[108:109], v[108:109]
	v_pk_fma_f32 v[150:151], v[110:111], v[110:111], v[150:151]
	v_pk_fma_f32 v[152:153], v[112:113], v[112:113], v[152:153]
	v_add_f32_e32 v150, v150, v151
	v_add_f32_e32 v151, v152, v153
	v_add_f32_e32 v152, v150, v151
	v_lshlrev_b32_e32 v150, 16, v146
	v_and_b32_e32 v151, 0xffff0000, v146
	v_lshlrev_b32_e32 v146, 16, v147
	v_and_b32_e32 v147, 0xffff0000, v147
	v_pk_add_f32 v[104:105], v[104:105], v[146:147]
	v_lshlrev_b32_e32 v146, 16, v148
	v_and_b32_e32 v147, 0xffff0000, v148
	v_lshlrev_b32_e32 v148, 16, v149
	v_and_b32_e32 v149, 0xffff0000, v149
	v_pk_add_f32 v[100:101], v[100:101], v[148:149]
	v_pk_add_f32 v[98:99], v[98:99], v[146:147]
	v_pk_add_f32 v[102:103], v[102:103], v[150:151]
	v_pk_mul_f32 v[146:147], v[98:99], v[98:99]
	v_pk_mul_f32 v[148:149], v[100:101], v[100:101]
	v_pk_fma_f32 v[146:147], v[102:103], v[102:103], v[146:147]
	v_pk_fma_f32 v[148:149], v[104:105], v[104:105], v[148:149]
	v_add_f32_e32 v146, v146, v147
	v_add_f32_e32 v147, v148, v149
	v_add_f32_e32 v146, v146, v147
	v_add_f32_e32 v146, v152, v146
	v_mov_b32_e32 v147, v146
	s_nop 1
	v_permlane16_swap_b32_e32 v147, v146
	v_lshl_add_u64 v[182:183], v[166:167], 3, s[4:5]
	s_waitcnt lgkmcnt(0)
	v_add_f32_e32 v146, v146, v147
	v_mov_b32_e32 v147, v146
	s_nop 1
	v_permlane32_swap_b32_e32 v147, v146
	s_and_saveexec_b64 s[2:3], vcc
	s_cbranch_execz .LBB0_2958
	s_waitcnt lgkmcnt(0)
	v_add_f32_e32 v146, v146, v147
	v_mul_f32_e32 v146, 0x4b800000, v146
	v_trunc_f32_e32 v146, v146
	v_mul_f32_e32 v147, 0x2f800000, v146
	v_floor_f32_e32 v147, v147
	v_fmac_f32_e32 v146, 0xcf800000, v147
	v_cvt_u32_f32_e32 v146, v146
	v_cvt_u32_f32_e32 v147, v147
	global_atomic_add_x2 v[182:183], v[146:147], off
.LBB0_2958:
	s_or_b64 exec, exec, s[2:3]
	v_lshlrev_b32_e32 v146, 16, v142
	s_waitcnt lgkmcnt(0)
	v_and_b32_e32 v147, 0xffff0000, v142
	v_lshlrev_b32_e32 v142, 16, v143
	v_and_b32_e32 v143, 0xffff0000, v143
	v_pk_add_f32 v[96:97], v[96:97], v[142:143]
	v_lshlrev_b32_e32 v142, 16, v144
	v_and_b32_e32 v143, 0xffff0000, v144
	v_lshlrev_b32_e32 v144, 16, v145
	v_and_b32_e32 v145, 0xffff0000, v145
	v_pk_add_f32 v[92:93], v[92:93], v[144:145]
	v_pk_add_f32 v[142:143], v[90:91], v[142:143]
	v_pk_add_f32 v[94:95], v[94:95], v[146:147]
	v_pk_mul_f32 v[90:91], v[142:143], v[142:143]
	v_pk_mul_f32 v[144:145], v[92:93], v[92:93]
	v_pk_fma_f32 v[90:91], v[94:95], v[94:95], v[90:91]
	v_pk_fma_f32 v[144:145], v[96:97], v[96:97], v[144:145]
	v_add_f32_e32 v90, v90, v91
	v_add_f32_e32 v91, v144, v145
	v_add_f32_e32 v148, v90, v91
	v_lshlrev_b32_e32 v90, 16, v134
	v_and_b32_e32 v91, 0xffff0000, v134
	v_lshlrev_b32_e32 v134, 16, v135
	v_and_b32_e32 v135, 0xffff0000, v135
	v_pk_add_f32 v[134:135], v[88:89], v[134:135]
	v_pk_add_f32 v[144:145], v[86:87], v[90:91]
	v_lshlrev_b32_e32 v86, 16, v136
	v_and_b32_e32 v87, 0xffff0000, v136
	v_lshlrev_b32_e32 v88, 16, v137
	v_and_b32_e32 v89, 0xffff0000, v137
	v_pk_add_f32 v[136:137], v[84:85], v[88:89]
	v_pk_add_f32 v[146:147], v[82:83], v[86:87]
	v_pk_mul_f32 v[84:85], v[136:137], v[136:137]
	v_pk_mul_f32 v[82:83], v[146:147], v[146:147]
	v_pk_fma_f32 v[84:85], v[134:135], v[134:135], v[84:85]
	v_pk_fma_f32 v[82:83], v[144:145], v[144:145], v[82:83]
	v_lshl_add_u64 v[184:185], v[164:165], 3, s[4:5]
	v_add_f32_e32 v82, v82, v83
	v_add_f32_e32 v83, v84, v85
	v_add_f32_e32 v82, v82, v83
	v_add_f32_e32 v82, v148, v82
	v_mov_b32_e32 v83, v82
	s_nop 1
	v_permlane16_swap_b32_e32 v83, v82
	s_waitcnt lgkmcnt(0)
	v_add_f32_e32 v82, v82, v83
	v_mov_b32_e32 v83, v82
	s_nop 1
	v_permlane32_swap_b32_e32 v83, v82
	s_and_saveexec_b64 s[2:3], vcc
	s_cbranch_execz .LBB0_2960
	s_waitcnt lgkmcnt(0)
	v_add_f32_e32 v82, v82, v83
	v_mul_f32_e32 v82, 0x4b800000, v82
	v_trunc_f32_e32 v82, v82
	v_mul_f32_e32 v83, 0x2f800000, v82
	v_floor_f32_e32 v83, v83
	v_fmac_f32_e32 v82, 0xcf800000, v83
	v_cvt_u32_f32_e32 v82, v82
	v_cvt_u32_f32_e32 v83, v83
	global_atomic_add_x2 v[184:185], v[82:83], off
.LBB0_2960:
	s_or_b64 exec, exec, s[2:3]
	v_lshlrev_b32_e32 v82, 16, v138
	s_waitcnt lgkmcnt(0)
	v_and_b32_e32 v83, 0xffff0000, v138
	v_lshlrev_b32_e32 v84, 16, v139
	v_and_b32_e32 v85, 0xffff0000, v139
	v_pk_add_f32 v[138:139], v[80:81], v[84:85]
	v_pk_add_f32 v[148:149], v[78:79], v[82:83]
	v_lshlrev_b32_e32 v78, 16, v140
	v_and_b32_e32 v79, 0xffff0000, v140
	v_lshlrev_b32_e32 v80, 16, v141
	v_and_b32_e32 v81, 0xffff0000, v141
	v_pk_add_f32 v[140:141], v[76:77], v[80:81]
	v_pk_add_f32 v[150:151], v[74:75], v[78:79]
	v_pk_mul_f32 v[76:77], v[140:141], v[140:141]
	v_pk_mul_f32 v[74:75], v[150:151], v[150:151]
	v_pk_fma_f32 v[76:77], v[138:139], v[138:139], v[76:77]
	v_pk_fma_f32 v[74:75], v[148:149], v[148:149], v[74:75]
	v_lshl_add_u64 v[186:187], v[162:163], 3, s[4:5]
	v_add_f32_e32 v74, v74, v75
	v_add_f32_e32 v75, v76, v77
	v_add_f32_e32 v78, v74, v75
	v_lshlrev_b32_e32 v74, 16, v130
	v_and_b32_e32 v75, 0xffff0000, v130
	v_lshlrev_b32_e32 v76, 16, v131
	v_and_b32_e32 v77, 0xffff0000, v131
	v_pk_add_f32 v[152:153], v[72:73], v[76:77]
	v_pk_add_f32 v[174:175], v[70:71], v[74:75]
	v_lshlrev_b32_e32 v70, 16, v132
	v_and_b32_e32 v71, 0xffff0000, v132
	v_lshlrev_b32_e32 v72, 16, v133
	v_and_b32_e32 v73, 0xffff0000, v133
	v_pk_add_f32 v[172:173], v[68:69], v[72:73]
	v_pk_add_f32 v[176:177], v[66:67], v[70:71]
	v_pk_mul_f32 v[68:69], v[172:173], v[172:173]
	v_pk_mul_f32 v[66:67], v[176:177], v[176:177]
	v_pk_fma_f32 v[68:69], v[152:153], v[152:153], v[68:69]
	v_pk_fma_f32 v[66:67], v[174:175], v[174:175], v[66:67]
	s_nop 0
	v_add_f32_e32 v66, v66, v67
	v_add_f32_e32 v67, v68, v69
	v_add_f32_e32 v66, v66, v67
	v_add_f32_e32 v66, v78, v66
	v_mov_b32_e32 v67, v66
	s_nop 1
	v_permlane16_swap_b32_e32 v67, v66
	s_waitcnt lgkmcnt(0)
	v_add_f32_e32 v66, v66, v67
	v_mov_b32_e32 v67, v66
	s_nop 1
	v_permlane32_swap_b32_e32 v67, v66
	s_and_saveexec_b64 s[2:3], vcc
	s_cbranch_execz .LBB0_2962
	s_waitcnt lgkmcnt(0)
	v_add_f32_e32 v66, v66, v67
	v_mul_f32_e32 v66, 0x4b800000, v66
	v_trunc_f32_e32 v66, v66
	v_mul_f32_e32 v67, 0x2f800000, v66
	v_floor_f32_e32 v67, v67
	v_fmac_f32_e32 v66, 0xcf800000, v67
	v_cvt_u32_f32_e32 v66, v66
	v_cvt_u32_f32_e32 v67, v67
	global_atomic_add_x2 v[186:187], v[66:67], off
.LBB0_2962:
	s_or_b64 exec, exec, s[2:3]
	v_add_u32_e32 v178, 0x80, v168
	v_ashrrev_i32_e32 v179, 31, v178
	s_waitcnt lgkmcnt(0)
	v_lshlrev_b64 v[66:67], 11, v[178:179]
	v_lshl_add_u64 v[66:67], v[188:189], 0, v[66:67]
	global_load_dwordx4 v[194:197], v[66:67], off
	global_load_dwordx4 v[198:201], v[66:67], off offset:256
	v_add_u32_e32 v132, 0x90, v168
	v_ashrrev_i32_e32 v133, 31, v132
	v_lshlrev_b64 v[66:67], 11, v[132:133]
	v_add_u32_e32 v130, 0xa0, v168
	v_lshl_add_u64 v[66:67], v[188:189], 0, v[66:67]
	v_ashrrev_i32_e32 v131, 31, v130
	global_load_dwordx4 v[86:89], v[66:67], off
	global_load_dwordx4 v[82:85], v[66:67], off offset:256
	v_lshlrev_b64 v[66:67], 11, v[130:131]
	v_add_u32_e32 v90, 0xb0, v168
	v_lshl_add_u64 v[66:67], v[188:189], 0, v[66:67]
	v_ashrrev_i32_e32 v91, 31, v90
	global_load_dwordx4 v[78:81], v[66:67], off
	global_load_dwordx4 v[70:73], v[66:67], off offset:256
	v_lshlrev_b64 v[66:67], 11, v[90:91]
	v_lshl_add_u64 v[66:67], v[188:189], 0, v[66:67]
	global_load_dwordx4 v[74:77], v[66:67], off
	s_nop 0
	global_load_dwordx4 v[66:69], v[66:67], off offset:256
	s_waitcnt vmcnt(7)
	v_lshlrev_b32_e32 v158, 16, v194
	v_and_b32_e32 v159, 0xffff0000, v194
	v_lshlrev_b32_e32 v160, 16, v195
	v_and_b32_e32 v161, 0xffff0000, v195
	v_pk_add_f32 v[64:65], v[64:65], v[160:161]
	v_pk_add_f32 v[62:63], v[62:63], v[158:159]
	v_lshlrev_b32_e32 v158, 16, v196
	v_and_b32_e32 v159, 0xffff0000, v196
	v_lshlrev_b32_e32 v160, 16, v197
	v_and_b32_e32 v161, 0xffff0000, v197
	v_pk_add_f32 v[60:61], v[60:61], v[160:161]
	v_pk_add_f32 v[58:59], v[58:59], v[158:159]
	v_pk_mul_f32 v[160:161], v[60:61], v[60:61]
	v_pk_mul_f32 v[158:159], v[58:59], v[58:59]
	v_pk_fma_f32 v[160:161], v[64:65], v[64:65], v[160:161]
	v_pk_fma_f32 v[158:159], v[62:63], v[62:63], v[158:159]
	s_nop 0
	v_add_f32_e32 v158, v158, v159
	v_add_f32_e32 v159, v160, v161
	v_add_f32_e32 v188, v158, v159
	s_waitcnt vmcnt(6)
	v_lshlrev_b32_e32 v158, 16, v198
	v_and_b32_e32 v159, 0xffff0000, v198
	v_lshlrev_b32_e32 v160, 16, v199
	v_and_b32_e32 v161, 0xffff0000, v199
	v_pk_add_f32 v[56:57], v[56:57], v[160:161]
	v_pk_add_f32 v[54:55], v[54:55], v[158:159]
	v_lshlrev_b32_e32 v158, 16, v200
	v_and_b32_e32 v159, 0xffff0000, v200
	v_lshlrev_b32_e32 v160, 16, v201
	v_and_b32_e32 v161, 0xffff0000, v201
	v_pk_add_f32 v[52:53], v[52:53], v[160:161]
	v_pk_add_f32 v[50:51], v[50:51], v[158:159]
	v_pk_mul_f32 v[160:161], v[52:53], v[52:53]
	v_pk_mul_f32 v[158:159], v[50:51], v[50:51]
	v_pk_fma_f32 v[160:161], v[56:57], v[56:57], v[160:161]
	v_pk_fma_f32 v[158:159], v[54:55], v[54:55], v[158:159]
	s_nop 0
	v_add_f32_e32 v158, v158, v159
	v_add_f32_e32 v159, v160, v161
	v_add_f32_e32 v158, v158, v159
	v_add_f32_e32 v158, v188, v158
	v_mov_b32_e32 v159, v158
	s_nop 1
	v_permlane16_swap_b32_e32 v159, v158
	v_lshl_add_u64 v[188:189], v[178:179], 3, s[4:5]
	s_waitcnt lgkmcnt(0)
	v_add_f32_e32 v193, v158, v159
	v_mov_b32_e32 v194, v193
	s_nop 1
	v_permlane32_swap_b32_e32 v194, v193
	s_and_saveexec_b64 s[2:3], vcc
	s_cbranch_execz .LBB0_2964
	s_waitcnt lgkmcnt(0)
	v_add_f32_e32 v158, v193, v194
	v_mul_f32_e32 v158, 0x4b800000, v158
	v_trunc_f32_e32 v158, v158
	v_mul_f32_e32 v159, 0x2f800000, v158
	v_floor_f32_e32 v159, v159
	v_fmac_f32_e32 v158, 0xcf800000, v159
	v_cvt_u32_f32_e32 v158, v158
	v_cvt_u32_f32_e32 v159, v159
	global_atomic_add_x2 v[188:189], v[158:159], off
.LBB0_2964:
	s_or_b64 exec, exec, s[2:3]
	s_waitcnt vmcnt(5)
	v_lshlrev_b32_e32 v158, 16, v86
	v_and_b32_e32 v159, 0xffff0000, v86
	v_lshlrev_b32_e32 v86, 16, v87
	v_and_b32_e32 v87, 0xffff0000, v87
	v_pk_add_f32 v[48:49], v[48:49], v[86:87]
	v_lshlrev_b32_e32 v86, 16, v88
	v_and_b32_e32 v87, 0xffff0000, v88
	v_lshlrev_b32_e32 v88, 16, v89
	v_and_b32_e32 v89, 0xffff0000, v89
	v_pk_add_f32 v[44:45], v[44:45], v[88:89]
	v_pk_add_f32 v[42:43], v[42:43], v[86:87]
	v_pk_add_f32 v[46:47], v[46:47], v[158:159]
	v_pk_mul_f32 v[86:87], v[42:43], v[42:43]
	v_pk_mul_f32 v[88:89], v[44:45], v[44:45]
	v_pk_fma_f32 v[86:87], v[46:47], v[46:47], v[86:87]
	v_pk_fma_f32 v[88:89], v[48:49], v[48:49], v[88:89]
	v_add_f32_e32 v86, v86, v87
	v_add_f32_e32 v87, v88, v89
	v_add_f32_e32 v88, v86, v87
	s_waitcnt vmcnt(4)
	v_lshlrev_b32_e32 v86, 16, v82
	v_and_b32_e32 v87, 0xffff0000, v82
	v_lshlrev_b32_e32 v82, 16, v83
	v_and_b32_e32 v83, 0xffff0000, v83
	v_pk_add_f32 v[40:41], v[40:41], v[82:83]
	v_lshlrev_b32_e32 v82, 16, v84
	v_and_b32_e32 v83, 0xffff0000, v84
	v_lshlrev_b32_e32 v84, 16, v85
	v_and_b32_e32 v85, 0xffff0000, v85
	v_pk_add_f32 v[36:37], v[36:37], v[84:85]
	v_pk_add_f32 v[34:35], v[34:35], v[82:83]
	v_pk_add_f32 v[38:39], v[38:39], v[86:87]
	v_pk_mul_f32 v[82:83], v[34:35], v[34:35]
	v_pk_mul_f32 v[84:85], v[36:37], v[36:37]
	v_pk_fma_f32 v[82:83], v[38:39], v[38:39], v[82:83]
	v_pk_fma_f32 v[84:85], v[40:41], v[40:41], v[84:85]
	v_add_f32_e32 v82, v82, v83
	v_add_f32_e32 v83, v84, v85
	v_add_f32_e32 v82, v82, v83
	v_add_f32_e32 v82, v88, v82
	v_mov_b32_e32 v83, v82
	s_nop 1
	v_permlane16_swap_b32_e32 v83, v82
	s_waitcnt lgkmcnt(0)
	v_add_f32_e32 v84, v82, v83
	v_mov_b32_e32 v85, v84
	s_nop 1
	v_permlane32_swap_b32_e32 v85, v84
	v_lshl_add_u64 v[82:83], v[132:133], 3, s[4:5]
	s_and_saveexec_b64 s[2:3], vcc
	s_cbranch_execz .LBB0_2966
	s_waitcnt lgkmcnt(0)
	v_add_f32_e32 v84, v84, v85
	v_mul_f32_e32 v84, 0x4b800000, v84
	v_trunc_f32_e32 v84, v84
	v_mul_f32_e32 v85, 0x2f800000, v84
	v_floor_f32_e32 v85, v85
	v_fmac_f32_e32 v84, 0xcf800000, v85
	v_cvt_u32_f32_e32 v84, v84
	v_cvt_u32_f32_e32 v85, v85
	global_atomic_add_x2 v[82:83], v[84:85], off
.LBB0_2966:
	s_or_b64 exec, exec, s[2:3]
	s_waitcnt vmcnt(3)
	v_lshlrev_b32_e32 v84, 16, v78
	s_waitcnt lgkmcnt(0)
	v_and_b32_e32 v85, 0xffff0000, v78
	v_lshlrev_b32_e32 v78, 16, v79
	v_and_b32_e32 v79, 0xffff0000, v79
	v_pk_add_f32 v[30:31], v[30:31], v[78:79]
	v_lshlrev_b32_e32 v78, 16, v80
	v_and_b32_e32 v79, 0xffff0000, v80
	v_lshlrev_b32_e32 v80, 16, v81
	v_and_b32_e32 v81, 0xffff0000, v81
	v_pk_add_f32 v[26:27], v[26:27], v[80:81]
	v_pk_add_f32 v[24:25], v[24:25], v[78:79]
	v_pk_add_f32 v[28:29], v[28:29], v[84:85]
	v_pk_mul_f32 v[78:79], v[24:25], v[24:25]
	v_pk_mul_f32 v[80:81], v[26:27], v[26:27]
	v_pk_fma_f32 v[78:79], v[28:29], v[28:29], v[78:79]
	v_pk_fma_f32 v[80:81], v[30:31], v[30:31], v[80:81]
	v_add_f32_e32 v78, v78, v79
	v_add_f32_e32 v79, v80, v81
	v_add_f32_e32 v80, v78, v79
	s_waitcnt vmcnt(2)
	v_lshlrev_b32_e32 v78, 16, v70
	v_and_b32_e32 v79, 0xffff0000, v70
	v_lshlrev_b32_e32 v70, 16, v71
	v_and_b32_e32 v71, 0xffff0000, v71
	v_pk_add_f32 v[22:23], v[22:23], v[70:71]
	v_lshlrev_b32_e32 v70, 16, v72
	v_and_b32_e32 v71, 0xffff0000, v72
	v_lshlrev_b32_e32 v72, 16, v73
	v_and_b32_e32 v73, 0xffff0000, v73
	v_pk_add_f32 v[18:19], v[18:19], v[72:73]
	v_pk_add_f32 v[16:17], v[16:17], v[70:71]
	v_pk_add_f32 v[20:21], v[20:21], v[78:79]
	v_pk_mul_f32 v[70:71], v[16:17], v[16:17]
	v_pk_mul_f32 v[72:73], v[18:19], v[18:19]
	v_pk_fma_f32 v[70:71], v[20:21], v[20:21], v[70:71]
	v_pk_fma_f32 v[72:73], v[22:23], v[22:23], v[72:73]
	v_add_f32_e32 v70, v70, v71
	v_add_f32_e32 v71, v72, v73
	v_add_f32_e32 v70, v70, v71
	v_add_f32_e32 v70, v80, v70
	v_mov_b32_e32 v71, v70
	s_nop 1
	v_permlane16_swap_b32_e32 v71, v70
	v_lshl_add_u64 v[84:85], v[130:131], 3, s[4:5]
	s_waitcnt lgkmcnt(0)
	v_add_f32_e32 v70, v70, v71
	v_mov_b32_e32 v71, v70
	s_nop 1
	v_permlane32_swap_b32_e32 v71, v70
	s_and_saveexec_b64 s[2:3], vcc
	s_cbranch_execz .LBB0_2968
	s_waitcnt lgkmcnt(0)
	v_add_f32_e32 v70, v70, v71
	v_mul_f32_e32 v70, 0x4b800000, v70
	v_trunc_f32_e32 v70, v70
	v_mul_f32_e32 v71, 0x2f800000, v70
	v_floor_f32_e32 v71, v71
	v_fmac_f32_e32 v70, 0xcf800000, v71
	v_cvt_u32_f32_e32 v70, v70
	v_cvt_u32_f32_e32 v71, v71
	global_atomic_add_x2 v[84:85], v[70:71], off
.LBB0_2968:
	s_or_b64 exec, exec, s[2:3]
	s_waitcnt vmcnt(1)
	v_lshlrev_b32_e32 v72, 16, v74
	v_and_b32_e32 v73, 0xffff0000, v74
	v_lshlrev_b32_e32 v70, 16, v75
	s_waitcnt lgkmcnt(0)
	v_and_b32_e32 v71, 0xffff0000, v75
	v_pk_add_f32 v[70:71], v[14:15], v[70:71]
	v_pk_add_f32 v[74:75], v[12:13], v[72:73]
	v_lshlrev_b32_e32 v12, 16, v76
	v_and_b32_e32 v13, 0xffff0000, v76
	v_lshlrev_b32_e32 v14, 16, v77
	v_and_b32_e32 v15, 0xffff0000, v77
	v_pk_add_f32 v[72:73], v[10:11], v[14:15]
	v_pk_add_f32 v[76:77], v[8:9], v[12:13]
	v_pk_mul_f32 v[10:11], v[72:73], v[72:73]
	v_pk_mul_f32 v[8:9], v[76:77], v[76:77]
	v_pk_fma_f32 v[10:11], v[70:71], v[70:71], v[10:11]
	v_pk_fma_f32 v[8:9], v[74:75], v[74:75], v[8:9]
	s_nop 0
	v_add_f32_e32 v8, v8, v9
	v_add_f32_e32 v9, v10, v11
	v_add_f32_e32 v12, v8, v9
	s_waitcnt vmcnt(0)
	v_lshlrev_b32_e32 v8, 16, v66
	v_and_b32_e32 v9, 0xffff0000, v66
	v_lshlrev_b32_e32 v10, 16, v67
	v_and_b32_e32 v11, 0xffff0000, v67
	v_pk_add_f32 v[66:67], v[6:7], v[10:11]
	v_pk_add_f32 v[78:79], v[4:5], v[8:9]
	v_lshlrev_b32_e32 v4, 16, v68
	v_and_b32_e32 v5, 0xffff0000, v68
	v_lshlrev_b32_e32 v6, 16, v69
	v_and_b32_e32 v7, 0xffff0000, v69
	v_pk_add_f32 v[68:69], v[2:3], v[6:7]
	v_pk_add_f32 v[80:81], v[0:1], v[4:5]
	v_pk_mul_f32 v[2:3], v[68:69], v[68:69]
	v_pk_mul_f32 v[0:1], v[80:81], v[80:81]
	v_pk_fma_f32 v[2:3], v[66:67], v[66:67], v[2:3]
	v_pk_fma_f32 v[0:1], v[78:79], v[78:79], v[0:1]
	s_nop 0
	v_add_f32_e32 v0, v0, v1
	v_add_f32_e32 v1, v2, v3
	v_add_f32_e32 v0, v0, v1
	v_add_f32_e32 v0, v12, v0
	v_mov_b32_e32 v1, v0
	s_nop 1
	v_permlane16_swap_b32_e32 v1, v0
	s_waitcnt lgkmcnt(0)
	v_add_f32_e32 v2, v0, v1
	v_mov_b32_e32 v3, v2
	s_nop 1
	v_permlane32_swap_b32_e32 v3, v2
	v_lshl_add_u64 v[0:1], v[90:91], 3, s[4:5]
	s_and_saveexec_b64 s[2:3], vcc
	s_cbranch_execz .LBB0_2970
	s_waitcnt lgkmcnt(0)
	v_add_f32_e32 v2, v2, v3
	v_mul_f32_e32 v2, 0x4b800000, v2
	v_trunc_f32_e32 v2, v2
	v_mul_f32_e32 v3, 0x2f800000, v2
	v_floor_f32_e32 v3, v3
	v_fmac_f32_e32 v2, 0xcf800000, v3
	v_cvt_u32_f32_e32 v2, v2
	v_cvt_u32_f32_e32 v3, v3
	global_atomic_add_x2 v[0:1], v[2:3], off
